# adds: dilated-phase start stagger (odd 8-groups of workgroups start half a step late so their load bursts overlap the others' compute) and all flat_load/flat_store converted to global_load/global_stor
# speedup vs baseline: 1.0099x; 1.0099x over previous
.LBB0_80:
	s_waitcnt lgkmcnt(0)
	global_load_dwordx4 v[12:15], v[2:3], off offset:-2048
	global_load_dwordx4 v[16:19], v[2:3], off offset:-1024
	global_load_dwordx4 v[20:23], v[2:3], off
	global_load_dwordx4 v[24:27], v[2:3], off offset:1024
	v_lshl_add_u64 v[28:29], s[20:21], 0, v[0:1]
	v_add_co_u32_e64 v28, s[2:3], s24, v28
	s_waitcnt vmcnt(0)
	v_mul_f32_e32 v11, v13, v13
	v_mul_f32_e32 v30, v15, v15
	s_waitcnt vmcnt(2)
	v_mul_f32_e32 v31, v17, v17
	v_mul_f32_e32 v32, v19, v19
	s_waitcnt vmcnt(1)
	v_mul_f32_e32 v33, v21, v21
	v_mul_f32_e32 v34, v23, v23
	v_fmac_f32_e32 v11, v12, v12
	v_fmac_f32_e32 v30, v14, v14
	v_fmac_f32_e32 v31, v16, v16
	v_fmac_f32_e32 v32, v18, v18
	s_waitcnt vmcnt(0)
	v_mul_f32_e32 v35, v25, v25
	v_mul_f32_e32 v36, v27, v27
	v_fmac_f32_e32 v33, v20, v20
	v_fmac_f32_e32 v34, v22, v22
	v_add_f32_e32 v11, v11, v30
	v_add_f32_e32 v30, v31, v32
	v_fmac_f32_e32 v35, v24, v24
	v_fmac_f32_e32 v36, v26, v26
	v_add_f32_e32 v31, v33, v34
	v_add_f32_e32 v11, v11, v30
	v_add_f32_e32 v32, v35, v36
	v_add_f32_e32 v11, v11, v31
	v_add_f32_e32 v11, v11, v32
	ds_bpermute_b32 v30, v4, v11
	v_bfe_u32 v37, v12, 16, 1
	v_bfe_u32 v39, v14, 16, 1
	v_bfe_u32 v44, v18, 16, 1
	v_bfe_u32 v38, v13, 16, 1
	s_waitcnt lgkmcnt(0)
	v_add_f32_e32 v11, v11, v30
	ds_bpermute_b32 v30, v5, v11
	v_bfe_u32 v41, v15, 16, 1
	v_bfe_u32 v45, v19, 16, 1
	v_add3_u32 v12, v12, v37, s13
	v_add3_u32 v14, v14, v39, s13
	s_waitcnt lgkmcnt(0)
	v_add_f32_e32 v11, v11, v30
	ds_bpermute_b32 v30, v6, v11
	v_add3_u32 v18, v18, v44, s13
	v_add3_u32 v13, v13, v38, s13
	v_add3_u32 v15, v15, v41, s13
	v_add3_u32 v19, v19, v45, s13
	s_waitcnt lgkmcnt(0)
	v_add_f32_e32 v11, v11, v30
	ds_bpermute_b32 v30, v7, v11
	v_lshrrev_b32_e32 v12, 16, v12
	v_lshrrev_b32_e32 v14, 16, v14
	v_lshrrev_b32_e32 v18, 16, v18
	v_and_or_b32 v12, v13, s15, v12
	s_waitcnt lgkmcnt(0)
	v_add_f32_e32 v11, v11, v30
	v_and_or_b32 v13, v15, s15, v14
	v_and_or_b32 v15, v19, s15, v18
	ds_bpermute_b32 v19, v8, v11
	v_bfe_u32 v42, v16, 16, 1
	v_bfe_u32 v46, v20, 16, 1
	v_bfe_u32 v48, v22, 16, 1
	v_bfe_u32 v43, v17, 16, 1
	v_bfe_u32 v47, v21, 16, 1
	v_bfe_u32 v49, v23, 16, 1
	v_add3_u32 v16, v16, v42, s13
	v_add3_u32 v20, v20, v46, s13
	v_add3_u32 v22, v22, v48, s13
	v_addc_co_u32_e64 v29, s[2:3], 0, v29, s[2:3]
	v_add3_u32 v17, v17, v43, s13
	v_add3_u32 v21, v21, v47, s13
	v_add3_u32 v23, v23, v49, s13
	v_lshrrev_b32_e32 v16, 16, v16
	v_lshrrev_b32_e32 v20, 16, v20
	v_lshrrev_b32_e32 v22, 16, v22
	s_waitcnt lgkmcnt(0)
	v_add_f32_e32 v11, v11, v19
	v_and_or_b32 v14, v17, s15, v16
	v_and_or_b32 v16, v21, s15, v20
	v_and_or_b32 v17, v23, s15, v22
	global_store_dwordx2 v[28:29], v[12:13], off
	global_store_dwordx2 v[28:29], v[14:15], off offset:512
	global_store_dwordx2 v[28:29], v[16:17], off offset:1024
	ds_bpermute_b32 v12, v9, v11
	v_bfe_u32 v50, v24, 16, 1
	v_bfe_u32 v52, v26, 16, 1
	v_bfe_u32 v51, v25, 16, 1
	v_add3_u32 v24, v24, v50, s13
	v_add3_u32 v26, v26, v52, s13
	v_bfe_u32 v14, v27, 16, 1
	v_add3_u32 v25, v25, v51, s13
	v_lshrrev_b32_e32 v24, 16, v24
	v_lshrrev_b32_e32 v13, 16, v26
	v_add3_u32 v14, v27, v14, s13
	v_and_or_b32 v18, v25, s15, v24
	v_and_or_b32 v19, v14, s15, v13
	global_store_dwordx2 v[28:29], v[18:19], off offset:1536
	s_and_saveexec_b64 s[10:11], vcc
	s_cbranch_execz .LBB0_79
	s_waitcnt lgkmcnt(0)
	v_add_f32_e32 v11, v11, v12
	v_fmamk_f32 v11, v11, 0x3a800000, v10
	v_mul_f32_e32 v12, 0x4b800000, v11
	v_cmp_gt_f32_e64 s[2:3], s25, v11
	s_add_u32 s28, s20, s22
	s_addc_u32 s29, s21, s23
	v_cndmask_b32_e64 v11, v11, v12, s[2:3]
	v_rsq_f32_e32 v11, v11
	s_nop 0
	v_mul_f32_e32 v12, 0x45800000, v11
	v_cndmask_b32_e64 v11, v11, v12, s[2:3]
	v_mov_b64_e32 v[12:13], s[28:29]
	global_store_dword v[12:13], v11, off
	s_branch .LBB0_79

.LBB0_84:
	v_ashrrev_i32_e32 v26, 4, v0
	v_ashrrev_i32_e32 v27, 31, v26
	v_lshl_add_u64 v[26:27], v[26:27], 2, s[0:1]
	global_load_dword v1, v[26:27], off
	v_add_co_u32_e32 v26, vcc, 0xfff00000, v2
	v_add_u32_e32 v0, s18, v0
	s_nop 0
	v_addc_co_u32_e32 v27, vcc, -1, v3, vcc
	v_cmp_lt_i32_e32 vcc, s13, v0
	s_or_b64 s[8:9], vcc, s[8:9]
	s_waitcnt vmcnt(0)
	v_cvt_f32_i32_e32 v1, v1
	v_mul_f32_e32 v1, v24, v1
	v_cvt_f64_f32_e32 v[28:29], v1
	v_mul_f64 v[30:31], v[28:29], s[10:11]
	v_rndne_f64_e32 v[30:31], v[30:31]
	v_fmac_f64_e32 v[28:29], s[20:21], v[30:31]
	v_fmac_f64_e32 v[28:29], s[22:23], v[30:31]
	v_cvt_i32_f64_e32 v1, v[30:31]
	v_mul_f64 v[30:31], v[28:29], v[28:29]
	v_fma_f64 v[32:33], s[24:25], v[30:31], v[4:5]
	v_fma_f64 v[34:35], s[26:27], v[30:31], v[14:15]
	v_fma_f64 v[32:33], v[30:31], v[32:33], v[6:7]
	v_fma_f64 v[34:35], v[30:31], v[34:35], v[16:17]
	v_fma_f64 v[32:33], v[30:31], v[32:33], v[8:9]
	v_fma_f64 v[34:35], v[30:31], v[34:35], v[18:19]
	v_fma_f64 v[32:33], v[30:31], v[32:33], v[10:11]
	v_fma_f64 v[34:35], v[30:31], v[34:35], v[20:21]
	v_fma_f64 v[32:33], v[30:31], v[32:33], v[12:13]
	v_fma_f64 v[34:35], v[30:31], v[34:35], v[22:23]
	v_and_b32_e32 v25, 3, v1
	v_and_b32_e32 v1, 1, v1
	v_fma_f64 v[32:33], v[30:31], v[32:33], 1.0
	v_fma_f64 v[34:35], v[30:31], v[34:35], -0.5
	v_mul_f64 v[28:29], v[28:29], v[32:33]
	v_fma_f64 v[30:31], v[30:31], v[34:35], 1.0
	v_cmp_eq_u32_e32 vcc, 0, v1
	v_cmp_eq_u32_e64 s[2:3], 1, v25
	s_nop 0
	v_cndmask_b32_e32 v1, v31, v29, vcc
	v_cndmask_b32_e32 v29, v29, v31, vcc
	v_cndmask_b32_e32 v32, v30, v28, vcc
	v_cndmask_b32_e32 v28, v28, v30, vcc
	v_xor_b32_e32 v30, 0x80000000, v29
	v_xor_b32_e32 v31, 0x80000000, v1
	v_cmp_eq_u32_e32 vcc, 2, v25
	v_cndmask_b32_e64 v29, v29, v30, s[2:3]
	v_xor_b32_e32 v30, 0x80000000, v29
	v_cndmask_b32_e32 v1, v1, v31, vcc
	v_xor_b32_e32 v31, 0x80000000, v1
	v_cmp_eq_u32_e64 s[2:3], 3, v25
	v_cndmask_b32_e32 v29, v29, v30, vcc
	s_nop 0
	v_cndmask_b32_e64 v33, v1, v31, s[2:3]
	v_cvt_f32_f64_e32 v1, v[28:29]
	v_cvt_f32_f64_e32 v25, v[32:33]
	global_store_dword v[26:27], v1, off
	global_store_dword v[2:3], v25, off
	v_lshl_add_u64 v[2:3], v[2:3], 0, s[6:7]
	s_andn2_b64 exec, exec, s[8:9]
	s_cbranch_execnz .LBB0_84

.LBB0_138:
	global_load_dword v4, v[0:1], off
	v_add_u32_e32 v2, 0x200, v2
	v_cmp_lt_i32_e32 vcc, s8, v2
	v_lshl_add_u64 v[0:1], v[0:1], 0, s[6:7]
	s_or_b64 s[4:5], vcc, s[4:5]
	s_waitcnt vmcnt(0) lgkmcnt(0)
	ds_write_b32 v3, v4
	v_add_u32_e32 v3, 0x800, v3
	s_andn2_b64 exec, exec, s[4:5]
	s_cbranch_execnz .LBB0_138

.LBB0_154:
	v_lshl_add_u32 v149, s34, 8, v129
	v_and_b32_e32 v150, 0x7cf, v149
	v_lshl_add_u32 v150, v150, 2, s53
	ds_read_b32 v153, v150
	v_pk_mul_f32 v[124:125], v[124:125], v[116:117]
	v_pk_mul_f32 v[126:127], v[126:127], v[118:119]
	v_pk_mul_f32 v[120:121], v[120:121], v[112:113]
	v_pk_mul_f32 v[122:123], v[122:123], v[114:115]
	s_waitcnt lgkmcnt(0)
	v_mul_f32_e32 v152, 0xbfb8aa3b, v153
	v_pk_mul_f32 v[116:117], v[116:117], v[152:153] op_sel_hi:[1,0]
	v_pk_mul_f32 v[118:119], v[118:119], v[152:153] op_sel_hi:[1,0]
	v_exp_f32_e32 v116, v116
	v_exp_f32_e32 v117, v117
	v_pk_mul_f32 v[112:113], v[112:113], v[152:153] op_sel_hi:[1,0]
	v_exp_f32_e32 v118, v118
	v_exp_f32_e32 v119, v119
	v_exp_f32_e32 v112, v112
	v_exp_f32_e32 v113, v113
	v_pk_mul_f32 v[114:115], v[114:115], v[152:153] op_sel_hi:[1,0]
	v_pk_add_f32 v[116:117], v[116:117], 1.0 op_sel_hi:[1,0]
	v_exp_f32_e32 v114, v114
	v_exp_f32_e32 v115, v115
	v_rcp_f32_e32 v116, v116
	v_rcp_f32_e32 v117, v117
	v_pk_add_f32 v[118:119], v[118:119], 1.0 op_sel_hi:[1,0]
	v_pk_add_f32 v[112:113], v[112:113], 1.0 op_sel_hi:[1,0]
	v_rcp_f32_e32 v118, v118
	v_rcp_f32_e32 v119, v119
	v_rcp_f32_e32 v112, v112
	v_rcp_f32_e32 v113, v113
	v_pk_add_f32 v[114:115], v[114:115], 1.0 op_sel_hi:[1,0]
	v_mul_f32_e32 v154, v153, v153
	v_rcp_f32_e32 v114, v114
	v_rcp_f32_e32 v115, v115
	v_pk_mul_f32 v[124:125], v[124:125], v[154:155] op_sel_hi:[1,0]
	v_pk_mul_f32 v[120:121], v[120:121], v[154:155] op_sel_hi:[1,0]
	v_pk_mul_f32 v[116:117], v[124:125], v[116:117]
	v_pk_mul_f32 v[124:125], v[126:127], v[154:155] op_sel_hi:[1,0]
	v_lshl_add_u32 v150, s59, 7, v147
	v_pk_mul_f32 v[118:119], v[124:125], v[118:119]
	v_pk_mul_f32 v[112:113], v[120:121], v[112:113]
	v_pk_mul_f32 v[120:121], v[122:123], v[154:155] op_sel_hi:[1,0]
	v_ashrrev_i32_e32 v151, 31, v150
	v_pk_mul_f32 v[114:115], v[120:121], v[114:115]
	v_cvt_pk_bf16_f32 v116, v116, v117
	v_cvt_pk_bf16_f32 v117, v118, v119
	v_cvt_pk_bf16_f32 v118, v112, v113
	v_mov_b64_e32 v[112:113], s[18:19]
	v_cvt_pk_bf16_f32 v119, v114, v115
	v_mad_i64_i32 v[120:121], s[0:1], v149, s54, v[112:113]
	v_lshlrev_b64 v[114:115], 1, v[150:151]
	v_lshl_add_u64 v[120:121], v[120:121], 0, v[114:115]
	global_store_dwordx4 v[120:121], v[116:119], off
	v_pk_mul_f32 v[108:109], v[108:109], v[100:101]
	v_pk_mul_f32 v[104:105], v[104:105], v[96:97]
	v_bitop3_b32 v116, v149, s55, 16 bitop3:0xc8
	v_lshl_add_u32 v116, v116, 2, s53
	ds_read_b32 v117, v116
	v_pk_mul_f32 v[106:107], v[106:107], v[98:99]
	v_pk_mul_f32 v[110:111], v[110:111], v[102:103]
	v_or_b32_e32 v119, 16, v149
	v_pk_mul_f32 v[92:93], v[92:93], v[84:85]
	s_waitcnt lgkmcnt(0)
	v_mul_f32_e32 v116, 0xbfb8aa3b, v117
	v_pk_mul_f32 v[100:101], v[100:101], v[116:117] op_sel_hi:[1,0]
	v_pk_mul_f32 v[96:97], v[96:97], v[116:117] op_sel_hi:[1,0]
	v_exp_f32_e32 v100, v100
	v_exp_f32_e32 v101, v101
	v_exp_f32_e32 v96, v96
	v_exp_f32_e32 v97, v97
	v_pk_mul_f32 v[98:99], v[98:99], v[116:117] op_sel_hi:[1,0]
	v_pk_mul_f32 v[102:103], v[102:103], v[116:117] op_sel_hi:[1,0]
	v_exp_f32_e32 v98, v98
	v_exp_f32_e32 v99, v99
	v_exp_f32_e32 v102, v102
	v_exp_f32_e32 v103, v103
	v_pk_add_f32 v[100:101], v[100:101], 1.0 op_sel_hi:[1,0]
	v_pk_add_f32 v[96:97], v[96:97], 1.0 op_sel_hi:[1,0]
	v_rcp_f32_e32 v100, v100
	v_rcp_f32_e32 v101, v101
	v_rcp_f32_e32 v96, v96
	v_rcp_f32_e32 v97, v97
	v_pk_add_f32 v[98:99], v[98:99], 1.0 op_sel_hi:[1,0]
	v_mul_f32_e32 v118, v117, v117
	v_rcp_f32_e32 v98, v98
	v_rcp_f32_e32 v99, v99
	v_pk_add_f32 v[102:103], v[102:103], 1.0 op_sel_hi:[1,0]
	v_pk_mul_f32 v[108:109], v[108:109], v[118:119] op_sel_hi:[1,0]
	v_rcp_f32_e32 v102, v102
	v_rcp_f32_e32 v103, v103
	v_pk_mul_f32 v[104:105], v[104:105], v[118:119] op_sel_hi:[1,0]
	v_pk_mul_f32 v[100:101], v[108:109], v[100:101]
	v_pk_mul_f32 v[104:105], v[104:105], v[96:97]
	v_pk_mul_f32 v[96:97], v[106:107], v[118:119] op_sel_hi:[1,0]
	v_pk_mul_f32 v[108:109], v[110:111], v[118:119] op_sel_hi:[1,0]
	v_pk_mul_f32 v[106:107], v[96:97], v[98:99]
	v_cvt_pk_bf16_f32 v96, v100, v101
	v_mad_i64_i32 v[100:101], s[0:1], v119, s54, v[112:113]
	v_lshl_add_u64 v[100:101], v[100:101], 0, v[114:115]
	v_pk_mul_f32 v[102:103], v[108:109], v[102:103]
	v_pk_mul_f32 v[88:89], v[88:89], v[80:81]
	v_cvt_pk_bf16_f32 v97, v102, v103
	v_cvt_pk_bf16_f32 v98, v104, v105
	v_cvt_pk_bf16_f32 v99, v106, v107
	global_store_dwordx4 v[100:101], v[96:99], off
	v_pk_mul_f32 v[90:91], v[90:91], v[82:83]
	v_pk_mul_f32 v[94:95], v[94:95], v[86:87]
	v_bitop3_b32 v96, v149, s56, 32 bitop3:0xc8
	v_lshl_add_u32 v96, v96, 2, s53
	ds_read_b32 v97, v96
	v_or_b32_e32 v99, 32, v149
	v_pk_mul_f32 v[76:77], v[76:77], v[64:65]
	v_pk_mul_f32 v[72:73], v[72:73], v[56:57]
	v_pk_mul_f32 v[74:75], v[74:75], v[58:59]
	s_waitcnt lgkmcnt(0)
	v_mul_f32_e32 v96, 0xbfb8aa3b, v97
	v_pk_mul_f32 v[84:85], v[84:85], v[96:97] op_sel_hi:[1,0]
	v_pk_mul_f32 v[80:81], v[80:81], v[96:97] op_sel_hi:[1,0]
	v_exp_f32_e32 v84, v84
	v_exp_f32_e32 v85, v85
	v_exp_f32_e32 v80, v80
	v_exp_f32_e32 v81, v81
	v_pk_mul_f32 v[82:83], v[82:83], v[96:97] op_sel_hi:[1,0]
	v_pk_mul_f32 v[86:87], v[86:87], v[96:97] op_sel_hi:[1,0]
	v_exp_f32_e32 v82, v82
	v_exp_f32_e32 v83, v83
	v_exp_f32_e32 v86, v86
	v_exp_f32_e32 v87, v87
	v_pk_add_f32 v[84:85], v[84:85], 1.0 op_sel_hi:[1,0]
	v_pk_add_f32 v[80:81], v[80:81], 1.0 op_sel_hi:[1,0]
	v_rcp_f32_e32 v84, v84
	v_rcp_f32_e32 v85, v85
	v_rcp_f32_e32 v80, v80
	v_rcp_f32_e32 v81, v81
	v_pk_add_f32 v[82:83], v[82:83], 1.0 op_sel_hi:[1,0]
	v_mul_f32_e32 v98, v97, v97
	v_rcp_f32_e32 v82, v82
	v_rcp_f32_e32 v83, v83
	v_pk_add_f32 v[86:87], v[86:87], 1.0 op_sel_hi:[1,0]
	v_pk_mul_f32 v[92:93], v[92:93], v[98:99] op_sel_hi:[1,0]
	v_rcp_f32_e32 v86, v86
	v_rcp_f32_e32 v87, v87
	v_pk_mul_f32 v[88:89], v[88:89], v[98:99] op_sel_hi:[1,0]
	v_pk_mul_f32 v[84:85], v[92:93], v[84:85]
	v_pk_mul_f32 v[88:89], v[88:89], v[80:81]
	v_pk_mul_f32 v[80:81], v[90:91], v[98:99] op_sel_hi:[1,0]
	v_pk_mul_f32 v[92:93], v[94:95], v[98:99] op_sel_hi:[1,0]
	v_pk_mul_f32 v[90:91], v[80:81], v[82:83]
	v_cvt_pk_bf16_f32 v80, v84, v85
	v_mad_i64_i32 v[84:85], s[0:1], v99, s54, v[112:113]
	v_lshl_add_u64 v[84:85], v[84:85], 0, v[114:115]
	v_pk_mul_f32 v[86:87], v[92:93], v[86:87]
	v_pk_mul_f32 v[78:79], v[78:79], v[66:67]
	v_cvt_pk_bf16_f32 v81, v86, v87
	v_cvt_pk_bf16_f32 v82, v88, v89
	v_cvt_pk_bf16_f32 v83, v90, v91
	global_store_dwordx4 v[84:85], v[80:83], off
	v_pk_mul_f32 v[60:61], v[60:61], v[48:49]
	v_pk_mul_f32 v[62:63], v[62:63], v[50:51]
	v_bitop3_b32 v80, v149, s57, 48 bitop3:0xc8
	v_lshl_add_u32 v80, v80, 2, s53
	ds_read_b32 v81, v80
	v_or_b32_e32 v83, 48, v149
	v_pk_mul_f32 v[44:45], v[44:45], v[36:37]
	v_pk_mul_f32 v[40:41], v[40:41], v[32:33]
	v_pk_mul_f32 v[42:43], v[42:43], v[34:35]
	s_waitcnt lgkmcnt(0)
	v_mul_f32_e32 v80, 0xbfb8aa3b, v81
	v_pk_mul_f32 v[64:65], v[64:65], v[80:81] op_sel_hi:[1,0]
	v_pk_mul_f32 v[56:57], v[56:57], v[80:81] op_sel_hi:[1,0]
	v_exp_f32_e32 v64, v64
	v_exp_f32_e32 v65, v65
	v_exp_f32_e32 v56, v56
	v_exp_f32_e32 v57, v57
	v_pk_mul_f32 v[58:59], v[58:59], v[80:81] op_sel_hi:[1,0]
	v_pk_mul_f32 v[66:67], v[66:67], v[80:81] op_sel_hi:[1,0]
	v_exp_f32_e32 v58, v58
	v_exp_f32_e32 v59, v59
	v_exp_f32_e32 v66, v66
	v_exp_f32_e32 v67, v67
	v_pk_add_f32 v[64:65], v[64:65], 1.0 op_sel_hi:[1,0]
	v_pk_add_f32 v[56:57], v[56:57], 1.0 op_sel_hi:[1,0]
	v_rcp_f32_e32 v64, v64
	v_rcp_f32_e32 v65, v65
	v_rcp_f32_e32 v56, v56
	v_rcp_f32_e32 v57, v57
	v_pk_add_f32 v[58:59], v[58:59], 1.0 op_sel_hi:[1,0]
	v_pk_add_f32 v[66:67], v[66:67], 1.0 op_sel_hi:[1,0]
	v_rcp_f32_e32 v58, v58
	v_rcp_f32_e32 v59, v59
	v_mul_f32_e32 v82, v81, v81
	v_rcp_f32_e32 v66, v66
	v_rcp_f32_e32 v67, v67
	v_pk_mul_f32 v[76:77], v[76:77], v[82:83] op_sel_hi:[1,0]
	v_pk_mul_f32 v[72:73], v[72:73], v[82:83] op_sel_hi:[1,0]
	v_pk_mul_f32 v[64:65], v[76:77], v[64:65]
	v_pk_mul_f32 v[72:73], v[72:73], v[56:57]
	v_pk_mul_f32 v[56:57], v[74:75], v[82:83] op_sel_hi:[1,0]
	v_pk_mul_f32 v[76:77], v[78:79], v[82:83] op_sel_hi:[1,0]
	v_pk_mul_f32 v[74:75], v[56:57], v[58:59]
	v_cvt_pk_bf16_f32 v56, v64, v65
	v_mad_i64_i32 v[64:65], s[0:1], v83, s54, v[112:113]
	v_pk_mul_f32 v[66:67], v[76:77], v[66:67]
	v_lshl_add_u64 v[64:65], v[64:65], 0, v[114:115]
	v_cvt_pk_bf16_f32 v57, v66, v67
	v_cvt_pk_bf16_f32 v58, v72, v73
	v_add_u32_e32 v72, 0x80, v149
	v_cvt_pk_bf16_f32 v59, v74, v75
	global_store_dwordx4 v[64:65], v[56:59], off
	v_pk_mul_f32 v[66:67], v[68:69], v[52:53]
	v_pk_mul_f32 v[64:65], v[70:71], v[54:55]
	v_and_b32_e32 v56, 0x7cf, v72
	v_lshl_add_u32 v56, v56, 2, s53
	ds_read_b32 v57, v56
	v_pk_mul_f32 v[46:47], v[46:47], v[38:39]
	v_pk_mul_f32 v[28:29], v[28:29], v[20:21]
	v_pk_mul_f32 v[24:25], v[24:25], v[12:13]
	v_pk_mul_f32 v[26:27], v[26:27], v[14:15]
	s_waitcnt lgkmcnt(0)
	v_mul_f32_e32 v56, 0xbfb8aa3b, v57
	v_pk_mul_f32 v[52:53], v[52:53], v[56:57] op_sel_hi:[1,0]
	v_pk_mul_f32 v[48:49], v[48:49], v[56:57] op_sel_hi:[1,0]
	v_exp_f32_e32 v52, v52
	v_exp_f32_e32 v53, v53
	v_exp_f32_e32 v48, v48
	v_exp_f32_e32 v49, v49
	v_pk_mul_f32 v[50:51], v[50:51], v[56:57] op_sel_hi:[1,0]
	v_pk_mul_f32 v[54:55], v[54:55], v[56:57] op_sel_hi:[1,0]
	v_exp_f32_e32 v50, v50
	v_exp_f32_e32 v51, v51
	v_exp_f32_e32 v54, v54
	v_exp_f32_e32 v55, v55
	v_pk_add_f32 v[52:53], v[52:53], 1.0 op_sel_hi:[1,0]
	v_pk_add_f32 v[48:49], v[48:49], 1.0 op_sel_hi:[1,0]
	v_rcp_f32_e32 v52, v52
	v_rcp_f32_e32 v53, v53
	v_rcp_f32_e32 v48, v48
	v_rcp_f32_e32 v49, v49
	v_pk_add_f32 v[50:51], v[50:51], 1.0 op_sel_hi:[1,0]
	v_pk_add_f32 v[54:55], v[54:55], 1.0 op_sel_hi:[1,0]
	v_rcp_f32_e32 v50, v50
	v_rcp_f32_e32 v51, v51
	v_mul_f32_e32 v58, v57, v57
	v_rcp_f32_e32 v54, v54
	v_rcp_f32_e32 v55, v55
	v_pk_mul_f32 v[66:67], v[66:67], v[58:59] op_sel_hi:[1,0]
	v_pk_mul_f32 v[56:57], v[60:61], v[58:59] op_sel_hi:[1,0]
	v_pk_mul_f32 v[52:53], v[66:67], v[52:53]
	v_pk_mul_f32 v[56:57], v[56:57], v[48:49]
	v_pk_mul_f32 v[48:49], v[62:63], v[58:59] op_sel_hi:[1,0]
	v_pk_mul_f32 v[64:65], v[64:65], v[58:59] op_sel_hi:[1,0]
	v_pk_mul_f32 v[58:59], v[48:49], v[50:51]
	v_cvt_pk_bf16_f32 v48, v52, v53
	v_mad_i64_i32 v[52:53], s[0:1], v72, s54, v[112:113]
	v_pk_mul_f32 v[54:55], v[64:65], v[54:55]
	v_lshl_add_u64 v[52:53], v[52:53], 0, v[114:115]
	v_cvt_pk_bf16_f32 v49, v54, v55
	v_cvt_pk_bf16_f32 v50, v56, v57
	v_cvt_pk_bf16_f32 v51, v58, v59
	global_store_dwordx4 v[52:53], v[48:51], off
	v_pk_mul_f32 v[30:31], v[30:31], v[22:23]
	v_pk_mul_f32 v[16:17], v[16:17], v[4:5]
	v_add_u32_e32 v49, 0x90, v149
	v_and_b32_e32 v48, 0x7df, v49
	v_lshl_add_u32 v48, v48, 2, s53
	ds_read_b32 v50, v48
	v_pk_mul_f32 v[10:11], v[10:11], v[2:3]
	v_pk_mul_f32 v[8:9], v[8:9], v[0:1]
	s_and_b64 vcc, exec, s[2:3]
	s_waitcnt lgkmcnt(0)
	v_mul_f32_e32 v48, 0xbfb8aa3b, v50
	v_pk_mul_f32 v[36:37], v[36:37], v[48:49] op_sel_hi:[1,0]
	v_pk_mul_f32 v[32:33], v[32:33], v[48:49] op_sel_hi:[1,0]
	v_exp_f32_e32 v36, v36
	v_exp_f32_e32 v37, v37
	v_exp_f32_e32 v32, v32
	v_exp_f32_e32 v33, v33
	v_pk_mul_f32 v[34:35], v[34:35], v[48:49] op_sel_hi:[1,0]
	v_pk_mul_f32 v[38:39], v[38:39], v[48:49] op_sel_hi:[1,0]
	v_exp_f32_e32 v34, v34
	v_exp_f32_e32 v35, v35
	v_exp_f32_e32 v38, v38
	v_exp_f32_e32 v39, v39
	v_pk_add_f32 v[36:37], v[36:37], 1.0 op_sel_hi:[1,0]
	v_pk_add_f32 v[32:33], v[32:33], 1.0 op_sel_hi:[1,0]
	v_rcp_f32_e32 v36, v36
	v_rcp_f32_e32 v37, v37
	v_rcp_f32_e32 v32, v32
	v_rcp_f32_e32 v33, v33
	v_pk_add_f32 v[34:35], v[34:35], 1.0 op_sel_hi:[1,0]
	v_pk_add_f32 v[38:39], v[38:39], 1.0 op_sel_hi:[1,0]
	v_rcp_f32_e32 v34, v34
	v_rcp_f32_e32 v35, v35
	v_mul_f32_e32 v50, v50, v50
	v_rcp_f32_e32 v38, v38
	v_rcp_f32_e32 v39, v39
	v_pk_mul_f32 v[44:45], v[44:45], v[50:51] op_sel_hi:[1,0]
	v_pk_mul_f32 v[40:41], v[40:41], v[50:51] op_sel_hi:[1,0]
	v_pk_mul_f32 v[36:37], v[44:45], v[36:37]
	v_pk_mul_f32 v[40:41], v[40:41], v[32:33]
	v_pk_mul_f32 v[32:33], v[42:43], v[50:51] op_sel_hi:[1,0]
	v_pk_mul_f32 v[44:45], v[46:47], v[50:51] op_sel_hi:[1,0]
	v_pk_mul_f32 v[42:43], v[32:33], v[34:35]
	v_cvt_pk_bf16_f32 v32, v36, v37
	v_mad_i64_i32 v[36:37], s[0:1], v49, s54, v[112:113]
	v_pk_mul_f32 v[38:39], v[44:45], v[38:39]
	v_lshl_add_u64 v[36:37], v[36:37], 0, v[114:115]
	v_cvt_pk_bf16_f32 v33, v38, v39
	v_cvt_pk_bf16_f32 v34, v40, v41
	v_cvt_pk_bf16_f32 v35, v42, v43
	global_store_dwordx4 v[36:37], v[32:35], off
	s_nop 1
	v_add_u32_e32 v33, 0xa0, v149
	v_and_b32_e32 v32, 0x7ef, v33
	v_lshl_add_u32 v32, v32, 2, s53
	ds_read_b32 v34, v32
	s_waitcnt lgkmcnt(0)
	v_mul_f32_e32 v32, 0xbfb8aa3b, v34
	v_pk_mul_f32 v[20:21], v[20:21], v[32:33] op_sel_hi:[1,0]
	v_pk_mul_f32 v[12:13], v[12:13], v[32:33] op_sel_hi:[1,0]
	v_exp_f32_e32 v20, v20
	v_exp_f32_e32 v21, v21
	v_exp_f32_e32 v12, v12
	v_exp_f32_e32 v13, v13
	v_pk_mul_f32 v[14:15], v[14:15], v[32:33] op_sel_hi:[1,0]
	v_pk_mul_f32 v[22:23], v[22:23], v[32:33] op_sel_hi:[1,0]
	v_exp_f32_e32 v14, v14
	v_exp_f32_e32 v15, v15
	v_exp_f32_e32 v22, v22
	v_exp_f32_e32 v23, v23
	v_pk_add_f32 v[20:21], v[20:21], 1.0 op_sel_hi:[1,0]
	v_pk_add_f32 v[12:13], v[12:13], 1.0 op_sel_hi:[1,0]
	v_rcp_f32_e32 v20, v20
	v_rcp_f32_e32 v21, v21
	v_rcp_f32_e32 v12, v12
	v_rcp_f32_e32 v13, v13
	v_pk_add_f32 v[14:15], v[14:15], 1.0 op_sel_hi:[1,0]
	v_pk_add_f32 v[22:23], v[22:23], 1.0 op_sel_hi:[1,0]
	v_rcp_f32_e32 v14, v14
	v_rcp_f32_e32 v15, v15
	v_mul_f32_e32 v34, v34, v34
	v_rcp_f32_e32 v22, v22
	v_rcp_f32_e32 v23, v23
	v_pk_mul_f32 v[28:29], v[28:29], v[34:35] op_sel_hi:[1,0]
	v_pk_mul_f32 v[24:25], v[24:25], v[34:35] op_sel_hi:[1,0]
	v_pk_mul_f32 v[20:21], v[28:29], v[20:21]
	v_pk_mul_f32 v[24:25], v[24:25], v[12:13]
	v_pk_mul_f32 v[12:13], v[26:27], v[34:35] op_sel_hi:[1,0]
	v_pk_mul_f32 v[28:29], v[30:31], v[34:35] op_sel_hi:[1,0]
	v_pk_mul_f32 v[26:27], v[12:13], v[14:15]
	v_cvt_pk_bf16_f32 v12, v20, v21
	v_mad_i64_i32 v[20:21], s[0:1], v33, s54, v[112:113]
	v_pk_mul_f32 v[22:23], v[28:29], v[22:23]
	v_lshl_add_u64 v[20:21], v[20:21], 0, v[114:115]
	v_cvt_pk_bf16_f32 v13, v22, v23
	v_cvt_pk_bf16_f32 v14, v24, v25
	v_cvt_pk_bf16_f32 v15, v26, v27
	global_store_dwordx4 v[20:21], v[12:15], off
	s_nop 1
	v_add_u32_e32 v13, 0xb0, v149
	v_and_b32_e32 v12, 0x7ff, v13
	v_lshl_add_u32 v12, v12, 2, s53
	ds_read_b32 v20, v12
	v_pk_mul_f32 v[14:15], v[18:19], v[6:7]
	s_waitcnt lgkmcnt(0)
	v_mul_f32_e32 v18, 0xbfb8aa3b, v20
	v_pk_mul_f32 v[6:7], v[6:7], v[18:19] op_sel_hi:[1,0]
	v_pk_mul_f32 v[4:5], v[4:5], v[18:19] op_sel_hi:[1,0]
	v_exp_f32_e32 v6, v6
	v_exp_f32_e32 v7, v7
	v_pk_mul_f32 v[2:3], v[2:3], v[18:19] op_sel_hi:[1,0]
	v_pk_mul_f32 v[0:1], v[0:1], v[18:19] op_sel_hi:[1,0]
	v_exp_f32_e32 v4, v4
	v_exp_f32_e32 v5, v5
	v_exp_f32_e32 v2, v2
	v_exp_f32_e32 v3, v3
	v_exp_f32_e32 v0, v0
	v_exp_f32_e32 v1, v1
	v_pk_add_f32 v[6:7], v[6:7], 1.0 op_sel_hi:[1,0]
	v_pk_add_f32 v[4:5], v[4:5], 1.0 op_sel_hi:[1,0]
	v_rcp_f32_e32 v6, v6
	v_rcp_f32_e32 v7, v7
	v_pk_add_f32 v[2:3], v[2:3], 1.0 op_sel_hi:[1,0]
	v_pk_add_f32 v[0:1], v[0:1], 1.0 op_sel_hi:[1,0]
	v_rcp_f32_e32 v4, v4
	v_rcp_f32_e32 v5, v5
	v_rcp_f32_e32 v2, v2
	v_rcp_f32_e32 v3, v3
	v_rcp_f32_e32 v0, v0
	v_rcp_f32_e32 v1, v1
	v_mul_f32_e32 v12, v20, v20
	v_pk_mul_f32 v[14:15], v[14:15], v[12:13] op_sel_hi:[1,0]
	v_pk_mul_f32 v[10:11], v[10:11], v[12:13] op_sel_hi:[1,0]
	v_pk_mul_f32 v[6:7], v[14:15], v[6:7]
	v_pk_mul_f32 v[14:15], v[16:17], v[12:13] op_sel_hi:[1,0]
	v_pk_mul_f32 v[8:9], v[8:9], v[12:13] op_sel_hi:[1,0]
	v_pk_mul_f32 v[4:5], v[14:15], v[4:5]
	v_pk_mul_f32 v[2:3], v[10:11], v[2:3]
	v_pk_mul_f32 v[0:1], v[8:9], v[0:1]
	s_nop 0
	v_cvt_pk_bf16_f32 v0, v0, v1
	v_cvt_pk_bf16_f32 v1, v2, v3
	v_cvt_pk_bf16_f32 v2, v4, v5
	v_mad_i64_i32 v[4:5], s[0:1], v13, s54, v[112:113]
	v_cvt_pk_bf16_f32 v3, v6, v7
	v_lshl_add_u64 v[4:5], v[4:5], 0, v[114:115]
	s_mov_b64 s[0:1], -1
	global_store_dwordx4 v[4:5], v[0:3], off
	s_cbranch_vccnz .LBB0_144
	s_andn2_b64 vcc, exec, s[10:11]
	v_pk_mov_b32 v[116:117], 0, 0
	v_pk_mov_b32 v[118:119], 0, 0
	v_pk_mov_b32 v[112:113], 0, 0
	v_pk_mov_b32 v[114:115], 0, 0
	v_pk_mov_b32 v[100:101], 0, 0
	v_pk_mov_b32 v[102:103], 0, 0
	v_pk_mov_b32 v[96:97], 0, 0
	v_pk_mov_b32 v[98:99], 0, 0
	v_pk_mov_b32 v[84:85], 0, 0
	v_pk_mov_b32 v[86:87], 0, 0
	v_pk_mov_b32 v[80:81], 0, 0
	v_pk_mov_b32 v[82:83], 0, 0
	v_pk_mov_b32 v[64:65], 0, 0
	v_pk_mov_b32 v[66:67], 0, 0
	v_pk_mov_b32 v[56:57], 0, 0
	v_pk_mov_b32 v[58:59], 0, 0
	v_pk_mov_b32 v[124:125], 0, 0
	v_pk_mov_b32 v[126:127], 0, 0
	v_pk_mov_b32 v[120:121], 0, 0
	v_pk_mov_b32 v[122:123], 0, 0
	v_pk_mov_b32 v[108:109], 0, 0
	v_pk_mov_b32 v[110:111], 0, 0
	v_pk_mov_b32 v[104:105], 0, 0
	v_pk_mov_b32 v[106:107], 0, 0
	v_pk_mov_b32 v[92:93], 0, 0
	v_pk_mov_b32 v[94:95], 0, 0
	v_pk_mov_b32 v[88:89], 0, 0
	v_pk_mov_b32 v[90:91], 0, 0
	v_pk_mov_b32 v[76:77], 0, 0
	v_pk_mov_b32 v[78:79], 0, 0
	v_pk_mov_b32 v[72:73], 0, 0
	v_pk_mov_b32 v[74:75], 0, 0
	v_pk_mov_b32 v[52:53], 0, 0
	v_pk_mov_b32 v[54:55], 0, 0
	v_pk_mov_b32 v[48:49], 0, 0
	v_pk_mov_b32 v[50:51], 0, 0
	v_pk_mov_b32 v[36:37], 0, 0
	v_pk_mov_b32 v[38:39], 0, 0
	v_pk_mov_b32 v[32:33], 0, 0
	v_pk_mov_b32 v[34:35], 0, 0
	v_pk_mov_b32 v[20:21], 0, 0
	v_pk_mov_b32 v[22:23], 0, 0
	v_pk_mov_b32 v[12:13], 0, 0
	v_pk_mov_b32 v[14:15], 0, 0
	v_pk_mov_b32 v[0:1], 0, 0
	v_pk_mov_b32 v[2:3], 0, 0
	v_pk_mov_b32 v[4:5], 0, 0
	v_pk_mov_b32 v[6:7], 0, 0
	v_pk_mov_b32 v[68:69], 0, 0
	v_pk_mov_b32 v[70:71], 0, 0
	v_pk_mov_b32 v[60:61], 0, 0
	v_pk_mov_b32 v[62:63], 0, 0
	v_pk_mov_b32 v[44:45], 0, 0
	v_pk_mov_b32 v[46:47], 0, 0
	v_pk_mov_b32 v[40:41], 0, 0
	v_pk_mov_b32 v[42:43], 0, 0
	v_pk_mov_b32 v[28:29], 0, 0
	v_pk_mov_b32 v[30:31], 0, 0
	v_pk_mov_b32 v[24:25], 0, 0
	v_pk_mov_b32 v[26:27], 0, 0
	v_pk_mov_b32 v[8:9], 0, 0
	v_pk_mov_b32 v[10:11], 0, 0
	v_pk_mov_b32 v[16:17], 0, 0
	v_pk_mov_b32 v[18:19], 0, 0
	s_cbranch_vccnz .LBB0_143
	s_barrier
	s_branch .LBB0_143

.LBB0_281:
	v_lshl_add_u32 v146, s58, 8, v148
	v_ashrrev_i32_e32 v147, 31, v146
	v_lshl_add_u32 v144, s18, 8, v150
	v_lshlrev_b64 v[154:155], 11, v[146:147]
	v_ashrrev_i32_e32 v145, 31, v144
	v_lshl_add_u64 v[154:155], s[22:23], 0, v[154:155]
	v_lshl_add_u64 v[158:159], v[144:145], 1, v[154:155]
	global_load_dwordx4 v[154:157], v[158:159], off
	s_lshl_b32 s36, s18, 2
	s_ashr_i32 s37, s36, 31
	s_waitcnt vmcnt(0) lgkmcnt(0)
	v_lshlrev_b32_e32 v160, 16, v154
	v_and_b32_e32 v161, 0xffff0000, v154
	v_lshlrev_b32_e32 v154, 16, v155
	v_and_b32_e32 v155, 0xffff0000, v155
	v_lshlrev_b32_e32 v162, 16, v156
	v_and_b32_e32 v163, 0xffff0000, v156
	v_lshlrev_b32_e32 v156, 16, v157
	v_and_b32_e32 v157, 0xffff0000, v157
	v_pk_fma_f32 v[154:155], v[126:127], 0.5, v[154:155] op_sel_hi:[1,0,1]
	v_pk_fma_f32 v[160:161], v[124:125], 0.5, v[160:161] op_sel_hi:[1,0,1]
	v_pk_fma_f32 v[156:157], v[122:123], 0.5, v[156:157] op_sel_hi:[1,0,1]
	v_pk_fma_f32 v[162:163], v[120:121], 0.5, v[162:163] op_sel_hi:[1,0,1]
	v_cvt_pk_bf16_f32 v120, v160, v161
	v_cvt_pk_bf16_f32 v121, v154, v155
	v_mul_f32_e32 v161, v161, v161
	v_cvt_pk_bf16_f32 v122, v162, v163
	v_cvt_pk_bf16_f32 v123, v156, v157
	global_load_dwordx4 v[124:127], v[158:159], off offset:256
	v_mul_f32_e32 v155, v155, v155
	v_mul_f32_e32 v163, v163, v163
	v_mul_f32_e32 v157, v157, v157
	v_fmac_f32_e32 v161, v160, v160
	v_fmac_f32_e32 v155, v154, v154
	v_fmac_f32_e32 v163, v162, v162
	v_fmac_f32_e32 v157, v156, v156
	v_add_f32_e32 v154, v161, v155
	v_add_f32_e32 v155, v163, v157
	v_add_f32_e32 v160, v154, v155
	global_store_dwordx4 v[158:159], v[120:123], off
	s_waitcnt vmcnt(0) lgkmcnt(0)
	v_lshlrev_b32_e32 v154, 16, v124
	v_and_b32_e32 v155, 0xffff0000, v124
	v_lshlrev_b32_e32 v124, 16, v125
	v_and_b32_e32 v125, 0xffff0000, v125
	v_lshlrev_b32_e32 v156, 16, v126
	v_and_b32_e32 v157, 0xffff0000, v126
	v_lshlrev_b32_e32 v126, 16, v127
	v_and_b32_e32 v127, 0xffff0000, v127
	v_pk_fma_f32 v[118:119], v[118:119], 0.5, v[124:125] op_sel_hi:[1,0,1]
	v_pk_fma_f32 v[116:117], v[116:117], 0.5, v[154:155] op_sel_hi:[1,0,1]
	v_pk_fma_f32 v[124:125], v[114:115], 0.5, v[126:127] op_sel_hi:[1,0,1]
	v_pk_fma_f32 v[126:127], v[112:113], 0.5, v[156:157] op_sel_hi:[1,0,1]
	v_mul_f32_e32 v112, v117, v117
	v_mul_f32_e32 v113, v119, v119
	v_mul_f32_e32 v114, v127, v127
	v_mul_f32_e32 v115, v125, v125
	v_fmac_f32_e32 v112, v116, v116
	v_fmac_f32_e32 v113, v118, v118
	v_fmac_f32_e32 v114, v126, v126
	v_fmac_f32_e32 v115, v124, v124
	v_add_f32_e32 v112, v112, v113
	v_add_f32_e32 v113, v114, v115
	v_add_f32_e32 v112, v112, v113
	v_add_f32_e32 v112, v160, v112
	ds_bpermute_b32 v113, v151, v112
	v_cvt_pk_bf16_f32 v114, v116, v117
	v_cvt_pk_bf16_f32 v115, v118, v119
	v_cvt_pk_bf16_f32 v116, v126, v127
	v_cvt_pk_bf16_f32 v117, v124, v125
	s_waitcnt lgkmcnt(0)
	v_add_f32_e32 v112, v112, v113
	ds_bpermute_b32 v113, v152, v112
	global_store_dwordx4 v[158:159], v[114:117], off offset:256
	s_and_saveexec_b64 s[0:1], s[2:3]
	s_cbranch_execz .LBB0_283
	v_lshlrev_b64 v[114:115], 6, v[146:147]
	v_lshl_add_u64 v[114:115], s[24:25], 0, v[114:115]
	v_lshl_add_u64 v[114:115], s[36:37], 2, v[114:115]
	s_lshl_b32 s18, s48, 2
	v_lshl_add_u64 v[114:115], v[114:115], 0, s[18:19]
	s_waitcnt lgkmcnt(0)
	v_add_f32_e32 v112, v112, v113
	global_store_dword v[114:115], v112, off
.LBB0_283:
	s_or_b64 exec, exec, s[0:1]
	v_or_b32_e32 v112, 16, v146
	s_waitcnt lgkmcnt(0)
	v_ashrrev_i32_e32 v113, 31, v112
	v_lshlrev_b64 v[114:115], 11, v[112:113]
	v_lshl_add_u64 v[114:115], s[22:23], 0, v[114:115]
	v_lshl_add_u64 v[118:119], v[144:145], 1, v[114:115]
	global_load_dwordx4 v[114:117], v[118:119], off
	s_waitcnt vmcnt(0) lgkmcnt(0)
	v_lshlrev_b32_e32 v120, 16, v114
	v_and_b32_e32 v121, 0xffff0000, v114
	v_lshlrev_b32_e32 v114, 16, v115
	v_and_b32_e32 v115, 0xffff0000, v115
	v_lshlrev_b32_e32 v122, 16, v116
	v_and_b32_e32 v123, 0xffff0000, v116
	v_lshlrev_b32_e32 v116, 16, v117
	v_and_b32_e32 v117, 0xffff0000, v117
	v_pk_fma_f32 v[114:115], v[110:111], 0.5, v[114:115] op_sel_hi:[1,0,1]
	v_pk_fma_f32 v[120:121], v[108:109], 0.5, v[120:121] op_sel_hi:[1,0,1]
	v_pk_fma_f32 v[116:117], v[106:107], 0.5, v[116:117] op_sel_hi:[1,0,1]
	v_pk_fma_f32 v[122:123], v[104:105], 0.5, v[122:123] op_sel_hi:[1,0,1]
	v_cvt_pk_bf16_f32 v104, v120, v121
	v_cvt_pk_bf16_f32 v105, v114, v115
	v_mul_f32_e32 v121, v121, v121
	v_cvt_pk_bf16_f32 v106, v122, v123
	v_cvt_pk_bf16_f32 v107, v116, v117
	global_load_dwordx4 v[108:111], v[118:119], off offset:256
	v_mul_f32_e32 v115, v115, v115
	v_mul_f32_e32 v123, v123, v123
	v_mul_f32_e32 v117, v117, v117
	v_fmac_f32_e32 v121, v120, v120
	v_fmac_f32_e32 v115, v114, v114
	v_fmac_f32_e32 v123, v122, v122
	v_fmac_f32_e32 v117, v116, v116
	v_add_f32_e32 v114, v121, v115
	v_add_f32_e32 v115, v123, v117
	v_add_f32_e32 v120, v114, v115
	global_store_dwordx4 v[118:119], v[104:107], off
	s_waitcnt vmcnt(0) lgkmcnt(0)
	v_lshlrev_b32_e32 v114, 16, v108
	v_and_b32_e32 v115, 0xffff0000, v108
	v_lshlrev_b32_e32 v108, 16, v109
	v_and_b32_e32 v109, 0xffff0000, v109
	v_lshlrev_b32_e32 v116, 16, v110
	v_and_b32_e32 v117, 0xffff0000, v110
	v_lshlrev_b32_e32 v110, 16, v111
	v_and_b32_e32 v111, 0xffff0000, v111
	v_pk_fma_f32 v[102:103], v[102:103], 0.5, v[108:109] op_sel_hi:[1,0,1]
	v_pk_fma_f32 v[100:101], v[100:101], 0.5, v[114:115] op_sel_hi:[1,0,1]
	v_pk_fma_f32 v[108:109], v[98:99], 0.5, v[110:111] op_sel_hi:[1,0,1]
	v_pk_fma_f32 v[110:111], v[96:97], 0.5, v[116:117] op_sel_hi:[1,0,1]
	v_mul_f32_e32 v96, v101, v101
	v_mul_f32_e32 v97, v103, v103
	v_mul_f32_e32 v98, v111, v111
	v_mul_f32_e32 v99, v109, v109
	v_fmac_f32_e32 v96, v100, v100
	v_fmac_f32_e32 v97, v102, v102
	v_fmac_f32_e32 v98, v110, v110
	v_fmac_f32_e32 v99, v108, v108
	v_add_f32_e32 v96, v96, v97
	v_add_f32_e32 v97, v98, v99
	v_add_f32_e32 v96, v96, v97
	v_add_f32_e32 v96, v120, v96
	ds_bpermute_b32 v97, v151, v96
	v_cvt_pk_bf16_f32 v98, v100, v101
	v_cvt_pk_bf16_f32 v99, v102, v103
	v_cvt_pk_bf16_f32 v100, v110, v111
	v_cvt_pk_bf16_f32 v101, v108, v109
	s_waitcnt lgkmcnt(0)
	v_add_f32_e32 v96, v96, v97
	ds_bpermute_b32 v97, v152, v96
	global_store_dwordx4 v[118:119], v[98:101], off offset:256
	s_and_saveexec_b64 s[0:1], s[2:3]
	s_cbranch_execz .LBB0_285
	v_lshlrev_b64 v[98:99], 6, v[112:113]
	v_lshl_add_u64 v[98:99], s[24:25], 0, v[98:99]
	v_lshl_add_u64 v[98:99], s[36:37], 2, v[98:99]
	s_lshl_b32 s18, s48, 2
	v_lshl_add_u64 v[98:99], v[98:99], 0, s[18:19]
	s_waitcnt lgkmcnt(0)
	v_add_f32_e32 v96, v96, v97
	global_store_dword v[98:99], v96, off
.LBB0_285:
	s_or_b64 exec, exec, s[0:1]
	v_or_b32_e32 v96, 32, v146
	s_waitcnt lgkmcnt(0)
	v_ashrrev_i32_e32 v97, 31, v96
	v_lshlrev_b64 v[98:99], 11, v[96:97]
	v_lshl_add_u64 v[98:99], s[22:23], 0, v[98:99]
	v_lshl_add_u64 v[102:103], v[144:145], 1, v[98:99]
	global_load_dwordx4 v[98:101], v[102:103], off
	s_waitcnt vmcnt(0) lgkmcnt(0)
	v_lshlrev_b32_e32 v104, 16, v98
	v_and_b32_e32 v105, 0xffff0000, v98
	v_lshlrev_b32_e32 v98, 16, v99
	v_and_b32_e32 v99, 0xffff0000, v99
	v_lshlrev_b32_e32 v106, 16, v100
	v_and_b32_e32 v107, 0xffff0000, v100
	v_lshlrev_b32_e32 v100, 16, v101
	v_and_b32_e32 v101, 0xffff0000, v101
	v_pk_fma_f32 v[98:99], v[94:95], 0.5, v[98:99] op_sel_hi:[1,0,1]
	v_pk_fma_f32 v[104:105], v[92:93], 0.5, v[104:105] op_sel_hi:[1,0,1]
	v_pk_fma_f32 v[100:101], v[90:91], 0.5, v[100:101] op_sel_hi:[1,0,1]
	v_pk_fma_f32 v[106:107], v[88:89], 0.5, v[106:107] op_sel_hi:[1,0,1]
	v_cvt_pk_bf16_f32 v88, v104, v105
	v_cvt_pk_bf16_f32 v89, v98, v99
	v_mul_f32_e32 v105, v105, v105
	v_cvt_pk_bf16_f32 v90, v106, v107
	v_cvt_pk_bf16_f32 v91, v100, v101
	global_load_dwordx4 v[92:95], v[102:103], off offset:256
	v_mul_f32_e32 v99, v99, v99
	v_mul_f32_e32 v107, v107, v107
	v_mul_f32_e32 v101, v101, v101
	v_fmac_f32_e32 v105, v104, v104
	v_fmac_f32_e32 v99, v98, v98
	v_fmac_f32_e32 v107, v106, v106
	v_fmac_f32_e32 v101, v100, v100
	v_add_f32_e32 v98, v105, v99
	v_add_f32_e32 v99, v107, v101
	v_add_f32_e32 v104, v98, v99
	global_store_dwordx4 v[102:103], v[88:91], off
	s_waitcnt vmcnt(0) lgkmcnt(0)
	v_lshlrev_b32_e32 v98, 16, v92
	v_and_b32_e32 v99, 0xffff0000, v92
	v_lshlrev_b32_e32 v92, 16, v93
	v_and_b32_e32 v93, 0xffff0000, v93
	v_lshlrev_b32_e32 v100, 16, v94
	v_and_b32_e32 v101, 0xffff0000, v94
	v_lshlrev_b32_e32 v94, 16, v95
	v_and_b32_e32 v95, 0xffff0000, v95
	v_pk_fma_f32 v[86:87], v[86:87], 0.5, v[92:93] op_sel_hi:[1,0,1]
	v_pk_fma_f32 v[84:85], v[84:85], 0.5, v[98:99] op_sel_hi:[1,0,1]
	v_pk_fma_f32 v[92:93], v[82:83], 0.5, v[94:95] op_sel_hi:[1,0,1]
	v_pk_fma_f32 v[94:95], v[80:81], 0.5, v[100:101] op_sel_hi:[1,0,1]
	v_mul_f32_e32 v80, v85, v85
	v_mul_f32_e32 v81, v87, v87
	v_mul_f32_e32 v82, v95, v95
	v_mul_f32_e32 v83, v93, v93
	v_fmac_f32_e32 v80, v84, v84
	v_fmac_f32_e32 v81, v86, v86
	v_fmac_f32_e32 v82, v94, v94
	v_fmac_f32_e32 v83, v92, v92
	v_add_f32_e32 v80, v80, v81
	v_add_f32_e32 v81, v82, v83
	v_add_f32_e32 v80, v80, v81
	v_add_f32_e32 v80, v104, v80
	ds_bpermute_b32 v81, v151, v80
	v_cvt_pk_bf16_f32 v82, v84, v85
	v_cvt_pk_bf16_f32 v83, v86, v87
	v_cvt_pk_bf16_f32 v84, v94, v95
	v_cvt_pk_bf16_f32 v85, v92, v93
	s_waitcnt lgkmcnt(0)
	v_add_f32_e32 v80, v80, v81
	ds_bpermute_b32 v81, v152, v80
	global_store_dwordx4 v[102:103], v[82:85], off offset:256
	s_and_saveexec_b64 s[0:1], s[2:3]
	s_cbranch_execz .LBB0_287
	v_lshlrev_b64 v[82:83], 6, v[96:97]
	v_lshl_add_u64 v[82:83], s[24:25], 0, v[82:83]
	v_lshl_add_u64 v[82:83], s[36:37], 2, v[82:83]
	s_lshl_b32 s18, s48, 2
	v_lshl_add_u64 v[82:83], v[82:83], 0, s[18:19]
	s_waitcnt lgkmcnt(0)
	v_add_f32_e32 v80, v80, v81
	global_store_dword v[82:83], v80, off
.LBB0_287:
	s_or_b64 exec, exec, s[0:1]
	v_or_b32_e32 v80, 48, v146
	s_waitcnt lgkmcnt(0)
	v_ashrrev_i32_e32 v81, 31, v80
	v_lshlrev_b64 v[82:83], 11, v[80:81]
	v_lshl_add_u64 v[82:83], s[22:23], 0, v[82:83]
	v_lshl_add_u64 v[86:87], v[144:145], 1, v[82:83]
	global_load_dwordx4 v[82:85], v[86:87], off
	s_waitcnt vmcnt(0) lgkmcnt(0)
	v_lshlrev_b32_e32 v88, 16, v82
	v_and_b32_e32 v89, 0xffff0000, v82
	v_lshlrev_b32_e32 v82, 16, v83
	v_and_b32_e32 v83, 0xffff0000, v83
	v_lshlrev_b32_e32 v90, 16, v84
	v_and_b32_e32 v91, 0xffff0000, v84
	v_lshlrev_b32_e32 v84, 16, v85
	v_and_b32_e32 v85, 0xffff0000, v85
	v_pk_fma_f32 v[82:83], v[78:79], 0.5, v[82:83] op_sel_hi:[1,0,1]
	v_pk_fma_f32 v[88:89], v[76:77], 0.5, v[88:89] op_sel_hi:[1,0,1]
	v_pk_fma_f32 v[84:85], v[74:75], 0.5, v[84:85] op_sel_hi:[1,0,1]
	v_pk_fma_f32 v[90:91], v[72:73], 0.5, v[90:91] op_sel_hi:[1,0,1]
	v_cvt_pk_bf16_f32 v72, v88, v89
	v_cvt_pk_bf16_f32 v73, v82, v83
	v_mul_f32_e32 v89, v89, v89
	v_cvt_pk_bf16_f32 v74, v90, v91
	v_cvt_pk_bf16_f32 v75, v84, v85
	global_load_dwordx4 v[76:79], v[86:87], off offset:256
	v_mul_f32_e32 v83, v83, v83
	v_mul_f32_e32 v91, v91, v91
	v_mul_f32_e32 v85, v85, v85
	v_fmac_f32_e32 v89, v88, v88
	v_fmac_f32_e32 v83, v82, v82
	v_fmac_f32_e32 v91, v90, v90
	v_fmac_f32_e32 v85, v84, v84
	v_add_f32_e32 v82, v89, v83
	v_add_f32_e32 v83, v91, v85
	v_add_f32_e32 v88, v82, v83
	global_store_dwordx4 v[86:87], v[72:75], off
	s_waitcnt vmcnt(0) lgkmcnt(0)
	v_lshlrev_b32_e32 v82, 16, v76
	v_and_b32_e32 v83, 0xffff0000, v76
	v_lshlrev_b32_e32 v76, 16, v77
	v_and_b32_e32 v77, 0xffff0000, v77
	v_lshlrev_b32_e32 v84, 16, v78
	v_and_b32_e32 v85, 0xffff0000, v78
	v_lshlrev_b32_e32 v78, 16, v79
	v_and_b32_e32 v79, 0xffff0000, v79
	v_pk_fma_f32 v[70:71], v[70:71], 0.5, v[76:77] op_sel_hi:[1,0,1]
	v_pk_fma_f32 v[68:69], v[68:69], 0.5, v[82:83] op_sel_hi:[1,0,1]
	v_pk_fma_f32 v[76:77], v[66:67], 0.5, v[78:79] op_sel_hi:[1,0,1]
	v_pk_fma_f32 v[78:79], v[64:65], 0.5, v[84:85] op_sel_hi:[1,0,1]
	v_mul_f32_e32 v64, v69, v69
	v_mul_f32_e32 v65, v71, v71
	v_mul_f32_e32 v66, v79, v79
	v_mul_f32_e32 v67, v77, v77
	v_fmac_f32_e32 v64, v68, v68
	v_fmac_f32_e32 v65, v70, v70
	v_fmac_f32_e32 v66, v78, v78
	v_fmac_f32_e32 v67, v76, v76
	v_add_f32_e32 v64, v64, v65
	v_add_f32_e32 v65, v66, v67
	v_add_f32_e32 v64, v64, v65
	v_add_f32_e32 v64, v88, v64
	ds_bpermute_b32 v65, v151, v64
	v_cvt_pk_bf16_f32 v66, v68, v69
	v_cvt_pk_bf16_f32 v67, v70, v71
	v_cvt_pk_bf16_f32 v68, v78, v79
	v_cvt_pk_bf16_f32 v69, v76, v77
	s_waitcnt lgkmcnt(0)
	v_add_f32_e32 v64, v64, v65
	ds_bpermute_b32 v65, v152, v64
	global_store_dwordx4 v[86:87], v[66:69], off offset:256
	s_and_saveexec_b64 s[0:1], s[2:3]
	s_cbranch_execz .LBB0_289
	v_lshlrev_b64 v[66:67], 6, v[80:81]
	v_lshl_add_u64 v[66:67], s[24:25], 0, v[66:67]
	v_lshl_add_u64 v[66:67], s[36:37], 2, v[66:67]
	s_lshl_b32 s18, s48, 2
	v_lshl_add_u64 v[66:67], v[66:67], 0, s[18:19]
	s_waitcnt lgkmcnt(0)
	v_add_f32_e32 v64, v64, v65
	global_store_dword v[66:67], v64, off
.LBB0_289:
	s_or_b64 exec, exec, s[0:1]
	v_add_u32_e32 v64, 0x80, v146
	s_waitcnt lgkmcnt(0)
	v_ashrrev_i32_e32 v65, 31, v64
	v_lshlrev_b64 v[66:67], 11, v[64:65]
	v_lshl_add_u64 v[66:67], s[22:23], 0, v[66:67]
	v_lshl_add_u64 v[70:71], v[144:145], 1, v[66:67]
	global_load_dwordx4 v[66:69], v[70:71], off
	s_waitcnt vmcnt(0) lgkmcnt(0)
	v_lshlrev_b32_e32 v72, 16, v66
	v_and_b32_e32 v73, 0xffff0000, v66
	v_lshlrev_b32_e32 v66, 16, v67
	v_and_b32_e32 v67, 0xffff0000, v67
	v_lshlrev_b32_e32 v74, 16, v68
	v_and_b32_e32 v75, 0xffff0000, v68
	v_lshlrev_b32_e32 v68, 16, v69
	v_and_b32_e32 v69, 0xffff0000, v69
	v_pk_fma_f32 v[66:67], v[62:63], 0.5, v[66:67] op_sel_hi:[1,0,1]
	v_pk_fma_f32 v[72:73], v[60:61], 0.5, v[72:73] op_sel_hi:[1,0,1]
	v_pk_fma_f32 v[68:69], v[58:59], 0.5, v[68:69] op_sel_hi:[1,0,1]
	v_pk_fma_f32 v[74:75], v[56:57], 0.5, v[74:75] op_sel_hi:[1,0,1]
	v_cvt_pk_bf16_f32 v56, v72, v73
	v_cvt_pk_bf16_f32 v57, v66, v67
	v_mul_f32_e32 v73, v73, v73
	v_cvt_pk_bf16_f32 v58, v74, v75
	v_cvt_pk_bf16_f32 v59, v68, v69
	global_load_dwordx4 v[60:63], v[70:71], off offset:256
	v_mul_f32_e32 v67, v67, v67
	v_mul_f32_e32 v75, v75, v75
	v_mul_f32_e32 v69, v69, v69
	v_fmac_f32_e32 v73, v72, v72
	v_fmac_f32_e32 v67, v66, v66
	v_fmac_f32_e32 v75, v74, v74
	v_fmac_f32_e32 v69, v68, v68
	v_add_f32_e32 v66, v73, v67
	v_add_f32_e32 v67, v75, v69
	v_add_f32_e32 v72, v66, v67
	global_store_dwordx4 v[70:71], v[56:59], off
	s_waitcnt vmcnt(0) lgkmcnt(0)
	v_lshlrev_b32_e32 v66, 16, v60
	v_and_b32_e32 v67, 0xffff0000, v60
	v_lshlrev_b32_e32 v60, 16, v61
	v_and_b32_e32 v61, 0xffff0000, v61
	v_lshlrev_b32_e32 v68, 16, v62
	v_and_b32_e32 v69, 0xffff0000, v62
	v_lshlrev_b32_e32 v62, 16, v63
	v_and_b32_e32 v63, 0xffff0000, v63
	v_pk_fma_f32 v[54:55], v[54:55], 0.5, v[60:61] op_sel_hi:[1,0,1]
	v_pk_fma_f32 v[52:53], v[52:53], 0.5, v[66:67] op_sel_hi:[1,0,1]
	v_pk_fma_f32 v[60:61], v[50:51], 0.5, v[62:63] op_sel_hi:[1,0,1]
	v_pk_fma_f32 v[62:63], v[48:49], 0.5, v[68:69] op_sel_hi:[1,0,1]
	v_mul_f32_e32 v48, v53, v53
	v_mul_f32_e32 v49, v55, v55
	v_mul_f32_e32 v50, v63, v63
	v_mul_f32_e32 v51, v61, v61
	v_fmac_f32_e32 v48, v52, v52
	v_fmac_f32_e32 v49, v54, v54
	v_fmac_f32_e32 v50, v62, v62
	v_fmac_f32_e32 v51, v60, v60
	v_add_f32_e32 v48, v48, v49
	v_add_f32_e32 v49, v50, v51
	v_add_f32_e32 v48, v48, v49
	v_add_f32_e32 v48, v72, v48
	ds_bpermute_b32 v49, v151, v48
	v_cvt_pk_bf16_f32 v50, v52, v53
	v_cvt_pk_bf16_f32 v51, v54, v55
	v_cvt_pk_bf16_f32 v52, v62, v63
	v_cvt_pk_bf16_f32 v53, v60, v61
	s_waitcnt lgkmcnt(0)
	v_add_f32_e32 v48, v48, v49
	ds_bpermute_b32 v49, v152, v48
	global_store_dwordx4 v[70:71], v[50:53], off offset:256
	s_and_saveexec_b64 s[0:1], s[2:3]
	s_cbranch_execz .LBB0_291
	v_lshlrev_b64 v[50:51], 6, v[64:65]
	v_lshl_add_u64 v[50:51], s[24:25], 0, v[50:51]
	v_lshl_add_u64 v[50:51], s[36:37], 2, v[50:51]
	s_lshl_b32 s18, s48, 2
	v_lshl_add_u64 v[50:51], v[50:51], 0, s[18:19]
	s_waitcnt lgkmcnt(0)
	v_add_f32_e32 v48, v48, v49
	global_store_dword v[50:51], v48, off
.LBB0_291:
	s_or_b64 exec, exec, s[0:1]
	v_add_u32_e32 v48, 0x90, v146
	s_waitcnt lgkmcnt(0)
	v_ashrrev_i32_e32 v49, 31, v48
	v_lshlrev_b64 v[50:51], 11, v[48:49]
	v_lshl_add_u64 v[50:51], s[22:23], 0, v[50:51]
	v_lshl_add_u64 v[54:55], v[144:145], 1, v[50:51]
	global_load_dwordx4 v[50:53], v[54:55], off
	s_waitcnt vmcnt(0) lgkmcnt(0)
	v_lshlrev_b32_e32 v56, 16, v50
	v_and_b32_e32 v57, 0xffff0000, v50
	v_lshlrev_b32_e32 v50, 16, v51
	v_and_b32_e32 v51, 0xffff0000, v51
	v_lshlrev_b32_e32 v58, 16, v52
	v_and_b32_e32 v59, 0xffff0000, v52
	v_lshlrev_b32_e32 v52, 16, v53
	v_and_b32_e32 v53, 0xffff0000, v53
	v_pk_fma_f32 v[50:51], v[46:47], 0.5, v[50:51] op_sel_hi:[1,0,1]
	v_pk_fma_f32 v[56:57], v[44:45], 0.5, v[56:57] op_sel_hi:[1,0,1]
	v_pk_fma_f32 v[52:53], v[42:43], 0.5, v[52:53] op_sel_hi:[1,0,1]
	v_pk_fma_f32 v[58:59], v[40:41], 0.5, v[58:59] op_sel_hi:[1,0,1]
	v_cvt_pk_bf16_f32 v40, v56, v57
	v_cvt_pk_bf16_f32 v41, v50, v51
	v_mul_f32_e32 v57, v57, v57
	v_cvt_pk_bf16_f32 v42, v58, v59
	v_cvt_pk_bf16_f32 v43, v52, v53
	global_load_dwordx4 v[44:47], v[54:55], off offset:256
	v_mul_f32_e32 v51, v51, v51
	v_mul_f32_e32 v59, v59, v59
	v_mul_f32_e32 v53, v53, v53
	v_fmac_f32_e32 v57, v56, v56
	v_fmac_f32_e32 v51, v50, v50
	v_fmac_f32_e32 v59, v58, v58
	v_fmac_f32_e32 v53, v52, v52
	v_add_f32_e32 v50, v57, v51
	v_add_f32_e32 v51, v59, v53
	v_add_f32_e32 v56, v50, v51
	global_store_dwordx4 v[54:55], v[40:43], off
	s_waitcnt vmcnt(0) lgkmcnt(0)
	v_lshlrev_b32_e32 v50, 16, v44
	v_and_b32_e32 v51, 0xffff0000, v44
	v_lshlrev_b32_e32 v44, 16, v45
	v_and_b32_e32 v45, 0xffff0000, v45
	v_lshlrev_b32_e32 v52, 16, v46
	v_and_b32_e32 v53, 0xffff0000, v46
	v_lshlrev_b32_e32 v46, 16, v47
	v_and_b32_e32 v47, 0xffff0000, v47
	v_pk_fma_f32 v[38:39], v[38:39], 0.5, v[44:45] op_sel_hi:[1,0,1]
	v_pk_fma_f32 v[36:37], v[36:37], 0.5, v[50:51] op_sel_hi:[1,0,1]
	v_pk_fma_f32 v[44:45], v[34:35], 0.5, v[46:47] op_sel_hi:[1,0,1]
	v_pk_fma_f32 v[46:47], v[32:33], 0.5, v[52:53] op_sel_hi:[1,0,1]
	v_mul_f32_e32 v32, v37, v37
	v_mul_f32_e32 v33, v39, v39
	v_mul_f32_e32 v34, v47, v47
	v_mul_f32_e32 v35, v45, v45
	v_fmac_f32_e32 v32, v36, v36
	v_fmac_f32_e32 v33, v38, v38
	v_fmac_f32_e32 v34, v46, v46
	v_fmac_f32_e32 v35, v44, v44
	v_add_f32_e32 v32, v32, v33
	v_add_f32_e32 v33, v34, v35
	v_add_f32_e32 v32, v32, v33
	v_add_f32_e32 v32, v56, v32
	ds_bpermute_b32 v33, v151, v32
	v_cvt_pk_bf16_f32 v34, v36, v37
	v_cvt_pk_bf16_f32 v35, v38, v39
	v_cvt_pk_bf16_f32 v36, v46, v47
	v_cvt_pk_bf16_f32 v37, v44, v45
	s_waitcnt lgkmcnt(0)
	v_add_f32_e32 v32, v32, v33
	ds_bpermute_b32 v33, v152, v32
	global_store_dwordx4 v[54:55], v[34:37], off offset:256
	s_and_saveexec_b64 s[0:1], s[2:3]
	s_cbranch_execz .LBB0_293
	v_lshlrev_b64 v[34:35], 6, v[48:49]
	v_lshl_add_u64 v[34:35], s[24:25], 0, v[34:35]
	v_lshl_add_u64 v[34:35], s[36:37], 2, v[34:35]
	s_lshl_b32 s18, s48, 2
	v_lshl_add_u64 v[34:35], v[34:35], 0, s[18:19]
	s_waitcnt lgkmcnt(0)
	v_add_f32_e32 v32, v32, v33
	global_store_dword v[34:35], v32, off
.LBB0_293:
	s_or_b64 exec, exec, s[0:1]
	v_add_u32_e32 v32, 0xa0, v146
	s_waitcnt lgkmcnt(0)
	v_ashrrev_i32_e32 v33, 31, v32
	v_lshlrev_b64 v[34:35], 11, v[32:33]
	v_lshl_add_u64 v[34:35], s[22:23], 0, v[34:35]
	v_lshl_add_u64 v[38:39], v[144:145], 1, v[34:35]
	global_load_dwordx4 v[34:37], v[38:39], off
	s_waitcnt vmcnt(0) lgkmcnt(0)
	v_lshlrev_b32_e32 v40, 16, v34
	v_and_b32_e32 v41, 0xffff0000, v34
	v_lshlrev_b32_e32 v34, 16, v35
	v_and_b32_e32 v35, 0xffff0000, v35
	v_lshlrev_b32_e32 v42, 16, v36
	v_and_b32_e32 v43, 0xffff0000, v36
	v_lshlrev_b32_e32 v36, 16, v37
	v_and_b32_e32 v37, 0xffff0000, v37
	v_pk_fma_f32 v[34:35], v[30:31], 0.5, v[34:35] op_sel_hi:[1,0,1]
	v_pk_fma_f32 v[40:41], v[28:29], 0.5, v[40:41] op_sel_hi:[1,0,1]
	v_pk_fma_f32 v[36:37], v[26:27], 0.5, v[36:37] op_sel_hi:[1,0,1]
	v_pk_fma_f32 v[42:43], v[24:25], 0.5, v[42:43] op_sel_hi:[1,0,1]
	v_cvt_pk_bf16_f32 v24, v40, v41
	v_cvt_pk_bf16_f32 v25, v34, v35
	v_mul_f32_e32 v41, v41, v41
	v_cvt_pk_bf16_f32 v26, v42, v43
	v_cvt_pk_bf16_f32 v27, v36, v37
	global_load_dwordx4 v[28:31], v[38:39], off offset:256
	v_mul_f32_e32 v35, v35, v35
	v_mul_f32_e32 v43, v43, v43
	v_mul_f32_e32 v37, v37, v37
	v_fmac_f32_e32 v41, v40, v40
	v_fmac_f32_e32 v35, v34, v34
	v_fmac_f32_e32 v43, v42, v42
	v_fmac_f32_e32 v37, v36, v36
	v_add_f32_e32 v34, v41, v35
	v_add_f32_e32 v35, v43, v37
	v_add_f32_e32 v40, v34, v35
	global_store_dwordx4 v[38:39], v[24:27], off
	s_waitcnt vmcnt(0) lgkmcnt(0)
	v_lshlrev_b32_e32 v34, 16, v28
	v_and_b32_e32 v35, 0xffff0000, v28
	v_lshlrev_b32_e32 v28, 16, v29
	v_and_b32_e32 v29, 0xffff0000, v29
	v_lshlrev_b32_e32 v36, 16, v30
	v_and_b32_e32 v37, 0xffff0000, v30
	v_lshlrev_b32_e32 v30, 16, v31
	v_and_b32_e32 v31, 0xffff0000, v31
	v_pk_fma_f32 v[22:23], v[22:23], 0.5, v[28:29] op_sel_hi:[1,0,1]
	v_pk_fma_f32 v[20:21], v[20:21], 0.5, v[34:35] op_sel_hi:[1,0,1]
	v_pk_fma_f32 v[28:29], v[18:19], 0.5, v[30:31] op_sel_hi:[1,0,1]
	v_pk_fma_f32 v[30:31], v[16:17], 0.5, v[36:37] op_sel_hi:[1,0,1]
	v_mul_f32_e32 v16, v21, v21
	v_mul_f32_e32 v17, v23, v23
	v_mul_f32_e32 v18, v31, v31
	v_mul_f32_e32 v19, v29, v29
	v_fmac_f32_e32 v16, v20, v20
	v_fmac_f32_e32 v17, v22, v22
	v_fmac_f32_e32 v18, v30, v30
	v_fmac_f32_e32 v19, v28, v28
	v_add_f32_e32 v16, v16, v17
	v_add_f32_e32 v17, v18, v19
	v_add_f32_e32 v16, v16, v17
	v_add_f32_e32 v16, v40, v16
	ds_bpermute_b32 v17, v151, v16
	v_cvt_pk_bf16_f32 v18, v20, v21
	v_cvt_pk_bf16_f32 v19, v22, v23
	v_cvt_pk_bf16_f32 v20, v30, v31
	v_cvt_pk_bf16_f32 v21, v28, v29
	s_waitcnt lgkmcnt(0)
	v_add_f32_e32 v16, v16, v17
	ds_bpermute_b32 v17, v152, v16
	global_store_dwordx4 v[38:39], v[18:21], off offset:256
	s_and_saveexec_b64 s[0:1], s[2:3]
	s_cbranch_execz .LBB0_295
	v_lshlrev_b64 v[18:19], 6, v[32:33]
	v_lshl_add_u64 v[18:19], s[24:25], 0, v[18:19]
	v_lshl_add_u64 v[18:19], s[36:37], 2, v[18:19]
	s_lshl_b32 s18, s48, 2
	v_lshl_add_u64 v[18:19], v[18:19], 0, s[18:19]
	s_waitcnt lgkmcnt(0)
	v_add_f32_e32 v16, v16, v17
	global_store_dword v[18:19], v16, off
.LBB0_295:
	s_or_b64 exec, exec, s[0:1]
	v_add_u32_e32 v16, 0xb0, v146
	s_waitcnt lgkmcnt(0)
	v_ashrrev_i32_e32 v17, 31, v16
	v_lshlrev_b64 v[18:19], 11, v[16:17]
	v_lshl_add_u64 v[18:19], s[22:23], 0, v[18:19]
	v_lshl_add_u64 v[22:23], v[144:145], 1, v[18:19]
	global_load_dwordx4 v[18:21], v[22:23], off
	s_waitcnt vmcnt(0) lgkmcnt(0)
	v_lshlrev_b32_e32 v24, 16, v18
	v_and_b32_e32 v25, 0xffff0000, v18
	v_lshlrev_b32_e32 v18, 16, v19
	v_and_b32_e32 v19, 0xffff0000, v19
	v_lshlrev_b32_e32 v26, 16, v20
	v_and_b32_e32 v27, 0xffff0000, v20
	v_lshlrev_b32_e32 v20, 16, v21
	v_and_b32_e32 v21, 0xffff0000, v21
	v_pk_fma_f32 v[18:19], v[14:15], 0.5, v[18:19] op_sel_hi:[1,0,1]
	v_pk_fma_f32 v[24:25], v[12:13], 0.5, v[24:25] op_sel_hi:[1,0,1]
	v_pk_fma_f32 v[20:21], v[10:11], 0.5, v[20:21] op_sel_hi:[1,0,1]
	v_pk_fma_f32 v[26:27], v[8:9], 0.5, v[26:27] op_sel_hi:[1,0,1]
	v_cvt_pk_bf16_f32 v8, v24, v25
	v_cvt_pk_bf16_f32 v9, v18, v19
	v_mul_f32_e32 v25, v25, v25
	v_cvt_pk_bf16_f32 v10, v26, v27
	v_cvt_pk_bf16_f32 v11, v20, v21
	global_load_dwordx4 v[12:15], v[22:23], off offset:256
	v_mul_f32_e32 v19, v19, v19
	v_mul_f32_e32 v27, v27, v27
	v_mul_f32_e32 v21, v21, v21
	v_fmac_f32_e32 v25, v24, v24
	v_fmac_f32_e32 v19, v18, v18
	v_fmac_f32_e32 v27, v26, v26
	v_fmac_f32_e32 v21, v20, v20
	v_add_f32_e32 v18, v25, v19
	v_add_f32_e32 v19, v27, v21
	v_add_f32_e32 v24, v18, v19
	global_store_dwordx4 v[22:23], v[8:11], off
	s_waitcnt vmcnt(0) lgkmcnt(0)
	v_lshlrev_b32_e32 v18, 16, v12
	v_and_b32_e32 v19, 0xffff0000, v12
	v_lshlrev_b32_e32 v12, 16, v13
	v_and_b32_e32 v13, 0xffff0000, v13
	v_lshlrev_b32_e32 v20, 16, v14
	v_and_b32_e32 v21, 0xffff0000, v14
	v_lshlrev_b32_e32 v14, 16, v15
	v_and_b32_e32 v15, 0xffff0000, v15
	v_pk_fma_f32 v[6:7], v[6:7], 0.5, v[12:13] op_sel_hi:[1,0,1]
	v_pk_fma_f32 v[4:5], v[4:5], 0.5, v[18:19] op_sel_hi:[1,0,1]
	v_pk_fma_f32 v[12:13], v[2:3], 0.5, v[14:15] op_sel_hi:[1,0,1]
	v_pk_fma_f32 v[14:15], v[0:1], 0.5, v[20:21] op_sel_hi:[1,0,1]
	v_mul_f32_e32 v0, v5, v5
	v_mul_f32_e32 v1, v7, v7
	v_mul_f32_e32 v2, v15, v15
	v_mul_f32_e32 v3, v13, v13
	v_fmac_f32_e32 v0, v4, v4
	v_fmac_f32_e32 v1, v6, v6
	v_fmac_f32_e32 v2, v14, v14
	v_fmac_f32_e32 v3, v12, v12
	v_add_f32_e32 v0, v0, v1
	v_add_f32_e32 v1, v2, v3
	v_add_f32_e32 v0, v0, v1
	v_add_f32_e32 v0, v24, v0
	ds_bpermute_b32 v1, v151, v0
	v_cvt_pk_bf16_f32 v2, v4, v5
	v_cvt_pk_bf16_f32 v3, v6, v7
	v_cvt_pk_bf16_f32 v4, v14, v15
	v_cvt_pk_bf16_f32 v5, v12, v13
	s_waitcnt lgkmcnt(0)
	v_add_f32_e32 v0, v0, v1
	ds_bpermute_b32 v1, v152, v0
	global_store_dwordx4 v[22:23], v[2:5], off offset:256
	s_and_saveexec_b64 s[0:1], s[2:3]
	s_cbranch_execz .LBB0_297
	v_lshlrev_b64 v[2:3], 6, v[16:17]
	v_lshl_add_u64 v[2:3], s[24:25], 0, v[2:3]
	v_lshl_add_u64 v[2:3], s[36:37], 2, v[2:3]
	s_lshl_b32 s18, s48, 2
	v_lshl_add_u64 v[2:3], v[2:3], 0, s[18:19]
	s_waitcnt lgkmcnt(0)
	v_add_f32_e32 v0, v0, v1
	global_store_dword v[2:3], v0, off

.LBB0_369:
	v_lshl_add_u32 v148, s38, 8, v158
	v_and_b32_e32 v149, 0x7cf, v148
	v_lshl_add_u32 v149, v149, 2, 0
	v_add_u32_e32 v149, 0x20000, v149
	ds_read_b32 v154, v149
	s_add_u32 s6, s6, s61
	s_addc_u32 s7, s7, 0
	v_lshl_add_u64 v[146:147], v[136:137], 1, s[6:7]
	v_ashrrev_i32_e32 v149, 31, v148
	v_mad_i64_i32 v[150:151], s[6:7], s40, v148, 0
	s_waitcnt lgkmcnt(0)
	v_pk_mul_f32 v[156:157], v[154:155], v[120:121] op_sel_hi:[0,1]
	v_pk_mul_f32 v[120:121], v[154:155], v[126:127] op_sel_hi:[0,1]
	v_cndmask_b32_e64 v126, 0, 1, s[0:1]
	s_lshl_b32 s18, s31, 3
	v_lshl_add_u64 v[152:153], v[150:151], 1, v[146:147]
	v_lshlrev_b64 v[150:151], 7, v[148:149]
	v_pk_mul_f32 v[122:123], v[154:155], v[122:123] op_sel_hi:[0,1]
	v_pk_mul_f32 v[124:125], v[154:155], v[124:125] op_sel_hi:[0,1]
	v_cmp_ne_u32_e64 s[6:7], 1, v126
	s_andn2_b64 vcc, exec, s[0:1]
	v_cvt_pk_bf16_f32 v164, v156, v157
	v_cvt_pk_bf16_f32 v165, v122, v123
	v_cvt_pk_bf16_f32 v166, v124, v125
	v_cvt_pk_bf16_f32 v167, v120, v121
	global_store_dwordx4 v[152:153], v[164:167], off
	s_cbranch_vccnz .LBB0_373
	v_mul_f32_e32 v126, v157, v157
	v_mul_f32_e32 v123, v123, v123
	v_fmac_f32_e32 v126, v156, v156
	v_fmac_f32_e32 v123, v122, v122
	v_add_f32_e32 v122, v126, v123
	v_mul_f32_e32 v123, v125, v125
	v_mul_f32_e32 v121, v121, v121
	v_fmac_f32_e32 v123, v124, v124
	v_fmac_f32_e32 v121, v120, v120
	v_add_f32_e32 v120, v123, v121
	v_add_f32_e32 v120, v122, v120
	ds_bpermute_b32 v121, v160, v120
	s_waitcnt lgkmcnt(0)
	v_add_f32_e32 v120, v120, v121
	ds_bpermute_b32 v121, v161, v120
	s_and_saveexec_b64 s[0:1], s[2:3]
	s_cbranch_execz .LBB0_372
	v_lshl_add_u64 v[122:123], s[22:23], 0, v[150:151]
	v_lshl_add_u64 v[122:123], s[18:19], 2, v[122:123]
	s_lshl_b32 s68, s53, 2
	s_mov_b32 s69, s19
	v_lshl_add_u64 v[122:123], v[122:123], 0, s[68:69]
	s_waitcnt lgkmcnt(0)
	v_add_f32_e32 v120, v120, v121
	global_store_dword v[122:123], v120, off

.LBB0_373:
	v_mov_b32_e32 v155, v154
	v_mov_b32_e32 v122, v154
	v_mov_b32_e32 v123, v154
	v_pk_mul_f32 v[114:115], v[122:123], v[114:115]
	s_waitcnt lgkmcnt(0)
	v_pk_mul_f32 v[120:121], v[154:155], v[112:113]
	v_pk_mul_f32 v[112:113], v[122:123], v[118:119]
	v_pk_mul_f32 v[116:117], v[154:155], v[116:117]
	s_and_b64 vcc, exec, s[6:7]
	v_cvt_pk_bf16_f32 v122, v120, v121
	v_cvt_pk_bf16_f32 v123, v114, v115
	v_cvt_pk_bf16_f32 v124, v116, v117
	v_cvt_pk_bf16_f32 v125, v112, v113
	global_store_dwordx4 v[152:153], v[122:125], off offset:256
	s_cbranch_vccnz .LBB0_377
	v_mul_f32_e32 v118, v121, v121
	v_mul_f32_e32 v115, v115, v115
	v_fmac_f32_e32 v118, v120, v120
	v_fmac_f32_e32 v115, v114, v114
	v_add_f32_e32 v114, v118, v115
	v_mul_f32_e32 v115, v117, v117
	v_mul_f32_e32 v113, v113, v113
	v_fmac_f32_e32 v115, v116, v116
	v_fmac_f32_e32 v113, v112, v112
	v_add_f32_e32 v112, v115, v113
	v_add_f32_e32 v112, v114, v112
	ds_bpermute_b32 v113, v160, v112
	s_waitcnt lgkmcnt(0)
	v_add_f32_e32 v112, v112, v113
	ds_bpermute_b32 v113, v161, v112
	s_and_saveexec_b64 s[0:1], s[2:3]
	s_cbranch_execz .LBB0_376
	v_lshl_add_u64 v[114:115], s[22:23], 0, v[150:151]
	v_lshl_add_u64 v[114:115], s[18:19], 2, v[114:115]
	s_lshl_b32 s68, s53, 2
	s_mov_b32 s69, s19
	v_lshl_add_u64 v[114:115], v[114:115], 0, s[68:69]
	s_waitcnt lgkmcnt(0)
	v_add_f32_e32 v112, v112, v113
	global_store_dword v[114:115], v112, off offset:16

.LBB0_377:
	s_waitcnt lgkmcnt(0)
	v_bitop3_b32 v113, v148, s62, 16 bitop3:0xc8
	v_lshl_add_u32 v113, v113, 2, 0
	v_add_u32_e32 v113, 0x20000, v113
	ds_read_b32 v116, v113
	v_or_b32_e32 v112, 16, v148
	v_ashrrev_i32_e32 v113, 31, v112
	v_mad_i64_i32 v[114:115], s[0:1], s40, v112, 0
	v_lshl_add_u64 v[114:115], v[114:115], 1, v[146:147]
	v_lshlrev_b64 v[112:113], 7, v[112:113]
	s_waitcnt lgkmcnt(0)
	v_pk_mul_f32 v[106:107], v[116:117], v[106:107] op_sel_hi:[0,1]
	v_pk_mul_f32 v[118:119], v[116:117], v[104:105] op_sel_hi:[0,1]
	v_pk_mul_f32 v[104:105], v[116:117], v[110:111] op_sel_hi:[0,1]
	v_pk_mul_f32 v[108:109], v[116:117], v[108:109] op_sel_hi:[0,1]
	s_and_b64 vcc, exec, s[6:7]
	v_cvt_pk_bf16_f32 v120, v118, v119
	v_cvt_pk_bf16_f32 v121, v106, v107
	v_cvt_pk_bf16_f32 v122, v108, v109
	v_cvt_pk_bf16_f32 v123, v104, v105
	global_store_dwordx4 v[114:115], v[120:123], off
	s_cbranch_vccnz .LBB0_381
	v_mul_f32_e32 v110, v119, v119
	v_mul_f32_e32 v107, v107, v107
	v_fmac_f32_e32 v110, v118, v118
	v_fmac_f32_e32 v107, v106, v106
	v_add_f32_e32 v106, v110, v107
	v_mul_f32_e32 v107, v109, v109
	v_mul_f32_e32 v105, v105, v105
	v_fmac_f32_e32 v107, v108, v108
	v_fmac_f32_e32 v105, v104, v104
	v_add_f32_e32 v104, v107, v105
	v_add_f32_e32 v104, v106, v104
	ds_bpermute_b32 v105, v160, v104
	s_waitcnt lgkmcnt(0)
	v_add_f32_e32 v104, v104, v105
	ds_bpermute_b32 v105, v161, v104
	s_and_saveexec_b64 s[0:1], s[2:3]
	s_cbranch_execz .LBB0_380
	v_lshl_add_u64 v[106:107], s[22:23], 0, v[112:113]
	v_lshl_add_u64 v[106:107], s[18:19], 2, v[106:107]
	s_lshl_b32 s68, s53, 2
	s_mov_b32 s69, s19
	v_lshl_add_u64 v[106:107], v[106:107], 0, s[68:69]
	s_waitcnt lgkmcnt(0)
	v_add_f32_e32 v104, v104, v105
	global_store_dword v[106:107], v104, off

.LBB0_381:
	v_mov_b32_e32 v117, v116
	v_mov_b32_e32 v106, v116
	v_mov_b32_e32 v107, v116
	v_pk_mul_f32 v[98:99], v[106:107], v[98:99]
	s_waitcnt lgkmcnt(0)
	v_pk_mul_f32 v[104:105], v[116:117], v[96:97]
	v_pk_mul_f32 v[96:97], v[106:107], v[102:103]
	v_pk_mul_f32 v[100:101], v[116:117], v[100:101]
	s_and_b64 vcc, exec, s[6:7]
	v_cvt_pk_bf16_f32 v106, v104, v105
	v_cvt_pk_bf16_f32 v107, v98, v99
	v_cvt_pk_bf16_f32 v108, v100, v101
	v_cvt_pk_bf16_f32 v109, v96, v97
	global_store_dwordx4 v[114:115], v[106:109], off offset:256
	s_cbranch_vccnz .LBB0_385
	v_mul_f32_e32 v102, v105, v105
	v_mul_f32_e32 v99, v99, v99
	v_fmac_f32_e32 v102, v104, v104
	v_fmac_f32_e32 v99, v98, v98
	v_add_f32_e32 v98, v102, v99
	v_mul_f32_e32 v99, v101, v101
	v_mul_f32_e32 v97, v97, v97
	v_fmac_f32_e32 v99, v100, v100
	v_fmac_f32_e32 v97, v96, v96
	v_add_f32_e32 v96, v99, v97
	v_add_f32_e32 v96, v98, v96
	ds_bpermute_b32 v97, v160, v96
	s_waitcnt lgkmcnt(0)
	v_add_f32_e32 v96, v96, v97
	ds_bpermute_b32 v97, v161, v96
	s_and_saveexec_b64 s[0:1], s[2:3]
	s_cbranch_execz .LBB0_384
	v_lshl_add_u64 v[98:99], s[22:23], 0, v[112:113]
	v_lshl_add_u64 v[98:99], s[18:19], 2, v[98:99]
	s_lshl_b32 s68, s53, 2
	s_mov_b32 s69, s19
	v_lshl_add_u64 v[98:99], v[98:99], 0, s[68:69]
	s_waitcnt lgkmcnt(0)
	v_add_f32_e32 v96, v96, v97
	global_store_dword v[98:99], v96, off offset:16

.LBB0_385:
	s_waitcnt lgkmcnt(0)
	v_bitop3_b32 v97, v148, s63, 32 bitop3:0xc8
	v_lshl_add_u32 v97, v97, 2, 0
	v_add_u32_e32 v97, 0x20000, v97
	ds_read_b32 v100, v97
	v_or_b32_e32 v96, 32, v148
	v_ashrrev_i32_e32 v97, 31, v96
	v_mad_i64_i32 v[98:99], s[0:1], s40, v96, 0
	v_lshl_add_u64 v[98:99], v[98:99], 1, v[146:147]
	v_lshlrev_b64 v[96:97], 7, v[96:97]
	s_waitcnt lgkmcnt(0)
	v_pk_mul_f32 v[90:91], v[100:101], v[90:91] op_sel_hi:[0,1]
	v_pk_mul_f32 v[102:103], v[100:101], v[88:89] op_sel_hi:[0,1]
	v_pk_mul_f32 v[88:89], v[100:101], v[94:95] op_sel_hi:[0,1]
	v_pk_mul_f32 v[92:93], v[100:101], v[92:93] op_sel_hi:[0,1]
	s_and_b64 vcc, exec, s[6:7]
	v_cvt_pk_bf16_f32 v104, v102, v103
	v_cvt_pk_bf16_f32 v105, v90, v91
	v_cvt_pk_bf16_f32 v106, v92, v93
	v_cvt_pk_bf16_f32 v107, v88, v89
	global_store_dwordx4 v[98:99], v[104:107], off
	s_cbranch_vccnz .LBB0_389
	v_mul_f32_e32 v94, v103, v103
	v_mul_f32_e32 v91, v91, v91
	v_fmac_f32_e32 v94, v102, v102
	v_fmac_f32_e32 v91, v90, v90
	v_add_f32_e32 v90, v94, v91
	v_mul_f32_e32 v91, v93, v93
	v_mul_f32_e32 v89, v89, v89
	v_fmac_f32_e32 v91, v92, v92
	v_fmac_f32_e32 v89, v88, v88
	v_add_f32_e32 v88, v91, v89
	v_add_f32_e32 v88, v90, v88
	ds_bpermute_b32 v89, v160, v88
	s_waitcnt lgkmcnt(0)
	v_add_f32_e32 v88, v88, v89
	ds_bpermute_b32 v89, v161, v88
	s_and_saveexec_b64 s[0:1], s[2:3]
	s_cbranch_execz .LBB0_388
	v_lshl_add_u64 v[90:91], s[22:23], 0, v[96:97]
	v_lshl_add_u64 v[90:91], s[18:19], 2, v[90:91]
	s_lshl_b32 s68, s53, 2
	s_mov_b32 s69, s19
	v_lshl_add_u64 v[90:91], v[90:91], 0, s[68:69]
	s_waitcnt lgkmcnt(0)
	v_add_f32_e32 v88, v88, v89
	global_store_dword v[90:91], v88, off

.LBB0_389:
	v_mov_b32_e32 v101, v100
	v_mov_b32_e32 v90, v100
	v_mov_b32_e32 v91, v100
	v_pk_mul_f32 v[82:83], v[90:91], v[82:83]
	s_waitcnt lgkmcnt(0)
	v_pk_mul_f32 v[88:89], v[100:101], v[80:81]
	v_pk_mul_f32 v[80:81], v[90:91], v[86:87]
	v_pk_mul_f32 v[84:85], v[100:101], v[84:85]
	s_and_b64 vcc, exec, s[6:7]
	v_cvt_pk_bf16_f32 v90, v88, v89
	v_cvt_pk_bf16_f32 v91, v82, v83
	v_cvt_pk_bf16_f32 v92, v84, v85
	v_cvt_pk_bf16_f32 v93, v80, v81
	global_store_dwordx4 v[98:99], v[90:93], off offset:256
	s_cbranch_vccnz .LBB0_393
	v_mul_f32_e32 v86, v89, v89
	v_mul_f32_e32 v83, v83, v83
	v_fmac_f32_e32 v86, v88, v88
	v_fmac_f32_e32 v83, v82, v82
	v_add_f32_e32 v82, v86, v83
	v_mul_f32_e32 v83, v85, v85
	v_mul_f32_e32 v81, v81, v81
	v_fmac_f32_e32 v83, v84, v84
	v_fmac_f32_e32 v81, v80, v80
	v_add_f32_e32 v80, v83, v81
	v_add_f32_e32 v80, v82, v80
	ds_bpermute_b32 v81, v160, v80
	s_waitcnt lgkmcnt(0)
	v_add_f32_e32 v80, v80, v81
	ds_bpermute_b32 v81, v161, v80
	s_and_saveexec_b64 s[0:1], s[2:3]
	s_cbranch_execz .LBB0_392
	v_lshl_add_u64 v[82:83], s[22:23], 0, v[96:97]
	v_lshl_add_u64 v[82:83], s[18:19], 2, v[82:83]
	s_lshl_b32 s68, s53, 2
	s_mov_b32 s69, s19
	v_lshl_add_u64 v[82:83], v[82:83], 0, s[68:69]
	s_waitcnt lgkmcnt(0)
	v_add_f32_e32 v80, v80, v81
	global_store_dword v[82:83], v80, off offset:16

.LBB0_393:
	s_waitcnt lgkmcnt(0)
	v_bitop3_b32 v81, v148, s64, 48 bitop3:0xc8
	v_lshl_add_u32 v81, v81, 2, 0
	v_add_u32_e32 v81, 0x20000, v81
	ds_read_b32 v84, v81
	v_or_b32_e32 v80, 48, v148
	v_ashrrev_i32_e32 v81, 31, v80
	v_mad_i64_i32 v[82:83], s[0:1], s40, v80, 0
	v_lshl_add_u64 v[82:83], v[82:83], 1, v[146:147]
	v_lshlrev_b64 v[80:81], 7, v[80:81]
	s_waitcnt lgkmcnt(0)
	v_pk_mul_f32 v[74:75], v[84:85], v[74:75] op_sel_hi:[0,1]
	v_pk_mul_f32 v[86:87], v[84:85], v[72:73] op_sel_hi:[0,1]
	v_pk_mul_f32 v[72:73], v[84:85], v[78:79] op_sel_hi:[0,1]
	v_pk_mul_f32 v[76:77], v[84:85], v[76:77] op_sel_hi:[0,1]
	s_and_b64 vcc, exec, s[6:7]
	v_cvt_pk_bf16_f32 v88, v86, v87
	v_cvt_pk_bf16_f32 v89, v74, v75
	v_cvt_pk_bf16_f32 v90, v76, v77
	v_cvt_pk_bf16_f32 v91, v72, v73
	global_store_dwordx4 v[82:83], v[88:91], off
	s_cbranch_vccnz .LBB0_397
	v_mul_f32_e32 v78, v87, v87
	v_mul_f32_e32 v75, v75, v75
	v_fmac_f32_e32 v78, v86, v86
	v_fmac_f32_e32 v75, v74, v74
	v_add_f32_e32 v74, v78, v75
	v_mul_f32_e32 v75, v77, v77
	v_mul_f32_e32 v73, v73, v73
	v_fmac_f32_e32 v75, v76, v76
	v_fmac_f32_e32 v73, v72, v72
	v_add_f32_e32 v72, v75, v73
	v_add_f32_e32 v72, v74, v72
	ds_bpermute_b32 v73, v160, v72
	s_waitcnt lgkmcnt(0)
	v_add_f32_e32 v72, v72, v73
	ds_bpermute_b32 v73, v161, v72
	s_and_saveexec_b64 s[0:1], s[2:3]
	s_cbranch_execz .LBB0_396
	v_lshl_add_u64 v[74:75], s[22:23], 0, v[80:81]
	v_lshl_add_u64 v[74:75], s[18:19], 2, v[74:75]
	s_lshl_b32 s68, s53, 2
	s_mov_b32 s69, s19
	v_lshl_add_u64 v[74:75], v[74:75], 0, s[68:69]
	s_waitcnt lgkmcnt(0)
	v_add_f32_e32 v72, v72, v73
	global_store_dword v[74:75], v72, off

.LBB0_397:
	v_mov_b32_e32 v85, v84
	v_mov_b32_e32 v74, v84
	v_mov_b32_e32 v75, v84
	v_pk_mul_f32 v[66:67], v[74:75], v[66:67]
	s_waitcnt lgkmcnt(0)
	v_pk_mul_f32 v[72:73], v[84:85], v[64:65]
	v_pk_mul_f32 v[64:65], v[74:75], v[70:71]
	v_pk_mul_f32 v[68:69], v[84:85], v[68:69]
	s_and_b64 vcc, exec, s[6:7]
	v_cvt_pk_bf16_f32 v74, v72, v73
	v_cvt_pk_bf16_f32 v75, v66, v67
	v_cvt_pk_bf16_f32 v76, v68, v69
	v_cvt_pk_bf16_f32 v77, v64, v65
	global_store_dwordx4 v[82:83], v[74:77], off offset:256
	s_cbranch_vccnz .LBB0_401
	v_mul_f32_e32 v70, v73, v73
	v_mul_f32_e32 v67, v67, v67
	v_fmac_f32_e32 v70, v72, v72
	v_fmac_f32_e32 v67, v66, v66
	v_add_f32_e32 v66, v70, v67
	v_mul_f32_e32 v67, v69, v69
	v_mul_f32_e32 v65, v65, v65
	v_fmac_f32_e32 v67, v68, v68
	v_fmac_f32_e32 v65, v64, v64
	v_add_f32_e32 v64, v67, v65
	v_add_f32_e32 v64, v66, v64
	ds_bpermute_b32 v65, v160, v64
	s_waitcnt lgkmcnt(0)
	v_add_f32_e32 v64, v64, v65
	ds_bpermute_b32 v65, v161, v64
	s_and_saveexec_b64 s[0:1], s[2:3]
	s_cbranch_execz .LBB0_400
	v_lshl_add_u64 v[66:67], s[22:23], 0, v[80:81]
	v_lshl_add_u64 v[66:67], s[18:19], 2, v[66:67]
	s_lshl_b32 s68, s53, 2
	s_mov_b32 s69, s19
	v_lshl_add_u64 v[66:67], v[66:67], 0, s[68:69]
	s_waitcnt lgkmcnt(0)
	v_add_f32_e32 v64, v64, v65
	global_store_dword v[66:67], v64, off offset:16

.LBB0_401:
	v_add_u32_e32 v64, 0x80, v148
	s_waitcnt lgkmcnt(0)
	v_and_b32_e32 v65, 0x7cf, v64
	v_lshl_add_u32 v65, v65, 2, 0
	v_add_u32_e32 v65, 0x20000, v65
	ds_read_b32 v68, v65
	v_ashrrev_i32_e32 v65, 31, v64
	v_mad_i64_i32 v[66:67], s[0:1], s40, v64, 0
	v_lshl_add_u64 v[66:67], v[66:67], 1, v[146:147]
	v_lshlrev_b64 v[64:65], 7, v[64:65]
	s_waitcnt lgkmcnt(0)
	v_pk_mul_f32 v[58:59], v[68:69], v[58:59] op_sel_hi:[0,1]
	v_pk_mul_f32 v[70:71], v[68:69], v[56:57] op_sel_hi:[0,1]
	v_pk_mul_f32 v[56:57], v[68:69], v[62:63] op_sel_hi:[0,1]
	v_pk_mul_f32 v[60:61], v[68:69], v[60:61] op_sel_hi:[0,1]
	s_and_b64 vcc, exec, s[6:7]
	v_cvt_pk_bf16_f32 v72, v70, v71
	v_cvt_pk_bf16_f32 v73, v58, v59
	v_cvt_pk_bf16_f32 v74, v60, v61
	v_cvt_pk_bf16_f32 v75, v56, v57
	global_store_dwordx4 v[66:67], v[72:75], off
	s_cbranch_vccnz .LBB0_405
	v_mul_f32_e32 v62, v71, v71
	v_mul_f32_e32 v59, v59, v59
	v_fmac_f32_e32 v62, v70, v70
	v_fmac_f32_e32 v59, v58, v58
	v_add_f32_e32 v58, v62, v59
	v_mul_f32_e32 v59, v61, v61
	v_mul_f32_e32 v57, v57, v57
	v_fmac_f32_e32 v59, v60, v60
	v_fmac_f32_e32 v57, v56, v56
	v_add_f32_e32 v56, v59, v57
	v_add_f32_e32 v56, v58, v56
	ds_bpermute_b32 v57, v160, v56
	s_waitcnt lgkmcnt(0)
	v_add_f32_e32 v56, v56, v57
	ds_bpermute_b32 v57, v161, v56
	s_and_saveexec_b64 s[0:1], s[2:3]
	s_cbranch_execz .LBB0_404
	v_lshl_add_u64 v[58:59], s[22:23], 0, v[64:65]
	v_lshl_add_u64 v[58:59], s[18:19], 2, v[58:59]
	s_lshl_b32 s68, s53, 2
	s_mov_b32 s69, s19
	v_lshl_add_u64 v[58:59], v[58:59], 0, s[68:69]
	s_waitcnt lgkmcnt(0)
	v_add_f32_e32 v56, v56, v57
	global_store_dword v[58:59], v56, off

.LBB0_405:
	v_mov_b32_e32 v69, v68
	v_mov_b32_e32 v58, v68
	v_mov_b32_e32 v59, v68
	v_pk_mul_f32 v[50:51], v[58:59], v[50:51]
	s_waitcnt lgkmcnt(0)
	v_pk_mul_f32 v[56:57], v[68:69], v[48:49]
	v_pk_mul_f32 v[48:49], v[58:59], v[54:55]
	v_pk_mul_f32 v[52:53], v[68:69], v[52:53]
	s_and_b64 vcc, exec, s[6:7]
	v_cvt_pk_bf16_f32 v58, v56, v57
	v_cvt_pk_bf16_f32 v59, v50, v51
	v_cvt_pk_bf16_f32 v60, v52, v53
	v_cvt_pk_bf16_f32 v61, v48, v49
	global_store_dwordx4 v[66:67], v[58:61], off offset:256
	s_cbranch_vccnz .LBB0_409
	v_mul_f32_e32 v54, v57, v57
	v_mul_f32_e32 v51, v51, v51
	v_fmac_f32_e32 v54, v56, v56
	v_fmac_f32_e32 v51, v50, v50
	v_add_f32_e32 v50, v54, v51
	v_mul_f32_e32 v51, v53, v53
	v_mul_f32_e32 v49, v49, v49
	v_fmac_f32_e32 v51, v52, v52
	v_fmac_f32_e32 v49, v48, v48
	v_add_f32_e32 v48, v51, v49
	v_add_f32_e32 v48, v50, v48
	ds_bpermute_b32 v49, v160, v48
	s_waitcnt lgkmcnt(0)
	v_add_f32_e32 v48, v48, v49
	ds_bpermute_b32 v49, v161, v48
	s_and_saveexec_b64 s[0:1], s[2:3]
	s_cbranch_execz .LBB0_408
	v_lshl_add_u64 v[50:51], s[22:23], 0, v[64:65]
	v_lshl_add_u64 v[50:51], s[18:19], 2, v[50:51]
	s_lshl_b32 s68, s53, 2
	s_mov_b32 s69, s19
	v_lshl_add_u64 v[50:51], v[50:51], 0, s[68:69]
	s_waitcnt lgkmcnt(0)
	v_add_f32_e32 v48, v48, v49
	global_store_dword v[50:51], v48, off offset:16

.LBB0_409:
	v_add_u32_e32 v48, 0x90, v148
	s_waitcnt lgkmcnt(0)
	v_and_b32_e32 v49, 0x7df, v48
	v_lshl_add_u32 v49, v49, 2, 0
	v_add_u32_e32 v49, 0x20000, v49
	ds_read_b32 v52, v49
	v_ashrrev_i32_e32 v49, 31, v48
	v_mad_i64_i32 v[50:51], s[0:1], s40, v48, 0
	v_lshl_add_u64 v[50:51], v[50:51], 1, v[146:147]
	v_lshlrev_b64 v[48:49], 7, v[48:49]
	s_waitcnt lgkmcnt(0)
	v_pk_mul_f32 v[42:43], v[52:53], v[42:43] op_sel_hi:[0,1]
	v_pk_mul_f32 v[54:55], v[52:53], v[40:41] op_sel_hi:[0,1]
	v_pk_mul_f32 v[40:41], v[52:53], v[46:47] op_sel_hi:[0,1]
	v_pk_mul_f32 v[44:45], v[52:53], v[44:45] op_sel_hi:[0,1]
	s_and_b64 vcc, exec, s[6:7]
	v_cvt_pk_bf16_f32 v56, v54, v55
	v_cvt_pk_bf16_f32 v57, v42, v43
	v_cvt_pk_bf16_f32 v58, v44, v45
	v_cvt_pk_bf16_f32 v59, v40, v41
	global_store_dwordx4 v[50:51], v[56:59], off
	s_cbranch_vccnz .LBB0_413
	v_mul_f32_e32 v46, v55, v55
	v_mul_f32_e32 v43, v43, v43
	v_fmac_f32_e32 v46, v54, v54
	v_fmac_f32_e32 v43, v42, v42
	v_add_f32_e32 v42, v46, v43
	v_mul_f32_e32 v43, v45, v45
	v_mul_f32_e32 v41, v41, v41
	v_fmac_f32_e32 v43, v44, v44
	v_fmac_f32_e32 v41, v40, v40
	v_add_f32_e32 v40, v43, v41
	v_add_f32_e32 v40, v42, v40
	ds_bpermute_b32 v41, v160, v40
	s_waitcnt lgkmcnt(0)
	v_add_f32_e32 v40, v40, v41
	ds_bpermute_b32 v41, v161, v40
	s_and_saveexec_b64 s[0:1], s[2:3]
	s_cbranch_execz .LBB0_412
	v_lshl_add_u64 v[42:43], s[22:23], 0, v[48:49]
	v_lshl_add_u64 v[42:43], s[18:19], 2, v[42:43]
	s_lshl_b32 s68, s53, 2
	s_mov_b32 s69, s19
	v_lshl_add_u64 v[42:43], v[42:43], 0, s[68:69]
	s_waitcnt lgkmcnt(0)
	v_add_f32_e32 v40, v40, v41
	global_store_dword v[42:43], v40, off

.LBB0_413:
	v_mov_b32_e32 v53, v52
	v_mov_b32_e32 v42, v52
	v_mov_b32_e32 v43, v52
	v_pk_mul_f32 v[34:35], v[42:43], v[34:35]
	s_waitcnt lgkmcnt(0)
	v_pk_mul_f32 v[40:41], v[52:53], v[32:33]
	v_pk_mul_f32 v[32:33], v[42:43], v[38:39]
	v_pk_mul_f32 v[36:37], v[52:53], v[36:37]
	s_and_b64 vcc, exec, s[6:7]
	v_cvt_pk_bf16_f32 v42, v40, v41
	v_cvt_pk_bf16_f32 v43, v34, v35
	v_cvt_pk_bf16_f32 v44, v36, v37
	v_cvt_pk_bf16_f32 v45, v32, v33
	global_store_dwordx4 v[50:51], v[42:45], off offset:256
	s_cbranch_vccnz .LBB0_417
	v_mul_f32_e32 v38, v41, v41
	v_mul_f32_e32 v35, v35, v35
	v_fmac_f32_e32 v38, v40, v40
	v_fmac_f32_e32 v35, v34, v34
	v_add_f32_e32 v34, v38, v35
	v_mul_f32_e32 v35, v37, v37
	v_mul_f32_e32 v33, v33, v33
	v_fmac_f32_e32 v35, v36, v36
	v_fmac_f32_e32 v33, v32, v32
	v_add_f32_e32 v32, v35, v33
	v_add_f32_e32 v32, v34, v32
	ds_bpermute_b32 v33, v160, v32
	s_waitcnt lgkmcnt(0)
	v_add_f32_e32 v32, v32, v33
	ds_bpermute_b32 v33, v161, v32
	s_and_saveexec_b64 s[0:1], s[2:3]
	s_cbranch_execz .LBB0_416
	v_lshl_add_u64 v[34:35], s[22:23], 0, v[48:49]
	v_lshl_add_u64 v[34:35], s[18:19], 2, v[34:35]
	s_lshl_b32 s68, s53, 2
	s_mov_b32 s69, s19
	v_lshl_add_u64 v[34:35], v[34:35], 0, s[68:69]
	s_waitcnt lgkmcnt(0)
	v_add_f32_e32 v32, v32, v33
	global_store_dword v[34:35], v32, off offset:16

.LBB0_417:
	v_add_u32_e32 v32, 0xa0, v148
	s_waitcnt lgkmcnt(0)
	v_and_b32_e32 v33, 0x7ef, v32
	v_lshl_add_u32 v33, v33, 2, 0
	v_add_u32_e32 v33, 0x20000, v33
	ds_read_b32 v36, v33
	v_ashrrev_i32_e32 v33, 31, v32
	v_mad_i64_i32 v[34:35], s[0:1], s40, v32, 0
	v_lshl_add_u64 v[34:35], v[34:35], 1, v[146:147]
	v_lshlrev_b64 v[32:33], 7, v[32:33]
	s_waitcnt lgkmcnt(0)
	v_pk_mul_f32 v[26:27], v[36:37], v[26:27] op_sel_hi:[0,1]
	v_pk_mul_f32 v[38:39], v[36:37], v[24:25] op_sel_hi:[0,1]
	v_pk_mul_f32 v[24:25], v[36:37], v[30:31] op_sel_hi:[0,1]
	v_pk_mul_f32 v[28:29], v[36:37], v[28:29] op_sel_hi:[0,1]
	s_and_b64 vcc, exec, s[6:7]
	v_cvt_pk_bf16_f32 v40, v38, v39
	v_cvt_pk_bf16_f32 v41, v26, v27
	v_cvt_pk_bf16_f32 v42, v28, v29
	v_cvt_pk_bf16_f32 v43, v24, v25
	global_store_dwordx4 v[34:35], v[40:43], off
	s_cbranch_vccnz .LBB0_421
	v_mul_f32_e32 v30, v39, v39
	v_mul_f32_e32 v27, v27, v27
	v_fmac_f32_e32 v30, v38, v38
	v_fmac_f32_e32 v27, v26, v26
	v_add_f32_e32 v26, v30, v27
	v_mul_f32_e32 v27, v29, v29
	v_mul_f32_e32 v25, v25, v25
	v_fmac_f32_e32 v27, v28, v28
	v_fmac_f32_e32 v25, v24, v24
	v_add_f32_e32 v24, v27, v25
	v_add_f32_e32 v24, v26, v24
	ds_bpermute_b32 v25, v160, v24
	s_waitcnt lgkmcnt(0)
	v_add_f32_e32 v24, v24, v25
	ds_bpermute_b32 v25, v161, v24
	s_and_saveexec_b64 s[0:1], s[2:3]
	s_cbranch_execz .LBB0_420
	v_lshl_add_u64 v[26:27], s[22:23], 0, v[32:33]
	v_lshl_add_u64 v[26:27], s[18:19], 2, v[26:27]
	s_lshl_b32 s68, s53, 2
	s_mov_b32 s69, s19
	v_lshl_add_u64 v[26:27], v[26:27], 0, s[68:69]
	s_waitcnt lgkmcnt(0)
	v_add_f32_e32 v24, v24, v25
	global_store_dword v[26:27], v24, off

.LBB0_421:
	v_mov_b32_e32 v37, v36
	v_mov_b32_e32 v26, v36
	v_mov_b32_e32 v27, v36
	v_pk_mul_f32 v[18:19], v[26:27], v[18:19]
	s_waitcnt lgkmcnt(0)
	v_pk_mul_f32 v[24:25], v[36:37], v[16:17]
	v_pk_mul_f32 v[16:17], v[26:27], v[22:23]
	v_pk_mul_f32 v[20:21], v[36:37], v[20:21]
	s_and_b64 vcc, exec, s[6:7]
	v_cvt_pk_bf16_f32 v26, v24, v25
	v_cvt_pk_bf16_f32 v27, v18, v19
	v_cvt_pk_bf16_f32 v28, v20, v21
	v_cvt_pk_bf16_f32 v29, v16, v17
	global_store_dwordx4 v[34:35], v[26:29], off offset:256
	s_cbranch_vccnz .LBB0_425
	v_mul_f32_e32 v22, v25, v25
	v_mul_f32_e32 v19, v19, v19
	v_fmac_f32_e32 v22, v24, v24
	v_fmac_f32_e32 v19, v18, v18
	v_add_f32_e32 v18, v22, v19
	v_mul_f32_e32 v19, v21, v21
	v_mul_f32_e32 v17, v17, v17
	v_fmac_f32_e32 v19, v20, v20
	v_fmac_f32_e32 v17, v16, v16
	v_add_f32_e32 v16, v19, v17
	v_add_f32_e32 v16, v18, v16
	ds_bpermute_b32 v17, v160, v16
	s_waitcnt lgkmcnt(0)
	v_add_f32_e32 v16, v16, v17
	ds_bpermute_b32 v17, v161, v16
	s_and_saveexec_b64 s[0:1], s[2:3]
	s_cbranch_execz .LBB0_424
	v_lshl_add_u64 v[18:19], s[22:23], 0, v[32:33]
	v_lshl_add_u64 v[18:19], s[18:19], 2, v[18:19]
	s_lshl_b32 s68, s53, 2
	s_mov_b32 s69, s19
	v_lshl_add_u64 v[18:19], v[18:19], 0, s[68:69]
	s_waitcnt lgkmcnt(0)
	v_add_f32_e32 v16, v16, v17
	global_store_dword v[18:19], v16, off offset:16

.LBB0_425:
	v_add_u32_e32 v16, 0xb0, v148
	s_waitcnt lgkmcnt(0)
	v_and_b32_e32 v17, 0x7ff, v16
	v_lshl_add_u32 v17, v17, 2, 0
	v_add_u32_e32 v17, 0x20000, v17
	ds_read_b32 v20, v17
	v_ashrrev_i32_e32 v17, 31, v16
	v_mad_i64_i32 v[18:19], s[0:1], s40, v16, 0
	v_lshl_add_u64 v[18:19], v[18:19], 1, v[146:147]
	v_lshlrev_b64 v[16:17], 7, v[16:17]
	s_waitcnt lgkmcnt(0)
	v_pk_mul_f32 v[10:11], v[20:21], v[10:11] op_sel_hi:[0,1]
	v_pk_mul_f32 v[22:23], v[20:21], v[8:9] op_sel_hi:[0,1]
	v_pk_mul_f32 v[8:9], v[20:21], v[14:15] op_sel_hi:[0,1]
	v_pk_mul_f32 v[12:13], v[20:21], v[12:13] op_sel_hi:[0,1]
	s_and_b64 vcc, exec, s[6:7]
	v_cvt_pk_bf16_f32 v24, v22, v23
	v_cvt_pk_bf16_f32 v25, v10, v11
	v_cvt_pk_bf16_f32 v26, v12, v13
	v_cvt_pk_bf16_f32 v27, v8, v9
	global_store_dwordx4 v[18:19], v[24:27], off
	s_cbranch_vccnz .LBB0_429
	v_mul_f32_e32 v14, v23, v23
	v_mul_f32_e32 v11, v11, v11
	v_fmac_f32_e32 v14, v22, v22
	v_fmac_f32_e32 v11, v10, v10
	v_add_f32_e32 v10, v14, v11
	v_mul_f32_e32 v11, v13, v13
	v_mul_f32_e32 v9, v9, v9
	v_fmac_f32_e32 v11, v12, v12
	v_fmac_f32_e32 v9, v8, v8
	v_add_f32_e32 v8, v11, v9
	v_add_f32_e32 v8, v10, v8
	ds_bpermute_b32 v9, v160, v8
	s_waitcnt lgkmcnt(0)
	v_add_f32_e32 v8, v8, v9
	ds_bpermute_b32 v9, v161, v8
	s_and_saveexec_b64 s[0:1], s[2:3]
	s_cbranch_execz .LBB0_428
	v_lshl_add_u64 v[10:11], s[22:23], 0, v[16:17]
	v_lshl_add_u64 v[10:11], s[18:19], 2, v[10:11]
	s_lshl_b32 s40, s53, 2
	s_mov_b32 s41, s19
	v_lshl_add_u64 v[10:11], v[10:11], 0, s[40:41]
	s_waitcnt lgkmcnt(0)
	v_add_f32_e32 v8, v8, v9
	global_store_dword v[10:11], v8, off

.LBB0_429:
	v_mov_b32_e32 v21, v20
	v_mov_b32_e32 v10, v20
	v_mov_b32_e32 v11, v20
	v_pk_mul_f32 v[2:3], v[10:11], v[2:3]
	s_waitcnt lgkmcnt(0)
	v_pk_mul_f32 v[8:9], v[20:21], v[0:1]
	v_pk_mul_f32 v[0:1], v[10:11], v[6:7]
	v_pk_mul_f32 v[4:5], v[20:21], v[4:5]
	s_and_b64 vcc, exec, s[6:7]
	v_cvt_pk_bf16_f32 v10, v8, v9
	v_cvt_pk_bf16_f32 v11, v2, v3
	v_cvt_pk_bf16_f32 v12, v4, v5
	v_cvt_pk_bf16_f32 v13, v0, v1
	global_store_dwordx4 v[18:19], v[10:13], off offset:256
	s_cbranch_vccnz .LBB0_433
	v_mul_f32_e32 v6, v9, v9
	v_mul_f32_e32 v3, v3, v3
	v_fmac_f32_e32 v6, v8, v8
	v_fmac_f32_e32 v3, v2, v2
	v_add_f32_e32 v2, v6, v3
	v_mul_f32_e32 v3, v5, v5
	v_mul_f32_e32 v1, v1, v1
	v_fmac_f32_e32 v3, v4, v4
	v_fmac_f32_e32 v1, v0, v0
	v_add_f32_e32 v0, v3, v1
	v_add_f32_e32 v0, v2, v0
	ds_bpermute_b32 v1, v160, v0
	s_waitcnt lgkmcnt(0)
	v_add_f32_e32 v0, v0, v1
	ds_bpermute_b32 v1, v161, v0
	s_and_saveexec_b64 s[0:1], s[2:3]
	s_cbranch_execz .LBB0_432
	v_lshl_add_u64 v[2:3], s[22:23], 0, v[16:17]
	v_lshl_add_u64 v[2:3], s[18:19], 2, v[2:3]
	s_lshl_b32 s18, s53, 2
	v_lshl_add_u64 v[2:3], v[2:3], 0, s[18:19]
	s_waitcnt lgkmcnt(0)
	v_add_f32_e32 v0, v0, v1
	global_store_dword v[2:3], v0, off offset:16

.LBB0_509:
	s_add_i32 s44, s7, 2
	s_lshl_b32 s0, s7, 8
	v_lshl_add_u32 v142, s6, 8, v156
	s_add_i32 s6, s0, 0x800
	s_lshl_b32 s20, s44, 8
	s_cmp_gt_i32 s7, -3
	s_cselect_b64 s[0:1], -1, 0
	s_and_b64 s[42:43], s[0:1], exec
	s_cselect_b32 s20, s20, s6
	s_cselect_b32 s6, s62, 0xb000000
	v_and_b32_e32 v143, 0x7cf, v142
	s_cselect_b32 s37, s63, 0x600
	s_add_u32 s6, s8, s6
	v_lshl_add_u32 v143, v143, 2, 0
	s_addc_u32 s45, s9, 0
	s_lshl_b64 s[42:43], s[20:21], 1
	v_add_u32_e32 v143, 0x20000, v143
	s_add_u32 s6, s6, s42
	ds_read_b32 v150, v143
	s_addc_u32 s20, s45, s43
	s_add_u32 s42, s6, s64
	s_addc_u32 s43, s20, 0
	s_lshl_b32 s20, s44, 3
	s_cmp_lt_i32 s7, -2
	v_lshl_add_u64 v[144:145], v[136:137], 1, s[42:43]
	v_ashrrev_i32_e32 v143, 31, v142
	v_mad_i64_i32 v[146:147], s[6:7], s37, v142, 0
	v_lshl_add_u64 v[148:149], v[146:147], 1, v[144:145]
	v_lshlrev_b64 v[146:147], 7, v[142:143]
	s_waitcnt lgkmcnt(0)
	v_pk_mul_f32 v[122:123], v[150:151], v[122:123] op_sel_hi:[0,1]
	v_pk_mul_f32 v[152:153], v[150:151], v[120:121] op_sel_hi:[0,1]
	v_pk_mul_f32 v[120:121], v[150:151], v[126:127] op_sel_hi:[0,1]
	v_pk_mul_f32 v[124:125], v[150:151], v[124:125] op_sel_hi:[0,1]
	v_cvt_pk_bf16_f32 v162, v152, v153
	v_cvt_pk_bf16_f32 v163, v122, v123
	v_cvt_pk_bf16_f32 v164, v124, v125
	v_cvt_pk_bf16_f32 v165, v120, v121
	global_store_dwordx4 v[148:149], v[162:165], off
	s_cbranch_scc1 .LBB0_513
	v_mul_f32_e32 v126, v153, v153
	v_mul_f32_e32 v123, v123, v123
	v_fmac_f32_e32 v126, v152, v152
	v_fmac_f32_e32 v123, v122, v122
	v_add_f32_e32 v122, v126, v123
	v_mul_f32_e32 v123, v125, v125
	v_mul_f32_e32 v121, v121, v121
	v_fmac_f32_e32 v123, v124, v124
	v_fmac_f32_e32 v121, v120, v120
	v_add_f32_e32 v120, v123, v121
	v_add_f32_e32 v120, v122, v120
	ds_bpermute_b32 v121, v158, v120
	s_waitcnt lgkmcnt(0)
	v_add_f32_e32 v120, v120, v121
	ds_bpermute_b32 v121, v159, v120
	s_and_saveexec_b64 s[6:7], s[2:3]
	s_cbranch_execz .LBB0_512
	v_lshl_add_u64 v[122:123], s[24:25], 0, v[146:147]
	v_lshl_add_u64 v[122:123], s[20:21], 2, v[122:123]
	s_lshl_b32 s42, s46, 2
	s_mov_b32 s43, s21
	v_lshl_add_u64 v[122:123], v[122:123], 0, s[42:43]
	s_waitcnt lgkmcnt(0)
	v_add_f32_e32 v120, v120, v121
	global_store_dword v[122:123], v120, off

.LBB0_513:
	v_mov_b32_e32 v151, v150
	v_mov_b32_e32 v122, v150
	v_mov_b32_e32 v123, v150
	s_waitcnt lgkmcnt(0)
	v_pk_mul_f32 v[120:121], v[150:151], v[112:113]
	v_pk_mul_f32 v[112:113], v[122:123], v[118:119]
	v_cndmask_b32_e64 v118, 0, 1, s[0:1]
	v_pk_mul_f32 v[114:115], v[122:123], v[114:115]
	v_pk_mul_f32 v[116:117], v[150:151], v[116:117]
	v_cmp_ne_u32_e64 s[6:7], 1, v118
	s_andn2_b64 vcc, exec, s[0:1]
	v_cvt_pk_bf16_f32 v122, v120, v121
	v_cvt_pk_bf16_f32 v123, v114, v115
	v_cvt_pk_bf16_f32 v124, v116, v117
	v_cvt_pk_bf16_f32 v125, v112, v113
	global_store_dwordx4 v[148:149], v[122:125], off offset:256
	s_cbranch_vccnz .LBB0_517
	v_mul_f32_e32 v118, v121, v121
	v_mul_f32_e32 v115, v115, v115
	v_fmac_f32_e32 v118, v120, v120
	v_fmac_f32_e32 v115, v114, v114
	v_add_f32_e32 v114, v118, v115
	v_mul_f32_e32 v115, v117, v117
	v_mul_f32_e32 v113, v113, v113
	v_fmac_f32_e32 v115, v116, v116
	v_fmac_f32_e32 v113, v112, v112
	v_add_f32_e32 v112, v115, v113
	v_add_f32_e32 v112, v114, v112
	ds_bpermute_b32 v113, v158, v112
	s_waitcnt lgkmcnt(0)
	v_add_f32_e32 v112, v112, v113
	ds_bpermute_b32 v113, v159, v112
	s_and_saveexec_b64 s[0:1], s[2:3]
	s_cbranch_execz .LBB0_516
	v_lshl_add_u64 v[114:115], s[24:25], 0, v[146:147]
	v_lshl_add_u64 v[114:115], s[20:21], 2, v[114:115]
	s_lshl_b32 s42, s46, 2
	s_mov_b32 s43, s21
	v_lshl_add_u64 v[114:115], v[114:115], 0, s[42:43]
	s_waitcnt lgkmcnt(0)
	v_add_f32_e32 v112, v112, v113
	global_store_dword v[114:115], v112, off offset:16

.LBB0_517:
	s_waitcnt lgkmcnt(0)
	v_bitop3_b32 v113, v142, s65, 16 bitop3:0xc8
	v_lshl_add_u32 v113, v113, 2, 0
	v_add_u32_e32 v113, 0x20000, v113
	ds_read_b32 v116, v113
	v_or_b32_e32 v112, 16, v142
	v_ashrrev_i32_e32 v113, 31, v112
	v_mad_i64_i32 v[114:115], s[0:1], s37, v112, 0
	v_lshl_add_u64 v[114:115], v[114:115], 1, v[144:145]
	v_lshlrev_b64 v[112:113], 7, v[112:113]
	s_waitcnt lgkmcnt(0)
	v_pk_mul_f32 v[106:107], v[116:117], v[106:107] op_sel_hi:[0,1]
	v_pk_mul_f32 v[118:119], v[116:117], v[104:105] op_sel_hi:[0,1]
	v_pk_mul_f32 v[104:105], v[116:117], v[110:111] op_sel_hi:[0,1]
	v_pk_mul_f32 v[108:109], v[116:117], v[108:109] op_sel_hi:[0,1]
	s_and_b64 vcc, exec, s[6:7]
	v_cvt_pk_bf16_f32 v120, v118, v119
	v_cvt_pk_bf16_f32 v121, v106, v107
	v_cvt_pk_bf16_f32 v122, v108, v109
	v_cvt_pk_bf16_f32 v123, v104, v105
	global_store_dwordx4 v[114:115], v[120:123], off
	s_cbranch_vccnz .LBB0_521
	v_mul_f32_e32 v110, v119, v119
	v_mul_f32_e32 v107, v107, v107
	v_fmac_f32_e32 v110, v118, v118
	v_fmac_f32_e32 v107, v106, v106
	v_add_f32_e32 v106, v110, v107
	v_mul_f32_e32 v107, v109, v109
	v_mul_f32_e32 v105, v105, v105
	v_fmac_f32_e32 v107, v108, v108
	v_fmac_f32_e32 v105, v104, v104
	v_add_f32_e32 v104, v107, v105
	v_add_f32_e32 v104, v106, v104
	ds_bpermute_b32 v105, v158, v104
	s_waitcnt lgkmcnt(0)
	v_add_f32_e32 v104, v104, v105
	ds_bpermute_b32 v105, v159, v104
	s_and_saveexec_b64 s[0:1], s[2:3]
	s_cbranch_execz .LBB0_520
	v_lshl_add_u64 v[106:107], s[24:25], 0, v[112:113]
	v_lshl_add_u64 v[106:107], s[20:21], 2, v[106:107]
	s_lshl_b32 s42, s46, 2
	s_mov_b32 s43, s21
	v_lshl_add_u64 v[106:107], v[106:107], 0, s[42:43]
	s_waitcnt lgkmcnt(0)
	v_add_f32_e32 v104, v104, v105
	global_store_dword v[106:107], v104, off

.LBB0_521:
	v_mov_b32_e32 v117, v116
	v_mov_b32_e32 v106, v116
	v_mov_b32_e32 v107, v116
	v_pk_mul_f32 v[98:99], v[106:107], v[98:99]
	s_waitcnt lgkmcnt(0)
	v_pk_mul_f32 v[104:105], v[116:117], v[96:97]
	v_pk_mul_f32 v[96:97], v[106:107], v[102:103]
	v_pk_mul_f32 v[100:101], v[116:117], v[100:101]
	s_and_b64 vcc, exec, s[6:7]
	v_cvt_pk_bf16_f32 v106, v104, v105
	v_cvt_pk_bf16_f32 v107, v98, v99
	v_cvt_pk_bf16_f32 v108, v100, v101
	v_cvt_pk_bf16_f32 v109, v96, v97
	global_store_dwordx4 v[114:115], v[106:109], off offset:256
	s_cbranch_vccnz .LBB0_525
	v_mul_f32_e32 v102, v105, v105
	v_mul_f32_e32 v99, v99, v99
	v_fmac_f32_e32 v102, v104, v104
	v_fmac_f32_e32 v99, v98, v98
	v_add_f32_e32 v98, v102, v99
	v_mul_f32_e32 v99, v101, v101
	v_mul_f32_e32 v97, v97, v97
	v_fmac_f32_e32 v99, v100, v100
	v_fmac_f32_e32 v97, v96, v96
	v_add_f32_e32 v96, v99, v97
	v_add_f32_e32 v96, v98, v96
	ds_bpermute_b32 v97, v158, v96
	s_waitcnt lgkmcnt(0)
	v_add_f32_e32 v96, v96, v97
	ds_bpermute_b32 v97, v159, v96
	s_and_saveexec_b64 s[0:1], s[2:3]
	s_cbranch_execz .LBB0_524
	v_lshl_add_u64 v[98:99], s[24:25], 0, v[112:113]
	v_lshl_add_u64 v[98:99], s[20:21], 2, v[98:99]
	s_lshl_b32 s42, s46, 2
	s_mov_b32 s43, s21
	v_lshl_add_u64 v[98:99], v[98:99], 0, s[42:43]
	s_waitcnt lgkmcnt(0)
	v_add_f32_e32 v96, v96, v97
	global_store_dword v[98:99], v96, off offset:16

.LBB0_525:
	s_waitcnt lgkmcnt(0)
	v_bitop3_b32 v97, v142, s66, 32 bitop3:0xc8
	v_lshl_add_u32 v97, v97, 2, 0
	v_add_u32_e32 v97, 0x20000, v97
	ds_read_b32 v100, v97
	v_or_b32_e32 v96, 32, v142
	v_ashrrev_i32_e32 v97, 31, v96
	v_mad_i64_i32 v[98:99], s[0:1], s37, v96, 0
	v_lshl_add_u64 v[98:99], v[98:99], 1, v[144:145]
	v_lshlrev_b64 v[96:97], 7, v[96:97]
	s_waitcnt lgkmcnt(0)
	v_pk_mul_f32 v[90:91], v[100:101], v[90:91] op_sel_hi:[0,1]
	v_pk_mul_f32 v[102:103], v[100:101], v[88:89] op_sel_hi:[0,1]
	v_pk_mul_f32 v[88:89], v[100:101], v[94:95] op_sel_hi:[0,1]
	v_pk_mul_f32 v[92:93], v[100:101], v[92:93] op_sel_hi:[0,1]
	s_and_b64 vcc, exec, s[6:7]
	v_cvt_pk_bf16_f32 v104, v102, v103
	v_cvt_pk_bf16_f32 v105, v90, v91
	v_cvt_pk_bf16_f32 v106, v92, v93
	v_cvt_pk_bf16_f32 v107, v88, v89
	global_store_dwordx4 v[98:99], v[104:107], off
	s_cbranch_vccnz .LBB0_529
	v_mul_f32_e32 v94, v103, v103
	v_mul_f32_e32 v91, v91, v91
	v_fmac_f32_e32 v94, v102, v102
	v_fmac_f32_e32 v91, v90, v90
	v_add_f32_e32 v90, v94, v91
	v_mul_f32_e32 v91, v93, v93
	v_mul_f32_e32 v89, v89, v89
	v_fmac_f32_e32 v91, v92, v92
	v_fmac_f32_e32 v89, v88, v88
	v_add_f32_e32 v88, v91, v89
	v_add_f32_e32 v88, v90, v88
	ds_bpermute_b32 v89, v158, v88
	s_waitcnt lgkmcnt(0)
	v_add_f32_e32 v88, v88, v89
	ds_bpermute_b32 v89, v159, v88
	s_and_saveexec_b64 s[0:1], s[2:3]
	s_cbranch_execz .LBB0_528
	v_lshl_add_u64 v[90:91], s[24:25], 0, v[96:97]
	v_lshl_add_u64 v[90:91], s[20:21], 2, v[90:91]
	s_lshl_b32 s42, s46, 2
	s_mov_b32 s43, s21
	v_lshl_add_u64 v[90:91], v[90:91], 0, s[42:43]
	s_waitcnt lgkmcnt(0)
	v_add_f32_e32 v88, v88, v89
	global_store_dword v[90:91], v88, off

.LBB0_529:
	v_mov_b32_e32 v101, v100
	v_mov_b32_e32 v90, v100
	v_mov_b32_e32 v91, v100
	v_pk_mul_f32 v[82:83], v[90:91], v[82:83]
	s_waitcnt lgkmcnt(0)
	v_pk_mul_f32 v[88:89], v[100:101], v[80:81]
	v_pk_mul_f32 v[80:81], v[90:91], v[86:87]
	v_pk_mul_f32 v[84:85], v[100:101], v[84:85]
	s_and_b64 vcc, exec, s[6:7]
	v_cvt_pk_bf16_f32 v90, v88, v89
	v_cvt_pk_bf16_f32 v91, v82, v83
	v_cvt_pk_bf16_f32 v92, v84, v85
	v_cvt_pk_bf16_f32 v93, v80, v81
	global_store_dwordx4 v[98:99], v[90:93], off offset:256
	s_cbranch_vccnz .LBB0_533
	v_mul_f32_e32 v86, v89, v89
	v_mul_f32_e32 v83, v83, v83
	v_fmac_f32_e32 v86, v88, v88
	v_fmac_f32_e32 v83, v82, v82
	v_add_f32_e32 v82, v86, v83
	v_mul_f32_e32 v83, v85, v85
	v_mul_f32_e32 v81, v81, v81
	v_fmac_f32_e32 v83, v84, v84
	v_fmac_f32_e32 v81, v80, v80
	v_add_f32_e32 v80, v83, v81
	v_add_f32_e32 v80, v82, v80
	ds_bpermute_b32 v81, v158, v80
	s_waitcnt lgkmcnt(0)
	v_add_f32_e32 v80, v80, v81
	ds_bpermute_b32 v81, v159, v80
	s_and_saveexec_b64 s[0:1], s[2:3]
	s_cbranch_execz .LBB0_532
	v_lshl_add_u64 v[82:83], s[24:25], 0, v[96:97]
	v_lshl_add_u64 v[82:83], s[20:21], 2, v[82:83]
	s_lshl_b32 s42, s46, 2
	s_mov_b32 s43, s21
	v_lshl_add_u64 v[82:83], v[82:83], 0, s[42:43]
	s_waitcnt lgkmcnt(0)
	v_add_f32_e32 v80, v80, v81
	global_store_dword v[82:83], v80, off offset:16

.LBB0_533:
	s_waitcnt lgkmcnt(0)
	v_bitop3_b32 v81, v142, s67, 48 bitop3:0xc8
	v_lshl_add_u32 v81, v81, 2, 0
	v_add_u32_e32 v81, 0x20000, v81
	ds_read_b32 v84, v81
	v_or_b32_e32 v80, 48, v142
	v_ashrrev_i32_e32 v81, 31, v80
	v_mad_i64_i32 v[82:83], s[0:1], s37, v80, 0
	v_lshl_add_u64 v[82:83], v[82:83], 1, v[144:145]
	v_lshlrev_b64 v[80:81], 7, v[80:81]
	s_waitcnt lgkmcnt(0)
	v_pk_mul_f32 v[74:75], v[84:85], v[74:75] op_sel_hi:[0,1]
	v_pk_mul_f32 v[86:87], v[84:85], v[72:73] op_sel_hi:[0,1]
	v_pk_mul_f32 v[72:73], v[84:85], v[78:79] op_sel_hi:[0,1]
	v_pk_mul_f32 v[76:77], v[84:85], v[76:77] op_sel_hi:[0,1]
	s_and_b64 vcc, exec, s[6:7]
	v_cvt_pk_bf16_f32 v88, v86, v87
	v_cvt_pk_bf16_f32 v89, v74, v75
	v_cvt_pk_bf16_f32 v90, v76, v77
	v_cvt_pk_bf16_f32 v91, v72, v73
	global_store_dwordx4 v[82:83], v[88:91], off
	s_cbranch_vccnz .LBB0_537
	v_mul_f32_e32 v78, v87, v87
	v_mul_f32_e32 v75, v75, v75
	v_fmac_f32_e32 v78, v86, v86
	v_fmac_f32_e32 v75, v74, v74
	v_add_f32_e32 v74, v78, v75
	v_mul_f32_e32 v75, v77, v77
	v_mul_f32_e32 v73, v73, v73
	v_fmac_f32_e32 v75, v76, v76
	v_fmac_f32_e32 v73, v72, v72
	v_add_f32_e32 v72, v75, v73
	v_add_f32_e32 v72, v74, v72
	ds_bpermute_b32 v73, v158, v72
	s_waitcnt lgkmcnt(0)
	v_add_f32_e32 v72, v72, v73
	ds_bpermute_b32 v73, v159, v72
	s_and_saveexec_b64 s[0:1], s[2:3]
	s_cbranch_execz .LBB0_536
	v_lshl_add_u64 v[74:75], s[24:25], 0, v[80:81]
	v_lshl_add_u64 v[74:75], s[20:21], 2, v[74:75]
	s_lshl_b32 s42, s46, 2
	s_mov_b32 s43, s21
	v_lshl_add_u64 v[74:75], v[74:75], 0, s[42:43]
	s_waitcnt lgkmcnt(0)
	v_add_f32_e32 v72, v72, v73
	global_store_dword v[74:75], v72, off

.LBB0_537:
	v_mov_b32_e32 v85, v84
	v_mov_b32_e32 v74, v84
	v_mov_b32_e32 v75, v84
	v_pk_mul_f32 v[66:67], v[74:75], v[66:67]
	s_waitcnt lgkmcnt(0)
	v_pk_mul_f32 v[72:73], v[84:85], v[64:65]
	v_pk_mul_f32 v[64:65], v[74:75], v[70:71]
	v_pk_mul_f32 v[68:69], v[84:85], v[68:69]
	s_and_b64 vcc, exec, s[6:7]
	v_cvt_pk_bf16_f32 v74, v72, v73
	v_cvt_pk_bf16_f32 v75, v66, v67
	v_cvt_pk_bf16_f32 v76, v68, v69
	v_cvt_pk_bf16_f32 v77, v64, v65
	global_store_dwordx4 v[82:83], v[74:77], off offset:256
	s_cbranch_vccnz .LBB0_541
	v_mul_f32_e32 v70, v73, v73
	v_mul_f32_e32 v67, v67, v67
	v_fmac_f32_e32 v70, v72, v72
	v_fmac_f32_e32 v67, v66, v66
	v_add_f32_e32 v66, v70, v67
	v_mul_f32_e32 v67, v69, v69
	v_mul_f32_e32 v65, v65, v65
	v_fmac_f32_e32 v67, v68, v68
	v_fmac_f32_e32 v65, v64, v64
	v_add_f32_e32 v64, v67, v65
	v_add_f32_e32 v64, v66, v64
	ds_bpermute_b32 v65, v158, v64
	s_waitcnt lgkmcnt(0)
	v_add_f32_e32 v64, v64, v65
	ds_bpermute_b32 v65, v159, v64
	s_and_saveexec_b64 s[0:1], s[2:3]
	s_cbranch_execz .LBB0_540
	v_lshl_add_u64 v[66:67], s[24:25], 0, v[80:81]
	v_lshl_add_u64 v[66:67], s[20:21], 2, v[66:67]
	s_lshl_b32 s42, s46, 2
	s_mov_b32 s43, s21
	v_lshl_add_u64 v[66:67], v[66:67], 0, s[42:43]
	s_waitcnt lgkmcnt(0)
	v_add_f32_e32 v64, v64, v65
	global_store_dword v[66:67], v64, off offset:16

.LBB0_541:
	v_add_u32_e32 v64, 0x80, v142
	s_waitcnt lgkmcnt(0)
	v_and_b32_e32 v65, 0x7cf, v64
	v_lshl_add_u32 v65, v65, 2, 0
	v_add_u32_e32 v65, 0x20000, v65
	ds_read_b32 v68, v65
	v_ashrrev_i32_e32 v65, 31, v64
	v_mad_i64_i32 v[66:67], s[0:1], s37, v64, 0
	v_lshl_add_u64 v[66:67], v[66:67], 1, v[144:145]
	v_lshlrev_b64 v[64:65], 7, v[64:65]
	s_waitcnt lgkmcnt(0)
	v_pk_mul_f32 v[58:59], v[68:69], v[58:59] op_sel_hi:[0,1]
	v_pk_mul_f32 v[70:71], v[68:69], v[56:57] op_sel_hi:[0,1]
	v_pk_mul_f32 v[56:57], v[68:69], v[62:63] op_sel_hi:[0,1]
	v_pk_mul_f32 v[60:61], v[68:69], v[60:61] op_sel_hi:[0,1]
	s_and_b64 vcc, exec, s[6:7]
	v_cvt_pk_bf16_f32 v72, v70, v71
	v_cvt_pk_bf16_f32 v73, v58, v59
	v_cvt_pk_bf16_f32 v74, v60, v61
	v_cvt_pk_bf16_f32 v75, v56, v57
	global_store_dwordx4 v[66:67], v[72:75], off
	s_cbranch_vccnz .LBB0_545
	v_mul_f32_e32 v62, v71, v71
	v_mul_f32_e32 v59, v59, v59
	v_fmac_f32_e32 v62, v70, v70
	v_fmac_f32_e32 v59, v58, v58
	v_add_f32_e32 v58, v62, v59
	v_mul_f32_e32 v59, v61, v61
	v_mul_f32_e32 v57, v57, v57
	v_fmac_f32_e32 v59, v60, v60
	v_fmac_f32_e32 v57, v56, v56
	v_add_f32_e32 v56, v59, v57
	v_add_f32_e32 v56, v58, v56
	ds_bpermute_b32 v57, v158, v56
	s_waitcnt lgkmcnt(0)
	v_add_f32_e32 v56, v56, v57
	ds_bpermute_b32 v57, v159, v56
	s_and_saveexec_b64 s[0:1], s[2:3]
	s_cbranch_execz .LBB0_544
	v_lshl_add_u64 v[58:59], s[24:25], 0, v[64:65]
	v_lshl_add_u64 v[58:59], s[20:21], 2, v[58:59]
	s_lshl_b32 s42, s46, 2
	s_mov_b32 s43, s21
	v_lshl_add_u64 v[58:59], v[58:59], 0, s[42:43]
	s_waitcnt lgkmcnt(0)
	v_add_f32_e32 v56, v56, v57
	global_store_dword v[58:59], v56, off

.LBB0_545:
	v_mov_b32_e32 v69, v68
	v_mov_b32_e32 v58, v68
	v_mov_b32_e32 v59, v68
	v_pk_mul_f32 v[50:51], v[58:59], v[50:51]
	s_waitcnt lgkmcnt(0)
	v_pk_mul_f32 v[56:57], v[68:69], v[48:49]
	v_pk_mul_f32 v[48:49], v[58:59], v[54:55]
	v_pk_mul_f32 v[52:53], v[68:69], v[52:53]
	s_and_b64 vcc, exec, s[6:7]
	v_cvt_pk_bf16_f32 v58, v56, v57
	v_cvt_pk_bf16_f32 v59, v50, v51
	v_cvt_pk_bf16_f32 v60, v52, v53
	v_cvt_pk_bf16_f32 v61, v48, v49
	global_store_dwordx4 v[66:67], v[58:61], off offset:256
	s_cbranch_vccnz .LBB0_549
	v_mul_f32_e32 v54, v57, v57
	v_mul_f32_e32 v51, v51, v51
	v_fmac_f32_e32 v54, v56, v56
	v_fmac_f32_e32 v51, v50, v50
	v_add_f32_e32 v50, v54, v51
	v_mul_f32_e32 v51, v53, v53
	v_mul_f32_e32 v49, v49, v49
	v_fmac_f32_e32 v51, v52, v52
	v_fmac_f32_e32 v49, v48, v48
	v_add_f32_e32 v48, v51, v49
	v_add_f32_e32 v48, v50, v48
	ds_bpermute_b32 v49, v158, v48
	s_waitcnt lgkmcnt(0)
	v_add_f32_e32 v48, v48, v49
	ds_bpermute_b32 v49, v159, v48
	s_and_saveexec_b64 s[0:1], s[2:3]
	s_cbranch_execz .LBB0_548
	v_lshl_add_u64 v[50:51], s[24:25], 0, v[64:65]
	v_lshl_add_u64 v[50:51], s[20:21], 2, v[50:51]
	s_lshl_b32 s42, s46, 2
	s_mov_b32 s43, s21
	v_lshl_add_u64 v[50:51], v[50:51], 0, s[42:43]
	s_waitcnt lgkmcnt(0)
	v_add_f32_e32 v48, v48, v49
	global_store_dword v[50:51], v48, off offset:16

.LBB0_549:
	v_add_u32_e32 v48, 0x90, v142
	s_waitcnt lgkmcnt(0)
	v_and_b32_e32 v49, 0x7df, v48
	v_lshl_add_u32 v49, v49, 2, 0
	v_add_u32_e32 v49, 0x20000, v49
	ds_read_b32 v52, v49
	v_ashrrev_i32_e32 v49, 31, v48
	v_mad_i64_i32 v[50:51], s[0:1], s37, v48, 0
	v_lshl_add_u64 v[50:51], v[50:51], 1, v[144:145]
	v_lshlrev_b64 v[48:49], 7, v[48:49]
	s_waitcnt lgkmcnt(0)
	v_pk_mul_f32 v[42:43], v[52:53], v[42:43] op_sel_hi:[0,1]
	v_pk_mul_f32 v[54:55], v[52:53], v[40:41] op_sel_hi:[0,1]
	v_pk_mul_f32 v[40:41], v[52:53], v[46:47] op_sel_hi:[0,1]
	v_pk_mul_f32 v[44:45], v[52:53], v[44:45] op_sel_hi:[0,1]
	s_and_b64 vcc, exec, s[6:7]
	v_cvt_pk_bf16_f32 v56, v54, v55
	v_cvt_pk_bf16_f32 v57, v42, v43
	v_cvt_pk_bf16_f32 v58, v44, v45
	v_cvt_pk_bf16_f32 v59, v40, v41
	global_store_dwordx4 v[50:51], v[56:59], off
	s_cbranch_vccnz .LBB0_553
	v_mul_f32_e32 v46, v55, v55
	v_mul_f32_e32 v43, v43, v43
	v_fmac_f32_e32 v46, v54, v54
	v_fmac_f32_e32 v43, v42, v42
	v_add_f32_e32 v42, v46, v43
	v_mul_f32_e32 v43, v45, v45
	v_mul_f32_e32 v41, v41, v41
	v_fmac_f32_e32 v43, v44, v44
	v_fmac_f32_e32 v41, v40, v40
	v_add_f32_e32 v40, v43, v41
	v_add_f32_e32 v40, v42, v40
	ds_bpermute_b32 v41, v158, v40
	s_waitcnt lgkmcnt(0)
	v_add_f32_e32 v40, v40, v41
	ds_bpermute_b32 v41, v159, v40
	s_and_saveexec_b64 s[0:1], s[2:3]
	s_cbranch_execz .LBB0_552
	v_lshl_add_u64 v[42:43], s[24:25], 0, v[48:49]
	v_lshl_add_u64 v[42:43], s[20:21], 2, v[42:43]
	s_lshl_b32 s42, s46, 2
	s_mov_b32 s43, s21
	v_lshl_add_u64 v[42:43], v[42:43], 0, s[42:43]
	s_waitcnt lgkmcnt(0)
	v_add_f32_e32 v40, v40, v41
	global_store_dword v[42:43], v40, off

.LBB0_553:
	v_mov_b32_e32 v53, v52
	v_mov_b32_e32 v42, v52
	v_mov_b32_e32 v43, v52
	v_pk_mul_f32 v[34:35], v[42:43], v[34:35]
	s_waitcnt lgkmcnt(0)
	v_pk_mul_f32 v[40:41], v[52:53], v[32:33]
	v_pk_mul_f32 v[32:33], v[42:43], v[38:39]
	v_pk_mul_f32 v[36:37], v[52:53], v[36:37]
	s_and_b64 vcc, exec, s[6:7]
	v_cvt_pk_bf16_f32 v42, v40, v41
	v_cvt_pk_bf16_f32 v43, v34, v35
	v_cvt_pk_bf16_f32 v44, v36, v37
	v_cvt_pk_bf16_f32 v45, v32, v33
	global_store_dwordx4 v[50:51], v[42:45], off offset:256
	s_cbranch_vccnz .LBB0_557
	v_mul_f32_e32 v38, v41, v41
	v_mul_f32_e32 v35, v35, v35
	v_fmac_f32_e32 v38, v40, v40
	v_fmac_f32_e32 v35, v34, v34
	v_add_f32_e32 v34, v38, v35
	v_mul_f32_e32 v35, v37, v37
	v_mul_f32_e32 v33, v33, v33
	v_fmac_f32_e32 v35, v36, v36
	v_fmac_f32_e32 v33, v32, v32
	v_add_f32_e32 v32, v35, v33
	v_add_f32_e32 v32, v34, v32
	ds_bpermute_b32 v33, v158, v32
	s_waitcnt lgkmcnt(0)
	v_add_f32_e32 v32, v32, v33
	ds_bpermute_b32 v33, v159, v32
	s_and_saveexec_b64 s[0:1], s[2:3]
	s_cbranch_execz .LBB0_556
	v_lshl_add_u64 v[34:35], s[24:25], 0, v[48:49]
	v_lshl_add_u64 v[34:35], s[20:21], 2, v[34:35]
	s_lshl_b32 s42, s46, 2
	s_mov_b32 s43, s21
	v_lshl_add_u64 v[34:35], v[34:35], 0, s[42:43]
	s_waitcnt lgkmcnt(0)
	v_add_f32_e32 v32, v32, v33
	global_store_dword v[34:35], v32, off offset:16

.LBB0_557:
	v_add_u32_e32 v32, 0xa0, v142
	s_waitcnt lgkmcnt(0)
	v_and_b32_e32 v33, 0x7ef, v32
	v_lshl_add_u32 v33, v33, 2, 0
	v_add_u32_e32 v33, 0x20000, v33
	ds_read_b32 v36, v33
	v_ashrrev_i32_e32 v33, 31, v32
	v_mad_i64_i32 v[34:35], s[0:1], s37, v32, 0
	v_lshl_add_u64 v[34:35], v[34:35], 1, v[144:145]
	v_lshlrev_b64 v[32:33], 7, v[32:33]
	s_waitcnt lgkmcnt(0)
	v_pk_mul_f32 v[26:27], v[36:37], v[26:27] op_sel_hi:[0,1]
	v_pk_mul_f32 v[38:39], v[36:37], v[24:25] op_sel_hi:[0,1]
	v_pk_mul_f32 v[24:25], v[36:37], v[30:31] op_sel_hi:[0,1]
	v_pk_mul_f32 v[28:29], v[36:37], v[28:29] op_sel_hi:[0,1]
	s_and_b64 vcc, exec, s[6:7]
	v_cvt_pk_bf16_f32 v40, v38, v39
	v_cvt_pk_bf16_f32 v41, v26, v27
	v_cvt_pk_bf16_f32 v42, v28, v29
	v_cvt_pk_bf16_f32 v43, v24, v25
	global_store_dwordx4 v[34:35], v[40:43], off
	s_cbranch_vccnz .LBB0_561
	v_mul_f32_e32 v30, v39, v39
	v_mul_f32_e32 v27, v27, v27
	v_fmac_f32_e32 v30, v38, v38
	v_fmac_f32_e32 v27, v26, v26
	v_add_f32_e32 v26, v30, v27
	v_mul_f32_e32 v27, v29, v29
	v_mul_f32_e32 v25, v25, v25
	v_fmac_f32_e32 v27, v28, v28
	v_fmac_f32_e32 v25, v24, v24
	v_add_f32_e32 v24, v27, v25
	v_add_f32_e32 v24, v26, v24
	ds_bpermute_b32 v25, v158, v24
	s_waitcnt lgkmcnt(0)
	v_add_f32_e32 v24, v24, v25
	ds_bpermute_b32 v25, v159, v24
	s_and_saveexec_b64 s[0:1], s[2:3]
	s_cbranch_execz .LBB0_560
	v_lshl_add_u64 v[26:27], s[24:25], 0, v[32:33]
	v_lshl_add_u64 v[26:27], s[20:21], 2, v[26:27]
	s_lshl_b32 s42, s46, 2
	s_mov_b32 s43, s21
	v_lshl_add_u64 v[26:27], v[26:27], 0, s[42:43]
	s_waitcnt lgkmcnt(0)
	v_add_f32_e32 v24, v24, v25
	global_store_dword v[26:27], v24, off

.LBB0_561:
	v_mov_b32_e32 v37, v36
	v_mov_b32_e32 v26, v36
	v_mov_b32_e32 v27, v36
	v_pk_mul_f32 v[18:19], v[26:27], v[18:19]
	s_waitcnt lgkmcnt(0)
	v_pk_mul_f32 v[24:25], v[36:37], v[16:17]
	v_pk_mul_f32 v[16:17], v[26:27], v[22:23]
	v_pk_mul_f32 v[20:21], v[36:37], v[20:21]
	s_and_b64 vcc, exec, s[6:7]
	v_cvt_pk_bf16_f32 v26, v24, v25
	v_cvt_pk_bf16_f32 v27, v18, v19
	v_cvt_pk_bf16_f32 v28, v20, v21
	v_cvt_pk_bf16_f32 v29, v16, v17
	global_store_dwordx4 v[34:35], v[26:29], off offset:256
	s_cbranch_vccnz .LBB0_565
	v_mul_f32_e32 v22, v25, v25
	v_mul_f32_e32 v19, v19, v19
	v_fmac_f32_e32 v22, v24, v24
	v_fmac_f32_e32 v19, v18, v18
	v_add_f32_e32 v18, v22, v19
	v_mul_f32_e32 v19, v21, v21
	v_mul_f32_e32 v17, v17, v17
	v_fmac_f32_e32 v19, v20, v20
	v_fmac_f32_e32 v17, v16, v16
	v_add_f32_e32 v16, v19, v17
	v_add_f32_e32 v16, v18, v16
	ds_bpermute_b32 v17, v158, v16
	s_waitcnt lgkmcnt(0)
	v_add_f32_e32 v16, v16, v17
	ds_bpermute_b32 v17, v159, v16
	s_and_saveexec_b64 s[0:1], s[2:3]
	s_cbranch_execz .LBB0_564
	v_lshl_add_u64 v[18:19], s[24:25], 0, v[32:33]
	v_lshl_add_u64 v[18:19], s[20:21], 2, v[18:19]
	s_lshl_b32 s42, s46, 2
	s_mov_b32 s43, s21
	v_lshl_add_u64 v[18:19], v[18:19], 0, s[42:43]
	s_waitcnt lgkmcnt(0)
	v_add_f32_e32 v16, v16, v17
	global_store_dword v[18:19], v16, off offset:16

.LBB0_565:
	v_add_u32_e32 v16, 0xb0, v142
	s_waitcnt lgkmcnt(0)
	v_and_b32_e32 v17, 0x7ff, v16
	v_lshl_add_u32 v17, v17, 2, 0
	v_add_u32_e32 v17, 0x20000, v17
	ds_read_b32 v20, v17
	v_ashrrev_i32_e32 v17, 31, v16
	v_mad_i64_i32 v[18:19], s[0:1], s37, v16, 0
	v_lshl_add_u64 v[18:19], v[18:19], 1, v[144:145]
	v_lshlrev_b64 v[16:17], 7, v[16:17]
	s_waitcnt lgkmcnt(0)
	v_pk_mul_f32 v[10:11], v[20:21], v[10:11] op_sel_hi:[0,1]
	v_pk_mul_f32 v[22:23], v[20:21], v[8:9] op_sel_hi:[0,1]
	v_pk_mul_f32 v[8:9], v[20:21], v[14:15] op_sel_hi:[0,1]
	v_pk_mul_f32 v[12:13], v[20:21], v[12:13] op_sel_hi:[0,1]
	s_and_b64 vcc, exec, s[6:7]
	v_cvt_pk_bf16_f32 v24, v22, v23
	v_cvt_pk_bf16_f32 v25, v10, v11
	v_cvt_pk_bf16_f32 v26, v12, v13
	v_cvt_pk_bf16_f32 v27, v8, v9
	global_store_dwordx4 v[18:19], v[24:27], off
	s_cbranch_vccnz .LBB0_569
	v_mul_f32_e32 v14, v23, v23
	v_mul_f32_e32 v11, v11, v11
	v_fmac_f32_e32 v14, v22, v22
	v_fmac_f32_e32 v11, v10, v10
	v_add_f32_e32 v10, v14, v11
	v_mul_f32_e32 v11, v13, v13
	v_mul_f32_e32 v9, v9, v9
	v_fmac_f32_e32 v11, v12, v12
	v_fmac_f32_e32 v9, v8, v8
	v_add_f32_e32 v8, v11, v9
	v_add_f32_e32 v8, v10, v8
	ds_bpermute_b32 v9, v158, v8
	s_waitcnt lgkmcnt(0)
	v_add_f32_e32 v8, v8, v9
	ds_bpermute_b32 v9, v159, v8
	s_and_saveexec_b64 s[0:1], s[2:3]
	s_cbranch_execz .LBB0_568
	v_lshl_add_u64 v[10:11], s[24:25], 0, v[16:17]
	v_lshl_add_u64 v[10:11], s[20:21], 2, v[10:11]
	s_lshl_b32 s42, s46, 2
	s_mov_b32 s43, s21
	v_lshl_add_u64 v[10:11], v[10:11], 0, s[42:43]
	s_waitcnt lgkmcnt(0)
	v_add_f32_e32 v8, v8, v9
	global_store_dword v[10:11], v8, off

.LBB0_569:
	v_mov_b32_e32 v21, v20
	v_mov_b32_e32 v10, v20
	v_mov_b32_e32 v11, v20
	v_pk_mul_f32 v[2:3], v[10:11], v[2:3]
	s_waitcnt lgkmcnt(0)
	v_pk_mul_f32 v[8:9], v[20:21], v[0:1]
	v_pk_mul_f32 v[0:1], v[10:11], v[6:7]
	v_pk_mul_f32 v[4:5], v[20:21], v[4:5]
	s_and_b64 vcc, exec, s[6:7]
	v_cvt_pk_bf16_f32 v10, v8, v9
	v_cvt_pk_bf16_f32 v11, v2, v3
	v_cvt_pk_bf16_f32 v12, v4, v5
	v_cvt_pk_bf16_f32 v13, v0, v1
	global_store_dwordx4 v[18:19], v[10:13], off offset:256
	s_cbranch_vccnz .LBB0_573
	v_mul_f32_e32 v6, v9, v9
	v_mul_f32_e32 v3, v3, v3
	v_fmac_f32_e32 v6, v8, v8
	v_fmac_f32_e32 v3, v2, v2
	v_add_f32_e32 v2, v6, v3
	v_mul_f32_e32 v3, v5, v5
	v_mul_f32_e32 v1, v1, v1
	v_fmac_f32_e32 v3, v4, v4
	v_fmac_f32_e32 v1, v0, v0
	v_add_f32_e32 v0, v3, v1
	v_add_f32_e32 v0, v2, v0
	ds_bpermute_b32 v1, v158, v0
	s_waitcnt lgkmcnt(0)
	v_add_f32_e32 v0, v0, v1
	ds_bpermute_b32 v1, v159, v0
	s_and_saveexec_b64 s[0:1], s[2:3]
	s_cbranch_execz .LBB0_572
	v_lshl_add_u64 v[2:3], s[24:25], 0, v[16:17]
	v_lshl_add_u64 v[2:3], s[20:21], 2, v[2:3]
	s_lshl_b32 s20, s46, 2
	v_lshl_add_u64 v[2:3], v[2:3], 0, s[20:21]
	s_waitcnt lgkmcnt(0)
	v_add_f32_e32 v0, v0, v1
	global_store_dword v[2:3], v0, off offset:16

.LBB0_578:
	s_cmpk_eq_i32 s79, 0x100
	s_cselect_b64 s[4:5], -1, 0
	s_and_b64 s[8:9], s[4:5], exec
	s_mov_b64 s[0:1], s[70:71]
	s_cselect_b32 s3, s3, 0
	s_cselect_b32 s34, s2, 0x600
	s_add_i32 s35, s3, s82
	s_load_dwordx2 s[0:1], s[0:1], 0xb8
	s_movk_i32 s27, 0x600
	s_mov_b64 s[2:3], s[70:71]
	s_cmp_ge_i32 s35, s34
	s_waitcnt lgkmcnt(0)
	s_cbranch_scc1 .LBB0_614
	s_bfe_u32 s98, s82, 0x10003
	s_cmp_eq_u32 s98, 0
	s_cbranch_scc1 .Lp4_go
.Lp4_dl:
	s_sleep 127
	s_sleep 40
	s_sub_u32 s98, s98, 1
	s_cmp_lg_u32 s98, 0
	s_cbranch_scc1 .Lp4_dl
.Lp4_go:
	s_and_b64 s[4:5], s[4:5], exec
	s_cselect_b32 s36, s6, s79
	s_add_u32 s16, s0, 0x5000000
	s_addc_u32 s17, s1, 0
	s_add_u32 s18, s0, 0x8000000
	s_addc_u32 s19, s1, 0
	s_add_u32 s20, s0, 0xb000000
	s_addc_u32 s21, s1, 0
	v_lshrrev_b32_e32 v1, 5, v155
	s_add_u32 s24, s0, 0x800000
	v_and_b32_e32 v73, 31, v155
	v_subrev_u32_e32 v114, 35, v154
	s_movk_i32 s0, 0x81
	v_lshlrev_b32_e32 v10, 2, v1
	s_load_dwordx2 s[22:23], s[2:3], 0x10
	v_lshlrev_b32_e32 v2, 3, v155
	v_cmp_gt_u32_e64 s[2:3], s0, v114
	v_lshlrev_b32_e32 v3, 4, v155
	s_movk_i32 s0, 0x70
	v_sub_u32_e32 v11, v73, v10
	v_add_u32_e32 v10, s15, v10
	v_lshlrev_b32_e32 v12, 1, v155
	v_bitop3_b32 v4, v154, s0, v3 bitop3:0x48
	v_sub_u32_e32 v116, 0x80, v10
	v_and_b32_e32 v10, 24, v2
	v_and_b32_e32 v3, 0xc0, v3
	v_and_b32_e32 v12, 32, v12
	v_and_b32_e32 v72, 56, v2
	v_bfe_u32 v5, v2, 5, 1
	v_and_b32_e32 v2, 0x100, v2
	v_or3_b32 v3, v10, v3, v12
	v_or3_b32 v2, v3, v2, s33
	v_add_u32_e32 v3, 0x200, v154
	v_ashrrev_i32_e32 v122, 3, v3
	v_add_u32_e32 v3, 0x400, v154
	v_ashrrev_i32_e32 v121, 3, v154
	v_ashrrev_i32_e32 v123, 3, v3
	v_add_u32_e32 v3, 0x600, v154
	s_addc_u32 s25, s1, 0
	s_lshl_b32 s1, s13, 16
	v_ashrrev_i32_e32 v124, 3, v3
	v_and_b32_e32 v3, 0x1fffff0, v121
	v_lshlrev_b32_e32 v10, 1, v121
	v_and_b32_e32 v13, 0x1fffff0, v122
	v_lshlrev_b32_e32 v14, 1, v122
	v_and_b32_e32 v16, 0x1fffff0, v123
	v_lshlrev_b32_e32 v17, 1, v123
	s_add_i32 s1, s1, 0
	v_or_b32_e32 v7, s15, v73
	v_and_or_b32 v3, v10, 8, v3
	v_and_or_b32 v13, v14, 8, v13
	v_and_or_b32 v16, v17, 8, v16
	v_and_b32_e32 v19, 0x1fffff0, v124
	v_lshlrev_b32_e32 v20, 1, v124
	v_lshlrev_b32_e32 v74, 1, v72
	s_movk_i32 s0, 0xff
	v_lshl_add_u32 v7, v7, 7, s1
	s_add_i32 s9, s1, 0x8000
	s_add_i32 s1, s1, s33
	v_lshrrev_b32_e32 v10, 1, v121
	v_lshrrev_b32_e32 v3, 2, v3
	v_and_b32_e32 v12, 3, v121
	v_lshrrev_b32_e32 v14, 1, v122
	v_lshrrev_b32_e32 v13, 2, v13
	v_and_b32_e32 v15, 3, v122
	v_lshrrev_b32_e32 v17, 1, v123
	v_lshrrev_b32_e32 v16, 2, v16
	v_and_b32_e32 v18, 3, v123
	v_and_or_b32 v19, v20, 8, v19
	v_cmp_lt_i32_e64 s[4:5], s0, v154
	s_add_i32 s0, 0, 0x20000
	s_lshl_b32 s6, s13, 10
	v_add_u32_e32 v118, s9, v2
	v_lshl_add_u32 v119, v73, 1, s1
	v_add_u32_e32 v2, s1, v74
	v_or_b32_e32 v3, v3, v5
	v_and_or_b32 v10, v10, 4, v12
	v_or_b32_e32 v13, v13, v5
	v_and_or_b32 v14, v14, 4, v15
	v_or_b32_e32 v16, v16, v5
	v_and_or_b32 v17, v17, 4, v18
	v_lshrrev_b32_e32 v19, 2, v19
	s_add_i32 s1, 0, 0x10000
	v_lshl_add_u32 v115, v154, 2, s0
	s_add_i32 s0, s0, s6
	s_lshl_b32 s6, s83, 7
	v_lshlrev_b32_e32 v3, 9, v3
	v_lshlrev_b32_e32 v10, 6, v10
	v_lshlrev_b32_e32 v13, 9, v13
	v_lshlrev_b32_e32 v14, 6, v14
	v_lshlrev_b32_e32 v16, 9, v16
	v_lshlrev_b32_e32 v17, 6, v17
	v_lshrrev_b32_e32 v20, 1, v124
	v_or_b32_e32 v5, v19, v5
	v_and_b32_e32 v19, 3, v124
	v_add_u32_e32 v130, s1, v4
	s_add_i32 s1, 0, 0x18000
	s_add_i32 s6, s6, 0
	v_lshrrev_b32_e32 v8, 1, v155
	v_bfe_u32 v9, v155, 1, 3
	v_lshrrev_b32_e32 v120, 3, v155
	v_add_u32_e32 v125, 0, v4
	v_add3_u32 v12, 0, v3, v10
	v_add3_u32 v15, 0, v13, v14
	v_add3_u32 v18, 0, v16, v17
	v_and_or_b32 v19, v20, 4, v19
	v_add3_u32 v3, s1, v3, v10
	v_add3_u32 v4, s1, v13, v14
	v_add3_u32 v10, s1, v16, v17
	v_add_u32_e32 v14, 2, v1
	v_add_u32_e32 v16, 6, v1
	s_add_i32 s8, s6, 0x20800
	v_lshlrev_b32_e32 v5, 9, v5
	v_lshlrev_b32_e32 v19, 6, v19
	v_bitop3_b32 v13, v8, v1, 7 bitop3:0x6c
	v_bitop3_b32 v14, v14, v8, 7 bitop3:0x78
	v_bitop3_b32 v9, v1, v9, 4 bitop3:0x36
	v_bitop3_b32 v8, v16, v8, 7 bitop3:0x78
	v_lshlrev_b32_e32 v132, 9, v1
	v_add_u32_e32 v133, 8, v120
	v_or_b32_e32 v134, 16, v120
	v_add_u32_e32 v135, 24, v120
	v_mov_b32_e32 v75, 0
	v_and_b32_e32 v6, 48, v74
	v_lshlrev_b32_e32 v0, 3, v1
	v_lshl_add_u32 v11, v11, 2, 16
	v_add3_u32 v20, 0, v5, v19
	v_add3_u32 v5, s1, v5, v19
	v_lshlrev_b32_e32 v13, 4, v13
	v_lshlrev_b32_e32 v14, 4, v14
	v_lshlrev_b32_e32 v9, 4, v9
	v_lshlrev_b32_e32 v8, 4, v8
	v_lshl_add_u32 v131, v1, 4, s8
	v_or_b32_e32 v1, 0x100, v132
	v_add_u32_e32 v16, 0x400, v132
	v_add_u32_e32 v17, 0x500, v132
	v_or_b32_e32 v19, 0x800, v132
	v_or_b32_e32 v21, 0x900, v132
	v_add_u32_e32 v22, 0xc00, v132
	v_add_u32_e32 v23, 0xd00, v132
	v_lshlrev_b32_e32 v24, 7, v120
	v_lshlrev_b32_e32 v25, 7, v133
	v_lshlrev_b32_e32 v26, 7, v134
	v_lshlrev_b32_e32 v27, 7, v135
	v_cmp_gt_u32_e64 s[6:7], 32, v155
	v_lshl_add_u32 v117, v73, 2, s8
	v_lshl_add_u64 v[76:77], s[16:17], 0, v[74:75]
	v_lshlrev_b32_e32 v126, 7, v121
	v_lshlrev_b32_e32 v127, 7, v122
	v_lshlrev_b32_e32 v128, 7, v123
	v_lshlrev_b32_e32 v129, 7, v124
	s_movk_i32 s33, 0xc00
	s_lshl_b32 s37, s35, 1
	s_lshl_b32 s38, s36, 1
	s_mov_b32 s39, 0x800000
	s_mov_b32 s40, 0x3f317217
	s_mov_b32 s41, 0x7f800000
	s_mov_b32 s42, 0x409b43d5
	v_add_u32_e32 v136, v12, v6
	v_add_u32_e32 v137, v15, v6
	v_add_u32_e32 v138, v18, v6
	v_add_u32_e32 v139, v20, v6
	v_lshlrev_b32_e32 v74, 1, v0
	v_add_u32_e32 v140, v7, v13
	v_add_u32_e32 v141, v7, v14
	v_add_u32_e32 v142, v7, v9
	v_add_u32_e32 v143, v7, v8
	v_add_u32_e32 v144, s0, v11
	s_mov_b32 s26, 0x3e38aa3b
	s_movk_i32 s43, 0x41
	s_movk_i32 s44, 0x42
	s_movk_i32 s45, 0x43
	s_movk_i32 s46, 0x44
	s_movk_i32 s47, 0x49
	s_movk_i32 s48, 0x4a
	s_movk_i32 s49, 0x4b
	s_movk_i32 s50, 0x4c
	s_movk_i32 s51, 0x51
	s_movk_i32 s52, 0x52
	s_movk_i32 s53, 0x53
	s_movk_i32 s54, 0x54
	s_movk_i32 s55, 0x59
	s_movk_i32 s56, 0x5a
	s_movk_i32 s57, 0x5b
	s_movk_i32 s58, 0x5c
	s_movk_i32 s59, 0x61
	s_movk_i32 s60, 0x62
	s_movk_i32 s61, 0x63
	s_movk_i32 s62, 0x64
	s_movk_i32 s63, 0x69
	s_movk_i32 s64, 0x6a
	s_movk_i32 s65, 0x6b
	s_movk_i32 s66, 0x6c
	s_movk_i32 s67, 0x71
	s_movk_i32 s68, 0x72
	s_movk_i32 s69, 0x73
	s_movk_i32 s70, 0x74
	s_movk_i32 s71, 0x79
	s_movk_i32 s72, 0x7a
	s_movk_i32 s73, 0x7b
	s_movk_i32 s74, 0x7c
	s_movk_i32 s75, 0x60
	v_add_u32_e32 v145, v119, v1
	v_add_u32_e32 v146, v119, v16
	v_add_u32_e32 v147, v119, v17
	v_add_u32_e32 v148, v119, v19
	v_add_u32_e32 v149, v119, v21
	v_add_u32_e32 v150, v119, v22
	v_add_u32_e32 v151, v119, v23
	v_add_u32_e32 v152, v2, v24
	v_add_u32_e32 v153, v2, v25
	v_add_u32_e32 v154, v2, v26
	v_add_u32_e32 v155, v2, v27
	v_mov_b32_e32 v156, 0x41b17218
	v_add_u32_e32 v157, v3, v6
	v_add_u32_e32 v158, v4, v6
	v_add_u32_e32 v159, v10, v6
	v_add_u32_e32 v160, v5, v6
	v_mov_b32_e32 v161, 0xff800000
	s_branch .LBB0_581

.LBB0_680:
	v_lshl_add_u64 v[12:13], s[4:5], 0, v[4:5]
	v_add_co_u32_e64 v30, s[2:3], s13, v12
	v_lshl_add_u64 v[14:15], s[4:5], 0, v[0:1]
	s_nop 0
	v_addc_co_u32_e64 v31, s[2:3], 0, v13, s[2:3]
	v_lshl_add_u64 v[20:21], s[4:5], 0, v[8:9]
	v_add_co_u32_e64 v32, s[2:3], s20, v14
	v_add_co_u32_e32 v28, vcc, 0x800000, v20
	s_nop 0
	v_addc_co_u32_e64 v33, s[2:3], 0, v15, s[2:3]
	v_add_co_u32_e64 v34, s[2:3], s21, v14
	v_addc_co_u32_e32 v29, vcc, 0, v21, vcc
	s_nop 0
	v_addc_co_u32_e64 v35, s[2:3], 0, v15, s[2:3]
	global_load_dwordx4 v[12:15], v[30:31], off offset:1024
	global_load_dwordx4 v[16:19], v[30:31], off offset:2048
	global_load_dword v44, v[28:29], off
	global_load_dword v45, v[28:29], off offset:32
	global_load_dword v46, v[28:29], off offset:64
	global_load_dwordx4 v[20:23], v[30:31], off
	v_lshl_add_u64 v[24:25], s[4:5], 0, v[2:3]
	v_lshl_add_u64 v[26:27], s[4:5], 0, v[6:7]
	s_add_i32 s12, s12, s14
	v_lshl_add_u64 v[0:1], v[0:1], 0, s[0:1]
	v_lshl_add_u64 v[2:3], v[2:3], 0, s[6:7]
	v_lshl_add_u64 v[4:5], v[4:5], 0, s[8:9]
	v_lshl_add_u64 v[6:7], v[6:7], 0, s[16:17]
	v_lshl_add_u64 v[8:9], v[8:9], 0, s[18:19]
	s_cmpk_gt_i32 s12, 0x3fff
	s_waitcnt vmcnt(0) lgkmcnt(0)
	v_lshlrev_b32_e32 v28, 16, v12
	v_max3_f32 v47, v44, v45, v46
	v_sub_f32_e32 v44, v44, v47
	v_sub_f32_e32 v45, v45, v47
	v_sub_f32_e32 v46, v46, v47
	v_mul_f32_e32 v44, 0x3fb8aa3b, v44
	v_mul_f32_e32 v45, 0x3fb8aa3b, v45
	v_mul_f32_e32 v46, 0x3fb8aa3b, v46
	v_exp_f32_e32 v44, v44
	v_exp_f32_e32 v45, v45
	v_exp_f32_e32 v47, v46
	v_and_b32_e32 v29, 0xffff0000, v12
	v_lshlrev_b32_e32 v12, 16, v13
	v_add_f32_e32 v46, v44, v45
	v_add_f32_e32 v46, v47, v46
	v_div_scale_f32 v48, s[2:3], v46, v46, 1.0
	v_rcp_f32_e32 v50, v48
	v_div_scale_f32 v49, vcc, 1.0, v46, 1.0
	v_and_b32_e32 v13, 0xffff0000, v13
	v_fma_f32 v51, -v48, v50, 1.0
	v_fmac_f32_e32 v50, v51, v50
	v_mul_f32_e32 v51, v49, v50
	v_fma_f32 v52, -v48, v51, v49
	v_fmac_f32_e32 v51, v52, v50
	v_fma_f32 v48, -v48, v51, v49
	v_div_fmas_f32 v48, v48, v50, v51
	v_div_fixup_f32 v48, v48, v46, 1.0
	v_lshlrev_b32_e32 v36, 16, v14
	v_and_b32_e32 v37, 0xffff0000, v14
	v_lshlrev_b32_e32 v14, 16, v15
	v_and_b32_e32 v15, 0xffff0000, v15
	v_mul_f32_e32 v46, v45, v48
	v_lshlrev_b32_e32 v40, 16, v20
	v_and_b32_e32 v41, 0xffff0000, v20
	v_lshlrev_b32_e32 v20, 16, v21
	v_and_b32_e32 v21, 0xffff0000, v21
	v_lshlrev_b32_e32 v42, 16, v22
	v_and_b32_e32 v43, 0xffff0000, v22
	v_lshlrev_b32_e32 v22, 16, v23
	v_and_b32_e32 v23, 0xffff0000, v23
	v_mul_f32_e32 v44, v44, v48
	v_pk_mul_f32 v[12:13], v[46:47], v[12:13] op_sel_hi:[0,1]
	v_pk_mul_f32 v[28:29], v[46:47], v[28:29] op_sel_hi:[0,1]
	v_pk_mul_f32 v[14:15], v[46:47], v[14:15] op_sel_hi:[0,1]
	v_pk_mul_f32 v[36:37], v[46:47], v[36:37] op_sel_hi:[0,1]
	v_lshlrev_b32_e32 v30, 16, v16
	v_and_b32_e32 v31, 0xffff0000, v16
	v_lshlrev_b32_e32 v16, 16, v17
	v_and_b32_e32 v17, 0xffff0000, v17
	v_lshlrev_b32_e32 v38, 16, v18
	v_and_b32_e32 v39, 0xffff0000, v18
	v_lshlrev_b32_e32 v18, 16, v19
	v_and_b32_e32 v19, 0xffff0000, v19
	v_mul_f32_e32 v48, v47, v48
	v_pk_fma_f32 v[28:29], v[44:45], v[40:41], v[28:29] op_sel_hi:[0,1,1]
	v_pk_fma_f32 v[12:13], v[44:45], v[20:21], v[12:13] op_sel_hi:[0,1,1]
	v_pk_fma_f32 v[20:21], v[44:45], v[42:43], v[36:37] op_sel_hi:[0,1,1]
	v_pk_fma_f32 v[14:15], v[44:45], v[22:23], v[14:15] op_sel_hi:[0,1,1]
	v_pk_fma_f32 v[16:17], v[48:49], v[16:17], v[12:13] op_sel_hi:[0,1,1]
	v_pk_fma_f32 v[12:13], v[48:49], v[30:31], v[28:29] op_sel_hi:[0,1,1]
	v_pk_fma_f32 v[18:19], v[48:49], v[18:19], v[14:15] op_sel_hi:[0,1,1]
	v_pk_fma_f32 v[14:15], v[48:49], v[38:39], v[20:21] op_sel_hi:[0,1,1]
	v_cvt_pk_bf16_f32 v12, v12, v13
	v_cvt_pk_bf16_f32 v13, v16, v17
	v_cvt_pk_bf16_f32 v14, v14, v15
	v_cvt_pk_bf16_f32 v15, v18, v19
	global_store_dwordx4 v[24:25], v[12:15], off
	global_load_dword v18, v[26:27], off
	global_load_dword v19, v[26:27], off offset:32
	s_nop 0
	global_load_dwordx2 v[12:13], v[34:35], off
	global_load_dwordx2 v[14:15], v[32:33], off
	v_lshl_add_u64 v[16:17], s[4:5], 0, v[10:11]
	v_add_co_u32_e32 v16, vcc, s23, v16
	v_lshl_add_u64 v[10:11], v[10:11], 0, s[16:17]
	s_nop 0
	v_addc_co_u32_e32 v17, vcc, 0, v17, vcc
	s_waitcnt vmcnt(0) lgkmcnt(0)
	v_lshlrev_b32_e32 v20, 16, v18
	v_lshlrev_b32_e32 v21, 16, v19
	v_and_b32_e32 v19, 0xffff0000, v19
	v_mul_f32_e32 v22, v12, v21
	v_and_b32_e32 v18, 0xffff0000, v18
	v_mul_f32_e32 v23, v13, v19
	v_mul_f32_e32 v12, v12, v20
	v_fma_f32 v20, v14, v20, -v22
	v_mul_f32_e32 v13, v13, v18
	v_fma_f32 v18, v15, v18, -v23
	v_fmac_f32_e32 v12, v14, v21
	v_bfe_u32 v14, v20, 16, 1
	v_fmac_f32_e32 v13, v15, v19
	v_bfe_u32 v15, v18, 16, 1
	v_bfe_u32 v19, v12, 16, 1
	v_add3_u32 v14, v20, v14, s22
	v_bfe_u32 v21, v13, 16, 1
	v_add3_u32 v15, v18, v15, s22
	v_add3_u32 v12, v12, v19, s22
	v_lshrrev_b32_e32 v14, 16, v14
	v_add3_u32 v13, v13, v21, s22
	v_lshrrev_b32_e32 v12, 16, v12
	v_and_or_b32 v14, v15, s15, v14
	v_and_or_b32 v12, v13, s15, v12
	global_store_dword v[16:17], v14, off offset:128
	global_store_dword v[16:17], v12, off offset:160
	s_cbranch_scc0 .LBB0_680

.LBB0_700:
	v_lshl_add_u32 v160, s31, 8, v170
	v_and_b32_e32 v161, 0x7cf, v160
	s_lshl_b32 s0, s30, 8
	v_lshl_add_u32 v161, v161, 2, 0
	s_or_b32 s30, s0, s51
	v_add_u32_e32 v161, 0x20000, v161
	ds_read_b32 v162, v161
	s_mul_hi_i32 s0, s30, 0x2aaaaaab
	s_lshr_b32 s1, s0, 31
	s_lshr_b32 s0, s0, 4
	s_add_i32 s0, s0, s1
	v_ashrrev_i32_e32 v161, 31, v160
	s_mulk_i32 s0, 0x60
	v_lshlrev_b64 v[174:175], 4, v[160:161]
	s_sub_i32 s6, s30, s0
	s_cmp_eq_u32 s6, 64
	s_waitcnt lgkmcnt(0)
	v_pk_mul_f32 v[164:165], v[162:163], v[122:123] op_sel_hi:[0,1]
	v_lshlrev_b64 v[122:123], 2, v[174:175]
	s_cselect_b64 s[0:1], -1, 0
	s_cmp_lg_u32 s6, 64
	v_pk_mul_f32 v[126:127], v[162:163], v[126:127] op_sel_hi:[0,1]
	v_pk_mul_f32 v[124:125], v[162:163], v[124:125] op_sel_hi:[0,1]
	v_pk_mul_f32 v[166:167], v[162:163], v[120:121] op_sel_hi:[0,1]
	v_lshl_add_u64 v[120:121], v[148:149], 0, v[122:123]
	v_lshl_add_u64 v[122:123], v[150:151], 0, v[122:123]
	s_cbranch_scc1 .LBB0_702
	global_load_dwordx4 v[174:177], v[122:123], off
	global_load_dwordx4 v[178:181], v[120:121], off
	s_waitcnt vmcnt(0) lgkmcnt(0)
	v_pk_mul_f32 v[182:183], v[164:165], v[176:177]
	v_pk_mul_f32 v[184:185], v[166:167], v[174:175]
	v_pk_mul_f32 v[176:177], v[126:127], v[176:177]
	v_pk_mul_f32 v[174:175], v[124:125], v[174:175]
	v_pk_fma_f32 v[126:127], v[126:127], v[180:181], v[182:183] neg_lo:[0,0,1] neg_hi:[0,0,1]
	v_pk_fma_f32 v[124:125], v[124:125], v[178:179], v[184:185] neg_lo:[0,0,1] neg_hi:[0,0,1]
	v_pk_fma_f32 v[164:165], v[164:165], v[180:181], v[176:177]
	v_pk_fma_f32 v[166:167], v[166:167], v[178:179], v[174:175]
.LBB0_702:
	v_cvt_pk_bf16_f32 v124, v124, v125
	v_cvt_pk_bf16_f32 v125, v126, v127
	s_nop 0
	v_cvt_pk_bf16_f32 v126, v166, v167
	v_cvt_pk_bf16_f32 v127, v164, v165
	s_ashr_i32 s31, s30, 31
	v_cndmask_b32_e64 v161, v124, v126, s[2:3]
	v_cndmask_b32_e64 v163, v125, v127, s[2:3]
	ds_bpermute_b32 v161, v172, v161
	ds_bpermute_b32 v165, v172, v163
	v_mov_b32_e32 v163, v162
	v_pk_mul_f32 v[116:117], v[162:163], v[116:117]
	v_pk_mul_f32 v[112:113], v[162:163], v[112:113]
	s_waitcnt lgkmcnt(0)
	v_cndmask_b32_e64 v164, v161, v124, s[2:3]
	v_cndmask_b32_e64 v167, v127, v165, s[2:3]
	v_cndmask_b32_e64 v165, v165, v125, s[2:3]
	v_mov_b64_e32 v[124:125], s[18:19]
	v_mad_i64_i32 v[124:125], s[6:7], v160, s57, v[124:125]
	s_or_b32 s6, s30, 0x80
	s_mul_hi_i32 s7, s6, 0x2aaaaaab
	s_lshr_b32 s8, s7, 31
	s_lshr_b32 s7, s7, 4
	s_add_i32 s7, s7, s8
	s_mulk_i32 s7, 0x60
	v_lshl_add_u64 v[124:125], s[30:31], 1, v[124:125]
	s_sub_i32 s6, s6, s7
	v_cndmask_b32_e64 v166, v126, v161, s[2:3]
	v_lshl_add_u64 v[124:125], v[146:147], 1, v[124:125]
	s_cmp_eq_u32 s6, 64
	v_mov_b32_e32 v126, v162
	v_mov_b32_e32 v127, v162
	v_lshl_add_u64 v[124:125], v[124:125], 0, v[144:145]
	s_cselect_b64 s[34:35], -1, 0
	s_cmp_lg_u32 s6, 64
	v_pk_mul_f32 v[118:119], v[126:127], v[118:119]
	v_pk_mul_f32 v[114:115], v[126:127], v[114:115]
	global_store_dwordx4 v[124:125], v[164:167], off
	s_cbranch_scc1 .LBB0_704
	global_load_dwordx4 v[162:165], v[122:123], off
	s_nop 0
	global_load_dwordx4 v[120:123], v[120:121], off
	s_waitcnt vmcnt(0) lgkmcnt(0)
	v_pk_mul_f32 v[126:127], v[114:115], v[164:165]
	v_pk_mul_f32 v[166:167], v[112:113], v[162:163]
	v_pk_mul_f32 v[164:165], v[118:119], v[164:165]
	v_pk_mul_f32 v[162:163], v[116:117], v[162:163]
	v_pk_fma_f32 v[118:119], v[118:119], v[122:123], v[126:127] neg_lo:[0,0,1] neg_hi:[0,0,1]
	v_pk_fma_f32 v[116:117], v[116:117], v[120:121], v[166:167] neg_lo:[0,0,1] neg_hi:[0,0,1]
	v_pk_fma_f32 v[114:115], v[114:115], v[122:123], v[164:165]
	v_pk_fma_f32 v[112:113], v[112:113], v[120:121], v[162:163]
.LBB0_704:
	v_cvt_pk_bf16_f32 v116, v116, v117
	v_cvt_pk_bf16_f32 v117, v118, v119
	s_nop 0
	v_cvt_pk_bf16_f32 v112, v112, v113
	v_cvt_pk_bf16_f32 v113, v114, v115
	s_andn2_b64 vcc, exec, s[0:1]
	v_cndmask_b32_e64 v114, v116, v112, s[2:3]
	ds_bpermute_b32 v115, v172, v114
	v_cndmask_b32_e64 v114, v117, v113, s[2:3]
	ds_bpermute_b32 v118, v172, v114
	s_waitcnt lgkmcnt(0)
	v_cndmask_b32_e64 v114, v112, v115, s[2:3]
	v_cndmask_b32_e64 v112, v115, v116, s[2:3]
	v_cndmask_b32_e64 v115, v113, v118, s[2:3]
	v_cndmask_b32_e64 v113, v118, v117, s[2:3]
	global_store_dwordx4 v[124:125], v[112:115], off offset:256
	s_nop 1
	v_bitop3_b32 v112, v160, s58, 16 bitop3:0xc8
	v_lshl_add_u32 v112, v112, 2, 0
	v_add_u32_e32 v112, 0x20000, v112
	ds_read_b32 v112, v112
	v_or_b32_e32 v114, 16, v160
	v_ashrrev_i32_e32 v115, 31, v114
	v_lshlrev_b64 v[120:121], 4, v[114:115]
	s_waitcnt lgkmcnt(0)
	v_pk_mul_f32 v[116:117], v[112:113], v[106:107] op_sel_hi:[0,1]
	v_pk_mul_f32 v[118:119], v[112:113], v[104:105] op_sel_hi:[0,1]
	v_cndmask_b32_e64 v104, 0, 1, s[0:1]
	v_lshlrev_b64 v[106:107], 2, v[120:121]
	v_pk_mul_f32 v[110:111], v[112:113], v[110:111] op_sel_hi:[0,1]
	v_pk_mul_f32 v[108:109], v[112:113], v[108:109] op_sel_hi:[0,1]
	v_cmp_ne_u32_e64 s[6:7], 1, v104
	v_lshl_add_u64 v[104:105], v[148:149], 0, v[106:107]
	v_lshl_add_u64 v[106:107], v[150:151], 0, v[106:107]
	s_cbranch_vccnz .LBB0_706
	global_load_dwordx4 v[120:123], v[106:107], off
	global_load_dwordx4 v[124:127], v[104:105], off
	s_waitcnt vmcnt(0) lgkmcnt(0)
	v_pk_mul_f32 v[162:163], v[116:117], v[122:123]
	v_pk_mul_f32 v[164:165], v[118:119], v[120:121]
	v_pk_mul_f32 v[122:123], v[110:111], v[122:123]
	v_pk_mul_f32 v[120:121], v[108:109], v[120:121]
	v_pk_fma_f32 v[110:111], v[110:111], v[126:127], v[162:163] neg_lo:[0,0,1] neg_hi:[0,0,1]
	v_pk_fma_f32 v[108:109], v[108:109], v[124:125], v[164:165] neg_lo:[0,0,1] neg_hi:[0,0,1]
	v_pk_fma_f32 v[116:117], v[116:117], v[126:127], v[122:123]
	v_pk_fma_f32 v[118:119], v[118:119], v[124:125], v[120:121]
.LBB0_706:
	v_cvt_pk_bf16_f32 v108, v108, v109
	v_cvt_pk_bf16_f32 v109, v110, v111
	s_nop 0
	v_cvt_pk_bf16_f32 v110, v118, v119
	v_cvt_pk_bf16_f32 v111, v116, v117
	s_andn2_b64 vcc, exec, s[34:35]
	v_cndmask_b32_e64 v113, v108, v110, s[2:3]
	ds_bpermute_b32 v115, v172, v113
	v_cndmask_b32_e64 v113, v109, v111, s[2:3]
	ds_bpermute_b32 v117, v172, v113
	v_mov_b32_e32 v113, v112
	v_pk_mul_f32 v[100:101], v[112:113], v[100:101]
	s_waitcnt lgkmcnt(0)
	v_cndmask_b32_e64 v116, v115, v108, s[2:3]
	v_cndmask_b32_e64 v118, v110, v115, s[2:3]
	v_cndmask_b32_e64 v119, v111, v117, s[2:3]
	v_cndmask_b32_e64 v117, v117, v109, s[2:3]
	v_mov_b64_e32 v[108:109], s[18:19]
	v_mad_i64_i32 v[108:109], s[0:1], v114, s57, v[108:109]
	v_lshl_add_u64 v[108:109], s[30:31], 1, v[108:109]
	v_mov_b32_e32 v110, v112
	v_mov_b32_e32 v111, v112
	v_lshl_add_u64 v[108:109], v[146:147], 1, v[108:109]
	v_pk_mul_f32 v[102:103], v[110:111], v[102:103]
	v_pk_mul_f32 v[98:99], v[110:111], v[98:99]
	v_cndmask_b32_e64 v110, 0, 1, s[34:35]
	v_lshl_add_u64 v[108:109], v[108:109], 0, v[144:145]
	v_cmp_ne_u32_e64 s[8:9], 1, v110
	v_pk_mul_f32 v[96:97], v[112:113], v[96:97]
	global_store_dwordx4 v[108:109], v[116:119], off
	s_cbranch_vccnz .LBB0_708
	global_load_dwordx4 v[110:113], v[106:107], off
	s_nop 0
	global_load_dwordx4 v[104:107], v[104:105], off
	s_waitcnt vmcnt(0) lgkmcnt(0)
	v_pk_mul_f32 v[114:115], v[98:99], v[112:113]
	v_pk_mul_f32 v[116:117], v[96:97], v[110:111]
	v_pk_mul_f32 v[112:113], v[102:103], v[112:113]
	v_pk_mul_f32 v[110:111], v[100:101], v[110:111]
	v_pk_fma_f32 v[102:103], v[102:103], v[106:107], v[114:115] neg_lo:[0,0,1] neg_hi:[0,0,1]
	v_pk_fma_f32 v[100:101], v[100:101], v[104:105], v[116:117] neg_lo:[0,0,1] neg_hi:[0,0,1]
	v_pk_fma_f32 v[98:99], v[98:99], v[106:107], v[112:113]
	v_pk_fma_f32 v[96:97], v[96:97], v[104:105], v[110:111]
.LBB0_708:
	v_cvt_pk_bf16_f32 v100, v100, v101
	v_cvt_pk_bf16_f32 v101, v102, v103
	s_nop 0
	v_cvt_pk_bf16_f32 v96, v96, v97
	v_cvt_pk_bf16_f32 v97, v98, v99
	s_and_b64 vcc, exec, s[6:7]
	v_cndmask_b32_e64 v98, v100, v96, s[2:3]
	ds_bpermute_b32 v99, v172, v98
	v_cndmask_b32_e64 v98, v101, v97, s[2:3]
	ds_bpermute_b32 v102, v172, v98
	s_waitcnt lgkmcnt(0)
	v_cndmask_b32_e64 v98, v96, v99, s[2:3]
	v_cndmask_b32_e64 v96, v99, v100, s[2:3]
	v_cndmask_b32_e64 v99, v97, v102, s[2:3]
	v_cndmask_b32_e64 v97, v102, v101, s[2:3]
	global_store_dwordx4 v[108:109], v[96:99], off offset:256
	s_nop 1
	v_bitop3_b32 v96, v160, s59, 32 bitop3:0xc8
	v_lshl_add_u32 v96, v96, 2, 0
	v_add_u32_e32 v96, 0x20000, v96
	ds_read_b32 v96, v96
	v_or_b32_e32 v98, 32, v160
	v_ashrrev_i32_e32 v99, 31, v98
	v_lshlrev_b64 v[104:105], 4, v[98:99]
	s_waitcnt lgkmcnt(0)
	v_pk_mul_f32 v[100:101], v[96:97], v[90:91] op_sel_hi:[0,1]
	v_lshlrev_b64 v[90:91], 2, v[104:105]
	v_pk_mul_f32 v[94:95], v[96:97], v[94:95] op_sel_hi:[0,1]
	v_pk_mul_f32 v[92:93], v[96:97], v[92:93] op_sel_hi:[0,1]
	v_pk_mul_f32 v[102:103], v[96:97], v[88:89] op_sel_hi:[0,1]
	v_lshl_add_u64 v[88:89], v[148:149], 0, v[90:91]
	v_lshl_add_u64 v[90:91], v[150:151], 0, v[90:91]
	s_cbranch_vccnz .LBB0_710
	global_load_dwordx4 v[104:107], v[90:91], off
	global_load_dwordx4 v[108:111], v[88:89], off
	s_waitcnt vmcnt(0) lgkmcnt(0)
	v_pk_mul_f32 v[112:113], v[100:101], v[106:107]
	v_pk_mul_f32 v[114:115], v[102:103], v[104:105]
	v_pk_mul_f32 v[106:107], v[94:95], v[106:107]
	v_pk_mul_f32 v[104:105], v[92:93], v[104:105]
	v_pk_fma_f32 v[94:95], v[94:95], v[110:111], v[112:113] neg_lo:[0,0,1] neg_hi:[0,0,1]
	v_pk_fma_f32 v[92:93], v[92:93], v[108:109], v[114:115] neg_lo:[0,0,1] neg_hi:[0,0,1]
	v_pk_fma_f32 v[100:101], v[100:101], v[110:111], v[106:107]
	v_pk_fma_f32 v[102:103], v[102:103], v[108:109], v[104:105]
.LBB0_710:
	v_cvt_pk_bf16_f32 v92, v92, v93
	v_cvt_pk_bf16_f32 v93, v94, v95
	s_nop 0
	v_cvt_pk_bf16_f32 v94, v102, v103
	v_cvt_pk_bf16_f32 v95, v100, v101
	s_and_b64 vcc, exec, s[8:9]
	v_cndmask_b32_e64 v97, v92, v94, s[2:3]
	ds_bpermute_b32 v99, v172, v97
	v_cndmask_b32_e64 v97, v93, v95, s[2:3]
	ds_bpermute_b32 v101, v172, v97
	v_mov_b32_e32 v97, v96
	v_pk_mul_f32 v[84:85], v[96:97], v[84:85]
	s_waitcnt lgkmcnt(0)
	v_cndmask_b32_e64 v100, v99, v92, s[2:3]
	v_cndmask_b32_e64 v102, v94, v99, s[2:3]
	v_cndmask_b32_e64 v103, v95, v101, s[2:3]
	v_cndmask_b32_e64 v101, v101, v93, s[2:3]
	v_mov_b64_e32 v[92:93], s[18:19]
	v_mad_i64_i32 v[92:93], s[0:1], v98, s57, v[92:93]
	v_lshl_add_u64 v[92:93], s[30:31], 1, v[92:93]
	v_lshl_add_u64 v[92:93], v[146:147], 1, v[92:93]
	v_mov_b32_e32 v94, v96
	v_mov_b32_e32 v95, v96
	v_lshl_add_u64 v[92:93], v[92:93], 0, v[144:145]
	v_pk_mul_f32 v[86:87], v[94:95], v[86:87]
	v_pk_mul_f32 v[82:83], v[94:95], v[82:83]
	v_pk_mul_f32 v[80:81], v[96:97], v[80:81]
	global_store_dwordx4 v[92:93], v[100:103], off
	s_cbranch_vccnz .LBB0_712
	global_load_dwordx4 v[94:97], v[90:91], off
	s_nop 0
	global_load_dwordx4 v[88:91], v[88:89], off
	s_waitcnt vmcnt(0) lgkmcnt(0)
	v_pk_mul_f32 v[98:99], v[82:83], v[96:97]
	v_pk_mul_f32 v[100:101], v[80:81], v[94:95]
	v_pk_mul_f32 v[96:97], v[86:87], v[96:97]
	v_pk_mul_f32 v[94:95], v[84:85], v[94:95]
	v_pk_fma_f32 v[86:87], v[86:87], v[90:91], v[98:99] neg_lo:[0,0,1] neg_hi:[0,0,1]
	v_pk_fma_f32 v[84:85], v[84:85], v[88:89], v[100:101] neg_lo:[0,0,1] neg_hi:[0,0,1]
	v_pk_fma_f32 v[82:83], v[82:83], v[90:91], v[96:97]
	v_pk_fma_f32 v[80:81], v[80:81], v[88:89], v[94:95]
.LBB0_712:
	v_cvt_pk_bf16_f32 v84, v84, v85
	v_cvt_pk_bf16_f32 v85, v86, v87
	s_nop 0
	v_cvt_pk_bf16_f32 v80, v80, v81
	v_cvt_pk_bf16_f32 v81, v82, v83
	s_and_b64 vcc, exec, s[6:7]
	v_cndmask_b32_e64 v82, v84, v80, s[2:3]
	ds_bpermute_b32 v83, v172, v82
	v_cndmask_b32_e64 v82, v85, v81, s[2:3]
	ds_bpermute_b32 v86, v172, v82
	s_waitcnt lgkmcnt(0)
	v_cndmask_b32_e64 v82, v80, v83, s[2:3]
	v_cndmask_b32_e64 v80, v83, v84, s[2:3]
	v_cndmask_b32_e64 v83, v81, v86, s[2:3]
	v_cndmask_b32_e64 v81, v86, v85, s[2:3]
	global_store_dwordx4 v[92:93], v[80:83], off offset:256
	s_nop 1
	v_bitop3_b32 v80, v160, s60, 48 bitop3:0xc8
	v_lshl_add_u32 v80, v80, 2, 0
	v_add_u32_e32 v80, 0x20000, v80
	ds_read_b32 v80, v80
	v_or_b32_e32 v82, 48, v160
	v_ashrrev_i32_e32 v83, 31, v82
	v_lshlrev_b64 v[88:89], 4, v[82:83]
	s_waitcnt lgkmcnt(0)
	v_pk_mul_f32 v[84:85], v[80:81], v[74:75] op_sel_hi:[0,1]
	v_lshlrev_b64 v[74:75], 2, v[88:89]
	v_pk_mul_f32 v[78:79], v[80:81], v[78:79] op_sel_hi:[0,1]
	v_pk_mul_f32 v[76:77], v[80:81], v[76:77] op_sel_hi:[0,1]
	v_pk_mul_f32 v[86:87], v[80:81], v[72:73] op_sel_hi:[0,1]
	v_lshl_add_u64 v[72:73], v[148:149], 0, v[74:75]
	v_lshl_add_u64 v[74:75], v[150:151], 0, v[74:75]
	s_cbranch_vccnz .LBB0_714
	global_load_dwordx4 v[88:91], v[74:75], off
	global_load_dwordx4 v[92:95], v[72:73], off
	s_waitcnt vmcnt(0) lgkmcnt(0)
	v_pk_mul_f32 v[96:97], v[84:85], v[90:91]
	v_pk_mul_f32 v[98:99], v[86:87], v[88:89]
	v_pk_mul_f32 v[90:91], v[78:79], v[90:91]
	v_pk_mul_f32 v[88:89], v[76:77], v[88:89]
	v_pk_fma_f32 v[78:79], v[78:79], v[94:95], v[96:97] neg_lo:[0,0,1] neg_hi:[0,0,1]
	v_pk_fma_f32 v[76:77], v[76:77], v[92:93], v[98:99] neg_lo:[0,0,1] neg_hi:[0,0,1]
	v_pk_fma_f32 v[84:85], v[84:85], v[94:95], v[90:91]
	v_pk_fma_f32 v[86:87], v[86:87], v[92:93], v[88:89]
.LBB0_714:
	v_cvt_pk_bf16_f32 v76, v76, v77
	v_cvt_pk_bf16_f32 v77, v78, v79
	s_nop 0
	v_cvt_pk_bf16_f32 v78, v86, v87
	v_cvt_pk_bf16_f32 v79, v84, v85
	s_and_b64 vcc, exec, s[8:9]
	v_cndmask_b32_e64 v81, v76, v78, s[2:3]
	ds_bpermute_b32 v83, v172, v81
	v_cndmask_b32_e64 v81, v77, v79, s[2:3]
	ds_bpermute_b32 v85, v172, v81
	v_mov_b32_e32 v81, v80
	v_pk_mul_f32 v[68:69], v[80:81], v[68:69]
	s_waitcnt lgkmcnt(0)
	v_cndmask_b32_e64 v84, v83, v76, s[2:3]
	v_cndmask_b32_e64 v86, v78, v83, s[2:3]
	v_cndmask_b32_e64 v87, v79, v85, s[2:3]
	v_cndmask_b32_e64 v85, v85, v77, s[2:3]
	v_mov_b64_e32 v[76:77], s[18:19]
	v_mad_i64_i32 v[76:77], s[0:1], v82, s57, v[76:77]
	v_lshl_add_u64 v[76:77], s[30:31], 1, v[76:77]
	v_lshl_add_u64 v[76:77], v[146:147], 1, v[76:77]
	v_mov_b32_e32 v78, v80
	v_mov_b32_e32 v79, v80
	v_lshl_add_u64 v[76:77], v[76:77], 0, v[144:145]
	v_pk_mul_f32 v[70:71], v[78:79], v[70:71]
	v_pk_mul_f32 v[66:67], v[78:79], v[66:67]
	v_pk_mul_f32 v[64:65], v[80:81], v[64:65]
	global_store_dwordx4 v[76:77], v[84:87], off
	s_cbranch_vccnz .LBB0_716
	global_load_dwordx4 v[78:81], v[74:75], off
	s_nop 0
	global_load_dwordx4 v[72:75], v[72:73], off
	s_waitcnt vmcnt(0) lgkmcnt(0)
	v_pk_mul_f32 v[82:83], v[66:67], v[80:81]
	v_pk_mul_f32 v[84:85], v[64:65], v[78:79]
	v_pk_mul_f32 v[80:81], v[70:71], v[80:81]
	v_pk_mul_f32 v[78:79], v[68:69], v[78:79]
	v_pk_fma_f32 v[70:71], v[70:71], v[74:75], v[82:83] neg_lo:[0,0,1] neg_hi:[0,0,1]
	v_pk_fma_f32 v[68:69], v[68:69], v[72:73], v[84:85] neg_lo:[0,0,1] neg_hi:[0,0,1]
	v_pk_fma_f32 v[66:67], v[66:67], v[74:75], v[80:81]
	v_pk_fma_f32 v[64:65], v[64:65], v[72:73], v[78:79]
.LBB0_716:
	v_cvt_pk_bf16_f32 v68, v68, v69
	v_cvt_pk_bf16_f32 v69, v70, v71
	s_nop 0
	v_cvt_pk_bf16_f32 v64, v64, v65
	v_cvt_pk_bf16_f32 v65, v66, v67
	s_and_b64 vcc, exec, s[6:7]
	v_cndmask_b32_e64 v66, v68, v64, s[2:3]
	ds_bpermute_b32 v67, v172, v66
	v_cndmask_b32_e64 v66, v69, v65, s[2:3]
	ds_bpermute_b32 v70, v172, v66
	s_waitcnt lgkmcnt(0)
	v_cndmask_b32_e64 v66, v64, v67, s[2:3]
	v_cndmask_b32_e64 v64, v67, v68, s[2:3]
	v_cndmask_b32_e64 v67, v65, v70, s[2:3]
	v_cndmask_b32_e64 v65, v70, v69, s[2:3]
	global_store_dwordx4 v[76:77], v[64:67], off offset:256
	s_nop 1
	v_add_u32_e32 v66, 0x80, v160
	v_and_b32_e32 v64, 0x7cf, v66
	v_lshl_add_u32 v64, v64, 2, 0
	v_add_u32_e32 v64, 0x20000, v64
	ds_read_b32 v64, v64
	v_ashrrev_i32_e32 v67, 31, v66
	v_lshlrev_b64 v[72:73], 4, v[66:67]
	s_waitcnt lgkmcnt(0)
	v_pk_mul_f32 v[68:69], v[64:65], v[58:59] op_sel_hi:[0,1]
	v_lshlrev_b64 v[58:59], 2, v[72:73]
	v_pk_mul_f32 v[62:63], v[64:65], v[62:63] op_sel_hi:[0,1]
	v_pk_mul_f32 v[60:61], v[64:65], v[60:61] op_sel_hi:[0,1]
	v_pk_mul_f32 v[70:71], v[64:65], v[56:57] op_sel_hi:[0,1]
	v_lshl_add_u64 v[56:57], v[148:149], 0, v[58:59]
	v_lshl_add_u64 v[58:59], v[150:151], 0, v[58:59]
	s_cbranch_vccnz .LBB0_718
	global_load_dwordx4 v[72:75], v[58:59], off
	global_load_dwordx4 v[76:79], v[56:57], off
	s_waitcnt vmcnt(0) lgkmcnt(0)
	v_pk_mul_f32 v[80:81], v[68:69], v[74:75]
	v_pk_mul_f32 v[82:83], v[70:71], v[72:73]
	v_pk_mul_f32 v[74:75], v[62:63], v[74:75]
	v_pk_mul_f32 v[72:73], v[60:61], v[72:73]
	v_pk_fma_f32 v[62:63], v[62:63], v[78:79], v[80:81] neg_lo:[0,0,1] neg_hi:[0,0,1]
	v_pk_fma_f32 v[60:61], v[60:61], v[76:77], v[82:83] neg_lo:[0,0,1] neg_hi:[0,0,1]
	v_pk_fma_f32 v[68:69], v[68:69], v[78:79], v[74:75]
	v_pk_fma_f32 v[70:71], v[70:71], v[76:77], v[72:73]
.LBB0_718:
	v_cvt_pk_bf16_f32 v60, v60, v61
	v_cvt_pk_bf16_f32 v61, v62, v63
	s_nop 0
	v_cvt_pk_bf16_f32 v62, v70, v71
	v_cvt_pk_bf16_f32 v63, v68, v69
	s_and_b64 vcc, exec, s[8:9]
	v_cndmask_b32_e64 v65, v60, v62, s[2:3]
	ds_bpermute_b32 v67, v172, v65
	v_cndmask_b32_e64 v65, v61, v63, s[2:3]
	ds_bpermute_b32 v69, v172, v65
	v_mov_b32_e32 v65, v64
	v_pk_mul_f32 v[52:53], v[64:65], v[52:53]
	s_waitcnt lgkmcnt(0)
	v_cndmask_b32_e64 v68, v67, v60, s[2:3]
	v_cndmask_b32_e64 v70, v62, v67, s[2:3]
	v_cndmask_b32_e64 v71, v63, v69, s[2:3]
	v_cndmask_b32_e64 v69, v69, v61, s[2:3]
	v_mov_b64_e32 v[60:61], s[18:19]
	v_mad_i64_i32 v[60:61], s[0:1], v66, s57, v[60:61]
	v_lshl_add_u64 v[60:61], s[30:31], 1, v[60:61]
	v_lshl_add_u64 v[60:61], v[146:147], 1, v[60:61]
	v_mov_b32_e32 v62, v64
	v_mov_b32_e32 v63, v64
	v_lshl_add_u64 v[60:61], v[60:61], 0, v[144:145]
	v_pk_mul_f32 v[54:55], v[62:63], v[54:55]
	v_pk_mul_f32 v[50:51], v[62:63], v[50:51]
	v_pk_mul_f32 v[48:49], v[64:65], v[48:49]
	global_store_dwordx4 v[60:61], v[68:71], off
	s_cbranch_vccnz .LBB0_720
	global_load_dwordx4 v[62:65], v[58:59], off
	s_nop 0
	global_load_dwordx4 v[56:59], v[56:57], off
	s_waitcnt vmcnt(0) lgkmcnt(0)
	v_pk_mul_f32 v[66:67], v[50:51], v[64:65]
	v_pk_mul_f32 v[68:69], v[48:49], v[62:63]
	v_pk_mul_f32 v[64:65], v[54:55], v[64:65]
	v_pk_mul_f32 v[62:63], v[52:53], v[62:63]
	v_pk_fma_f32 v[54:55], v[54:55], v[58:59], v[66:67] neg_lo:[0,0,1] neg_hi:[0,0,1]
	v_pk_fma_f32 v[52:53], v[52:53], v[56:57], v[68:69] neg_lo:[0,0,1] neg_hi:[0,0,1]
	v_pk_fma_f32 v[50:51], v[50:51], v[58:59], v[64:65]
	v_pk_fma_f32 v[48:49], v[48:49], v[56:57], v[62:63]
.LBB0_720:
	v_cvt_pk_bf16_f32 v52, v52, v53
	v_cvt_pk_bf16_f32 v53, v54, v55
	s_nop 0
	v_cvt_pk_bf16_f32 v48, v48, v49
	v_cvt_pk_bf16_f32 v49, v50, v51
	s_and_b64 vcc, exec, s[6:7]
	v_cndmask_b32_e64 v50, v52, v48, s[2:3]
	ds_bpermute_b32 v51, v172, v50
	v_cndmask_b32_e64 v50, v53, v49, s[2:3]
	ds_bpermute_b32 v54, v172, v50
	s_waitcnt lgkmcnt(0)
	v_cndmask_b32_e64 v50, v48, v51, s[2:3]
	v_cndmask_b32_e64 v48, v51, v52, s[2:3]
	v_cndmask_b32_e64 v51, v49, v54, s[2:3]
	v_cndmask_b32_e64 v49, v54, v53, s[2:3]
	global_store_dwordx4 v[60:61], v[48:51], off offset:256
	s_nop 1
	v_add_u32_e32 v50, 0x90, v160
	v_and_b32_e32 v48, 0x7df, v50
	v_lshl_add_u32 v48, v48, 2, 0
	v_add_u32_e32 v48, 0x20000, v48
	ds_read_b32 v48, v48
	v_ashrrev_i32_e32 v51, 31, v50
	v_lshlrev_b64 v[56:57], 4, v[50:51]
	s_waitcnt lgkmcnt(0)
	v_pk_mul_f32 v[52:53], v[48:49], v[42:43] op_sel_hi:[0,1]
	v_lshlrev_b64 v[42:43], 2, v[56:57]
	v_pk_mul_f32 v[46:47], v[48:49], v[46:47] op_sel_hi:[0,1]
	v_pk_mul_f32 v[44:45], v[48:49], v[44:45] op_sel_hi:[0,1]
	v_pk_mul_f32 v[54:55], v[48:49], v[40:41] op_sel_hi:[0,1]
	v_lshl_add_u64 v[40:41], v[148:149], 0, v[42:43]
	v_lshl_add_u64 v[42:43], v[150:151], 0, v[42:43]
	s_cbranch_vccnz .LBB0_722
	global_load_dwordx4 v[56:59], v[42:43], off
	global_load_dwordx4 v[60:63], v[40:41], off
	s_waitcnt vmcnt(0) lgkmcnt(0)
	v_pk_mul_f32 v[64:65], v[52:53], v[58:59]
	v_pk_mul_f32 v[66:67], v[54:55], v[56:57]
	v_pk_mul_f32 v[58:59], v[46:47], v[58:59]
	v_pk_mul_f32 v[56:57], v[44:45], v[56:57]
	v_pk_fma_f32 v[46:47], v[46:47], v[62:63], v[64:65] neg_lo:[0,0,1] neg_hi:[0,0,1]
	v_pk_fma_f32 v[44:45], v[44:45], v[60:61], v[66:67] neg_lo:[0,0,1] neg_hi:[0,0,1]
	v_pk_fma_f32 v[52:53], v[52:53], v[62:63], v[58:59]
	v_pk_fma_f32 v[54:55], v[54:55], v[60:61], v[56:57]
.LBB0_722:
	v_cvt_pk_bf16_f32 v44, v44, v45
	v_cvt_pk_bf16_f32 v45, v46, v47
	s_nop 0
	v_cvt_pk_bf16_f32 v46, v54, v55
	v_cvt_pk_bf16_f32 v47, v52, v53
	s_and_b64 vcc, exec, s[8:9]
	v_cndmask_b32_e64 v49, v44, v46, s[2:3]
	ds_bpermute_b32 v51, v172, v49
	v_cndmask_b32_e64 v49, v45, v47, s[2:3]
	ds_bpermute_b32 v53, v172, v49
	v_mov_b32_e32 v49, v48
	v_pk_mul_f32 v[36:37], v[48:49], v[36:37]
	s_waitcnt lgkmcnt(0)
	v_cndmask_b32_e64 v52, v51, v44, s[2:3]
	v_cndmask_b32_e64 v54, v46, v51, s[2:3]
	v_cndmask_b32_e64 v55, v47, v53, s[2:3]
	v_cndmask_b32_e64 v53, v53, v45, s[2:3]
	v_mov_b64_e32 v[44:45], s[18:19]
	v_mad_i64_i32 v[44:45], s[0:1], v50, s57, v[44:45]
	v_lshl_add_u64 v[44:45], s[30:31], 1, v[44:45]
	v_lshl_add_u64 v[44:45], v[146:147], 1, v[44:45]
	v_mov_b32_e32 v46, v48
	v_mov_b32_e32 v47, v48
	v_lshl_add_u64 v[44:45], v[44:45], 0, v[144:145]
	v_pk_mul_f32 v[38:39], v[46:47], v[38:39]
	v_pk_mul_f32 v[34:35], v[46:47], v[34:35]
	v_pk_mul_f32 v[32:33], v[48:49], v[32:33]
	global_store_dwordx4 v[44:45], v[52:55], off
	s_cbranch_vccnz .LBB0_724
	global_load_dwordx4 v[46:49], v[42:43], off
	s_nop 0
	global_load_dwordx4 v[40:43], v[40:41], off
	s_waitcnt vmcnt(0) lgkmcnt(0)
	v_pk_mul_f32 v[50:51], v[34:35], v[48:49]
	v_pk_mul_f32 v[52:53], v[32:33], v[46:47]
	v_pk_mul_f32 v[48:49], v[38:39], v[48:49]
	v_pk_mul_f32 v[46:47], v[36:37], v[46:47]
	v_pk_fma_f32 v[38:39], v[38:39], v[42:43], v[50:51] neg_lo:[0,0,1] neg_hi:[0,0,1]
	v_pk_fma_f32 v[36:37], v[36:37], v[40:41], v[52:53] neg_lo:[0,0,1] neg_hi:[0,0,1]
	v_pk_fma_f32 v[34:35], v[34:35], v[42:43], v[48:49]
	v_pk_fma_f32 v[32:33], v[32:33], v[40:41], v[46:47]
.LBB0_724:
	v_cvt_pk_bf16_f32 v36, v36, v37
	v_cvt_pk_bf16_f32 v37, v38, v39
	s_nop 0
	v_cvt_pk_bf16_f32 v32, v32, v33
	v_cvt_pk_bf16_f32 v33, v34, v35
	s_and_b64 vcc, exec, s[6:7]
	v_cndmask_b32_e64 v34, v36, v32, s[2:3]
	ds_bpermute_b32 v35, v172, v34
	v_cndmask_b32_e64 v34, v37, v33, s[2:3]
	ds_bpermute_b32 v38, v172, v34
	s_waitcnt lgkmcnt(0)
	v_cndmask_b32_e64 v34, v32, v35, s[2:3]
	v_cndmask_b32_e64 v32, v35, v36, s[2:3]
	v_cndmask_b32_e64 v35, v33, v38, s[2:3]
	v_cndmask_b32_e64 v33, v38, v37, s[2:3]
	global_store_dwordx4 v[44:45], v[32:35], off offset:256
	s_nop 1
	v_add_u32_e32 v34, 0xa0, v160
	v_and_b32_e32 v32, 0x7ef, v34
	v_lshl_add_u32 v32, v32, 2, 0
	v_add_u32_e32 v32, 0x20000, v32
	ds_read_b32 v32, v32
	v_ashrrev_i32_e32 v35, 31, v34
	v_lshlrev_b64 v[40:41], 4, v[34:35]
	s_waitcnt lgkmcnt(0)
	v_pk_mul_f32 v[36:37], v[32:33], v[26:27] op_sel_hi:[0,1]
	v_lshlrev_b64 v[26:27], 2, v[40:41]
	v_pk_mul_f32 v[30:31], v[32:33], v[30:31] op_sel_hi:[0,1]
	v_pk_mul_f32 v[28:29], v[32:33], v[28:29] op_sel_hi:[0,1]
	v_pk_mul_f32 v[38:39], v[32:33], v[24:25] op_sel_hi:[0,1]
	v_lshl_add_u64 v[24:25], v[148:149], 0, v[26:27]
	v_lshl_add_u64 v[26:27], v[150:151], 0, v[26:27]
	s_cbranch_vccnz .LBB0_726
	global_load_dwordx4 v[40:43], v[26:27], off
	global_load_dwordx4 v[44:47], v[24:25], off
	s_waitcnt vmcnt(0) lgkmcnt(0)
	v_pk_mul_f32 v[48:49], v[36:37], v[42:43]
	v_pk_mul_f32 v[50:51], v[38:39], v[40:41]
	v_pk_mul_f32 v[42:43], v[30:31], v[42:43]
	v_pk_mul_f32 v[40:41], v[28:29], v[40:41]
	v_pk_fma_f32 v[30:31], v[30:31], v[46:47], v[48:49] neg_lo:[0,0,1] neg_hi:[0,0,1]
	v_pk_fma_f32 v[28:29], v[28:29], v[44:45], v[50:51] neg_lo:[0,0,1] neg_hi:[0,0,1]
	v_pk_fma_f32 v[36:37], v[36:37], v[46:47], v[42:43]
	v_pk_fma_f32 v[38:39], v[38:39], v[44:45], v[40:41]
.LBB0_726:
	v_cvt_pk_bf16_f32 v28, v28, v29
	v_cvt_pk_bf16_f32 v29, v30, v31
	s_nop 0
	v_cvt_pk_bf16_f32 v30, v38, v39
	v_cvt_pk_bf16_f32 v31, v36, v37
	s_and_b64 vcc, exec, s[8:9]
	v_cndmask_b32_e64 v33, v28, v30, s[2:3]
	ds_bpermute_b32 v35, v172, v33
	v_cndmask_b32_e64 v33, v29, v31, s[2:3]
	ds_bpermute_b32 v37, v172, v33
	v_mov_b32_e32 v33, v32
	v_pk_mul_f32 v[20:21], v[32:33], v[20:21]
	s_waitcnt lgkmcnt(0)
	v_cndmask_b32_e64 v36, v35, v28, s[2:3]
	v_cndmask_b32_e64 v38, v30, v35, s[2:3]
	v_cndmask_b32_e64 v39, v31, v37, s[2:3]
	v_cndmask_b32_e64 v37, v37, v29, s[2:3]
	v_mov_b64_e32 v[28:29], s[18:19]
	v_mad_i64_i32 v[28:29], s[0:1], v34, s57, v[28:29]
	v_lshl_add_u64 v[28:29], s[30:31], 1, v[28:29]
	v_lshl_add_u64 v[28:29], v[146:147], 1, v[28:29]
	v_mov_b32_e32 v30, v32
	v_mov_b32_e32 v31, v32
	v_lshl_add_u64 v[28:29], v[28:29], 0, v[144:145]
	v_pk_mul_f32 v[22:23], v[30:31], v[22:23]
	v_pk_mul_f32 v[18:19], v[30:31], v[18:19]
	v_pk_mul_f32 v[16:17], v[32:33], v[16:17]
	global_store_dwordx4 v[28:29], v[36:39], off
	s_cbranch_vccnz .LBB0_728
	global_load_dwordx4 v[30:33], v[26:27], off
	s_nop 0
	global_load_dwordx4 v[24:27], v[24:25], off
	s_waitcnt vmcnt(0) lgkmcnt(0)
	v_pk_mul_f32 v[34:35], v[18:19], v[32:33]
	v_pk_mul_f32 v[36:37], v[16:17], v[30:31]
	v_pk_mul_f32 v[32:33], v[22:23], v[32:33]
	v_pk_mul_f32 v[30:31], v[20:21], v[30:31]
	v_pk_fma_f32 v[22:23], v[22:23], v[26:27], v[34:35] neg_lo:[0,0,1] neg_hi:[0,0,1]
	v_pk_fma_f32 v[20:21], v[20:21], v[24:25], v[36:37] neg_lo:[0,0,1] neg_hi:[0,0,1]
	v_pk_fma_f32 v[18:19], v[18:19], v[26:27], v[32:33]
	v_pk_fma_f32 v[16:17], v[16:17], v[24:25], v[30:31]
.LBB0_728:
	v_cvt_pk_bf16_f32 v20, v20, v21
	v_cvt_pk_bf16_f32 v21, v22, v23
	s_nop 0
	v_cvt_pk_bf16_f32 v16, v16, v17
	v_cvt_pk_bf16_f32 v17, v18, v19
	s_and_b64 vcc, exec, s[6:7]
	v_cndmask_b32_e64 v18, v20, v16, s[2:3]
	ds_bpermute_b32 v19, v172, v18
	v_cndmask_b32_e64 v18, v21, v17, s[2:3]
	ds_bpermute_b32 v22, v172, v18
	s_waitcnt lgkmcnt(0)
	v_cndmask_b32_e64 v18, v16, v19, s[2:3]
	v_cndmask_b32_e64 v16, v19, v20, s[2:3]
	v_cndmask_b32_e64 v19, v17, v22, s[2:3]
	v_cndmask_b32_e64 v17, v22, v21, s[2:3]
	global_store_dwordx4 v[28:29], v[16:19], off offset:256
	s_nop 1
	v_add_u32_e32 v18, 0xb0, v160
	v_and_b32_e32 v16, 0x7ff, v18
	v_lshl_add_u32 v16, v16, 2, 0
	v_add_u32_e32 v16, 0x20000, v16
	ds_read_b32 v16, v16
	v_ashrrev_i32_e32 v19, 31, v18
	v_lshlrev_b64 v[24:25], 4, v[18:19]
	s_waitcnt lgkmcnt(0)
	v_pk_mul_f32 v[20:21], v[16:17], v[10:11] op_sel_hi:[0,1]
	v_lshlrev_b64 v[10:11], 2, v[24:25]
	v_pk_mul_f32 v[14:15], v[16:17], v[14:15] op_sel_hi:[0,1]
	v_pk_mul_f32 v[12:13], v[16:17], v[12:13] op_sel_hi:[0,1]
	v_pk_mul_f32 v[22:23], v[16:17], v[8:9] op_sel_hi:[0,1]
	v_lshl_add_u64 v[8:9], v[148:149], 0, v[10:11]
	v_lshl_add_u64 v[10:11], v[150:151], 0, v[10:11]
	s_cbranch_vccnz .LBB0_730
	global_load_dwordx4 v[24:27], v[10:11], off
	global_load_dwordx4 v[28:31], v[8:9], off
	s_waitcnt vmcnt(0) lgkmcnt(0)
	v_pk_mul_f32 v[32:33], v[20:21], v[26:27]
	v_pk_mul_f32 v[34:35], v[22:23], v[24:25]
	v_pk_mul_f32 v[26:27], v[14:15], v[26:27]
	v_pk_mul_f32 v[24:25], v[12:13], v[24:25]
	v_pk_fma_f32 v[14:15], v[14:15], v[30:31], v[32:33] neg_lo:[0,0,1] neg_hi:[0,0,1]
	v_pk_fma_f32 v[12:13], v[12:13], v[28:29], v[34:35] neg_lo:[0,0,1] neg_hi:[0,0,1]
	v_pk_fma_f32 v[20:21], v[20:21], v[30:31], v[26:27]
	v_pk_fma_f32 v[22:23], v[22:23], v[28:29], v[24:25]
.LBB0_730:
	v_cvt_pk_bf16_f32 v12, v12, v13
	v_cvt_pk_bf16_f32 v13, v14, v15
	s_nop 0
	v_cvt_pk_bf16_f32 v14, v22, v23
	v_cvt_pk_bf16_f32 v15, v20, v21
	s_and_b64 vcc, exec, s[8:9]
	v_cndmask_b32_e64 v17, v12, v14, s[2:3]
	ds_bpermute_b32 v19, v172, v17
	v_cndmask_b32_e64 v17, v13, v15, s[2:3]
	ds_bpermute_b32 v21, v172, v17
	v_mov_b32_e32 v17, v16
	v_pk_mul_f32 v[4:5], v[16:17], v[4:5]
	s_waitcnt lgkmcnt(0)
	v_cndmask_b32_e64 v20, v19, v12, s[2:3]
	v_cndmask_b32_e64 v22, v14, v19, s[2:3]
	v_cndmask_b32_e64 v23, v15, v21, s[2:3]
	v_cndmask_b32_e64 v21, v21, v13, s[2:3]
	v_mov_b64_e32 v[12:13], s[18:19]
	v_mad_i64_i32 v[12:13], s[0:1], v18, s57, v[12:13]
	v_lshl_add_u64 v[12:13], s[30:31], 1, v[12:13]
	v_lshl_add_u64 v[12:13], v[146:147], 1, v[12:13]
	v_mov_b32_e32 v14, v16
	v_mov_b32_e32 v15, v16
	v_lshl_add_u64 v[12:13], v[12:13], 0, v[144:145]
	v_pk_mul_f32 v[6:7], v[14:15], v[6:7]
	v_pk_mul_f32 v[2:3], v[14:15], v[2:3]
	v_pk_mul_f32 v[0:1], v[16:17], v[0:1]
	global_store_dwordx4 v[12:13], v[20:23], off
	s_cbranch_vccnz .LBB0_732
	global_load_dwordx4 v[14:17], v[10:11], off
	s_nop 0
	global_load_dwordx4 v[8:11], v[8:9], off
	s_waitcnt vmcnt(0) lgkmcnt(0)
	v_pk_mul_f32 v[18:19], v[2:3], v[16:17]
	v_pk_mul_f32 v[20:21], v[0:1], v[14:15]
	v_pk_mul_f32 v[16:17], v[6:7], v[16:17]
	v_pk_mul_f32 v[14:15], v[4:5], v[14:15]
	v_pk_fma_f32 v[6:7], v[6:7], v[10:11], v[18:19] neg_lo:[0,0,1] neg_hi:[0,0,1]
	v_pk_fma_f32 v[4:5], v[4:5], v[8:9], v[20:21] neg_lo:[0,0,1] neg_hi:[0,0,1]
	v_pk_fma_f32 v[2:3], v[2:3], v[10:11], v[16:17]
	v_pk_fma_f32 v[0:1], v[0:1], v[8:9], v[14:15]
.LBB0_732:
	v_cvt_pk_bf16_f32 v4, v4, v5
	v_cvt_pk_bf16_f32 v5, v6, v7
	s_nop 0
	v_cvt_pk_bf16_f32 v0, v0, v1
	v_cvt_pk_bf16_f32 v1, v2, v3
	s_and_b64 vcc, exec, s[4:5]
	v_cndmask_b32_e64 v2, v4, v0, s[2:3]
	ds_bpermute_b32 v3, v172, v2
	v_cndmask_b32_e64 v2, v5, v1, s[2:3]
	ds_bpermute_b32 v6, v172, v2
	s_mov_b64 s[0:1], -1
	s_waitcnt lgkmcnt(0)
	v_cndmask_b32_e64 v2, v0, v3, s[2:3]
	v_cndmask_b32_e64 v0, v3, v4, s[2:3]
	v_cndmask_b32_e64 v3, v1, v6, s[2:3]
	v_cndmask_b32_e64 v1, v6, v5, s[2:3]
	global_store_dwordx4 v[12:13], v[0:3], off offset:256
	s_cbranch_vccnz .LBB0_688
	s_andn2_b64 vcc, exec, s[16:17]
	v_pk_mov_b32 v[124:125], 0, 0
	v_pk_mov_b32 v[126:127], 0, 0
	v_pk_mov_b32 v[120:121], 0, 0
	v_pk_mov_b32 v[122:123], 0, 0
	v_pk_mov_b32 v[108:109], 0, 0
	v_pk_mov_b32 v[110:111], 0, 0
	v_pk_mov_b32 v[104:105], 0, 0
	v_pk_mov_b32 v[106:107], 0, 0
	v_pk_mov_b32 v[92:93], 0, 0
	v_pk_mov_b32 v[94:95], 0, 0
	v_pk_mov_b32 v[88:89], 0, 0
	v_pk_mov_b32 v[90:91], 0, 0
	v_pk_mov_b32 v[76:77], 0, 0
	v_pk_mov_b32 v[78:79], 0, 0
	v_pk_mov_b32 v[72:73], 0, 0
	v_pk_mov_b32 v[74:75], 0, 0
	v_pk_mov_b32 v[116:117], 0, 0
	v_pk_mov_b32 v[118:119], 0, 0
	v_pk_mov_b32 v[112:113], 0, 0
	v_pk_mov_b32 v[114:115], 0, 0
	v_pk_mov_b32 v[100:101], 0, 0
	v_pk_mov_b32 v[102:103], 0, 0
	v_pk_mov_b32 v[96:97], 0, 0
	v_pk_mov_b32 v[98:99], 0, 0
	v_pk_mov_b32 v[84:85], 0, 0
	v_pk_mov_b32 v[86:87], 0, 0
	v_pk_mov_b32 v[80:81], 0, 0
	v_pk_mov_b32 v[82:83], 0, 0
	v_pk_mov_b32 v[68:69], 0, 0
	v_pk_mov_b32 v[70:71], 0, 0
	v_pk_mov_b32 v[64:65], 0, 0
	v_pk_mov_b32 v[66:67], 0, 0
	v_pk_mov_b32 v[60:61], 0, 0
	v_pk_mov_b32 v[62:63], 0, 0
	v_pk_mov_b32 v[56:57], 0, 0
	v_pk_mov_b32 v[58:59], 0, 0
	v_pk_mov_b32 v[44:45], 0, 0
	v_pk_mov_b32 v[46:47], 0, 0
	v_pk_mov_b32 v[40:41], 0, 0
	v_pk_mov_b32 v[42:43], 0, 0
	v_pk_mov_b32 v[28:29], 0, 0
	v_pk_mov_b32 v[30:31], 0, 0
	v_pk_mov_b32 v[24:25], 0, 0
	v_pk_mov_b32 v[26:27], 0, 0
	v_pk_mov_b32 v[12:13], 0, 0
	v_pk_mov_b32 v[14:15], 0, 0
	v_pk_mov_b32 v[8:9], 0, 0
	v_pk_mov_b32 v[10:11], 0, 0
	v_pk_mov_b32 v[52:53], 0, 0
	v_pk_mov_b32 v[54:55], 0, 0
	v_pk_mov_b32 v[48:49], 0, 0
	v_pk_mov_b32 v[50:51], 0, 0
	v_pk_mov_b32 v[36:37], 0, 0
	v_pk_mov_b32 v[38:39], 0, 0
	v_pk_mov_b32 v[32:33], 0, 0
	v_pk_mov_b32 v[34:35], 0, 0
	v_pk_mov_b32 v[20:21], 0, 0
	v_pk_mov_b32 v[22:23], 0, 0
	v_pk_mov_b32 v[16:17], 0, 0
	v_pk_mov_b32 v[18:19], 0, 0
	v_pk_mov_b32 v[4:5], 0, 0
	v_pk_mov_b32 v[6:7], 0, 0
	v_pk_mov_b32 v[0:1], 0, 0
	v_pk_mov_b32 v[2:3], 0, 0
	s_cbranch_vccnz .LBB0_687
	s_barrier
	s_branch .LBB0_687

.LBB0_767:
	s_waitcnt lgkmcnt(0)
	v_pk_mul_f32 v[120:121], v[148:149], v[120:121] op_sel_hi:[0,1]
	v_pk_mul_f32 v[122:123], v[148:149], v[122:123] op_sel_hi:[0,1]
	v_cvt_pk_bf16_f32 v120, v120, v121
	s_lshl_b32 s0, s51, 1
	v_pk_mul_f32 v[126:127], v[148:149], v[126:127] op_sel_hi:[0,1]
	v_pk_mul_f32 v[124:125], v[148:149], v[124:125] op_sel_hi:[0,1]
	v_cvt_pk_bf16_f32 v121, v122, v123
	v_cvt_pk_bf16_f32 v122, v124, v125
	v_cvt_pk_bf16_f32 v123, v126, v127
	global_store_dwordx4 v[154:155], v[120:123], off
	s_or_b32 s62, s0, 1
	s_andn2_b64 vcc, exec, s[24:25]
	v_cndmask_b32_e64 v120, 0, 1, s[24:25]
	v_cmp_ne_u32_e64 s[4:5], 1, v120
	s_mov_b64 s[0:1], -1
	s_cbranch_vccnz .LBB0_769
	s_lshl_b32 s0, s62, 6
	s_ashr_i32 s1, s0, 31
	v_lshl_add_u64 v[120:121], s[0:1], 1, v[150:151]
	v_lshl_add_u64 v[120:121], v[136:137], 1, v[120:121]
	v_lshl_add_u64 v[120:121], v[120:121], 0, s[26:27]
	s_mov_b64 s[0:1], 0

.LBB0_771:
	v_mov_b32_e32 v149, v148
	v_mov_b32_e32 v122, v148
	v_mov_b32_e32 v123, v148
	v_pk_mul_f32 v[112:113], v[148:149], v[112:113]
	v_pk_mul_f32 v[114:115], v[122:123], v[114:115]
	v_cvt_pk_bf16_f32 v112, v112, v113
	v_pk_mul_f32 v[118:119], v[122:123], v[118:119]
	v_pk_mul_f32 v[116:117], v[148:149], v[116:117]
	v_cvt_pk_bf16_f32 v113, v114, v115
	s_mov_b64 s[0:1], -1
	v_cvt_pk_bf16_f32 v114, v116, v117
	v_cvt_pk_bf16_f32 v115, v118, v119
	global_store_dwordx4 v[120:121], v[112:115], off
	v_or_b32_e32 v116, 16, v146
	v_ashrrev_i32_e32 v117, 31, v116
	v_bitop3_b32 v112, v146, s57, 16 bitop3:0xc8
	v_lshl_add_u32 v112, v112, 2, 0
	v_add_u32_e32 v112, 0x20000, v112
	ds_read_b32 v112, v112
	v_lshlrev_b64 v[114:115], 10, v[116:117]
	s_and_b64 vcc, exec, s[4:5]
	v_lshl_add_u64 v[114:115], s[16:17], 0, v[114:115]
	s_cbranch_vccnz .LBB0_773
	s_lshl_b32 s0, s51, 7
	s_ashr_i32 s1, s0, 31
	v_lshl_add_u64 v[118:119], s[0:1], 1, v[114:115]
	v_lshl_add_u64 v[118:119], v[136:137], 1, v[118:119]
	v_lshl_add_u64 v[118:119], v[118:119], 0, s[26:27]
	s_mov_b64 s[0:1], 0

.LBB0_775:
	s_waitcnt lgkmcnt(0)
	v_pk_mul_f32 v[104:105], v[112:113], v[104:105] op_sel_hi:[0,1]
	v_pk_mul_f32 v[106:107], v[112:113], v[106:107] op_sel_hi:[0,1]
	v_cvt_pk_bf16_f32 v104, v104, v105
	v_cvt_pk_bf16_f32 v105, v106, v107
	s_and_b64 vcc, exec, s[4:5]
	s_mov_b64 s[0:1], -1
	v_pk_mul_f32 v[110:111], v[112:113], v[110:111] op_sel_hi:[0,1]
	v_pk_mul_f32 v[108:109], v[112:113], v[108:109] op_sel_hi:[0,1]
	v_cvt_pk_bf16_f32 v106, v108, v109
	v_cvt_pk_bf16_f32 v107, v110, v111
	global_store_dwordx4 v[118:119], v[104:107], off
	s_cbranch_vccnz .LBB0_777
	s_lshl_b32 s0, s62, 6
	s_ashr_i32 s1, s0, 31
	v_lshl_add_u64 v[104:105], s[0:1], 1, v[114:115]
	v_lshl_add_u64 v[104:105], v[136:137], 1, v[104:105]
	v_lshl_add_u64 v[104:105], v[104:105], 0, s[26:27]
	s_mov_b64 s[0:1], 0

.LBB0_779:
	v_mov_b32_e32 v113, v112
	v_mov_b32_e32 v106, v112
	v_mov_b32_e32 v107, v112
	v_pk_mul_f32 v[96:97], v[112:113], v[96:97]
	v_pk_mul_f32 v[98:99], v[106:107], v[98:99]
	v_cvt_pk_bf16_f32 v96, v96, v97
	v_pk_mul_f32 v[102:103], v[106:107], v[102:103]
	v_pk_mul_f32 v[100:101], v[112:113], v[100:101]
	v_cvt_pk_bf16_f32 v97, v98, v99
	s_mov_b64 s[0:1], -1
	v_cvt_pk_bf16_f32 v98, v100, v101
	v_cvt_pk_bf16_f32 v99, v102, v103
	global_store_dwordx4 v[104:105], v[96:99], off
	v_or_b32_e32 v100, 32, v146
	v_ashrrev_i32_e32 v101, 31, v100
	v_bitop3_b32 v96, v146, s58, 32 bitop3:0xc8
	v_lshl_add_u32 v96, v96, 2, 0
	v_add_u32_e32 v96, 0x20000, v96
	ds_read_b32 v96, v96
	v_lshlrev_b64 v[98:99], 10, v[100:101]
	s_and_b64 vcc, exec, s[4:5]
	v_lshl_add_u64 v[98:99], s[16:17], 0, v[98:99]
	s_cbranch_vccnz .LBB0_781
	s_lshl_b32 s0, s51, 7
	s_ashr_i32 s1, s0, 31
	v_lshl_add_u64 v[102:103], s[0:1], 1, v[98:99]
	v_lshl_add_u64 v[102:103], v[136:137], 1, v[102:103]
	v_lshl_add_u64 v[102:103], v[102:103], 0, s[26:27]
	s_mov_b64 s[0:1], 0

.LBB0_783:
	s_waitcnt lgkmcnt(0)
	v_pk_mul_f32 v[88:89], v[96:97], v[88:89] op_sel_hi:[0,1]
	v_pk_mul_f32 v[90:91], v[96:97], v[90:91] op_sel_hi:[0,1]
	v_cvt_pk_bf16_f32 v88, v88, v89
	v_cvt_pk_bf16_f32 v89, v90, v91
	s_and_b64 vcc, exec, s[4:5]
	s_mov_b64 s[0:1], -1
	v_pk_mul_f32 v[94:95], v[96:97], v[94:95] op_sel_hi:[0,1]
	v_pk_mul_f32 v[92:93], v[96:97], v[92:93] op_sel_hi:[0,1]
	v_cvt_pk_bf16_f32 v90, v92, v93
	v_cvt_pk_bf16_f32 v91, v94, v95
	global_store_dwordx4 v[102:103], v[88:91], off
	s_cbranch_vccnz .LBB0_785
	s_lshl_b32 s0, s62, 6
	s_ashr_i32 s1, s0, 31
	v_lshl_add_u64 v[88:89], s[0:1], 1, v[98:99]
	v_lshl_add_u64 v[88:89], v[136:137], 1, v[88:89]
	v_lshl_add_u64 v[88:89], v[88:89], 0, s[26:27]
	s_mov_b64 s[0:1], 0

.LBB0_787:
	v_mov_b32_e32 v97, v96
	v_mov_b32_e32 v90, v96
	v_mov_b32_e32 v91, v96
	v_pk_mul_f32 v[80:81], v[96:97], v[80:81]
	v_pk_mul_f32 v[82:83], v[90:91], v[82:83]
	v_cvt_pk_bf16_f32 v80, v80, v81
	v_pk_mul_f32 v[86:87], v[90:91], v[86:87]
	v_pk_mul_f32 v[84:85], v[96:97], v[84:85]
	v_cvt_pk_bf16_f32 v81, v82, v83
	s_mov_b64 s[0:1], -1
	v_cvt_pk_bf16_f32 v82, v84, v85
	v_cvt_pk_bf16_f32 v83, v86, v87
	global_store_dwordx4 v[88:89], v[80:83], off
	v_or_b32_e32 v84, 48, v146
	v_ashrrev_i32_e32 v85, 31, v84
	v_bitop3_b32 v80, v146, s59, 48 bitop3:0xc8
	v_lshl_add_u32 v80, v80, 2, 0
	v_add_u32_e32 v80, 0x20000, v80
	ds_read_b32 v80, v80
	v_lshlrev_b64 v[82:83], 10, v[84:85]
	s_and_b64 vcc, exec, s[4:5]
	v_lshl_add_u64 v[82:83], s[16:17], 0, v[82:83]
	s_cbranch_vccnz .LBB0_789
	s_lshl_b32 s0, s51, 7
	s_ashr_i32 s1, s0, 31
	v_lshl_add_u64 v[86:87], s[0:1], 1, v[82:83]
	v_lshl_add_u64 v[86:87], v[136:137], 1, v[86:87]
	v_lshl_add_u64 v[86:87], v[86:87], 0, s[26:27]
	s_mov_b64 s[0:1], 0

.LBB0_791:
	s_waitcnt lgkmcnt(0)
	v_pk_mul_f32 v[72:73], v[80:81], v[72:73] op_sel_hi:[0,1]
	v_pk_mul_f32 v[74:75], v[80:81], v[74:75] op_sel_hi:[0,1]
	v_cvt_pk_bf16_f32 v72, v72, v73
	v_cvt_pk_bf16_f32 v73, v74, v75
	s_and_b64 vcc, exec, s[4:5]
	s_mov_b64 s[0:1], -1
	v_pk_mul_f32 v[78:79], v[80:81], v[78:79] op_sel_hi:[0,1]
	v_pk_mul_f32 v[76:77], v[80:81], v[76:77] op_sel_hi:[0,1]
	v_cvt_pk_bf16_f32 v74, v76, v77
	v_cvt_pk_bf16_f32 v75, v78, v79
	global_store_dwordx4 v[86:87], v[72:75], off
	s_cbranch_vccnz .LBB0_793
	s_lshl_b32 s0, s62, 6
	s_ashr_i32 s1, s0, 31
	v_lshl_add_u64 v[72:73], s[0:1], 1, v[82:83]
	v_lshl_add_u64 v[72:73], v[136:137], 1, v[72:73]
	v_lshl_add_u64 v[72:73], v[72:73], 0, s[26:27]
	s_mov_b64 s[0:1], 0

.LBB0_795:
	v_mov_b32_e32 v81, v80
	v_mov_b32_e32 v74, v80
	v_mov_b32_e32 v75, v80
	v_pk_mul_f32 v[66:67], v[74:75], v[66:67]
	v_pk_mul_f32 v[64:65], v[80:81], v[64:65]
	v_pk_mul_f32 v[68:69], v[80:81], v[68:69]
	v_cvt_pk_bf16_f32 v64, v64, v65
	v_cvt_pk_bf16_f32 v65, v66, v67
	v_pk_mul_f32 v[70:71], v[74:75], v[70:71]
	v_cvt_pk_bf16_f32 v66, v68, v69
	v_add_u32_e32 v68, 0x80, v146
	v_cvt_pk_bf16_f32 v67, v70, v71
	global_store_dwordx4 v[72:73], v[64:67], off
	v_ashrrev_i32_e32 v69, 31, v68
	s_mov_b64 s[0:1], -1
	v_and_b32_e32 v64, 0x7cf, v68
	v_lshl_add_u32 v64, v64, 2, 0
	v_add_u32_e32 v64, 0x20000, v64
	ds_read_b32 v64, v64
	v_lshlrev_b64 v[66:67], 10, v[68:69]
	s_and_b64 vcc, exec, s[4:5]
	v_lshl_add_u64 v[66:67], s[16:17], 0, v[66:67]
	s_cbranch_vccnz .LBB0_797
	s_lshl_b32 s0, s51, 7
	s_ashr_i32 s1, s0, 31
	v_lshl_add_u64 v[70:71], s[0:1], 1, v[66:67]
	v_lshl_add_u64 v[70:71], v[136:137], 1, v[70:71]
	v_lshl_add_u64 v[70:71], v[70:71], 0, s[26:27]
	s_mov_b64 s[0:1], 0

.LBB0_799:
	s_waitcnt lgkmcnt(0)
	v_pk_mul_f32 v[56:57], v[64:65], v[56:57] op_sel_hi:[0,1]
	v_pk_mul_f32 v[58:59], v[64:65], v[58:59] op_sel_hi:[0,1]
	v_cvt_pk_bf16_f32 v56, v56, v57
	v_cvt_pk_bf16_f32 v57, v58, v59
	s_and_b64 vcc, exec, s[4:5]
	s_mov_b64 s[0:1], -1
	v_pk_mul_f32 v[62:63], v[64:65], v[62:63] op_sel_hi:[0,1]
	v_pk_mul_f32 v[60:61], v[64:65], v[60:61] op_sel_hi:[0,1]
	v_cvt_pk_bf16_f32 v58, v60, v61
	v_cvt_pk_bf16_f32 v59, v62, v63
	global_store_dwordx4 v[70:71], v[56:59], off
	s_cbranch_vccnz .LBB0_801
	s_lshl_b32 s0, s62, 6
	s_ashr_i32 s1, s0, 31
	v_lshl_add_u64 v[56:57], s[0:1], 1, v[66:67]
	v_lshl_add_u64 v[56:57], v[136:137], 1, v[56:57]
	v_lshl_add_u64 v[56:57], v[56:57], 0, s[26:27]
	s_mov_b64 s[0:1], 0

.LBB0_803:
	v_mov_b32_e32 v65, v64
	v_mov_b32_e32 v58, v64
	v_mov_b32_e32 v59, v64
	v_pk_mul_f32 v[50:51], v[58:59], v[50:51]
	v_pk_mul_f32 v[48:49], v[64:65], v[48:49]
	v_pk_mul_f32 v[52:53], v[64:65], v[52:53]
	v_cvt_pk_bf16_f32 v48, v48, v49
	v_cvt_pk_bf16_f32 v49, v50, v51
	v_pk_mul_f32 v[54:55], v[58:59], v[54:55]
	v_cvt_pk_bf16_f32 v50, v52, v53
	v_add_u32_e32 v52, 0x90, v146
	v_cvt_pk_bf16_f32 v51, v54, v55
	global_store_dwordx4 v[56:57], v[48:51], off
	v_ashrrev_i32_e32 v53, 31, v52
	s_mov_b64 s[0:1], -1
	v_and_b32_e32 v48, 0x7df, v52
	v_lshl_add_u32 v48, v48, 2, 0
	v_add_u32_e32 v48, 0x20000, v48
	ds_read_b32 v48, v48
	v_lshlrev_b64 v[50:51], 10, v[52:53]
	s_and_b64 vcc, exec, s[4:5]
	v_lshl_add_u64 v[50:51], s[16:17], 0, v[50:51]
	s_cbranch_vccnz .LBB0_805
	s_lshl_b32 s0, s51, 7
	s_ashr_i32 s1, s0, 31
	v_lshl_add_u64 v[54:55], s[0:1], 1, v[50:51]
	v_lshl_add_u64 v[54:55], v[136:137], 1, v[54:55]
	v_lshl_add_u64 v[54:55], v[54:55], 0, s[26:27]
	s_mov_b64 s[0:1], 0

.LBB0_807:
	s_waitcnt lgkmcnt(0)
	v_pk_mul_f32 v[40:41], v[48:49], v[40:41] op_sel_hi:[0,1]
	v_pk_mul_f32 v[42:43], v[48:49], v[42:43] op_sel_hi:[0,1]
	v_cvt_pk_bf16_f32 v40, v40, v41
	v_cvt_pk_bf16_f32 v41, v42, v43
	s_and_b64 vcc, exec, s[4:5]
	s_mov_b64 s[0:1], -1
	v_pk_mul_f32 v[46:47], v[48:49], v[46:47] op_sel_hi:[0,1]
	v_pk_mul_f32 v[44:45], v[48:49], v[44:45] op_sel_hi:[0,1]
	v_cvt_pk_bf16_f32 v42, v44, v45
	v_cvt_pk_bf16_f32 v43, v46, v47
	global_store_dwordx4 v[54:55], v[40:43], off
	s_cbranch_vccnz .LBB0_809
	s_lshl_b32 s0, s62, 6
	s_ashr_i32 s1, s0, 31
	v_lshl_add_u64 v[40:41], s[0:1], 1, v[50:51]
	v_lshl_add_u64 v[40:41], v[136:137], 1, v[40:41]
	v_lshl_add_u64 v[40:41], v[40:41], 0, s[26:27]
	s_mov_b64 s[0:1], 0

.LBB0_811:
	v_mov_b32_e32 v49, v48
	v_mov_b32_e32 v42, v48
	v_mov_b32_e32 v43, v48
	v_pk_mul_f32 v[34:35], v[42:43], v[34:35]
	v_pk_mul_f32 v[32:33], v[48:49], v[32:33]
	v_pk_mul_f32 v[36:37], v[48:49], v[36:37]
	v_cvt_pk_bf16_f32 v32, v32, v33
	v_cvt_pk_bf16_f32 v33, v34, v35
	v_pk_mul_f32 v[38:39], v[42:43], v[38:39]
	v_cvt_pk_bf16_f32 v34, v36, v37
	v_add_u32_e32 v36, 0xa0, v146
	v_cvt_pk_bf16_f32 v35, v38, v39
	global_store_dwordx4 v[40:41], v[32:35], off
	v_ashrrev_i32_e32 v37, 31, v36
	s_mov_b64 s[0:1], -1
	v_and_b32_e32 v32, 0x7ef, v36
	v_lshl_add_u32 v32, v32, 2, 0
	v_add_u32_e32 v32, 0x20000, v32
	ds_read_b32 v32, v32
	v_lshlrev_b64 v[34:35], 10, v[36:37]
	s_and_b64 vcc, exec, s[4:5]
	v_lshl_add_u64 v[34:35], s[16:17], 0, v[34:35]
	s_cbranch_vccnz .LBB0_813
	s_lshl_b32 s0, s51, 7
	s_ashr_i32 s1, s0, 31
	v_lshl_add_u64 v[38:39], s[0:1], 1, v[34:35]
	v_lshl_add_u64 v[38:39], v[136:137], 1, v[38:39]
	v_lshl_add_u64 v[38:39], v[38:39], 0, s[26:27]
	s_mov_b64 s[0:1], 0

.LBB0_815:
	s_waitcnt lgkmcnt(0)
	v_pk_mul_f32 v[24:25], v[32:33], v[24:25] op_sel_hi:[0,1]
	v_pk_mul_f32 v[26:27], v[32:33], v[26:27] op_sel_hi:[0,1]
	v_cvt_pk_bf16_f32 v24, v24, v25
	v_cvt_pk_bf16_f32 v25, v26, v27
	s_and_b64 vcc, exec, s[4:5]
	s_mov_b64 s[0:1], -1
	v_pk_mul_f32 v[30:31], v[32:33], v[30:31] op_sel_hi:[0,1]
	v_pk_mul_f32 v[28:29], v[32:33], v[28:29] op_sel_hi:[0,1]
	v_cvt_pk_bf16_f32 v26, v28, v29
	v_cvt_pk_bf16_f32 v27, v30, v31
	global_store_dwordx4 v[38:39], v[24:27], off
	s_cbranch_vccnz .LBB0_817
	s_lshl_b32 s0, s62, 6
	s_ashr_i32 s1, s0, 31
	v_lshl_add_u64 v[24:25], s[0:1], 1, v[34:35]
	v_lshl_add_u64 v[24:25], v[136:137], 1, v[24:25]
	v_lshl_add_u64 v[24:25], v[24:25], 0, s[26:27]
	s_mov_b64 s[0:1], 0

.LBB0_819:
	v_mov_b32_e32 v33, v32
	v_mov_b32_e32 v26, v32
	v_mov_b32_e32 v27, v32
	v_pk_mul_f32 v[18:19], v[26:27], v[18:19]
	v_pk_mul_f32 v[16:17], v[32:33], v[16:17]
	v_pk_mul_f32 v[20:21], v[32:33], v[20:21]
	v_cvt_pk_bf16_f32 v16, v16, v17
	v_cvt_pk_bf16_f32 v17, v18, v19
	v_pk_mul_f32 v[22:23], v[26:27], v[22:23]
	v_cvt_pk_bf16_f32 v18, v20, v21
	v_add_u32_e32 v20, 0xb0, v146
	v_cvt_pk_bf16_f32 v19, v22, v23
	global_store_dwordx4 v[24:25], v[16:19], off
	v_ashrrev_i32_e32 v21, 31, v20
	s_mov_b64 s[0:1], -1
	v_and_b32_e32 v16, 0x7ff, v20
	v_lshl_add_u32 v16, v16, 2, 0
	v_add_u32_e32 v16, 0x20000, v16
	ds_read_b32 v16, v16
	v_lshlrev_b64 v[18:19], 10, v[20:21]
	s_and_b64 vcc, exec, s[4:5]
	v_lshl_add_u64 v[18:19], s[16:17], 0, v[18:19]
	s_cbranch_vccnz .LBB0_821
	s_lshl_b32 s0, s51, 7
	s_ashr_i32 s1, s0, 31
	v_lshl_add_u64 v[22:23], s[0:1], 1, v[18:19]
	v_lshl_add_u64 v[22:23], v[136:137], 1, v[22:23]
	v_lshl_add_u64 v[22:23], v[22:23], 0, s[26:27]
	s_mov_b64 s[0:1], 0

.LBB0_823:
	s_waitcnt lgkmcnt(0)
	v_pk_mul_f32 v[8:9], v[16:17], v[8:9] op_sel_hi:[0,1]
	v_pk_mul_f32 v[10:11], v[16:17], v[10:11] op_sel_hi:[0,1]
	v_cvt_pk_bf16_f32 v8, v8, v9
	v_cvt_pk_bf16_f32 v9, v10, v11
	s_and_b64 vcc, exec, s[4:5]
	s_mov_b64 s[0:1], -1
	v_pk_mul_f32 v[14:15], v[16:17], v[14:15] op_sel_hi:[0,1]
	v_pk_mul_f32 v[12:13], v[16:17], v[12:13] op_sel_hi:[0,1]
	v_cvt_pk_bf16_f32 v10, v12, v13
	v_cvt_pk_bf16_f32 v11, v14, v15
	global_store_dwordx4 v[22:23], v[8:11], off
	s_cbranch_vccnz .LBB0_825
	s_lshl_b32 s0, s62, 6
	s_ashr_i32 s1, s0, 31
	v_lshl_add_u64 v[8:9], s[0:1], 1, v[18:19]
	v_lshl_add_u64 v[8:9], v[136:137], 1, v[8:9]
	v_lshl_add_u64 v[8:9], v[8:9], 0, s[26:27]
	s_mov_b64 s[0:1], 0

.LBB0_827:
	v_mov_b32_e32 v17, v16
	v_mov_b32_e32 v10, v16
	v_mov_b32_e32 v11, v16
	v_pk_mul_f32 v[2:3], v[10:11], v[2:3]
	v_pk_mul_f32 v[0:1], v[16:17], v[0:1]
	v_pk_mul_f32 v[6:7], v[10:11], v[6:7]
	v_pk_mul_f32 v[4:5], v[16:17], v[4:5]
	v_cvt_pk_bf16_f32 v0, v0, v1
	v_cvt_pk_bf16_f32 v1, v2, v3
	s_and_b64 vcc, exec, s[2:3]
	v_cvt_pk_bf16_f32 v2, v4, v5
	v_cvt_pk_bf16_f32 v3, v6, v7
	global_store_dwordx4 v[8:9], v[0:3], off
	s_mov_b64 s[0:1], -1
	s_cbranch_vccnz .LBB0_747
	s_andn2_b64 vcc, exec, s[12:13]
	v_pk_mov_b32 v[120:121], 0, 0
	v_pk_mov_b32 v[122:123], 0, 0
	v_pk_mov_b32 v[124:125], 0, 0
	v_pk_mov_b32 v[126:127], 0, 0
	v_pk_mov_b32 v[104:105], 0, 0
	v_pk_mov_b32 v[106:107], 0, 0
	v_pk_mov_b32 v[108:109], 0, 0
	v_pk_mov_b32 v[110:111], 0, 0
	v_pk_mov_b32 v[88:89], 0, 0
	v_pk_mov_b32 v[90:91], 0, 0
	v_pk_mov_b32 v[92:93], 0, 0
	v_pk_mov_b32 v[94:95], 0, 0
	v_pk_mov_b32 v[72:73], 0, 0
	v_pk_mov_b32 v[74:75], 0, 0
	v_pk_mov_b32 v[76:77], 0, 0
	v_pk_mov_b32 v[78:79], 0, 0
	v_pk_mov_b32 v[112:113], 0, 0
	v_pk_mov_b32 v[114:115], 0, 0
	v_pk_mov_b32 v[116:117], 0, 0
	v_pk_mov_b32 v[118:119], 0, 0
	v_pk_mov_b32 v[96:97], 0, 0
	v_pk_mov_b32 v[98:99], 0, 0
	v_pk_mov_b32 v[100:101], 0, 0
	v_pk_mov_b32 v[102:103], 0, 0
	v_pk_mov_b32 v[80:81], 0, 0
	v_pk_mov_b32 v[82:83], 0, 0
	v_pk_mov_b32 v[84:85], 0, 0
	v_pk_mov_b32 v[86:87], 0, 0
	v_pk_mov_b32 v[64:65], 0, 0
	v_pk_mov_b32 v[66:67], 0, 0
	v_pk_mov_b32 v[68:69], 0, 0
	v_pk_mov_b32 v[70:71], 0, 0
	v_pk_mov_b32 v[56:57], 0, 0
	v_pk_mov_b32 v[58:59], 0, 0
	v_pk_mov_b32 v[60:61], 0, 0
	v_pk_mov_b32 v[62:63], 0, 0
	v_pk_mov_b32 v[40:41], 0, 0
	v_pk_mov_b32 v[42:43], 0, 0
	v_pk_mov_b32 v[44:45], 0, 0
	v_pk_mov_b32 v[46:47], 0, 0
	v_pk_mov_b32 v[24:25], 0, 0
	v_pk_mov_b32 v[26:27], 0, 0
	v_pk_mov_b32 v[28:29], 0, 0
	v_pk_mov_b32 v[30:31], 0, 0
	v_pk_mov_b32 v[8:9], 0, 0
	v_pk_mov_b32 v[10:11], 0, 0
	v_pk_mov_b32 v[12:13], 0, 0
	v_pk_mov_b32 v[14:15], 0, 0
	v_pk_mov_b32 v[48:49], 0, 0
	v_pk_mov_b32 v[50:51], 0, 0
	v_pk_mov_b32 v[52:53], 0, 0
	v_pk_mov_b32 v[54:55], 0, 0
	v_pk_mov_b32 v[32:33], 0, 0
	v_pk_mov_b32 v[34:35], 0, 0
	v_pk_mov_b32 v[36:37], 0, 0
	v_pk_mov_b32 v[38:39], 0, 0
	v_pk_mov_b32 v[16:17], 0, 0
	v_pk_mov_b32 v[18:19], 0, 0
	v_pk_mov_b32 v[20:21], 0, 0
	v_pk_mov_b32 v[22:23], 0, 0
	v_pk_mov_b32 v[0:1], 0, 0
	v_pk_mov_b32 v[2:3], 0, 0
	v_pk_mov_b32 v[4:5], 0, 0
	v_pk_mov_b32 v[6:7], 0, 0
	s_cbranch_vccnz .LBB0_746
	s_barrier
	s_branch .LBB0_746

.LBB0_995:
	v_lshl_add_u32 v148, s55, 8, v152
	v_ashrrev_i32_e32 v149, 31, v148
	s_waitcnt lgkmcnt(0)
	v_lshl_add_u64 v[144:145], v[148:149], 2, s[6:7]
	global_load_dwordx4 v[154:157], v[144:145], off
	global_load_dwordx4 v[158:161], v[144:145], off offset:16
	v_lshl_add_u32 v146, s30, 8, v150
	v_and_b32_e32 v162, 0x7cf, v146
	v_lshl_add_u32 v162, v162, 2, s50
	ds_read_b32 v164, v162
	v_ashrrev_i32_e32 v147, 31, v146
	v_lshlrev_b64 v[162:163], 12, v[146:147]
	v_lshlrev_b64 v[148:149], 1, v[148:149]
	v_lshl_add_u64 v[162:163], s[14:15], 0, v[162:163]
	s_waitcnt lgkmcnt(0)
	v_mul_f32_e32 v164, 0xbfb8aa3b, v164
	v_lshl_add_u64 v[162:163], v[162:163], 0, v[148:149]
	s_and_b64 vcc, exec, s[2:3]
	s_mov_b64 s[0:1], -1
	s_waitcnt vmcnt(0)
	v_pk_mul_f32 v[156:157], v[156:157], s[22:23] op_sel_hi:[1,0]
	v_pk_mul_f32 v[154:155], v[154:155], s[22:23] op_sel_hi:[1,0]
	v_pk_mul_f32 v[160:161], v[160:161], s[22:23] op_sel_hi:[1,0]
	v_pk_mul_f32 v[158:159], v[158:159], s[22:23] op_sel_hi:[1,0]
	v_pk_fma_f32 v[122:123], v[164:165], v[122:123], v[156:157] op_sel_hi:[0,1,1] neg_lo:[0,0,1] neg_hi:[0,0,1]
	v_pk_fma_f32 v[120:121], v[164:165], v[120:121], v[154:155] op_sel_hi:[0,1,1] neg_lo:[0,0,1] neg_hi:[0,0,1]
	v_pk_fma_f32 v[126:127], v[164:165], v[126:127], v[160:161] op_sel_hi:[0,1,1] neg_lo:[0,0,1] neg_hi:[0,0,1]
	v_pk_fma_f32 v[124:125], v[164:165], v[124:125], v[158:159] op_sel_hi:[0,1,1] neg_lo:[0,0,1] neg_hi:[0,0,1]
	v_exp_f32_e32 v120, v120
	v_exp_f32_e32 v121, v121
	v_exp_f32_e32 v122, v122
	v_exp_f32_e32 v123, v123
	v_exp_f32_e32 v124, v124
	v_exp_f32_e32 v126, v126
	v_exp_f32_e32 v127, v127
	v_exp_f32_e32 v125, v125
	v_pk_add_f32 v[122:123], v[122:123], 1.0 op_sel_hi:[1,0]
	v_pk_add_f32 v[120:121], v[120:121], 1.0 op_sel_hi:[1,0]
	v_pk_add_f32 v[126:127], v[126:127], 1.0 op_sel_hi:[1,0]
	v_pk_add_f32 v[124:125], v[124:125], 1.0 op_sel_hi:[1,0]
	v_rcp_f32_e32 v120, v120
	v_rcp_f32_e32 v121, v121
	v_rcp_f32_e32 v122, v122
	v_rcp_f32_e32 v123, v123
	v_rcp_f32_e32 v124, v124
	v_rcp_f32_e32 v125, v125
	v_rcp_f32_e32 v126, v126
	v_rcp_f32_e32 v127, v127
	v_cvt_pk_bf16_f32 v120, v120, v121
	v_cvt_pk_bf16_f32 v121, v122, v123
	v_cvt_pk_bf16_f32 v122, v124, v125
	v_cvt_pk_bf16_f32 v123, v126, v127
	global_store_dwordx4 v[162:163], v[120:123], off
	global_load_dwordx4 v[120:123], v[144:145], off offset:512
	s_nop 0
	global_load_dwordx4 v[124:127], v[144:145], off offset:528
	s_waitcnt vmcnt(0)
	v_pk_mul_f32 v[122:123], v[122:123], s[22:23] op_sel_hi:[1,0]
	v_pk_mul_f32 v[120:121], v[120:121], s[22:23] op_sel_hi:[1,0]
	v_pk_mul_f32 v[126:127], v[126:127], s[22:23] op_sel_hi:[1,0]
	v_pk_mul_f32 v[124:125], v[124:125], s[22:23] op_sel_hi:[1,0]
	v_pk_fma_f32 v[114:115], v[164:165], v[114:115], v[122:123] op_sel_hi:[0,1,1] neg_lo:[0,0,1] neg_hi:[0,0,1]
	v_pk_fma_f32 v[112:113], v[164:165], v[112:113], v[120:121] op_sel_hi:[0,1,1] neg_lo:[0,0,1] neg_hi:[0,0,1]
	v_pk_fma_f32 v[118:119], v[164:165], v[118:119], v[126:127] op_sel_hi:[0,1,1] neg_lo:[0,0,1] neg_hi:[0,0,1]
	v_pk_fma_f32 v[116:117], v[164:165], v[116:117], v[124:125] op_sel_hi:[0,1,1] neg_lo:[0,0,1] neg_hi:[0,0,1]
	v_exp_f32_e32 v112, v112
	v_exp_f32_e32 v113, v113
	v_exp_f32_e32 v114, v114
	v_exp_f32_e32 v115, v115
	v_exp_f32_e32 v116, v116
	v_exp_f32_e32 v118, v118
	v_exp_f32_e32 v119, v119
	v_exp_f32_e32 v117, v117
	v_pk_add_f32 v[114:115], v[114:115], 1.0 op_sel_hi:[1,0]
	v_pk_add_f32 v[112:113], v[112:113], 1.0 op_sel_hi:[1,0]
	v_pk_add_f32 v[118:119], v[118:119], 1.0 op_sel_hi:[1,0]
	v_pk_add_f32 v[116:117], v[116:117], 1.0 op_sel_hi:[1,0]
	v_rcp_f32_e32 v112, v112
	v_rcp_f32_e32 v113, v113
	v_rcp_f32_e32 v114, v114
	v_rcp_f32_e32 v115, v115
	v_rcp_f32_e32 v116, v116
	v_rcp_f32_e32 v117, v117
	v_rcp_f32_e32 v118, v118
	v_rcp_f32_e32 v119, v119
	v_cvt_pk_bf16_f32 v112, v112, v113
	v_cvt_pk_bf16_f32 v113, v114, v115
	v_cvt_pk_bf16_f32 v114, v116, v117
	v_cvt_pk_bf16_f32 v115, v118, v119
	global_store_dwordx4 v[162:163], v[112:115], off offset:256
	global_load_dwordx4 v[112:115], v[144:145], off
	s_nop 0
	global_load_dwordx4 v[116:119], v[144:145], off offset:16
	v_bitop3_b32 v121, v146, s51, 16 bitop3:0xc8
	v_lshl_add_u32 v121, v121, 2, s50
	ds_read_b32 v122, v121
	v_or_b32_e32 v120, 16, v146
	v_ashrrev_i32_e32 v121, 31, v120
	v_lshlrev_b64 v[120:121], 12, v[120:121]
	v_lshl_add_u64 v[120:121], s[14:15], 0, v[120:121]
	s_waitcnt lgkmcnt(0)
	v_mul_f32_e32 v122, 0xbfb8aa3b, v122
	v_lshl_add_u64 v[120:121], v[120:121], 0, v[148:149]
	s_waitcnt vmcnt(0)
	v_pk_mul_f32 v[114:115], v[114:115], s[22:23] op_sel_hi:[1,0]
	v_pk_mul_f32 v[112:113], v[112:113], s[22:23] op_sel_hi:[1,0]
	v_pk_mul_f32 v[118:119], v[118:119], s[22:23] op_sel_hi:[1,0]
	v_pk_mul_f32 v[116:117], v[116:117], s[22:23] op_sel_hi:[1,0]
	v_pk_fma_f32 v[106:107], v[122:123], v[106:107], v[114:115] op_sel_hi:[0,1,1] neg_lo:[0,0,1] neg_hi:[0,0,1]
	v_pk_fma_f32 v[104:105], v[122:123], v[104:105], v[112:113] op_sel_hi:[0,1,1] neg_lo:[0,0,1] neg_hi:[0,0,1]
	v_pk_fma_f32 v[110:111], v[122:123], v[110:111], v[118:119] op_sel_hi:[0,1,1] neg_lo:[0,0,1] neg_hi:[0,0,1]
	v_pk_fma_f32 v[108:109], v[122:123], v[108:109], v[116:117] op_sel_hi:[0,1,1] neg_lo:[0,0,1] neg_hi:[0,0,1]
	v_exp_f32_e32 v104, v104
	v_exp_f32_e32 v105, v105
	v_exp_f32_e32 v106, v106
	v_exp_f32_e32 v107, v107
	v_exp_f32_e32 v108, v108
	v_exp_f32_e32 v110, v110
	v_exp_f32_e32 v111, v111
	v_exp_f32_e32 v109, v109
	v_pk_add_f32 v[106:107], v[106:107], 1.0 op_sel_hi:[1,0]
	v_pk_add_f32 v[104:105], v[104:105], 1.0 op_sel_hi:[1,0]
	v_pk_add_f32 v[110:111], v[110:111], 1.0 op_sel_hi:[1,0]
	v_pk_add_f32 v[108:109], v[108:109], 1.0 op_sel_hi:[1,0]
	v_rcp_f32_e32 v104, v104
	v_rcp_f32_e32 v105, v105
	v_rcp_f32_e32 v106, v106
	v_rcp_f32_e32 v107, v107
	v_rcp_f32_e32 v108, v108
	v_rcp_f32_e32 v109, v109
	v_rcp_f32_e32 v110, v110
	v_rcp_f32_e32 v111, v111
	v_cvt_pk_bf16_f32 v104, v104, v105
	v_cvt_pk_bf16_f32 v105, v106, v107
	v_cvt_pk_bf16_f32 v106, v108, v109
	v_cvt_pk_bf16_f32 v107, v110, v111
	global_store_dwordx4 v[120:121], v[104:107], off
	global_load_dwordx4 v[104:107], v[144:145], off offset:512
	s_nop 0
	global_load_dwordx4 v[108:111], v[144:145], off offset:528
	s_waitcnt vmcnt(0)
	v_pk_mul_f32 v[106:107], v[106:107], s[22:23] op_sel_hi:[1,0]
	v_pk_mul_f32 v[104:105], v[104:105], s[22:23] op_sel_hi:[1,0]
	v_pk_mul_f32 v[110:111], v[110:111], s[22:23] op_sel_hi:[1,0]
	v_pk_mul_f32 v[108:109], v[108:109], s[22:23] op_sel_hi:[1,0]
	v_pk_fma_f32 v[98:99], v[122:123], v[98:99], v[106:107] op_sel_hi:[0,1,1] neg_lo:[0,0,1] neg_hi:[0,0,1]
	v_pk_fma_f32 v[96:97], v[122:123], v[96:97], v[104:105] op_sel_hi:[0,1,1] neg_lo:[0,0,1] neg_hi:[0,0,1]
	v_pk_fma_f32 v[102:103], v[122:123], v[102:103], v[110:111] op_sel_hi:[0,1,1] neg_lo:[0,0,1] neg_hi:[0,0,1]
	v_pk_fma_f32 v[100:101], v[122:123], v[100:101], v[108:109] op_sel_hi:[0,1,1] neg_lo:[0,0,1] neg_hi:[0,0,1]
	v_exp_f32_e32 v96, v96
	v_exp_f32_e32 v97, v97
	v_exp_f32_e32 v98, v98
	v_exp_f32_e32 v99, v99
	v_exp_f32_e32 v100, v100
	v_exp_f32_e32 v102, v102
	v_exp_f32_e32 v103, v103
	v_exp_f32_e32 v101, v101
	v_pk_add_f32 v[98:99], v[98:99], 1.0 op_sel_hi:[1,0]
	v_pk_add_f32 v[96:97], v[96:97], 1.0 op_sel_hi:[1,0]
	v_pk_add_f32 v[102:103], v[102:103], 1.0 op_sel_hi:[1,0]
	v_pk_add_f32 v[100:101], v[100:101], 1.0 op_sel_hi:[1,0]
	v_rcp_f32_e32 v96, v96
	v_rcp_f32_e32 v97, v97
	v_rcp_f32_e32 v98, v98
	v_rcp_f32_e32 v99, v99
	v_rcp_f32_e32 v100, v100
	v_rcp_f32_e32 v101, v101
	v_rcp_f32_e32 v102, v102
	v_rcp_f32_e32 v103, v103
	v_cvt_pk_bf16_f32 v96, v96, v97
	v_cvt_pk_bf16_f32 v97, v98, v99
	v_cvt_pk_bf16_f32 v98, v100, v101
	v_cvt_pk_bf16_f32 v99, v102, v103
	global_store_dwordx4 v[120:121], v[96:99], off offset:256
	global_load_dwordx4 v[96:99], v[144:145], off
	s_nop 0
	global_load_dwordx4 v[100:103], v[144:145], off offset:16
	v_bitop3_b32 v105, v146, s52, 32 bitop3:0xc8
	v_lshl_add_u32 v105, v105, 2, s50
	ds_read_b32 v106, v105
	v_or_b32_e32 v104, 32, v146
	v_ashrrev_i32_e32 v105, 31, v104
	v_lshlrev_b64 v[104:105], 12, v[104:105]
	v_lshl_add_u64 v[104:105], s[14:15], 0, v[104:105]
	s_waitcnt lgkmcnt(0)
	v_mul_f32_e32 v106, 0xbfb8aa3b, v106
	v_lshl_add_u64 v[104:105], v[104:105], 0, v[148:149]
	s_waitcnt vmcnt(0)
	v_pk_mul_f32 v[98:99], v[98:99], s[22:23] op_sel_hi:[1,0]
	v_pk_mul_f32 v[96:97], v[96:97], s[22:23] op_sel_hi:[1,0]
	v_pk_mul_f32 v[102:103], v[102:103], s[22:23] op_sel_hi:[1,0]
	v_pk_mul_f32 v[100:101], v[100:101], s[22:23] op_sel_hi:[1,0]
	v_pk_fma_f32 v[90:91], v[106:107], v[90:91], v[98:99] op_sel_hi:[0,1,1] neg_lo:[0,0,1] neg_hi:[0,0,1]
	v_pk_fma_f32 v[88:89], v[106:107], v[88:89], v[96:97] op_sel_hi:[0,1,1] neg_lo:[0,0,1] neg_hi:[0,0,1]
	v_pk_fma_f32 v[94:95], v[106:107], v[94:95], v[102:103] op_sel_hi:[0,1,1] neg_lo:[0,0,1] neg_hi:[0,0,1]
	v_pk_fma_f32 v[92:93], v[106:107], v[92:93], v[100:101] op_sel_hi:[0,1,1] neg_lo:[0,0,1] neg_hi:[0,0,1]
	v_exp_f32_e32 v88, v88
	v_exp_f32_e32 v89, v89
	v_exp_f32_e32 v90, v90
	v_exp_f32_e32 v91, v91
	v_exp_f32_e32 v92, v92
	v_exp_f32_e32 v94, v94
	v_exp_f32_e32 v95, v95
	v_exp_f32_e32 v93, v93
	v_pk_add_f32 v[90:91], v[90:91], 1.0 op_sel_hi:[1,0]
	v_pk_add_f32 v[88:89], v[88:89], 1.0 op_sel_hi:[1,0]
	v_pk_add_f32 v[94:95], v[94:95], 1.0 op_sel_hi:[1,0]
	v_pk_add_f32 v[92:93], v[92:93], 1.0 op_sel_hi:[1,0]
	v_rcp_f32_e32 v88, v88
	v_rcp_f32_e32 v89, v89
	v_rcp_f32_e32 v90, v90
	v_rcp_f32_e32 v91, v91
	v_rcp_f32_e32 v92, v92
	v_rcp_f32_e32 v93, v93
	v_rcp_f32_e32 v94, v94
	v_rcp_f32_e32 v95, v95
	v_cvt_pk_bf16_f32 v88, v88, v89
	v_cvt_pk_bf16_f32 v89, v90, v91
	v_cvt_pk_bf16_f32 v90, v92, v93
	v_cvt_pk_bf16_f32 v91, v94, v95
	global_store_dwordx4 v[104:105], v[88:91], off
	global_load_dwordx4 v[88:91], v[144:145], off offset:512
	s_nop 0
	global_load_dwordx4 v[92:95], v[144:145], off offset:528
	s_waitcnt vmcnt(0)
	v_pk_mul_f32 v[90:91], v[90:91], s[22:23] op_sel_hi:[1,0]
	v_pk_mul_f32 v[88:89], v[88:89], s[22:23] op_sel_hi:[1,0]
	v_pk_mul_f32 v[94:95], v[94:95], s[22:23] op_sel_hi:[1,0]
	v_pk_mul_f32 v[92:93], v[92:93], s[22:23] op_sel_hi:[1,0]
	v_pk_fma_f32 v[82:83], v[106:107], v[82:83], v[90:91] op_sel_hi:[0,1,1] neg_lo:[0,0,1] neg_hi:[0,0,1]
	v_pk_fma_f32 v[80:81], v[106:107], v[80:81], v[88:89] op_sel_hi:[0,1,1] neg_lo:[0,0,1] neg_hi:[0,0,1]
	v_pk_fma_f32 v[86:87], v[106:107], v[86:87], v[94:95] op_sel_hi:[0,1,1] neg_lo:[0,0,1] neg_hi:[0,0,1]
	v_pk_fma_f32 v[84:85], v[106:107], v[84:85], v[92:93] op_sel_hi:[0,1,1] neg_lo:[0,0,1] neg_hi:[0,0,1]
	v_exp_f32_e32 v80, v80
	v_exp_f32_e32 v81, v81
	v_exp_f32_e32 v82, v82
	v_exp_f32_e32 v83, v83
	v_exp_f32_e32 v84, v84
	v_exp_f32_e32 v86, v86
	v_exp_f32_e32 v87, v87
	v_exp_f32_e32 v85, v85
	v_pk_add_f32 v[82:83], v[82:83], 1.0 op_sel_hi:[1,0]
	v_pk_add_f32 v[80:81], v[80:81], 1.0 op_sel_hi:[1,0]
	v_pk_add_f32 v[86:87], v[86:87], 1.0 op_sel_hi:[1,0]
	v_pk_add_f32 v[84:85], v[84:85], 1.0 op_sel_hi:[1,0]
	v_rcp_f32_e32 v80, v80
	v_rcp_f32_e32 v81, v81
	v_rcp_f32_e32 v82, v82
	v_rcp_f32_e32 v83, v83
	v_rcp_f32_e32 v84, v84
	v_rcp_f32_e32 v85, v85
	v_rcp_f32_e32 v86, v86
	v_rcp_f32_e32 v87, v87
	v_cvt_pk_bf16_f32 v80, v80, v81
	v_cvt_pk_bf16_f32 v81, v82, v83
	v_cvt_pk_bf16_f32 v82, v84, v85
	v_cvt_pk_bf16_f32 v83, v86, v87
	global_store_dwordx4 v[104:105], v[80:83], off offset:256
	global_load_dwordx4 v[80:83], v[144:145], off
	s_nop 0
	global_load_dwordx4 v[84:87], v[144:145], off offset:16
	v_bitop3_b32 v89, v146, s53, 48 bitop3:0xc8
	v_lshl_add_u32 v89, v89, 2, s50
	ds_read_b32 v90, v89
	v_or_b32_e32 v88, 48, v146
	v_ashrrev_i32_e32 v89, 31, v88
	v_lshlrev_b64 v[88:89], 12, v[88:89]
	v_lshl_add_u64 v[88:89], s[14:15], 0, v[88:89]
	s_waitcnt lgkmcnt(0)
	v_mul_f32_e32 v90, 0xbfb8aa3b, v90
	v_lshl_add_u64 v[88:89], v[88:89], 0, v[148:149]
	s_waitcnt vmcnt(0)
	v_pk_mul_f32 v[82:83], v[82:83], s[22:23] op_sel_hi:[1,0]
	v_pk_mul_f32 v[80:81], v[80:81], s[22:23] op_sel_hi:[1,0]
	v_pk_mul_f32 v[86:87], v[86:87], s[22:23] op_sel_hi:[1,0]
	v_pk_mul_f32 v[84:85], v[84:85], s[22:23] op_sel_hi:[1,0]
	v_pk_fma_f32 v[74:75], v[90:91], v[74:75], v[82:83] op_sel_hi:[0,1,1] neg_lo:[0,0,1] neg_hi:[0,0,1]
	v_pk_fma_f32 v[72:73], v[90:91], v[72:73], v[80:81] op_sel_hi:[0,1,1] neg_lo:[0,0,1] neg_hi:[0,0,1]
	v_pk_fma_f32 v[78:79], v[90:91], v[78:79], v[86:87] op_sel_hi:[0,1,1] neg_lo:[0,0,1] neg_hi:[0,0,1]
	v_pk_fma_f32 v[76:77], v[90:91], v[76:77], v[84:85] op_sel_hi:[0,1,1] neg_lo:[0,0,1] neg_hi:[0,0,1]
	v_exp_f32_e32 v72, v72
	v_exp_f32_e32 v73, v73
	v_exp_f32_e32 v74, v74
	v_exp_f32_e32 v75, v75
	v_exp_f32_e32 v76, v76
	v_exp_f32_e32 v78, v78
	v_exp_f32_e32 v79, v79
	v_exp_f32_e32 v77, v77
	v_pk_add_f32 v[74:75], v[74:75], 1.0 op_sel_hi:[1,0]
	v_pk_add_f32 v[72:73], v[72:73], 1.0 op_sel_hi:[1,0]
	v_pk_add_f32 v[78:79], v[78:79], 1.0 op_sel_hi:[1,0]
	v_pk_add_f32 v[76:77], v[76:77], 1.0 op_sel_hi:[1,0]
	v_rcp_f32_e32 v72, v72
	v_rcp_f32_e32 v73, v73
	v_rcp_f32_e32 v74, v74
	v_rcp_f32_e32 v75, v75
	v_rcp_f32_e32 v76, v76
	v_rcp_f32_e32 v77, v77
	v_rcp_f32_e32 v78, v78
	v_rcp_f32_e32 v79, v79
	v_cvt_pk_bf16_f32 v72, v72, v73
	v_cvt_pk_bf16_f32 v73, v74, v75
	v_cvt_pk_bf16_f32 v74, v76, v77
	v_cvt_pk_bf16_f32 v75, v78, v79
	global_store_dwordx4 v[88:89], v[72:75], off
	global_load_dwordx4 v[72:75], v[144:145], off offset:512
	s_nop 0
	global_load_dwordx4 v[76:79], v[144:145], off offset:528
	s_waitcnt vmcnt(0)
	v_pk_mul_f32 v[74:75], v[74:75], s[22:23] op_sel_hi:[1,0]
	v_pk_mul_f32 v[72:73], v[72:73], s[22:23] op_sel_hi:[1,0]
	v_pk_mul_f32 v[78:79], v[78:79], s[22:23] op_sel_hi:[1,0]
	v_pk_mul_f32 v[76:77], v[76:77], s[22:23] op_sel_hi:[1,0]
	v_pk_fma_f32 v[66:67], v[90:91], v[66:67], v[74:75] op_sel_hi:[0,1,1] neg_lo:[0,0,1] neg_hi:[0,0,1]
	v_pk_fma_f32 v[64:65], v[90:91], v[64:65], v[72:73] op_sel_hi:[0,1,1] neg_lo:[0,0,1] neg_hi:[0,0,1]
	v_pk_fma_f32 v[70:71], v[90:91], v[70:71], v[78:79] op_sel_hi:[0,1,1] neg_lo:[0,0,1] neg_hi:[0,0,1]
	v_pk_fma_f32 v[68:69], v[90:91], v[68:69], v[76:77] op_sel_hi:[0,1,1] neg_lo:[0,0,1] neg_hi:[0,0,1]
	v_exp_f32_e32 v64, v64
	v_exp_f32_e32 v65, v65
	v_exp_f32_e32 v66, v66
	v_exp_f32_e32 v67, v67
	v_exp_f32_e32 v68, v68
	v_exp_f32_e32 v70, v70
	v_exp_f32_e32 v71, v71
	v_exp_f32_e32 v69, v69
	v_pk_add_f32 v[66:67], v[66:67], 1.0 op_sel_hi:[1,0]
	v_pk_add_f32 v[64:65], v[64:65], 1.0 op_sel_hi:[1,0]
	v_pk_add_f32 v[70:71], v[70:71], 1.0 op_sel_hi:[1,0]
	v_pk_add_f32 v[68:69], v[68:69], 1.0 op_sel_hi:[1,0]
	v_rcp_f32_e32 v64, v64
	v_rcp_f32_e32 v65, v65
	v_rcp_f32_e32 v66, v66
	v_rcp_f32_e32 v67, v67
	v_rcp_f32_e32 v68, v68
	v_rcp_f32_e32 v69, v69
	v_rcp_f32_e32 v70, v70
	v_rcp_f32_e32 v71, v71
	v_cvt_pk_bf16_f32 v64, v64, v65
	v_cvt_pk_bf16_f32 v65, v66, v67
	v_cvt_pk_bf16_f32 v66, v68, v69
	v_cvt_pk_bf16_f32 v67, v70, v71
	global_store_dwordx4 v[88:89], v[64:67], off offset:256
	global_load_dwordx4 v[64:67], v[144:145], off
	s_nop 0
	global_load_dwordx4 v[68:71], v[144:145], off offset:16
	v_add_u32_e32 v72, 0x80, v146
	v_and_b32_e32 v73, 0x7cf, v72
	v_lshl_add_u32 v73, v73, 2, s50
	ds_read_b32 v74, v73
	v_ashrrev_i32_e32 v73, 31, v72
	v_lshlrev_b64 v[72:73], 12, v[72:73]
	v_lshl_add_u64 v[72:73], s[14:15], 0, v[72:73]
	v_lshl_add_u64 v[72:73], v[72:73], 0, v[148:149]
	s_waitcnt lgkmcnt(0)
	v_mul_f32_e32 v74, 0xbfb8aa3b, v74
	s_waitcnt vmcnt(0)
	v_pk_mul_f32 v[66:67], v[66:67], s[22:23] op_sel_hi:[1,0]
	v_pk_mul_f32 v[64:65], v[64:65], s[22:23] op_sel_hi:[1,0]
	v_pk_mul_f32 v[70:71], v[70:71], s[22:23] op_sel_hi:[1,0]
	v_pk_mul_f32 v[68:69], v[68:69], s[22:23] op_sel_hi:[1,0]
	v_pk_fma_f32 v[58:59], v[74:75], v[58:59], v[66:67] op_sel_hi:[0,1,1] neg_lo:[0,0,1] neg_hi:[0,0,1]
	v_pk_fma_f32 v[56:57], v[74:75], v[56:57], v[64:65] op_sel_hi:[0,1,1] neg_lo:[0,0,1] neg_hi:[0,0,1]
	v_pk_fma_f32 v[62:63], v[74:75], v[62:63], v[70:71] op_sel_hi:[0,1,1] neg_lo:[0,0,1] neg_hi:[0,0,1]
	v_pk_fma_f32 v[60:61], v[74:75], v[60:61], v[68:69] op_sel_hi:[0,1,1] neg_lo:[0,0,1] neg_hi:[0,0,1]
	v_exp_f32_e32 v56, v56
	v_exp_f32_e32 v57, v57
	v_exp_f32_e32 v58, v58
	v_exp_f32_e32 v59, v59
	v_exp_f32_e32 v60, v60
	v_exp_f32_e32 v62, v62
	v_exp_f32_e32 v63, v63
	v_exp_f32_e32 v61, v61
	v_pk_add_f32 v[58:59], v[58:59], 1.0 op_sel_hi:[1,0]
	v_pk_add_f32 v[56:57], v[56:57], 1.0 op_sel_hi:[1,0]
	v_pk_add_f32 v[62:63], v[62:63], 1.0 op_sel_hi:[1,0]
	v_pk_add_f32 v[60:61], v[60:61], 1.0 op_sel_hi:[1,0]
	v_rcp_f32_e32 v56, v56
	v_rcp_f32_e32 v57, v57
	v_rcp_f32_e32 v58, v58
	v_rcp_f32_e32 v59, v59
	v_rcp_f32_e32 v60, v60
	v_rcp_f32_e32 v61, v61
	v_rcp_f32_e32 v62, v62
	v_rcp_f32_e32 v63, v63
	v_cvt_pk_bf16_f32 v56, v56, v57
	v_cvt_pk_bf16_f32 v57, v58, v59
	v_cvt_pk_bf16_f32 v58, v60, v61
	v_cvt_pk_bf16_f32 v59, v62, v63
	global_store_dwordx4 v[72:73], v[56:59], off
	global_load_dwordx4 v[56:59], v[144:145], off offset:512
	s_nop 0
	global_load_dwordx4 v[60:63], v[144:145], off offset:528
	s_waitcnt vmcnt(0)
	v_pk_mul_f32 v[58:59], v[58:59], s[22:23] op_sel_hi:[1,0]
	v_pk_mul_f32 v[56:57], v[56:57], s[22:23] op_sel_hi:[1,0]
	v_pk_mul_f32 v[62:63], v[62:63], s[22:23] op_sel_hi:[1,0]
	v_pk_mul_f32 v[60:61], v[60:61], s[22:23] op_sel_hi:[1,0]
	v_pk_fma_f32 v[50:51], v[74:75], v[50:51], v[58:59] op_sel_hi:[0,1,1] neg_lo:[0,0,1] neg_hi:[0,0,1]
	v_pk_fma_f32 v[48:49], v[74:75], v[48:49], v[56:57] op_sel_hi:[0,1,1] neg_lo:[0,0,1] neg_hi:[0,0,1]
	v_pk_fma_f32 v[54:55], v[74:75], v[54:55], v[62:63] op_sel_hi:[0,1,1] neg_lo:[0,0,1] neg_hi:[0,0,1]
	v_pk_fma_f32 v[52:53], v[74:75], v[52:53], v[60:61] op_sel_hi:[0,1,1] neg_lo:[0,0,1] neg_hi:[0,0,1]
	v_exp_f32_e32 v48, v48
	v_exp_f32_e32 v49, v49
	v_exp_f32_e32 v50, v50
	v_exp_f32_e32 v51, v51
	v_exp_f32_e32 v52, v52
	v_exp_f32_e32 v54, v54
	v_exp_f32_e32 v55, v55
	v_exp_f32_e32 v53, v53
	v_pk_add_f32 v[50:51], v[50:51], 1.0 op_sel_hi:[1,0]
	v_pk_add_f32 v[48:49], v[48:49], 1.0 op_sel_hi:[1,0]
	v_pk_add_f32 v[54:55], v[54:55], 1.0 op_sel_hi:[1,0]
	v_pk_add_f32 v[52:53], v[52:53], 1.0 op_sel_hi:[1,0]
	v_rcp_f32_e32 v48, v48
	v_rcp_f32_e32 v49, v49
	v_rcp_f32_e32 v50, v50
	v_rcp_f32_e32 v51, v51
	v_rcp_f32_e32 v52, v52
	v_rcp_f32_e32 v53, v53
	v_rcp_f32_e32 v54, v54
	v_rcp_f32_e32 v55, v55
	v_cvt_pk_bf16_f32 v48, v48, v49
	v_cvt_pk_bf16_f32 v49, v50, v51
	v_cvt_pk_bf16_f32 v50, v52, v53
	v_cvt_pk_bf16_f32 v51, v54, v55
	global_store_dwordx4 v[72:73], v[48:51], off offset:256
	global_load_dwordx4 v[48:51], v[144:145], off
	s_nop 0
	global_load_dwordx4 v[52:55], v[144:145], off offset:16
	v_add_u32_e32 v56, 0x90, v146
	v_and_b32_e32 v57, 0x7df, v56
	v_lshl_add_u32 v57, v57, 2, s50
	ds_read_b32 v58, v57
	v_ashrrev_i32_e32 v57, 31, v56
	v_lshlrev_b64 v[56:57], 12, v[56:57]
	v_lshl_add_u64 v[56:57], s[14:15], 0, v[56:57]
	v_lshl_add_u64 v[56:57], v[56:57], 0, v[148:149]
	s_waitcnt lgkmcnt(0)
	v_mul_f32_e32 v58, 0xbfb8aa3b, v58
	s_waitcnt vmcnt(0)
	v_pk_mul_f32 v[50:51], v[50:51], s[22:23] op_sel_hi:[1,0]
	v_pk_mul_f32 v[48:49], v[48:49], s[22:23] op_sel_hi:[1,0]
	v_pk_mul_f32 v[54:55], v[54:55], s[22:23] op_sel_hi:[1,0]
	v_pk_mul_f32 v[52:53], v[52:53], s[22:23] op_sel_hi:[1,0]
	v_pk_fma_f32 v[42:43], v[58:59], v[42:43], v[50:51] op_sel_hi:[0,1,1] neg_lo:[0,0,1] neg_hi:[0,0,1]
	v_pk_fma_f32 v[40:41], v[58:59], v[40:41], v[48:49] op_sel_hi:[0,1,1] neg_lo:[0,0,1] neg_hi:[0,0,1]
	v_pk_fma_f32 v[46:47], v[58:59], v[46:47], v[54:55] op_sel_hi:[0,1,1] neg_lo:[0,0,1] neg_hi:[0,0,1]
	v_pk_fma_f32 v[44:45], v[58:59], v[44:45], v[52:53] op_sel_hi:[0,1,1] neg_lo:[0,0,1] neg_hi:[0,0,1]
	v_exp_f32_e32 v40, v40
	v_exp_f32_e32 v41, v41
	v_exp_f32_e32 v42, v42
	v_exp_f32_e32 v43, v43
	v_exp_f32_e32 v44, v44
	v_exp_f32_e32 v46, v46
	v_exp_f32_e32 v47, v47
	v_exp_f32_e32 v45, v45
	v_pk_add_f32 v[42:43], v[42:43], 1.0 op_sel_hi:[1,0]
	v_pk_add_f32 v[40:41], v[40:41], 1.0 op_sel_hi:[1,0]
	v_pk_add_f32 v[46:47], v[46:47], 1.0 op_sel_hi:[1,0]
	v_pk_add_f32 v[44:45], v[44:45], 1.0 op_sel_hi:[1,0]
	v_rcp_f32_e32 v40, v40
	v_rcp_f32_e32 v41, v41
	v_rcp_f32_e32 v42, v42
	v_rcp_f32_e32 v43, v43
	v_rcp_f32_e32 v44, v44
	v_rcp_f32_e32 v45, v45
	v_rcp_f32_e32 v46, v46
	v_rcp_f32_e32 v47, v47
	v_cvt_pk_bf16_f32 v40, v40, v41
	v_cvt_pk_bf16_f32 v41, v42, v43
	v_cvt_pk_bf16_f32 v42, v44, v45
	v_cvt_pk_bf16_f32 v43, v46, v47
	global_store_dwordx4 v[56:57], v[40:43], off
	global_load_dwordx4 v[40:43], v[144:145], off offset:512
	s_nop 0
	global_load_dwordx4 v[44:47], v[144:145], off offset:528
	s_waitcnt vmcnt(0)
	v_pk_mul_f32 v[42:43], v[42:43], s[22:23] op_sel_hi:[1,0]
	v_pk_mul_f32 v[40:41], v[40:41], s[22:23] op_sel_hi:[1,0]
	v_pk_mul_f32 v[46:47], v[46:47], s[22:23] op_sel_hi:[1,0]
	v_pk_mul_f32 v[44:45], v[44:45], s[22:23] op_sel_hi:[1,0]
	v_pk_fma_f32 v[34:35], v[58:59], v[34:35], v[42:43] op_sel_hi:[0,1,1] neg_lo:[0,0,1] neg_hi:[0,0,1]
	v_pk_fma_f32 v[32:33], v[58:59], v[32:33], v[40:41] op_sel_hi:[0,1,1] neg_lo:[0,0,1] neg_hi:[0,0,1]
	v_pk_fma_f32 v[38:39], v[58:59], v[38:39], v[46:47] op_sel_hi:[0,1,1] neg_lo:[0,0,1] neg_hi:[0,0,1]
	v_pk_fma_f32 v[36:37], v[58:59], v[36:37], v[44:45] op_sel_hi:[0,1,1] neg_lo:[0,0,1] neg_hi:[0,0,1]
	v_exp_f32_e32 v32, v32
	v_exp_f32_e32 v33, v33
	v_exp_f32_e32 v34, v34
	v_exp_f32_e32 v35, v35
	v_exp_f32_e32 v36, v36
	v_exp_f32_e32 v38, v38
	v_exp_f32_e32 v39, v39
	v_exp_f32_e32 v37, v37
	v_pk_add_f32 v[34:35], v[34:35], 1.0 op_sel_hi:[1,0]
	v_pk_add_f32 v[32:33], v[32:33], 1.0 op_sel_hi:[1,0]
	v_pk_add_f32 v[38:39], v[38:39], 1.0 op_sel_hi:[1,0]
	v_pk_add_f32 v[36:37], v[36:37], 1.0 op_sel_hi:[1,0]
	v_rcp_f32_e32 v32, v32
	v_rcp_f32_e32 v33, v33
	v_rcp_f32_e32 v34, v34
	v_rcp_f32_e32 v35, v35
	v_rcp_f32_e32 v36, v36
	v_rcp_f32_e32 v37, v37
	v_rcp_f32_e32 v38, v38
	v_rcp_f32_e32 v39, v39
	v_cvt_pk_bf16_f32 v32, v32, v33
	v_cvt_pk_bf16_f32 v33, v34, v35
	v_cvt_pk_bf16_f32 v34, v36, v37
	v_cvt_pk_bf16_f32 v35, v38, v39
	global_store_dwordx4 v[56:57], v[32:35], off offset:256
	global_load_dwordx4 v[32:35], v[144:145], off
	s_nop 0
	global_load_dwordx4 v[36:39], v[144:145], off offset:16
	v_add_u32_e32 v40, 0xa0, v146
	v_and_b32_e32 v41, 0x7ef, v40
	v_lshl_add_u32 v41, v41, 2, s50
	ds_read_b32 v42, v41
	v_ashrrev_i32_e32 v41, 31, v40
	v_lshlrev_b64 v[40:41], 12, v[40:41]
	v_lshl_add_u64 v[40:41], s[14:15], 0, v[40:41]
	v_lshl_add_u64 v[40:41], v[40:41], 0, v[148:149]
	s_waitcnt lgkmcnt(0)
	v_mul_f32_e32 v42, 0xbfb8aa3b, v42
	s_waitcnt vmcnt(0)
	v_pk_mul_f32 v[34:35], v[34:35], s[22:23] op_sel_hi:[1,0]
	v_pk_mul_f32 v[32:33], v[32:33], s[22:23] op_sel_hi:[1,0]
	v_pk_mul_f32 v[38:39], v[38:39], s[22:23] op_sel_hi:[1,0]
	v_pk_mul_f32 v[36:37], v[36:37], s[22:23] op_sel_hi:[1,0]
	v_pk_fma_f32 v[26:27], v[42:43], v[26:27], v[34:35] op_sel_hi:[0,1,1] neg_lo:[0,0,1] neg_hi:[0,0,1]
	v_pk_fma_f32 v[24:25], v[42:43], v[24:25], v[32:33] op_sel_hi:[0,1,1] neg_lo:[0,0,1] neg_hi:[0,0,1]
	v_pk_fma_f32 v[30:31], v[42:43], v[30:31], v[38:39] op_sel_hi:[0,1,1] neg_lo:[0,0,1] neg_hi:[0,0,1]
	v_pk_fma_f32 v[28:29], v[42:43], v[28:29], v[36:37] op_sel_hi:[0,1,1] neg_lo:[0,0,1] neg_hi:[0,0,1]
	v_exp_f32_e32 v24, v24
	v_exp_f32_e32 v25, v25
	v_exp_f32_e32 v26, v26
	v_exp_f32_e32 v27, v27
	v_exp_f32_e32 v28, v28
	v_exp_f32_e32 v30, v30
	v_exp_f32_e32 v31, v31
	v_exp_f32_e32 v29, v29
	v_pk_add_f32 v[26:27], v[26:27], 1.0 op_sel_hi:[1,0]
	v_pk_add_f32 v[24:25], v[24:25], 1.0 op_sel_hi:[1,0]
	v_pk_add_f32 v[30:31], v[30:31], 1.0 op_sel_hi:[1,0]
	v_pk_add_f32 v[28:29], v[28:29], 1.0 op_sel_hi:[1,0]
	v_rcp_f32_e32 v24, v24
	v_rcp_f32_e32 v25, v25
	v_rcp_f32_e32 v26, v26
	v_rcp_f32_e32 v27, v27
	v_rcp_f32_e32 v28, v28
	v_rcp_f32_e32 v29, v29
	v_rcp_f32_e32 v30, v30
	v_rcp_f32_e32 v31, v31
	v_cvt_pk_bf16_f32 v24, v24, v25
	v_cvt_pk_bf16_f32 v25, v26, v27
	v_cvt_pk_bf16_f32 v26, v28, v29
	v_cvt_pk_bf16_f32 v27, v30, v31
	global_store_dwordx4 v[40:41], v[24:27], off
	global_load_dwordx4 v[24:27], v[144:145], off offset:512
	s_nop 0
	global_load_dwordx4 v[28:31], v[144:145], off offset:528
	s_waitcnt vmcnt(0)
	v_pk_mul_f32 v[26:27], v[26:27], s[22:23] op_sel_hi:[1,0]
	v_pk_mul_f32 v[24:25], v[24:25], s[22:23] op_sel_hi:[1,0]
	v_pk_mul_f32 v[30:31], v[30:31], s[22:23] op_sel_hi:[1,0]
	v_pk_mul_f32 v[28:29], v[28:29], s[22:23] op_sel_hi:[1,0]
	v_pk_fma_f32 v[18:19], v[42:43], v[18:19], v[26:27] op_sel_hi:[0,1,1] neg_lo:[0,0,1] neg_hi:[0,0,1]
	v_pk_fma_f32 v[16:17], v[42:43], v[16:17], v[24:25] op_sel_hi:[0,1,1] neg_lo:[0,0,1] neg_hi:[0,0,1]
	v_pk_fma_f32 v[22:23], v[42:43], v[22:23], v[30:31] op_sel_hi:[0,1,1] neg_lo:[0,0,1] neg_hi:[0,0,1]
	v_pk_fma_f32 v[20:21], v[42:43], v[20:21], v[28:29] op_sel_hi:[0,1,1] neg_lo:[0,0,1] neg_hi:[0,0,1]
	v_exp_f32_e32 v16, v16
	v_exp_f32_e32 v17, v17
	v_exp_f32_e32 v18, v18
	v_exp_f32_e32 v19, v19
	v_exp_f32_e32 v20, v20
	v_exp_f32_e32 v22, v22
	v_exp_f32_e32 v23, v23
	v_exp_f32_e32 v21, v21
	v_pk_add_f32 v[18:19], v[18:19], 1.0 op_sel_hi:[1,0]
	v_pk_add_f32 v[16:17], v[16:17], 1.0 op_sel_hi:[1,0]
	v_pk_add_f32 v[22:23], v[22:23], 1.0 op_sel_hi:[1,0]
	v_pk_add_f32 v[20:21], v[20:21], 1.0 op_sel_hi:[1,0]
	v_rcp_f32_e32 v16, v16
	v_rcp_f32_e32 v17, v17
	v_rcp_f32_e32 v18, v18
	v_rcp_f32_e32 v19, v19
	v_rcp_f32_e32 v20, v20
	v_rcp_f32_e32 v21, v21
	v_rcp_f32_e32 v22, v22
	v_rcp_f32_e32 v23, v23
	v_cvt_pk_bf16_f32 v16, v16, v17
	v_cvt_pk_bf16_f32 v17, v18, v19
	v_cvt_pk_bf16_f32 v18, v20, v21
	v_cvt_pk_bf16_f32 v19, v22, v23
	global_store_dwordx4 v[40:41], v[16:19], off offset:256
	global_load_dwordx4 v[16:19], v[144:145], off
	s_nop 0
	global_load_dwordx4 v[20:23], v[144:145], off offset:16
	v_add_u32_e32 v24, 0xb0, v146
	v_and_b32_e32 v25, 0x7ff, v24
	v_lshl_add_u32 v25, v25, 2, s50
	ds_read_b32 v26, v25
	v_ashrrev_i32_e32 v25, 31, v24
	v_lshlrev_b64 v[24:25], 12, v[24:25]
	v_lshl_add_u64 v[24:25], s[14:15], 0, v[24:25]
	v_lshl_add_u64 v[24:25], v[24:25], 0, v[148:149]
	s_waitcnt lgkmcnt(0)
	v_mul_f32_e32 v26, 0xbfb8aa3b, v26
	s_waitcnt vmcnt(0)
	v_pk_mul_f32 v[18:19], v[18:19], s[22:23] op_sel_hi:[1,0]
	v_pk_mul_f32 v[16:17], v[16:17], s[22:23] op_sel_hi:[1,0]
	v_pk_mul_f32 v[22:23], v[22:23], s[22:23] op_sel_hi:[1,0]
	v_pk_mul_f32 v[20:21], v[20:21], s[22:23] op_sel_hi:[1,0]
	v_pk_fma_f32 v[10:11], v[26:27], v[10:11], v[18:19] op_sel_hi:[0,1,1] neg_lo:[0,0,1] neg_hi:[0,0,1]
	v_pk_fma_f32 v[8:9], v[26:27], v[8:9], v[16:17] op_sel_hi:[0,1,1] neg_lo:[0,0,1] neg_hi:[0,0,1]
	v_pk_fma_f32 v[14:15], v[26:27], v[14:15], v[22:23] op_sel_hi:[0,1,1] neg_lo:[0,0,1] neg_hi:[0,0,1]
	v_pk_fma_f32 v[12:13], v[26:27], v[12:13], v[20:21] op_sel_hi:[0,1,1] neg_lo:[0,0,1] neg_hi:[0,0,1]
	v_exp_f32_e32 v8, v8
	v_exp_f32_e32 v9, v9
	v_exp_f32_e32 v10, v10
	v_exp_f32_e32 v11, v11
	v_exp_f32_e32 v12, v12
	v_exp_f32_e32 v14, v14
	v_exp_f32_e32 v15, v15
	v_exp_f32_e32 v13, v13
	v_pk_add_f32 v[10:11], v[10:11], 1.0 op_sel_hi:[1,0]
	v_pk_add_f32 v[8:9], v[8:9], 1.0 op_sel_hi:[1,0]
	v_pk_add_f32 v[14:15], v[14:15], 1.0 op_sel_hi:[1,0]
	v_pk_add_f32 v[12:13], v[12:13], 1.0 op_sel_hi:[1,0]
	v_rcp_f32_e32 v8, v8
	v_rcp_f32_e32 v9, v9
	v_rcp_f32_e32 v10, v10
	v_rcp_f32_e32 v11, v11
	v_rcp_f32_e32 v12, v12
	v_rcp_f32_e32 v13, v13
	v_rcp_f32_e32 v14, v14
	v_rcp_f32_e32 v15, v15
	v_cvt_pk_bf16_f32 v8, v8, v9
	v_cvt_pk_bf16_f32 v9, v10, v11
	v_cvt_pk_bf16_f32 v10, v12, v13
	v_cvt_pk_bf16_f32 v11, v14, v15
	global_store_dwordx4 v[24:25], v[8:11], off
	global_load_dwordx4 v[8:11], v[144:145], off offset:512
	s_nop 0
	global_load_dwordx4 v[12:15], v[144:145], off offset:528
	s_waitcnt vmcnt(0)
	v_pk_mul_f32 v[10:11], v[10:11], s[22:23] op_sel_hi:[1,0]
	v_pk_mul_f32 v[8:9], v[8:9], s[22:23] op_sel_hi:[1,0]
	v_pk_mul_f32 v[14:15], v[14:15], s[22:23] op_sel_hi:[1,0]
	v_pk_mul_f32 v[12:13], v[12:13], s[22:23] op_sel_hi:[1,0]
	v_pk_fma_f32 v[2:3], v[26:27], v[2:3], v[10:11] op_sel_hi:[0,1,1] neg_lo:[0,0,1] neg_hi:[0,0,1]
	v_pk_fma_f32 v[0:1], v[26:27], v[0:1], v[8:9] op_sel_hi:[0,1,1] neg_lo:[0,0,1] neg_hi:[0,0,1]
	v_pk_fma_f32 v[6:7], v[26:27], v[6:7], v[14:15] op_sel_hi:[0,1,1] neg_lo:[0,0,1] neg_hi:[0,0,1]
	v_pk_fma_f32 v[4:5], v[26:27], v[4:5], v[12:13] op_sel_hi:[0,1,1] neg_lo:[0,0,1] neg_hi:[0,0,1]
	v_exp_f32_e32 v0, v0
	v_exp_f32_e32 v1, v1
	v_exp_f32_e32 v2, v2
	v_exp_f32_e32 v3, v3
	v_exp_f32_e32 v4, v4
	v_exp_f32_e32 v6, v6
	v_exp_f32_e32 v7, v7
	v_exp_f32_e32 v5, v5
	v_pk_add_f32 v[2:3], v[2:3], 1.0 op_sel_hi:[1,0]
	v_pk_add_f32 v[0:1], v[0:1], 1.0 op_sel_hi:[1,0]
	v_pk_add_f32 v[6:7], v[6:7], 1.0 op_sel_hi:[1,0]
	v_pk_add_f32 v[4:5], v[4:5], 1.0 op_sel_hi:[1,0]
	v_rcp_f32_e32 v0, v0
	v_rcp_f32_e32 v1, v1
	v_rcp_f32_e32 v2, v2
	v_rcp_f32_e32 v3, v3
	v_rcp_f32_e32 v4, v4
	v_rcp_f32_e32 v5, v5
	v_rcp_f32_e32 v6, v6
	v_rcp_f32_e32 v7, v7
	v_cvt_pk_bf16_f32 v0, v0, v1
	v_cvt_pk_bf16_f32 v1, v2, v3
	v_cvt_pk_bf16_f32 v2, v4, v5
	v_cvt_pk_bf16_f32 v3, v6, v7
	global_store_dwordx4 v[24:25], v[0:3], off offset:256
	s_cbranch_vccnz .LBB0_981
	s_andn2_b64 vcc, exec, s[12:13]
	v_pk_mov_b32 v[120:121], 0, 0
	v_pk_mov_b32 v[122:123], 0, 0
	v_pk_mov_b32 v[124:125], 0, 0
	v_pk_mov_b32 v[126:127], 0, 0
	v_pk_mov_b32 v[104:105], 0, 0
	v_pk_mov_b32 v[106:107], 0, 0
	v_pk_mov_b32 v[108:109], 0, 0
	v_pk_mov_b32 v[110:111], 0, 0
	v_pk_mov_b32 v[88:89], 0, 0
	v_pk_mov_b32 v[90:91], 0, 0
	v_pk_mov_b32 v[92:93], 0, 0
	v_pk_mov_b32 v[94:95], 0, 0
	v_pk_mov_b32 v[72:73], 0, 0
	v_pk_mov_b32 v[74:75], 0, 0
	v_pk_mov_b32 v[76:77], 0, 0
	v_pk_mov_b32 v[78:79], 0, 0
	v_pk_mov_b32 v[112:113], 0, 0
	v_pk_mov_b32 v[114:115], 0, 0
	v_pk_mov_b32 v[116:117], 0, 0
	v_pk_mov_b32 v[118:119], 0, 0
	v_pk_mov_b32 v[96:97], 0, 0
	v_pk_mov_b32 v[98:99], 0, 0
	v_pk_mov_b32 v[100:101], 0, 0
	v_pk_mov_b32 v[102:103], 0, 0
	v_pk_mov_b32 v[80:81], 0, 0
	v_pk_mov_b32 v[82:83], 0, 0
	v_pk_mov_b32 v[84:85], 0, 0
	v_pk_mov_b32 v[86:87], 0, 0
	v_pk_mov_b32 v[64:65], 0, 0
	v_pk_mov_b32 v[66:67], 0, 0
	v_pk_mov_b32 v[68:69], 0, 0
	v_pk_mov_b32 v[70:71], 0, 0
	v_pk_mov_b32 v[56:57], 0, 0
	v_pk_mov_b32 v[58:59], 0, 0
	v_pk_mov_b32 v[60:61], 0, 0
	v_pk_mov_b32 v[62:63], 0, 0
	v_pk_mov_b32 v[40:41], 0, 0
	v_pk_mov_b32 v[42:43], 0, 0
	v_pk_mov_b32 v[44:45], 0, 0
	v_pk_mov_b32 v[46:47], 0, 0
	v_pk_mov_b32 v[24:25], 0, 0
	v_pk_mov_b32 v[26:27], 0, 0
	v_pk_mov_b32 v[28:29], 0, 0
	v_pk_mov_b32 v[30:31], 0, 0
	v_pk_mov_b32 v[8:9], 0, 0
	v_pk_mov_b32 v[10:11], 0, 0
	v_pk_mov_b32 v[12:13], 0, 0
	v_pk_mov_b32 v[14:15], 0, 0
	v_pk_mov_b32 v[48:49], 0, 0
	v_pk_mov_b32 v[50:51], 0, 0
	v_pk_mov_b32 v[52:53], 0, 0
	v_pk_mov_b32 v[54:55], 0, 0
	v_pk_mov_b32 v[32:33], 0, 0
	v_pk_mov_b32 v[34:35], 0, 0
	v_pk_mov_b32 v[36:37], 0, 0
	v_pk_mov_b32 v[38:39], 0, 0
	v_pk_mov_b32 v[16:17], 0, 0
	v_pk_mov_b32 v[18:19], 0, 0
	v_pk_mov_b32 v[20:21], 0, 0
	v_pk_mov_b32 v[22:23], 0, 0
	v_pk_mov_b32 v[0:1], 0, 0
	v_pk_mov_b32 v[2:3], 0, 0
	v_pk_mov_b32 v[4:5], 0, 0
	v_pk_mov_b32 v[6:7], 0, 0
	s_cbranch_vccnz .LBB0_980
	s_barrier
	s_branch .LBB0_980

.LBB0_1170:
	v_lshl_add_u32 v146, s14, 8, v148
	v_ashrrev_i32_e32 v147, 31, v146
	v_lshl_add_u32 v144, s57, 8, v150
	v_lshlrev_b64 v[154:155], 11, v[146:147]
	v_ashrrev_i32_e32 v145, 31, v144
	v_lshl_add_u64 v[154:155], s[18:19], 0, v[154:155]
	v_lshl_add_u64 v[158:159], v[144:145], 1, v[154:155]
	global_load_dwordx4 v[154:157], v[158:159], off
	s_lshl_b32 s6, s57, 2
	s_ashr_i32 s7, s6, 31
	s_waitcnt vmcnt(0) lgkmcnt(0)
	v_lshlrev_b32_e32 v160, 16, v154
	v_and_b32_e32 v161, 0xffff0000, v154
	v_lshlrev_b32_e32 v154, 16, v155
	v_and_b32_e32 v155, 0xffff0000, v155
	v_lshlrev_b32_e32 v162, 16, v156
	v_and_b32_e32 v163, 0xffff0000, v156
	v_lshlrev_b32_e32 v156, 16, v157
	v_and_b32_e32 v157, 0xffff0000, v157
	v_pk_add_f32 v[154:155], v[126:127], v[154:155]
	v_pk_add_f32 v[160:161], v[124:125], v[160:161]
	v_pk_add_f32 v[156:157], v[122:123], v[156:157]
	v_pk_add_f32 v[162:163], v[120:121], v[162:163]
	v_cvt_pk_bf16_f32 v120, v160, v161
	v_cvt_pk_bf16_f32 v121, v154, v155
	v_mul_f32_e32 v161, v161, v161
	v_cvt_pk_bf16_f32 v122, v162, v163
	v_cvt_pk_bf16_f32 v123, v156, v157
	global_load_dwordx4 v[124:127], v[158:159], off offset:256
	v_mul_f32_e32 v155, v155, v155
	v_mul_f32_e32 v163, v163, v163
	v_mul_f32_e32 v157, v157, v157
	v_fmac_f32_e32 v161, v160, v160
	v_fmac_f32_e32 v155, v154, v154
	v_fmac_f32_e32 v163, v162, v162
	v_fmac_f32_e32 v157, v156, v156
	v_add_f32_e32 v154, v161, v155
	v_add_f32_e32 v155, v163, v157
	v_add_f32_e32 v160, v154, v155
	global_store_dwordx4 v[158:159], v[120:123], off
	s_waitcnt vmcnt(0) lgkmcnt(0)
	v_lshlrev_b32_e32 v154, 16, v124
	v_and_b32_e32 v155, 0xffff0000, v124
	v_lshlrev_b32_e32 v124, 16, v125
	v_and_b32_e32 v125, 0xffff0000, v125
	v_lshlrev_b32_e32 v156, 16, v126
	v_and_b32_e32 v157, 0xffff0000, v126
	v_lshlrev_b32_e32 v126, 16, v127
	v_and_b32_e32 v127, 0xffff0000, v127
	v_pk_add_f32 v[118:119], v[118:119], v[124:125]
	v_pk_add_f32 v[116:117], v[116:117], v[154:155]
	v_pk_add_f32 v[124:125], v[114:115], v[126:127]
	v_pk_add_f32 v[126:127], v[112:113], v[156:157]
	v_mul_f32_e32 v112, v117, v117
	v_mul_f32_e32 v113, v119, v119
	v_mul_f32_e32 v114, v127, v127
	v_mul_f32_e32 v115, v125, v125
	v_fmac_f32_e32 v112, v116, v116
	v_fmac_f32_e32 v113, v118, v118
	v_fmac_f32_e32 v114, v126, v126
	v_fmac_f32_e32 v115, v124, v124
	v_add_f32_e32 v112, v112, v113
	v_add_f32_e32 v113, v114, v115
	v_add_f32_e32 v112, v112, v113
	v_add_f32_e32 v112, v160, v112
	ds_bpermute_b32 v113, v151, v112
	v_cvt_pk_bf16_f32 v114, v116, v117
	v_cvt_pk_bf16_f32 v115, v118, v119
	v_cvt_pk_bf16_f32 v116, v126, v127
	v_cvt_pk_bf16_f32 v117, v124, v125
	s_waitcnt lgkmcnt(0)
	v_add_f32_e32 v112, v112, v113
	ds_bpermute_b32 v113, v152, v112
	global_store_dwordx4 v[158:159], v[114:117], off offset:256
	s_and_saveexec_b64 s[0:1], s[2:3]
	s_cbranch_execz .LBB0_1172
	v_lshlrev_b64 v[114:115], 6, v[146:147]
	v_lshl_add_u64 v[114:115], s[20:21], 0, v[114:115]
	v_lshl_add_u64 v[114:115], s[6:7], 2, v[114:115]
	s_lshl_b32 s14, s48, 2
	v_lshl_add_u64 v[114:115], v[114:115], 0, s[14:15]
	s_waitcnt lgkmcnt(0)
	v_add_f32_e32 v112, v112, v113
	global_store_dword v[114:115], v112, off
.LBB0_1172:
	s_or_b64 exec, exec, s[0:1]
	v_or_b32_e32 v112, 16, v146
	s_waitcnt lgkmcnt(0)
	v_ashrrev_i32_e32 v113, 31, v112
	v_lshlrev_b64 v[114:115], 11, v[112:113]
	v_lshl_add_u64 v[114:115], s[18:19], 0, v[114:115]
	v_lshl_add_u64 v[118:119], v[144:145], 1, v[114:115]
	global_load_dwordx4 v[114:117], v[118:119], off
	s_waitcnt vmcnt(0) lgkmcnt(0)
	v_lshlrev_b32_e32 v120, 16, v114
	v_and_b32_e32 v121, 0xffff0000, v114
	v_lshlrev_b32_e32 v114, 16, v115
	v_and_b32_e32 v115, 0xffff0000, v115
	v_lshlrev_b32_e32 v122, 16, v116
	v_and_b32_e32 v123, 0xffff0000, v116
	v_lshlrev_b32_e32 v116, 16, v117
	v_and_b32_e32 v117, 0xffff0000, v117
	v_pk_add_f32 v[114:115], v[110:111], v[114:115]
	v_pk_add_f32 v[120:121], v[108:109], v[120:121]
	v_pk_add_f32 v[116:117], v[106:107], v[116:117]
	v_pk_add_f32 v[122:123], v[104:105], v[122:123]
	v_cvt_pk_bf16_f32 v104, v120, v121
	v_cvt_pk_bf16_f32 v105, v114, v115
	v_mul_f32_e32 v121, v121, v121
	v_cvt_pk_bf16_f32 v106, v122, v123
	v_cvt_pk_bf16_f32 v107, v116, v117
	global_load_dwordx4 v[108:111], v[118:119], off offset:256
	v_mul_f32_e32 v115, v115, v115
	v_mul_f32_e32 v123, v123, v123
	v_mul_f32_e32 v117, v117, v117
	v_fmac_f32_e32 v121, v120, v120
	v_fmac_f32_e32 v115, v114, v114
	v_fmac_f32_e32 v123, v122, v122
	v_fmac_f32_e32 v117, v116, v116
	v_add_f32_e32 v114, v121, v115
	v_add_f32_e32 v115, v123, v117
	v_add_f32_e32 v120, v114, v115
	global_store_dwordx4 v[118:119], v[104:107], off
	s_waitcnt vmcnt(0) lgkmcnt(0)
	v_lshlrev_b32_e32 v114, 16, v108
	v_and_b32_e32 v115, 0xffff0000, v108
	v_lshlrev_b32_e32 v108, 16, v109
	v_and_b32_e32 v109, 0xffff0000, v109
	v_lshlrev_b32_e32 v116, 16, v110
	v_and_b32_e32 v117, 0xffff0000, v110
	v_lshlrev_b32_e32 v110, 16, v111
	v_and_b32_e32 v111, 0xffff0000, v111
	v_pk_add_f32 v[102:103], v[102:103], v[108:109]
	v_pk_add_f32 v[100:101], v[100:101], v[114:115]
	v_pk_add_f32 v[108:109], v[98:99], v[110:111]
	v_pk_add_f32 v[110:111], v[96:97], v[116:117]
	v_mul_f32_e32 v96, v101, v101
	v_mul_f32_e32 v97, v103, v103
	v_mul_f32_e32 v98, v111, v111
	v_mul_f32_e32 v99, v109, v109
	v_fmac_f32_e32 v96, v100, v100
	v_fmac_f32_e32 v97, v102, v102
	v_fmac_f32_e32 v98, v110, v110
	v_fmac_f32_e32 v99, v108, v108
	v_add_f32_e32 v96, v96, v97
	v_add_f32_e32 v97, v98, v99
	v_add_f32_e32 v96, v96, v97
	v_add_f32_e32 v96, v120, v96
	ds_bpermute_b32 v97, v151, v96
	v_cvt_pk_bf16_f32 v98, v100, v101
	v_cvt_pk_bf16_f32 v99, v102, v103
	v_cvt_pk_bf16_f32 v100, v110, v111
	v_cvt_pk_bf16_f32 v101, v108, v109
	s_waitcnt lgkmcnt(0)
	v_add_f32_e32 v96, v96, v97
	ds_bpermute_b32 v97, v152, v96
	global_store_dwordx4 v[118:119], v[98:101], off offset:256
	s_and_saveexec_b64 s[0:1], s[2:3]
	s_cbranch_execz .LBB0_1174
	v_lshlrev_b64 v[98:99], 6, v[112:113]
	v_lshl_add_u64 v[98:99], s[20:21], 0, v[98:99]
	v_lshl_add_u64 v[98:99], s[6:7], 2, v[98:99]
	s_lshl_b32 s14, s48, 2
	v_lshl_add_u64 v[98:99], v[98:99], 0, s[14:15]
	s_waitcnt lgkmcnt(0)
	v_add_f32_e32 v96, v96, v97
	global_store_dword v[98:99], v96, off
.LBB0_1174:
	s_or_b64 exec, exec, s[0:1]
	v_or_b32_e32 v96, 32, v146
	s_waitcnt lgkmcnt(0)
	v_ashrrev_i32_e32 v97, 31, v96
	v_lshlrev_b64 v[98:99], 11, v[96:97]
	v_lshl_add_u64 v[98:99], s[18:19], 0, v[98:99]
	v_lshl_add_u64 v[102:103], v[144:145], 1, v[98:99]
	global_load_dwordx4 v[98:101], v[102:103], off
	s_waitcnt vmcnt(0) lgkmcnt(0)
	v_lshlrev_b32_e32 v104, 16, v98
	v_and_b32_e32 v105, 0xffff0000, v98
	v_lshlrev_b32_e32 v98, 16, v99
	v_and_b32_e32 v99, 0xffff0000, v99
	v_lshlrev_b32_e32 v106, 16, v100
	v_and_b32_e32 v107, 0xffff0000, v100
	v_lshlrev_b32_e32 v100, 16, v101
	v_and_b32_e32 v101, 0xffff0000, v101
	v_pk_add_f32 v[98:99], v[94:95], v[98:99]
	v_pk_add_f32 v[104:105], v[92:93], v[104:105]
	v_pk_add_f32 v[100:101], v[90:91], v[100:101]
	v_pk_add_f32 v[106:107], v[88:89], v[106:107]
	v_cvt_pk_bf16_f32 v88, v104, v105
	v_cvt_pk_bf16_f32 v89, v98, v99
	v_mul_f32_e32 v105, v105, v105
	v_cvt_pk_bf16_f32 v90, v106, v107
	v_cvt_pk_bf16_f32 v91, v100, v101
	global_load_dwordx4 v[92:95], v[102:103], off offset:256
	v_mul_f32_e32 v99, v99, v99
	v_mul_f32_e32 v107, v107, v107
	v_mul_f32_e32 v101, v101, v101
	v_fmac_f32_e32 v105, v104, v104
	v_fmac_f32_e32 v99, v98, v98
	v_fmac_f32_e32 v107, v106, v106
	v_fmac_f32_e32 v101, v100, v100
	v_add_f32_e32 v98, v105, v99
	v_add_f32_e32 v99, v107, v101
	v_add_f32_e32 v104, v98, v99
	global_store_dwordx4 v[102:103], v[88:91], off
	s_waitcnt vmcnt(0) lgkmcnt(0)
	v_lshlrev_b32_e32 v98, 16, v92
	v_and_b32_e32 v99, 0xffff0000, v92
	v_lshlrev_b32_e32 v92, 16, v93
	v_and_b32_e32 v93, 0xffff0000, v93
	v_lshlrev_b32_e32 v100, 16, v94
	v_and_b32_e32 v101, 0xffff0000, v94
	v_lshlrev_b32_e32 v94, 16, v95
	v_and_b32_e32 v95, 0xffff0000, v95
	v_pk_add_f32 v[86:87], v[86:87], v[92:93]
	v_pk_add_f32 v[84:85], v[84:85], v[98:99]
	v_pk_add_f32 v[92:93], v[82:83], v[94:95]
	v_pk_add_f32 v[94:95], v[80:81], v[100:101]
	v_mul_f32_e32 v80, v85, v85
	v_mul_f32_e32 v81, v87, v87
	v_mul_f32_e32 v82, v95, v95
	v_mul_f32_e32 v83, v93, v93
	v_fmac_f32_e32 v80, v84, v84
	v_fmac_f32_e32 v81, v86, v86
	v_fmac_f32_e32 v82, v94, v94
	v_fmac_f32_e32 v83, v92, v92
	v_add_f32_e32 v80, v80, v81
	v_add_f32_e32 v81, v82, v83
	v_add_f32_e32 v80, v80, v81
	v_add_f32_e32 v80, v104, v80
	ds_bpermute_b32 v81, v151, v80
	v_cvt_pk_bf16_f32 v82, v84, v85
	v_cvt_pk_bf16_f32 v83, v86, v87
	v_cvt_pk_bf16_f32 v84, v94, v95
	v_cvt_pk_bf16_f32 v85, v92, v93
	s_waitcnt lgkmcnt(0)
	v_add_f32_e32 v80, v80, v81
	ds_bpermute_b32 v81, v152, v80
	global_store_dwordx4 v[102:103], v[82:85], off offset:256
	s_and_saveexec_b64 s[0:1], s[2:3]
	s_cbranch_execz .LBB0_1176
	v_lshlrev_b64 v[82:83], 6, v[96:97]
	v_lshl_add_u64 v[82:83], s[20:21], 0, v[82:83]
	v_lshl_add_u64 v[82:83], s[6:7], 2, v[82:83]
	s_lshl_b32 s14, s48, 2
	v_lshl_add_u64 v[82:83], v[82:83], 0, s[14:15]
	s_waitcnt lgkmcnt(0)
	v_add_f32_e32 v80, v80, v81
	global_store_dword v[82:83], v80, off
.LBB0_1176:
	s_or_b64 exec, exec, s[0:1]
	v_or_b32_e32 v80, 48, v146
	s_waitcnt lgkmcnt(0)
	v_ashrrev_i32_e32 v81, 31, v80
	v_lshlrev_b64 v[82:83], 11, v[80:81]
	v_lshl_add_u64 v[82:83], s[18:19], 0, v[82:83]
	v_lshl_add_u64 v[86:87], v[144:145], 1, v[82:83]
	global_load_dwordx4 v[82:85], v[86:87], off
	s_waitcnt vmcnt(0) lgkmcnt(0)
	v_lshlrev_b32_e32 v88, 16, v82
	v_and_b32_e32 v89, 0xffff0000, v82
	v_lshlrev_b32_e32 v82, 16, v83
	v_and_b32_e32 v83, 0xffff0000, v83
	v_lshlrev_b32_e32 v90, 16, v84
	v_and_b32_e32 v91, 0xffff0000, v84
	v_lshlrev_b32_e32 v84, 16, v85
	v_and_b32_e32 v85, 0xffff0000, v85
	v_pk_add_f32 v[82:83], v[78:79], v[82:83]
	v_pk_add_f32 v[88:89], v[76:77], v[88:89]
	v_pk_add_f32 v[84:85], v[74:75], v[84:85]
	v_pk_add_f32 v[90:91], v[72:73], v[90:91]
	v_cvt_pk_bf16_f32 v72, v88, v89
	v_cvt_pk_bf16_f32 v73, v82, v83
	v_mul_f32_e32 v89, v89, v89
	v_cvt_pk_bf16_f32 v74, v90, v91
	v_cvt_pk_bf16_f32 v75, v84, v85
	global_load_dwordx4 v[76:79], v[86:87], off offset:256
	v_mul_f32_e32 v83, v83, v83
	v_mul_f32_e32 v91, v91, v91
	v_mul_f32_e32 v85, v85, v85
	v_fmac_f32_e32 v89, v88, v88
	v_fmac_f32_e32 v83, v82, v82
	v_fmac_f32_e32 v91, v90, v90
	v_fmac_f32_e32 v85, v84, v84
	v_add_f32_e32 v82, v89, v83
	v_add_f32_e32 v83, v91, v85
	v_add_f32_e32 v88, v82, v83
	global_store_dwordx4 v[86:87], v[72:75], off
	s_waitcnt vmcnt(0) lgkmcnt(0)
	v_lshlrev_b32_e32 v82, 16, v76
	v_and_b32_e32 v83, 0xffff0000, v76
	v_lshlrev_b32_e32 v76, 16, v77
	v_and_b32_e32 v77, 0xffff0000, v77
	v_lshlrev_b32_e32 v84, 16, v78
	v_and_b32_e32 v85, 0xffff0000, v78
	v_lshlrev_b32_e32 v78, 16, v79
	v_and_b32_e32 v79, 0xffff0000, v79
	v_pk_add_f32 v[70:71], v[70:71], v[76:77]
	v_pk_add_f32 v[68:69], v[68:69], v[82:83]
	v_pk_add_f32 v[76:77], v[66:67], v[78:79]
	v_pk_add_f32 v[78:79], v[64:65], v[84:85]
	v_mul_f32_e32 v64, v69, v69
	v_mul_f32_e32 v65, v71, v71
	v_mul_f32_e32 v66, v79, v79
	v_mul_f32_e32 v67, v77, v77
	v_fmac_f32_e32 v64, v68, v68
	v_fmac_f32_e32 v65, v70, v70
	v_fmac_f32_e32 v66, v78, v78
	v_fmac_f32_e32 v67, v76, v76
	v_add_f32_e32 v64, v64, v65
	v_add_f32_e32 v65, v66, v67
	v_add_f32_e32 v64, v64, v65
	v_add_f32_e32 v64, v88, v64
	ds_bpermute_b32 v65, v151, v64
	v_cvt_pk_bf16_f32 v66, v68, v69
	v_cvt_pk_bf16_f32 v67, v70, v71
	v_cvt_pk_bf16_f32 v68, v78, v79
	v_cvt_pk_bf16_f32 v69, v76, v77
	s_waitcnt lgkmcnt(0)
	v_add_f32_e32 v64, v64, v65
	ds_bpermute_b32 v65, v152, v64
	global_store_dwordx4 v[86:87], v[66:69], off offset:256
	s_and_saveexec_b64 s[0:1], s[2:3]
	s_cbranch_execz .LBB0_1178
	v_lshlrev_b64 v[66:67], 6, v[80:81]
	v_lshl_add_u64 v[66:67], s[20:21], 0, v[66:67]
	v_lshl_add_u64 v[66:67], s[6:7], 2, v[66:67]
	s_lshl_b32 s14, s48, 2
	v_lshl_add_u64 v[66:67], v[66:67], 0, s[14:15]
	s_waitcnt lgkmcnt(0)
	v_add_f32_e32 v64, v64, v65
	global_store_dword v[66:67], v64, off
.LBB0_1178:
	s_or_b64 exec, exec, s[0:1]
	v_add_u32_e32 v64, 0x80, v146
	s_waitcnt lgkmcnt(0)
	v_ashrrev_i32_e32 v65, 31, v64
	v_lshlrev_b64 v[66:67], 11, v[64:65]
	v_lshl_add_u64 v[66:67], s[18:19], 0, v[66:67]
	v_lshl_add_u64 v[70:71], v[144:145], 1, v[66:67]
	global_load_dwordx4 v[66:69], v[70:71], off
	s_waitcnt vmcnt(0) lgkmcnt(0)
	v_lshlrev_b32_e32 v72, 16, v66
	v_and_b32_e32 v73, 0xffff0000, v66
	v_lshlrev_b32_e32 v66, 16, v67
	v_and_b32_e32 v67, 0xffff0000, v67
	v_lshlrev_b32_e32 v74, 16, v68
	v_and_b32_e32 v75, 0xffff0000, v68
	v_lshlrev_b32_e32 v68, 16, v69
	v_and_b32_e32 v69, 0xffff0000, v69
	v_pk_add_f32 v[66:67], v[62:63], v[66:67]
	v_pk_add_f32 v[72:73], v[60:61], v[72:73]
	v_pk_add_f32 v[68:69], v[58:59], v[68:69]
	v_pk_add_f32 v[74:75], v[56:57], v[74:75]
	v_cvt_pk_bf16_f32 v56, v72, v73
	v_cvt_pk_bf16_f32 v57, v66, v67
	v_mul_f32_e32 v73, v73, v73
	v_cvt_pk_bf16_f32 v58, v74, v75
	v_cvt_pk_bf16_f32 v59, v68, v69
	global_load_dwordx4 v[60:63], v[70:71], off offset:256
	v_mul_f32_e32 v67, v67, v67
	v_mul_f32_e32 v75, v75, v75
	v_mul_f32_e32 v69, v69, v69
	v_fmac_f32_e32 v73, v72, v72
	v_fmac_f32_e32 v67, v66, v66
	v_fmac_f32_e32 v75, v74, v74
	v_fmac_f32_e32 v69, v68, v68
	v_add_f32_e32 v66, v73, v67
	v_add_f32_e32 v67, v75, v69
	v_add_f32_e32 v72, v66, v67
	global_store_dwordx4 v[70:71], v[56:59], off
	s_waitcnt vmcnt(0) lgkmcnt(0)
	v_lshlrev_b32_e32 v66, 16, v60
	v_and_b32_e32 v67, 0xffff0000, v60
	v_lshlrev_b32_e32 v60, 16, v61
	v_and_b32_e32 v61, 0xffff0000, v61
	v_lshlrev_b32_e32 v68, 16, v62
	v_and_b32_e32 v69, 0xffff0000, v62
	v_lshlrev_b32_e32 v62, 16, v63
	v_and_b32_e32 v63, 0xffff0000, v63
	v_pk_add_f32 v[54:55], v[54:55], v[60:61]
	v_pk_add_f32 v[52:53], v[52:53], v[66:67]
	v_pk_add_f32 v[60:61], v[50:51], v[62:63]
	v_pk_add_f32 v[62:63], v[48:49], v[68:69]
	v_mul_f32_e32 v48, v53, v53
	v_mul_f32_e32 v49, v55, v55
	v_mul_f32_e32 v50, v63, v63
	v_mul_f32_e32 v51, v61, v61
	v_fmac_f32_e32 v48, v52, v52
	v_fmac_f32_e32 v49, v54, v54
	v_fmac_f32_e32 v50, v62, v62
	v_fmac_f32_e32 v51, v60, v60
	v_add_f32_e32 v48, v48, v49
	v_add_f32_e32 v49, v50, v51
	v_add_f32_e32 v48, v48, v49
	v_add_f32_e32 v48, v72, v48
	ds_bpermute_b32 v49, v151, v48
	v_cvt_pk_bf16_f32 v50, v52, v53
	v_cvt_pk_bf16_f32 v51, v54, v55
	v_cvt_pk_bf16_f32 v52, v62, v63
	v_cvt_pk_bf16_f32 v53, v60, v61
	s_waitcnt lgkmcnt(0)
	v_add_f32_e32 v48, v48, v49
	ds_bpermute_b32 v49, v152, v48
	global_store_dwordx4 v[70:71], v[50:53], off offset:256
	s_and_saveexec_b64 s[0:1], s[2:3]
	s_cbranch_execz .LBB0_1180
	v_lshlrev_b64 v[50:51], 6, v[64:65]
	v_lshl_add_u64 v[50:51], s[20:21], 0, v[50:51]
	v_lshl_add_u64 v[50:51], s[6:7], 2, v[50:51]
	s_lshl_b32 s14, s48, 2
	v_lshl_add_u64 v[50:51], v[50:51], 0, s[14:15]
	s_waitcnt lgkmcnt(0)
	v_add_f32_e32 v48, v48, v49
	global_store_dword v[50:51], v48, off
.LBB0_1180:
	s_or_b64 exec, exec, s[0:1]
	v_add_u32_e32 v48, 0x90, v146
	s_waitcnt lgkmcnt(0)
	v_ashrrev_i32_e32 v49, 31, v48
	v_lshlrev_b64 v[50:51], 11, v[48:49]
	v_lshl_add_u64 v[50:51], s[18:19], 0, v[50:51]
	v_lshl_add_u64 v[54:55], v[144:145], 1, v[50:51]
	global_load_dwordx4 v[50:53], v[54:55], off
	s_waitcnt vmcnt(0) lgkmcnt(0)
	v_lshlrev_b32_e32 v56, 16, v50
	v_and_b32_e32 v57, 0xffff0000, v50
	v_lshlrev_b32_e32 v50, 16, v51
	v_and_b32_e32 v51, 0xffff0000, v51
	v_lshlrev_b32_e32 v58, 16, v52
	v_and_b32_e32 v59, 0xffff0000, v52
	v_lshlrev_b32_e32 v52, 16, v53
	v_and_b32_e32 v53, 0xffff0000, v53
	v_pk_add_f32 v[50:51], v[46:47], v[50:51]
	v_pk_add_f32 v[56:57], v[44:45], v[56:57]
	v_pk_add_f32 v[52:53], v[42:43], v[52:53]
	v_pk_add_f32 v[58:59], v[40:41], v[58:59]
	v_cvt_pk_bf16_f32 v40, v56, v57
	v_cvt_pk_bf16_f32 v41, v50, v51
	v_mul_f32_e32 v57, v57, v57
	v_cvt_pk_bf16_f32 v42, v58, v59
	v_cvt_pk_bf16_f32 v43, v52, v53
	global_load_dwordx4 v[44:47], v[54:55], off offset:256
	v_mul_f32_e32 v51, v51, v51
	v_mul_f32_e32 v59, v59, v59
	v_mul_f32_e32 v53, v53, v53
	v_fmac_f32_e32 v57, v56, v56
	v_fmac_f32_e32 v51, v50, v50
	v_fmac_f32_e32 v59, v58, v58
	v_fmac_f32_e32 v53, v52, v52
	v_add_f32_e32 v50, v57, v51
	v_add_f32_e32 v51, v59, v53
	v_add_f32_e32 v56, v50, v51
	global_store_dwordx4 v[54:55], v[40:43], off
	s_waitcnt vmcnt(0) lgkmcnt(0)
	v_lshlrev_b32_e32 v50, 16, v44
	v_and_b32_e32 v51, 0xffff0000, v44
	v_lshlrev_b32_e32 v44, 16, v45
	v_and_b32_e32 v45, 0xffff0000, v45
	v_lshlrev_b32_e32 v52, 16, v46
	v_and_b32_e32 v53, 0xffff0000, v46
	v_lshlrev_b32_e32 v46, 16, v47
	v_and_b32_e32 v47, 0xffff0000, v47
	v_pk_add_f32 v[38:39], v[38:39], v[44:45]
	v_pk_add_f32 v[36:37], v[36:37], v[50:51]
	v_pk_add_f32 v[44:45], v[34:35], v[46:47]
	v_pk_add_f32 v[46:47], v[32:33], v[52:53]
	v_mul_f32_e32 v32, v37, v37
	v_mul_f32_e32 v33, v39, v39
	v_mul_f32_e32 v34, v47, v47
	v_mul_f32_e32 v35, v45, v45
	v_fmac_f32_e32 v32, v36, v36
	v_fmac_f32_e32 v33, v38, v38
	v_fmac_f32_e32 v34, v46, v46
	v_fmac_f32_e32 v35, v44, v44
	v_add_f32_e32 v32, v32, v33
	v_add_f32_e32 v33, v34, v35
	v_add_f32_e32 v32, v32, v33
	v_add_f32_e32 v32, v56, v32
	ds_bpermute_b32 v33, v151, v32
	v_cvt_pk_bf16_f32 v34, v36, v37
	v_cvt_pk_bf16_f32 v35, v38, v39
	v_cvt_pk_bf16_f32 v36, v46, v47
	v_cvt_pk_bf16_f32 v37, v44, v45
	s_waitcnt lgkmcnt(0)
	v_add_f32_e32 v32, v32, v33
	ds_bpermute_b32 v33, v152, v32
	global_store_dwordx4 v[54:55], v[34:37], off offset:256
	s_and_saveexec_b64 s[0:1], s[2:3]
	s_cbranch_execz .LBB0_1182
	v_lshlrev_b64 v[34:35], 6, v[48:49]
	v_lshl_add_u64 v[34:35], s[20:21], 0, v[34:35]
	v_lshl_add_u64 v[34:35], s[6:7], 2, v[34:35]
	s_lshl_b32 s14, s48, 2
	v_lshl_add_u64 v[34:35], v[34:35], 0, s[14:15]
	s_waitcnt lgkmcnt(0)
	v_add_f32_e32 v32, v32, v33
	global_store_dword v[34:35], v32, off
.LBB0_1182:
	s_or_b64 exec, exec, s[0:1]
	v_add_u32_e32 v32, 0xa0, v146
	s_waitcnt lgkmcnt(0)
	v_ashrrev_i32_e32 v33, 31, v32
	v_lshlrev_b64 v[34:35], 11, v[32:33]
	v_lshl_add_u64 v[34:35], s[18:19], 0, v[34:35]
	v_lshl_add_u64 v[38:39], v[144:145], 1, v[34:35]
	global_load_dwordx4 v[34:37], v[38:39], off
	s_waitcnt vmcnt(0) lgkmcnt(0)
	v_lshlrev_b32_e32 v40, 16, v34
	v_and_b32_e32 v41, 0xffff0000, v34
	v_lshlrev_b32_e32 v34, 16, v35
	v_and_b32_e32 v35, 0xffff0000, v35
	v_lshlrev_b32_e32 v42, 16, v36
	v_and_b32_e32 v43, 0xffff0000, v36
	v_lshlrev_b32_e32 v36, 16, v37
	v_and_b32_e32 v37, 0xffff0000, v37
	v_pk_add_f32 v[34:35], v[30:31], v[34:35]
	v_pk_add_f32 v[40:41], v[28:29], v[40:41]
	v_pk_add_f32 v[36:37], v[26:27], v[36:37]
	v_pk_add_f32 v[42:43], v[24:25], v[42:43]
	v_cvt_pk_bf16_f32 v24, v40, v41
	v_cvt_pk_bf16_f32 v25, v34, v35
	v_mul_f32_e32 v41, v41, v41
	v_cvt_pk_bf16_f32 v26, v42, v43
	v_cvt_pk_bf16_f32 v27, v36, v37
	global_load_dwordx4 v[28:31], v[38:39], off offset:256
	v_mul_f32_e32 v35, v35, v35
	v_mul_f32_e32 v43, v43, v43
	v_mul_f32_e32 v37, v37, v37
	v_fmac_f32_e32 v41, v40, v40
	v_fmac_f32_e32 v35, v34, v34
	v_fmac_f32_e32 v43, v42, v42
	v_fmac_f32_e32 v37, v36, v36
	v_add_f32_e32 v34, v41, v35
	v_add_f32_e32 v35, v43, v37
	v_add_f32_e32 v40, v34, v35
	global_store_dwordx4 v[38:39], v[24:27], off
	s_waitcnt vmcnt(0) lgkmcnt(0)
	v_lshlrev_b32_e32 v34, 16, v28
	v_and_b32_e32 v35, 0xffff0000, v28
	v_lshlrev_b32_e32 v28, 16, v29
	v_and_b32_e32 v29, 0xffff0000, v29
	v_lshlrev_b32_e32 v36, 16, v30
	v_and_b32_e32 v37, 0xffff0000, v30
	v_lshlrev_b32_e32 v30, 16, v31
	v_and_b32_e32 v31, 0xffff0000, v31
	v_pk_add_f32 v[22:23], v[22:23], v[28:29]
	v_pk_add_f32 v[20:21], v[20:21], v[34:35]
	v_pk_add_f32 v[28:29], v[18:19], v[30:31]
	v_pk_add_f32 v[30:31], v[16:17], v[36:37]
	v_mul_f32_e32 v16, v21, v21
	v_mul_f32_e32 v17, v23, v23
	v_mul_f32_e32 v18, v31, v31
	v_mul_f32_e32 v19, v29, v29
	v_fmac_f32_e32 v16, v20, v20
	v_fmac_f32_e32 v17, v22, v22
	v_fmac_f32_e32 v18, v30, v30
	v_fmac_f32_e32 v19, v28, v28
	v_add_f32_e32 v16, v16, v17
	v_add_f32_e32 v17, v18, v19
	v_add_f32_e32 v16, v16, v17
	v_add_f32_e32 v16, v40, v16
	ds_bpermute_b32 v17, v151, v16
	v_cvt_pk_bf16_f32 v18, v20, v21
	v_cvt_pk_bf16_f32 v19, v22, v23
	v_cvt_pk_bf16_f32 v20, v30, v31
	v_cvt_pk_bf16_f32 v21, v28, v29
	s_waitcnt lgkmcnt(0)
	v_add_f32_e32 v16, v16, v17
	ds_bpermute_b32 v17, v152, v16
	global_store_dwordx4 v[38:39], v[18:21], off offset:256
	s_and_saveexec_b64 s[0:1], s[2:3]
	s_cbranch_execz .LBB0_1184
	v_lshlrev_b64 v[18:19], 6, v[32:33]
	v_lshl_add_u64 v[18:19], s[20:21], 0, v[18:19]
	v_lshl_add_u64 v[18:19], s[6:7], 2, v[18:19]
	s_lshl_b32 s14, s48, 2
	v_lshl_add_u64 v[18:19], v[18:19], 0, s[14:15]
	s_waitcnt lgkmcnt(0)
	v_add_f32_e32 v16, v16, v17
	global_store_dword v[18:19], v16, off
.LBB0_1184:
	s_or_b64 exec, exec, s[0:1]
	v_add_u32_e32 v16, 0xb0, v146
	s_waitcnt lgkmcnt(0)
	v_ashrrev_i32_e32 v17, 31, v16
	v_lshlrev_b64 v[18:19], 11, v[16:17]
	v_lshl_add_u64 v[18:19], s[18:19], 0, v[18:19]
	v_lshl_add_u64 v[22:23], v[144:145], 1, v[18:19]
	global_load_dwordx4 v[18:21], v[22:23], off
	s_waitcnt vmcnt(0) lgkmcnt(0)
	v_lshlrev_b32_e32 v24, 16, v18
	v_and_b32_e32 v25, 0xffff0000, v18
	v_lshlrev_b32_e32 v18, 16, v19
	v_and_b32_e32 v19, 0xffff0000, v19
	v_lshlrev_b32_e32 v26, 16, v20
	v_and_b32_e32 v27, 0xffff0000, v20
	v_lshlrev_b32_e32 v20, 16, v21
	v_and_b32_e32 v21, 0xffff0000, v21
	v_pk_add_f32 v[18:19], v[14:15], v[18:19]
	v_pk_add_f32 v[24:25], v[12:13], v[24:25]
	v_pk_add_f32 v[20:21], v[10:11], v[20:21]
	v_pk_add_f32 v[26:27], v[8:9], v[26:27]
	v_cvt_pk_bf16_f32 v8, v24, v25
	v_cvt_pk_bf16_f32 v9, v18, v19
	v_mul_f32_e32 v25, v25, v25
	v_cvt_pk_bf16_f32 v10, v26, v27
	v_cvt_pk_bf16_f32 v11, v20, v21
	global_load_dwordx4 v[12:15], v[22:23], off offset:256
	v_mul_f32_e32 v19, v19, v19
	v_mul_f32_e32 v27, v27, v27
	v_mul_f32_e32 v21, v21, v21
	v_fmac_f32_e32 v25, v24, v24
	v_fmac_f32_e32 v19, v18, v18
	v_fmac_f32_e32 v27, v26, v26
	v_fmac_f32_e32 v21, v20, v20
	v_add_f32_e32 v18, v25, v19
	v_add_f32_e32 v19, v27, v21
	v_add_f32_e32 v24, v18, v19
	global_store_dwordx4 v[22:23], v[8:11], off
	s_waitcnt vmcnt(0) lgkmcnt(0)
	v_lshlrev_b32_e32 v18, 16, v12
	v_and_b32_e32 v19, 0xffff0000, v12
	v_lshlrev_b32_e32 v12, 16, v13
	v_and_b32_e32 v13, 0xffff0000, v13
	v_lshlrev_b32_e32 v20, 16, v14
	v_and_b32_e32 v21, 0xffff0000, v14
	v_lshlrev_b32_e32 v14, 16, v15
	v_and_b32_e32 v15, 0xffff0000, v15
	v_pk_add_f32 v[6:7], v[6:7], v[12:13]
	v_pk_add_f32 v[4:5], v[4:5], v[18:19]
	v_pk_add_f32 v[12:13], v[2:3], v[14:15]
	v_pk_add_f32 v[14:15], v[0:1], v[20:21]
	v_mul_f32_e32 v0, v5, v5
	v_mul_f32_e32 v1, v7, v7
	v_mul_f32_e32 v2, v15, v15
	v_mul_f32_e32 v3, v13, v13
	v_fmac_f32_e32 v0, v4, v4
	v_fmac_f32_e32 v1, v6, v6
	v_fmac_f32_e32 v2, v14, v14
	v_fmac_f32_e32 v3, v12, v12
	v_add_f32_e32 v0, v0, v1
	v_add_f32_e32 v1, v2, v3
	v_add_f32_e32 v0, v0, v1
	v_add_f32_e32 v0, v24, v0
	ds_bpermute_b32 v1, v151, v0
	v_cvt_pk_bf16_f32 v2, v4, v5
	v_cvt_pk_bf16_f32 v3, v6, v7
	v_cvt_pk_bf16_f32 v4, v14, v15
	v_cvt_pk_bf16_f32 v5, v12, v13
	s_waitcnt lgkmcnt(0)
	v_add_f32_e32 v0, v0, v1
	ds_bpermute_b32 v1, v152, v0
	global_store_dwordx4 v[22:23], v[2:5], off offset:256
	s_and_saveexec_b64 s[0:1], s[2:3]
	s_cbranch_execz .LBB0_1186
	v_lshlrev_b64 v[2:3], 6, v[16:17]
	v_lshl_add_u64 v[2:3], s[20:21], 0, v[2:3]
	v_lshl_add_u64 v[2:3], s[6:7], 2, v[2:3]
	s_lshl_b32 s14, s48, 2
	v_lshl_add_u64 v[2:3], v[2:3], 0, s[14:15]
	s_waitcnt lgkmcnt(0)
	v_add_f32_e32 v0, v0, v1
	global_store_dword v[2:3], v0, off

.LBB0_1271:
	v_lshl_add_u32 v148, s28, 8, v144
	v_and_b32_e32 v149, 0x7cf, v148
	v_lshl_add_u32 v149, v149, 2, s51
	ds_read_b32 v149, v149
	v_pk_mul_f32 v[124:125], v[124:125], v[116:117]
	v_pk_mul_f32 v[126:127], v[126:127], v[118:119]
	v_pk_mul_f32 v[120:121], v[120:121], v[112:113]
	v_pk_mul_f32 v[122:123], v[122:123], v[114:115]
	s_waitcnt lgkmcnt(0)
	v_mul_f32_e32 v152, 0xbfb8aa3b, v149
	v_pk_mul_f32 v[116:117], v[116:117], v[152:153] op_sel_hi:[1,0]
	v_pk_mul_f32 v[118:119], v[118:119], v[152:153] op_sel_hi:[1,0]
	v_exp_f32_e32 v116, v116
	v_exp_f32_e32 v117, v117
	v_pk_mul_f32 v[112:113], v[112:113], v[152:153] op_sel_hi:[1,0]
	v_exp_f32_e32 v118, v118
	v_exp_f32_e32 v119, v119
	v_exp_f32_e32 v112, v112
	v_exp_f32_e32 v113, v113
	v_pk_mul_f32 v[114:115], v[114:115], v[152:153] op_sel_hi:[1,0]
	v_pk_add_f32 v[116:117], v[116:117], 1.0 op_sel_hi:[1,0]
	v_exp_f32_e32 v114, v114
	v_exp_f32_e32 v115, v115
	v_rcp_f32_e32 v116, v116
	v_rcp_f32_e32 v117, v117
	v_pk_add_f32 v[118:119], v[118:119], 1.0 op_sel_hi:[1,0]
	v_pk_add_f32 v[112:113], v[112:113], 1.0 op_sel_hi:[1,0]
	v_rcp_f32_e32 v118, v118
	v_rcp_f32_e32 v119, v119
	v_rcp_f32_e32 v112, v112
	v_rcp_f32_e32 v113, v113
	v_pk_add_f32 v[114:115], v[114:115], 1.0 op_sel_hi:[1,0]
	v_mul_f32_e32 v154, v149, v149
	v_rcp_f32_e32 v114, v114
	v_rcp_f32_e32 v115, v115
	v_pk_mul_f32 v[124:125], v[124:125], v[154:155] op_sel_hi:[1,0]
	v_pk_mul_f32 v[120:121], v[120:121], v[154:155] op_sel_hi:[1,0]
	v_pk_mul_f32 v[116:117], v[124:125], v[116:117]
	v_pk_mul_f32 v[124:125], v[126:127], v[154:155] op_sel_hi:[1,0]
	v_lshl_add_u32 v150, s57, 7, v146
	v_pk_mul_f32 v[118:119], v[124:125], v[118:119]
	v_pk_mul_f32 v[112:113], v[120:121], v[112:113]
	v_pk_mul_f32 v[120:121], v[122:123], v[154:155] op_sel_hi:[1,0]
	v_ashrrev_i32_e32 v151, 31, v150
	v_pk_mul_f32 v[114:115], v[120:121], v[114:115]
	v_cvt_pk_bf16_f32 v116, v116, v117
	v_cvt_pk_bf16_f32 v117, v118, v119
	v_cvt_pk_bf16_f32 v118, v112, v113
	v_mov_b64_e32 v[112:113], s[14:15]
	v_cvt_pk_bf16_f32 v119, v114, v115
	v_mad_i64_i32 v[120:121], s[0:1], v148, s52, v[112:113]
	v_lshlrev_b64 v[114:115], 1, v[150:151]
	v_lshl_add_u64 v[120:121], v[120:121], 0, v[114:115]
	global_store_dwordx4 v[120:121], v[116:119], off
	v_pk_mul_f32 v[108:109], v[108:109], v[100:101]
	v_pk_mul_f32 v[104:105], v[104:105], v[96:97]
	v_bitop3_b32 v116, v148, s53, 16 bitop3:0xc8
	v_lshl_add_u32 v116, v116, 2, s51
	ds_read_b32 v117, v116
	v_pk_mul_f32 v[106:107], v[106:107], v[98:99]
	v_pk_mul_f32 v[110:111], v[110:111], v[102:103]
	v_or_b32_e32 v119, 16, v148
	v_pk_mul_f32 v[92:93], v[92:93], v[84:85]
	s_waitcnt lgkmcnt(0)
	v_mul_f32_e32 v116, 0xbfb8aa3b, v117
	v_pk_mul_f32 v[100:101], v[100:101], v[116:117] op_sel_hi:[1,0]
	v_pk_mul_f32 v[96:97], v[96:97], v[116:117] op_sel_hi:[1,0]
	v_exp_f32_e32 v100, v100
	v_exp_f32_e32 v101, v101
	v_exp_f32_e32 v96, v96
	v_exp_f32_e32 v97, v97
	v_pk_mul_f32 v[98:99], v[98:99], v[116:117] op_sel_hi:[1,0]
	v_pk_mul_f32 v[102:103], v[102:103], v[116:117] op_sel_hi:[1,0]
	v_exp_f32_e32 v98, v98
	v_exp_f32_e32 v99, v99
	v_exp_f32_e32 v102, v102
	v_exp_f32_e32 v103, v103
	v_pk_add_f32 v[100:101], v[100:101], 1.0 op_sel_hi:[1,0]
	v_pk_add_f32 v[96:97], v[96:97], 1.0 op_sel_hi:[1,0]
	v_rcp_f32_e32 v100, v100
	v_rcp_f32_e32 v101, v101
	v_rcp_f32_e32 v96, v96
	v_rcp_f32_e32 v97, v97
	v_pk_add_f32 v[98:99], v[98:99], 1.0 op_sel_hi:[1,0]
	v_mul_f32_e32 v118, v117, v117
	v_rcp_f32_e32 v98, v98
	v_rcp_f32_e32 v99, v99
	v_pk_add_f32 v[102:103], v[102:103], 1.0 op_sel_hi:[1,0]
	v_pk_mul_f32 v[108:109], v[108:109], v[118:119] op_sel_hi:[1,0]
	v_rcp_f32_e32 v102, v102
	v_rcp_f32_e32 v103, v103
	v_pk_mul_f32 v[104:105], v[104:105], v[118:119] op_sel_hi:[1,0]
	v_pk_mul_f32 v[100:101], v[108:109], v[100:101]
	v_pk_mul_f32 v[104:105], v[104:105], v[96:97]
	v_pk_mul_f32 v[96:97], v[106:107], v[118:119] op_sel_hi:[1,0]
	v_pk_mul_f32 v[108:109], v[110:111], v[118:119] op_sel_hi:[1,0]
	v_pk_mul_f32 v[106:107], v[96:97], v[98:99]
	v_cvt_pk_bf16_f32 v96, v100, v101
	v_mad_i64_i32 v[100:101], s[0:1], v119, s52, v[112:113]
	v_lshl_add_u64 v[100:101], v[100:101], 0, v[114:115]
	v_pk_mul_f32 v[102:103], v[108:109], v[102:103]
	v_pk_mul_f32 v[88:89], v[88:89], v[80:81]
	v_cvt_pk_bf16_f32 v97, v102, v103
	v_cvt_pk_bf16_f32 v98, v104, v105
	v_cvt_pk_bf16_f32 v99, v106, v107
	global_store_dwordx4 v[100:101], v[96:99], off
	v_pk_mul_f32 v[90:91], v[90:91], v[82:83]
	v_pk_mul_f32 v[94:95], v[94:95], v[86:87]
	v_bitop3_b32 v96, v148, s54, 32 bitop3:0xc8
	v_lshl_add_u32 v96, v96, 2, s51
	ds_read_b32 v97, v96
	v_or_b32_e32 v99, 32, v148
	v_pk_mul_f32 v[76:77], v[76:77], v[64:65]
	v_pk_mul_f32 v[72:73], v[72:73], v[56:57]
	v_pk_mul_f32 v[74:75], v[74:75], v[58:59]
	s_waitcnt lgkmcnt(0)
	v_mul_f32_e32 v96, 0xbfb8aa3b, v97
	v_pk_mul_f32 v[84:85], v[84:85], v[96:97] op_sel_hi:[1,0]
	v_pk_mul_f32 v[80:81], v[80:81], v[96:97] op_sel_hi:[1,0]
	v_exp_f32_e32 v84, v84
	v_exp_f32_e32 v85, v85
	v_exp_f32_e32 v80, v80
	v_exp_f32_e32 v81, v81
	v_pk_mul_f32 v[82:83], v[82:83], v[96:97] op_sel_hi:[1,0]
	v_pk_mul_f32 v[86:87], v[86:87], v[96:97] op_sel_hi:[1,0]
	v_exp_f32_e32 v82, v82
	v_exp_f32_e32 v83, v83
	v_exp_f32_e32 v86, v86
	v_exp_f32_e32 v87, v87
	v_pk_add_f32 v[84:85], v[84:85], 1.0 op_sel_hi:[1,0]
	v_pk_add_f32 v[80:81], v[80:81], 1.0 op_sel_hi:[1,0]
	v_rcp_f32_e32 v84, v84
	v_rcp_f32_e32 v85, v85
	v_rcp_f32_e32 v80, v80
	v_rcp_f32_e32 v81, v81
	v_pk_add_f32 v[82:83], v[82:83], 1.0 op_sel_hi:[1,0]
	v_mul_f32_e32 v98, v97, v97
	v_rcp_f32_e32 v82, v82
	v_rcp_f32_e32 v83, v83
	v_pk_add_f32 v[86:87], v[86:87], 1.0 op_sel_hi:[1,0]
	v_pk_mul_f32 v[92:93], v[92:93], v[98:99] op_sel_hi:[1,0]
	v_rcp_f32_e32 v86, v86
	v_rcp_f32_e32 v87, v87
	v_pk_mul_f32 v[88:89], v[88:89], v[98:99] op_sel_hi:[1,0]
	v_pk_mul_f32 v[84:85], v[92:93], v[84:85]
	v_pk_mul_f32 v[88:89], v[88:89], v[80:81]
	v_pk_mul_f32 v[80:81], v[90:91], v[98:99] op_sel_hi:[1,0]
	v_pk_mul_f32 v[92:93], v[94:95], v[98:99] op_sel_hi:[1,0]
	v_pk_mul_f32 v[90:91], v[80:81], v[82:83]
	v_cvt_pk_bf16_f32 v80, v84, v85
	v_mad_i64_i32 v[84:85], s[0:1], v99, s52, v[112:113]
	v_lshl_add_u64 v[84:85], v[84:85], 0, v[114:115]
	v_pk_mul_f32 v[86:87], v[92:93], v[86:87]
	v_pk_mul_f32 v[78:79], v[78:79], v[66:67]
	v_cvt_pk_bf16_f32 v81, v86, v87
	v_cvt_pk_bf16_f32 v82, v88, v89
	v_cvt_pk_bf16_f32 v83, v90, v91
	global_store_dwordx4 v[84:85], v[80:83], off
	v_pk_mul_f32 v[60:61], v[60:61], v[48:49]
	v_pk_mul_f32 v[62:63], v[62:63], v[50:51]
	v_bitop3_b32 v80, v148, s55, 48 bitop3:0xc8
	v_lshl_add_u32 v80, v80, 2, s51
	ds_read_b32 v81, v80
	v_or_b32_e32 v83, 48, v148
	v_pk_mul_f32 v[44:45], v[44:45], v[36:37]
	v_pk_mul_f32 v[40:41], v[40:41], v[32:33]
	v_pk_mul_f32 v[42:43], v[42:43], v[34:35]
	s_waitcnt lgkmcnt(0)
	v_mul_f32_e32 v80, 0xbfb8aa3b, v81
	v_pk_mul_f32 v[64:65], v[64:65], v[80:81] op_sel_hi:[1,0]
	v_pk_mul_f32 v[56:57], v[56:57], v[80:81] op_sel_hi:[1,0]
	v_exp_f32_e32 v64, v64
	v_exp_f32_e32 v65, v65
	v_exp_f32_e32 v56, v56
	v_exp_f32_e32 v57, v57
	v_pk_mul_f32 v[58:59], v[58:59], v[80:81] op_sel_hi:[1,0]
	v_pk_mul_f32 v[66:67], v[66:67], v[80:81] op_sel_hi:[1,0]
	v_exp_f32_e32 v58, v58
	v_exp_f32_e32 v59, v59
	v_exp_f32_e32 v66, v66
	v_exp_f32_e32 v67, v67
	v_pk_add_f32 v[64:65], v[64:65], 1.0 op_sel_hi:[1,0]
	v_pk_add_f32 v[56:57], v[56:57], 1.0 op_sel_hi:[1,0]
	v_rcp_f32_e32 v64, v64
	v_rcp_f32_e32 v65, v65
	v_rcp_f32_e32 v56, v56
	v_rcp_f32_e32 v57, v57
	v_pk_add_f32 v[58:59], v[58:59], 1.0 op_sel_hi:[1,0]
	v_pk_add_f32 v[66:67], v[66:67], 1.0 op_sel_hi:[1,0]
	v_rcp_f32_e32 v58, v58
	v_rcp_f32_e32 v59, v59
	v_mul_f32_e32 v82, v81, v81
	v_rcp_f32_e32 v66, v66
	v_rcp_f32_e32 v67, v67
	v_pk_mul_f32 v[76:77], v[76:77], v[82:83] op_sel_hi:[1,0]
	v_pk_mul_f32 v[72:73], v[72:73], v[82:83] op_sel_hi:[1,0]
	v_pk_mul_f32 v[64:65], v[76:77], v[64:65]
	v_pk_mul_f32 v[72:73], v[72:73], v[56:57]
	v_pk_mul_f32 v[56:57], v[74:75], v[82:83] op_sel_hi:[1,0]
	v_pk_mul_f32 v[76:77], v[78:79], v[82:83] op_sel_hi:[1,0]
	v_pk_mul_f32 v[74:75], v[56:57], v[58:59]
	v_cvt_pk_bf16_f32 v56, v64, v65
	v_mad_i64_i32 v[64:65], s[0:1], v83, s52, v[112:113]
	v_pk_mul_f32 v[66:67], v[76:77], v[66:67]
	v_lshl_add_u64 v[64:65], v[64:65], 0, v[114:115]
	v_cvt_pk_bf16_f32 v57, v66, v67
	v_cvt_pk_bf16_f32 v58, v72, v73
	v_add_u32_e32 v72, 0x80, v148
	v_cvt_pk_bf16_f32 v59, v74, v75
	global_store_dwordx4 v[64:65], v[56:59], off
	v_pk_mul_f32 v[66:67], v[68:69], v[52:53]
	v_pk_mul_f32 v[64:65], v[70:71], v[54:55]
	v_and_b32_e32 v56, 0x7cf, v72
	v_lshl_add_u32 v56, v56, 2, s51
	ds_read_b32 v57, v56
	v_pk_mul_f32 v[46:47], v[46:47], v[38:39]
	v_pk_mul_f32 v[28:29], v[28:29], v[20:21]
	v_pk_mul_f32 v[24:25], v[24:25], v[12:13]
	v_pk_mul_f32 v[26:27], v[26:27], v[14:15]
	s_waitcnt lgkmcnt(0)
	v_mul_f32_e32 v56, 0xbfb8aa3b, v57
	v_pk_mul_f32 v[52:53], v[52:53], v[56:57] op_sel_hi:[1,0]
	v_pk_mul_f32 v[48:49], v[48:49], v[56:57] op_sel_hi:[1,0]
	v_exp_f32_e32 v52, v52
	v_exp_f32_e32 v53, v53
	v_exp_f32_e32 v48, v48
	v_exp_f32_e32 v49, v49
	v_pk_mul_f32 v[50:51], v[50:51], v[56:57] op_sel_hi:[1,0]
	v_pk_mul_f32 v[54:55], v[54:55], v[56:57] op_sel_hi:[1,0]
	v_exp_f32_e32 v50, v50
	v_exp_f32_e32 v51, v51
	v_exp_f32_e32 v54, v54
	v_exp_f32_e32 v55, v55
	v_pk_add_f32 v[52:53], v[52:53], 1.0 op_sel_hi:[1,0]
	v_pk_add_f32 v[48:49], v[48:49], 1.0 op_sel_hi:[1,0]
	v_rcp_f32_e32 v52, v52
	v_rcp_f32_e32 v53, v53
	v_rcp_f32_e32 v48, v48
	v_rcp_f32_e32 v49, v49
	v_pk_add_f32 v[50:51], v[50:51], 1.0 op_sel_hi:[1,0]
	v_pk_add_f32 v[54:55], v[54:55], 1.0 op_sel_hi:[1,0]
	v_rcp_f32_e32 v50, v50
	v_rcp_f32_e32 v51, v51
	v_mul_f32_e32 v58, v57, v57
	v_rcp_f32_e32 v54, v54
	v_rcp_f32_e32 v55, v55
	v_pk_mul_f32 v[66:67], v[66:67], v[58:59] op_sel_hi:[1,0]
	v_pk_mul_f32 v[56:57], v[60:61], v[58:59] op_sel_hi:[1,0]
	v_pk_mul_f32 v[52:53], v[66:67], v[52:53]
	v_pk_mul_f32 v[56:57], v[56:57], v[48:49]
	v_pk_mul_f32 v[48:49], v[62:63], v[58:59] op_sel_hi:[1,0]
	v_pk_mul_f32 v[64:65], v[64:65], v[58:59] op_sel_hi:[1,0]
	v_pk_mul_f32 v[58:59], v[48:49], v[50:51]
	v_cvt_pk_bf16_f32 v48, v52, v53
	v_mad_i64_i32 v[52:53], s[0:1], v72, s52, v[112:113]
	v_pk_mul_f32 v[54:55], v[64:65], v[54:55]
	v_lshl_add_u64 v[52:53], v[52:53], 0, v[114:115]
	v_cvt_pk_bf16_f32 v49, v54, v55
	v_cvt_pk_bf16_f32 v50, v56, v57
	v_cvt_pk_bf16_f32 v51, v58, v59
	global_store_dwordx4 v[52:53], v[48:51], off
	v_pk_mul_f32 v[30:31], v[30:31], v[22:23]
	v_pk_mul_f32 v[16:17], v[16:17], v[4:5]
	v_add_u32_e32 v49, 0x90, v148
	v_and_b32_e32 v48, 0x7df, v49
	v_lshl_add_u32 v48, v48, 2, s51
	ds_read_b32 v50, v48
	v_pk_mul_f32 v[10:11], v[10:11], v[2:3]
	v_pk_mul_f32 v[8:9], v[8:9], v[0:1]
	s_and_b64 vcc, exec, s[2:3]
	s_waitcnt lgkmcnt(0)
	v_mul_f32_e32 v48, 0xbfb8aa3b, v50
	v_pk_mul_f32 v[36:37], v[36:37], v[48:49] op_sel_hi:[1,0]
	v_pk_mul_f32 v[32:33], v[32:33], v[48:49] op_sel_hi:[1,0]
	v_exp_f32_e32 v36, v36
	v_exp_f32_e32 v37, v37
	v_exp_f32_e32 v32, v32
	v_exp_f32_e32 v33, v33
	v_pk_mul_f32 v[34:35], v[34:35], v[48:49] op_sel_hi:[1,0]
	v_pk_mul_f32 v[38:39], v[38:39], v[48:49] op_sel_hi:[1,0]
	v_exp_f32_e32 v34, v34
	v_exp_f32_e32 v35, v35
	v_exp_f32_e32 v38, v38
	v_exp_f32_e32 v39, v39
	v_pk_add_f32 v[36:37], v[36:37], 1.0 op_sel_hi:[1,0]
	v_pk_add_f32 v[32:33], v[32:33], 1.0 op_sel_hi:[1,0]
	v_rcp_f32_e32 v36, v36
	v_rcp_f32_e32 v37, v37
	v_rcp_f32_e32 v32, v32
	v_rcp_f32_e32 v33, v33
	v_pk_add_f32 v[34:35], v[34:35], 1.0 op_sel_hi:[1,0]
	v_pk_add_f32 v[38:39], v[38:39], 1.0 op_sel_hi:[1,0]
	v_rcp_f32_e32 v34, v34
	v_rcp_f32_e32 v35, v35
	v_mul_f32_e32 v50, v50, v50
	v_rcp_f32_e32 v38, v38
	v_rcp_f32_e32 v39, v39
	v_pk_mul_f32 v[44:45], v[44:45], v[50:51] op_sel_hi:[1,0]
	v_pk_mul_f32 v[40:41], v[40:41], v[50:51] op_sel_hi:[1,0]
	v_pk_mul_f32 v[36:37], v[44:45], v[36:37]
	v_pk_mul_f32 v[40:41], v[40:41], v[32:33]
	v_pk_mul_f32 v[32:33], v[42:43], v[50:51] op_sel_hi:[1,0]
	v_pk_mul_f32 v[44:45], v[46:47], v[50:51] op_sel_hi:[1,0]
	v_pk_mul_f32 v[42:43], v[32:33], v[34:35]
	v_cvt_pk_bf16_f32 v32, v36, v37
	v_mad_i64_i32 v[36:37], s[0:1], v49, s52, v[112:113]
	v_pk_mul_f32 v[38:39], v[44:45], v[38:39]
	v_lshl_add_u64 v[36:37], v[36:37], 0, v[114:115]
	v_cvt_pk_bf16_f32 v33, v38, v39
	v_cvt_pk_bf16_f32 v34, v40, v41
	v_cvt_pk_bf16_f32 v35, v42, v43
	global_store_dwordx4 v[36:37], v[32:35], off
	s_nop 1
	v_add_u32_e32 v33, 0xa0, v148
	v_and_b32_e32 v32, 0x7ef, v33
	v_lshl_add_u32 v32, v32, 2, s51
	ds_read_b32 v34, v32
	s_waitcnt lgkmcnt(0)
	v_mul_f32_e32 v32, 0xbfb8aa3b, v34
	v_pk_mul_f32 v[20:21], v[20:21], v[32:33] op_sel_hi:[1,0]
	v_pk_mul_f32 v[12:13], v[12:13], v[32:33] op_sel_hi:[1,0]
	v_exp_f32_e32 v20, v20
	v_exp_f32_e32 v21, v21
	v_exp_f32_e32 v12, v12
	v_exp_f32_e32 v13, v13
	v_pk_mul_f32 v[14:15], v[14:15], v[32:33] op_sel_hi:[1,0]
	v_pk_mul_f32 v[22:23], v[22:23], v[32:33] op_sel_hi:[1,0]
	v_exp_f32_e32 v14, v14
	v_exp_f32_e32 v15, v15
	v_exp_f32_e32 v22, v22
	v_exp_f32_e32 v23, v23
	v_pk_add_f32 v[20:21], v[20:21], 1.0 op_sel_hi:[1,0]
	v_pk_add_f32 v[12:13], v[12:13], 1.0 op_sel_hi:[1,0]
	v_rcp_f32_e32 v20, v20
	v_rcp_f32_e32 v21, v21
	v_rcp_f32_e32 v12, v12
	v_rcp_f32_e32 v13, v13
	v_pk_add_f32 v[14:15], v[14:15], 1.0 op_sel_hi:[1,0]
	v_pk_add_f32 v[22:23], v[22:23], 1.0 op_sel_hi:[1,0]
	v_rcp_f32_e32 v14, v14
	v_rcp_f32_e32 v15, v15
	v_mul_f32_e32 v34, v34, v34
	v_rcp_f32_e32 v22, v22
	v_rcp_f32_e32 v23, v23
	v_pk_mul_f32 v[28:29], v[28:29], v[34:35] op_sel_hi:[1,0]
	v_pk_mul_f32 v[24:25], v[24:25], v[34:35] op_sel_hi:[1,0]
	v_pk_mul_f32 v[20:21], v[28:29], v[20:21]
	v_pk_mul_f32 v[24:25], v[24:25], v[12:13]
	v_pk_mul_f32 v[12:13], v[26:27], v[34:35] op_sel_hi:[1,0]
	v_pk_mul_f32 v[28:29], v[30:31], v[34:35] op_sel_hi:[1,0]
	v_pk_mul_f32 v[26:27], v[12:13], v[14:15]
	v_cvt_pk_bf16_f32 v12, v20, v21
	v_mad_i64_i32 v[20:21], s[0:1], v33, s52, v[112:113]
	v_pk_mul_f32 v[22:23], v[28:29], v[22:23]
	v_lshl_add_u64 v[20:21], v[20:21], 0, v[114:115]
	v_cvt_pk_bf16_f32 v13, v22, v23
	v_cvt_pk_bf16_f32 v14, v24, v25
	v_cvt_pk_bf16_f32 v15, v26, v27
	global_store_dwordx4 v[20:21], v[12:15], off
	s_nop 1
	v_add_u32_e32 v13, 0xb0, v148
	v_and_b32_e32 v12, 0x7ff, v13
	v_lshl_add_u32 v12, v12, 2, s51
	ds_read_b32 v20, v12
	v_pk_mul_f32 v[14:15], v[18:19], v[6:7]
	s_waitcnt lgkmcnt(0)
	v_mul_f32_e32 v18, 0xbfb8aa3b, v20
	v_pk_mul_f32 v[6:7], v[6:7], v[18:19] op_sel_hi:[1,0]
	v_pk_mul_f32 v[4:5], v[4:5], v[18:19] op_sel_hi:[1,0]
	v_exp_f32_e32 v6, v6
	v_exp_f32_e32 v7, v7
	v_pk_mul_f32 v[2:3], v[2:3], v[18:19] op_sel_hi:[1,0]
	v_pk_mul_f32 v[0:1], v[0:1], v[18:19] op_sel_hi:[1,0]
	v_exp_f32_e32 v4, v4
	v_exp_f32_e32 v5, v5
	v_exp_f32_e32 v2, v2
	v_exp_f32_e32 v3, v3
	v_exp_f32_e32 v0, v0
	v_exp_f32_e32 v1, v1
	v_pk_add_f32 v[6:7], v[6:7], 1.0 op_sel_hi:[1,0]
	v_pk_add_f32 v[4:5], v[4:5], 1.0 op_sel_hi:[1,0]
	v_rcp_f32_e32 v6, v6
	v_rcp_f32_e32 v7, v7
	v_pk_add_f32 v[2:3], v[2:3], 1.0 op_sel_hi:[1,0]
	v_pk_add_f32 v[0:1], v[0:1], 1.0 op_sel_hi:[1,0]
	v_rcp_f32_e32 v4, v4
	v_rcp_f32_e32 v5, v5
	v_rcp_f32_e32 v2, v2
	v_rcp_f32_e32 v3, v3
	v_rcp_f32_e32 v0, v0
	v_rcp_f32_e32 v1, v1
	v_mul_f32_e32 v12, v20, v20
	v_pk_mul_f32 v[14:15], v[14:15], v[12:13] op_sel_hi:[1,0]
	v_pk_mul_f32 v[10:11], v[10:11], v[12:13] op_sel_hi:[1,0]
	v_pk_mul_f32 v[6:7], v[14:15], v[6:7]
	v_pk_mul_f32 v[14:15], v[16:17], v[12:13] op_sel_hi:[1,0]
	v_pk_mul_f32 v[8:9], v[8:9], v[12:13] op_sel_hi:[1,0]
	v_pk_mul_f32 v[4:5], v[14:15], v[4:5]
	v_pk_mul_f32 v[2:3], v[10:11], v[2:3]
	v_pk_mul_f32 v[0:1], v[8:9], v[0:1]
	s_nop 0
	v_cvt_pk_bf16_f32 v0, v0, v1
	v_cvt_pk_bf16_f32 v1, v2, v3
	v_cvt_pk_bf16_f32 v2, v4, v5
	v_mad_i64_i32 v[4:5], s[0:1], v13, s52, v[112:113]
	v_cvt_pk_bf16_f32 v3, v6, v7
	v_lshl_add_u64 v[4:5], v[4:5], 0, v[114:115]
	s_mov_b64 s[0:1], -1
	global_store_dwordx4 v[4:5], v[0:3], off
	s_cbranch_vccnz .LBB0_1261
	s_andn2_b64 vcc, exec, s[12:13]
	v_pk_mov_b32 v[116:117], 0, 0
	v_pk_mov_b32 v[118:119], 0, 0
	v_pk_mov_b32 v[112:113], 0, 0
	v_pk_mov_b32 v[114:115], 0, 0
	v_pk_mov_b32 v[100:101], 0, 0
	v_pk_mov_b32 v[102:103], 0, 0
	v_pk_mov_b32 v[96:97], 0, 0
	v_pk_mov_b32 v[98:99], 0, 0
	v_pk_mov_b32 v[84:85], 0, 0
	v_pk_mov_b32 v[86:87], 0, 0
	v_pk_mov_b32 v[80:81], 0, 0
	v_pk_mov_b32 v[82:83], 0, 0
	v_pk_mov_b32 v[64:65], 0, 0
	v_pk_mov_b32 v[66:67], 0, 0
	v_pk_mov_b32 v[56:57], 0, 0
	v_pk_mov_b32 v[58:59], 0, 0
	v_pk_mov_b32 v[124:125], 0, 0
	v_pk_mov_b32 v[126:127], 0, 0
	v_pk_mov_b32 v[120:121], 0, 0
	v_pk_mov_b32 v[122:123], 0, 0
	v_pk_mov_b32 v[108:109], 0, 0
	v_pk_mov_b32 v[110:111], 0, 0
	v_pk_mov_b32 v[104:105], 0, 0
	v_pk_mov_b32 v[106:107], 0, 0
	v_pk_mov_b32 v[92:93], 0, 0
	v_pk_mov_b32 v[94:95], 0, 0
	v_pk_mov_b32 v[88:89], 0, 0
	v_pk_mov_b32 v[90:91], 0, 0
	v_pk_mov_b32 v[76:77], 0, 0
	v_pk_mov_b32 v[78:79], 0, 0
	v_pk_mov_b32 v[72:73], 0, 0
	v_pk_mov_b32 v[74:75], 0, 0
	v_pk_mov_b32 v[52:53], 0, 0
	v_pk_mov_b32 v[54:55], 0, 0
	v_pk_mov_b32 v[48:49], 0, 0
	v_pk_mov_b32 v[50:51], 0, 0
	v_pk_mov_b32 v[36:37], 0, 0
	v_pk_mov_b32 v[38:39], 0, 0
	v_pk_mov_b32 v[32:33], 0, 0
	v_pk_mov_b32 v[34:35], 0, 0
	v_pk_mov_b32 v[20:21], 0, 0
	v_pk_mov_b32 v[22:23], 0, 0
	v_pk_mov_b32 v[12:13], 0, 0
	v_pk_mov_b32 v[14:15], 0, 0
	v_pk_mov_b32 v[0:1], 0, 0
	v_pk_mov_b32 v[2:3], 0, 0
	v_pk_mov_b32 v[4:5], 0, 0
	v_pk_mov_b32 v[6:7], 0, 0
	v_pk_mov_b32 v[68:69], 0, 0
	v_pk_mov_b32 v[70:71], 0, 0
	v_pk_mov_b32 v[60:61], 0, 0
	v_pk_mov_b32 v[62:63], 0, 0
	v_pk_mov_b32 v[44:45], 0, 0
	v_pk_mov_b32 v[46:47], 0, 0
	v_pk_mov_b32 v[40:41], 0, 0
	v_pk_mov_b32 v[42:43], 0, 0
	v_pk_mov_b32 v[28:29], 0, 0
	v_pk_mov_b32 v[30:31], 0, 0
	v_pk_mov_b32 v[24:25], 0, 0
	v_pk_mov_b32 v[26:27], 0, 0
	v_pk_mov_b32 v[8:9], 0, 0
	v_pk_mov_b32 v[10:11], 0, 0
	v_pk_mov_b32 v[16:17], 0, 0
	v_pk_mov_b32 v[18:19], 0, 0
	s_cbranch_vccnz .LBB0_1260
	s_barrier
	s_branch .LBB0_1260

.LBB0_1368:
	v_lshl_add_u32 v216, s65, 8, v229
	v_lshl_add_u32 v218, s16, 8, v231
	v_ashrrev_i32_e32 v219, 31, v218
	v_ashrrev_i32_e32 v217, 31, v216
	v_lshl_add_u64 v[128:129], v[218:219], 1, s[20:21]
	v_lshlrev_b64 v[130:131], 11, v[216:217]
	v_lshl_add_u64 v[130:131], v[128:129], 0, v[130:131]
	global_load_dwordx4 v[220:223], v[130:131], off
	global_load_dwordx4 v[224:227], v[130:131], off offset:256
	v_or_b32_e32 v214, 16, v216
	v_or_b32_e32 v212, 32, v216
	v_or_b32_e32 v210, 48, v216
	v_add_u32_e32 v208, 0x80, v216
	v_add_u32_e32 v206, 0x90, v216
	v_add_u32_e32 v204, 0xa0, v216
	v_add_u32_e32 v202, 0xb0, v216
	v_ashrrev_i32_e32 v215, 31, v214
	v_ashrrev_i32_e32 v213, 31, v212
	v_ashrrev_i32_e32 v211, 31, v210
	v_ashrrev_i32_e32 v209, 31, v208
	v_ashrrev_i32_e32 v207, 31, v206
	v_ashrrev_i32_e32 v205, 31, v204
	v_ashrrev_i32_e32 v203, 31, v202
	v_lshlrev_b64 v[130:131], 11, v[214:215]
	v_lshlrev_b64 v[132:133], 11, v[212:213]
	v_lshlrev_b64 v[134:135], 11, v[210:211]
	v_lshlrev_b64 v[136:137], 11, v[208:209]
	v_lshlrev_b64 v[138:139], 11, v[206:207]
	v_lshlrev_b64 v[140:141], 11, v[204:205]
	v_lshlrev_b64 v[142:143], 11, v[202:203]
	v_lshl_add_u64 v[130:131], v[128:129], 0, v[130:131]
	v_lshl_add_u64 v[132:133], v[128:129], 0, v[132:133]
	v_lshl_add_u64 v[134:135], v[128:129], 0, v[134:135]
	v_lshl_add_u64 v[136:137], v[128:129], 0, v[136:137]
	v_lshl_add_u64 v[138:139], v[128:129], 0, v[138:139]
	v_lshl_add_u64 v[236:237], v[128:129], 0, v[140:141]
	v_lshl_add_u64 v[128:129], v[128:129], 0, v[142:143]
	global_load_dwordx4 v[180:183], v[130:131], off
	global_load_dwordx4 v[176:179], v[130:131], off offset:256
	global_load_dwordx4 v[172:175], v[132:133], off
	global_load_dwordx4 v[168:171], v[132:133], off offset:256
	global_load_dwordx4 v[164:167], v[134:135], off
	global_load_dwordx4 v[160:163], v[134:135], off offset:256
	global_load_dwordx4 v[156:159], v[136:137], off
	global_load_dwordx4 v[152:155], v[136:137], off offset:256
	global_load_dwordx4 v[148:151], v[138:139], off
	global_load_dwordx4 v[144:147], v[138:139], off offset:256
	global_load_dwordx4 v[140:143], v[236:237], off
	s_nop 0
	global_load_dwordx4 v[136:139], v[236:237], off offset:256
	global_load_dwordx4 v[132:135], v[128:129], off
	s_nop 0
	global_load_dwordx4 v[128:131], v[128:129], off offset:256
	s_lshl_b32 s38, s16, 2
	s_ashr_i32 s39, s38, 31
	s_waitcnt vmcnt(0)
	v_lshlrev_b32_e32 v236, 16, v220
	v_and_b32_e32 v237, 0xffff0000, v220
	v_lshlrev_b32_e32 v220, 16, v221
	v_and_b32_e32 v221, 0xffff0000, v221
	v_lshlrev_b32_e32 v238, 16, v222
	v_and_b32_e32 v239, 0xffff0000, v222
	v_lshlrev_b32_e32 v222, 16, v223
	v_and_b32_e32 v223, 0xffff0000, v223
	v_lshlrev_b32_e32 v240, 16, v224
	v_and_b32_e32 v241, 0xffff0000, v224
	v_lshlrev_b32_e32 v242, 16, v225
	v_and_b32_e32 v243, 0xffff0000, v225
	v_lshlrev_b32_e32 v244, 16, v226
	v_and_b32_e32 v245, 0xffff0000, v226
	v_lshlrev_b32_e32 v246, 16, v227
	v_and_b32_e32 v247, 0xffff0000, v227
	v_pk_fma_f32 v[224:225], v[114:115], 0.5, v[220:221] op_sel_hi:[1,0,1]
	v_pk_fma_f32 v[226:227], v[112:113], 0.5, v[236:237] op_sel_hi:[1,0,1]
	v_pk_fma_f32 v[220:221], v[118:119], 0.5, v[222:223] op_sel_hi:[1,0,1]
	v_pk_fma_f32 v[222:223], v[116:117], 0.5, v[238:239] op_sel_hi:[1,0,1]
	v_pk_fma_f32 v[112:113], v[122:123], 0.5, v[246:247] op_sel_hi:[1,0,1]
	v_pk_fma_f32 v[114:115], v[120:121], 0.5, v[244:245] op_sel_hi:[1,0,1]
	v_mul_f32_e32 v120, v227, v227
	v_mul_f32_e32 v121, v225, v225
	v_mul_f32_e32 v122, v223, v223
	v_mul_f32_e32 v123, v221, v221
	v_pk_fma_f32 v[116:117], v[126:127], 0.5, v[242:243] op_sel_hi:[1,0,1]
	v_pk_fma_f32 v[118:119], v[124:125], 0.5, v[240:241] op_sel_hi:[1,0,1]
	v_fmac_f32_e32 v120, v226, v226
	v_fmac_f32_e32 v121, v224, v224
	v_fmac_f32_e32 v122, v222, v222
	v_fmac_f32_e32 v123, v220, v220
	v_mul_f32_e32 v124, v119, v119
	v_mul_f32_e32 v125, v117, v117
	v_add_f32_e32 v120, v120, v121
	v_add_f32_e32 v121, v122, v123
	v_mul_f32_e32 v122, v115, v115
	v_mul_f32_e32 v123, v113, v113
	v_fmac_f32_e32 v124, v118, v118
	v_fmac_f32_e32 v125, v116, v116
	v_fmac_f32_e32 v122, v114, v114
	v_fmac_f32_e32 v123, v112, v112
	v_add_f32_e32 v120, v120, v121
	v_add_f32_e32 v121, v124, v125
	v_add_f32_e32 v122, v122, v123
	v_add_f32_e32 v121, v121, v122
	v_add_f32_e32 v120, v120, v121
	ds_bpermute_b32 v121, v232, v120
	v_lshlrev_b64 v[124:125], 6, v[216:217]
	s_waitcnt lgkmcnt(0)
	v_add_f32_e32 v120, v120, v121
	ds_bpermute_b32 v121, v233, v120
	s_and_saveexec_b64 s[40:41], s[0:1]
	s_cbranch_execz .LBB0_1370
	s_waitcnt lgkmcnt(0)
	v_add_f32_e32 v122, v120, v121
	v_lshl_add_u64 v[120:121], s[22:23], 0, v[124:125]
	v_lshl_add_u64 v[120:121], s[38:39], 2, v[120:121]
	s_lshl_b32 s16, s54, 2
	v_lshl_add_u64 v[120:121], v[120:121], 0, s[16:17]
	global_store_dword v[120:121], v122, off sc1
.LBB0_1370:
	s_or_b64 exec, exec, s[40:41]
	v_lshlrev_b32_e32 v120, 16, v180
	s_waitcnt lgkmcnt(0)
	v_and_b32_e32 v121, 0xffff0000, v180
	v_lshlrev_b32_e32 v122, 16, v181
	v_and_b32_e32 v123, 0xffff0000, v181
	v_pk_fma_f32 v[106:107], v[106:107], 0.5, v[122:123] op_sel_hi:[1,0,1]
	v_pk_fma_f32 v[104:105], v[104:105], 0.5, v[120:121] op_sel_hi:[1,0,1]
	v_lshlrev_b32_e32 v120, 16, v182
	v_and_b32_e32 v121, 0xffff0000, v182
	v_lshlrev_b32_e32 v122, 16, v183
	v_and_b32_e32 v123, 0xffff0000, v183
	v_pk_fma_f32 v[96:97], v[96:97], 0.5, v[120:121] op_sel_hi:[1,0,1]
	v_mul_f32_e32 v120, v105, v105
	v_mul_f32_e32 v121, v107, v107
	v_pk_fma_f32 v[98:99], v[98:99], 0.5, v[122:123] op_sel_hi:[1,0,1]
	v_fmac_f32_e32 v120, v104, v104
	v_fmac_f32_e32 v121, v106, v106
	v_add_f32_e32 v120, v120, v121
	v_mul_f32_e32 v121, v97, v97
	v_mul_f32_e32 v122, v99, v99
	v_fmac_f32_e32 v121, v96, v96
	v_fmac_f32_e32 v122, v98, v98
	v_add_f32_e32 v121, v121, v122
	v_add_f32_e32 v126, v120, v121
	v_lshlrev_b32_e32 v120, 16, v176
	v_and_b32_e32 v121, 0xffff0000, v176
	v_lshlrev_b32_e32 v122, 16, v177
	v_and_b32_e32 v123, 0xffff0000, v177
	v_pk_fma_f32 v[110:111], v[110:111], 0.5, v[122:123] op_sel_hi:[1,0,1]
	v_pk_fma_f32 v[108:109], v[108:109], 0.5, v[120:121] op_sel_hi:[1,0,1]
	v_lshlrev_b32_e32 v120, 16, v178
	v_and_b32_e32 v121, 0xffff0000, v178
	v_lshlrev_b32_e32 v122, 16, v179
	v_and_b32_e32 v123, 0xffff0000, v179
	v_pk_fma_f32 v[100:101], v[100:101], 0.5, v[120:121] op_sel_hi:[1,0,1]
	v_mul_f32_e32 v120, v109, v109
	v_mul_f32_e32 v121, v111, v111
	v_pk_fma_f32 v[102:103], v[102:103], 0.5, v[122:123] op_sel_hi:[1,0,1]
	v_fmac_f32_e32 v120, v108, v108
	v_fmac_f32_e32 v121, v110, v110
	v_add_f32_e32 v120, v120, v121
	v_mul_f32_e32 v121, v101, v101
	v_mul_f32_e32 v122, v103, v103
	v_fmac_f32_e32 v121, v100, v100
	v_fmac_f32_e32 v122, v102, v102
	v_add_f32_e32 v121, v121, v122
	v_add_f32_e32 v120, v120, v121
	v_add_f32_e32 v120, v126, v120
	ds_bpermute_b32 v121, v232, v120
	v_lshlrev_b64 v[126:127], 6, v[214:215]
	s_waitcnt lgkmcnt(0)
	v_add_f32_e32 v120, v120, v121
	ds_bpermute_b32 v121, v233, v120
	s_and_saveexec_b64 s[40:41], s[0:1]
	s_cbranch_execz .LBB0_1372
	s_waitcnt lgkmcnt(0)
	v_add_f32_e32 v122, v120, v121
	v_lshl_add_u64 v[120:121], s[22:23], 0, v[126:127]
	v_lshl_add_u64 v[120:121], s[38:39], 2, v[120:121]
	s_lshl_b32 s16, s54, 2
	v_lshl_add_u64 v[120:121], v[120:121], 0, s[16:17]
	global_store_dword v[120:121], v122, off sc1
.LBB0_1372:
	s_or_b64 exec, exec, s[40:41]
	v_lshlrev_b32_e32 v120, 16, v172
	s_waitcnt lgkmcnt(0)
	v_and_b32_e32 v121, 0xffff0000, v172
	v_lshlrev_b32_e32 v122, 16, v173
	v_and_b32_e32 v123, 0xffff0000, v173
	v_pk_fma_f32 v[90:91], v[90:91], 0.5, v[122:123] op_sel_hi:[1,0,1]
	v_pk_fma_f32 v[88:89], v[88:89], 0.5, v[120:121] op_sel_hi:[1,0,1]
	v_lshlrev_b32_e32 v120, 16, v174
	v_and_b32_e32 v121, 0xffff0000, v174
	v_lshlrev_b32_e32 v122, 16, v175
	v_and_b32_e32 v123, 0xffff0000, v175
	v_pk_fma_f32 v[80:81], v[80:81], 0.5, v[120:121] op_sel_hi:[1,0,1]
	v_mul_f32_e32 v120, v89, v89
	v_mul_f32_e32 v121, v91, v91
	v_pk_fma_f32 v[82:83], v[82:83], 0.5, v[122:123] op_sel_hi:[1,0,1]
	v_fmac_f32_e32 v120, v88, v88
	v_fmac_f32_e32 v121, v90, v90
	v_add_f32_e32 v120, v120, v121
	v_mul_f32_e32 v121, v81, v81
	v_mul_f32_e32 v122, v83, v83
	v_fmac_f32_e32 v121, v80, v80
	v_fmac_f32_e32 v122, v82, v82
	v_add_f32_e32 v121, v121, v122
	v_add_f32_e32 v172, v120, v121
	v_lshlrev_b32_e32 v120, 16, v168
	v_and_b32_e32 v121, 0xffff0000, v168
	v_lshlrev_b32_e32 v122, 16, v169
	v_and_b32_e32 v123, 0xffff0000, v169
	v_pk_fma_f32 v[94:95], v[94:95], 0.5, v[122:123] op_sel_hi:[1,0,1]
	v_pk_fma_f32 v[92:93], v[92:93], 0.5, v[120:121] op_sel_hi:[1,0,1]
	v_lshlrev_b32_e32 v120, 16, v170
	v_and_b32_e32 v121, 0xffff0000, v170
	v_lshlrev_b32_e32 v122, 16, v171
	v_and_b32_e32 v123, 0xffff0000, v171
	v_pk_fma_f32 v[84:85], v[84:85], 0.5, v[120:121] op_sel_hi:[1,0,1]
	v_mul_f32_e32 v120, v93, v93
	v_mul_f32_e32 v121, v95, v95
	v_pk_fma_f32 v[86:87], v[86:87], 0.5, v[122:123] op_sel_hi:[1,0,1]
	v_fmac_f32_e32 v120, v92, v92
	v_fmac_f32_e32 v121, v94, v94
	v_add_f32_e32 v120, v120, v121
	v_mul_f32_e32 v121, v85, v85
	v_mul_f32_e32 v122, v87, v87
	v_fmac_f32_e32 v121, v84, v84
	v_fmac_f32_e32 v122, v86, v86
	v_add_f32_e32 v121, v121, v122
	v_add_f32_e32 v120, v120, v121
	v_add_f32_e32 v120, v172, v120
	ds_bpermute_b32 v121, v232, v120
	v_lshlrev_b64 v[168:169], 6, v[212:213]
	s_waitcnt lgkmcnt(0)
	v_add_f32_e32 v120, v120, v121
	ds_bpermute_b32 v121, v233, v120
	s_and_saveexec_b64 s[40:41], s[0:1]
	s_cbranch_execz .LBB0_1374
	s_waitcnt lgkmcnt(0)
	v_add_f32_e32 v122, v120, v121
	v_lshl_add_u64 v[120:121], s[22:23], 0, v[168:169]
	v_lshl_add_u64 v[120:121], s[38:39], 2, v[120:121]
	s_lshl_b32 s16, s54, 2
	v_lshl_add_u64 v[120:121], v[120:121], 0, s[16:17]
	global_store_dword v[120:121], v122, off sc1
.LBB0_1374:
	s_or_b64 exec, exec, s[40:41]
	v_lshlrev_b32_e32 v120, 16, v164
	s_waitcnt lgkmcnt(0)
	v_and_b32_e32 v121, 0xffff0000, v164
	v_lshlrev_b32_e32 v122, 16, v165
	v_and_b32_e32 v123, 0xffff0000, v165
	v_pk_fma_f32 v[74:75], v[74:75], 0.5, v[122:123] op_sel_hi:[1,0,1]
	v_pk_fma_f32 v[72:73], v[72:73], 0.5, v[120:121] op_sel_hi:[1,0,1]
	v_lshlrev_b32_e32 v120, 16, v166
	v_and_b32_e32 v121, 0xffff0000, v166
	v_lshlrev_b32_e32 v122, 16, v167
	v_and_b32_e32 v123, 0xffff0000, v167
	v_pk_fma_f32 v[64:65], v[64:65], 0.5, v[120:121] op_sel_hi:[1,0,1]
	v_mul_f32_e32 v120, v73, v73
	v_mul_f32_e32 v121, v75, v75
	v_pk_fma_f32 v[66:67], v[66:67], 0.5, v[122:123] op_sel_hi:[1,0,1]
	v_fmac_f32_e32 v120, v72, v72
	v_fmac_f32_e32 v121, v74, v74
	v_add_f32_e32 v120, v120, v121
	v_mul_f32_e32 v121, v65, v65
	v_mul_f32_e32 v122, v67, v67
	v_fmac_f32_e32 v121, v64, v64
	v_fmac_f32_e32 v122, v66, v66
	v_add_f32_e32 v121, v121, v122
	v_add_f32_e32 v164, v120, v121
	v_lshlrev_b32_e32 v120, 16, v160
	v_and_b32_e32 v121, 0xffff0000, v160
	v_lshlrev_b32_e32 v122, 16, v161
	v_and_b32_e32 v123, 0xffff0000, v161
	v_pk_fma_f32 v[78:79], v[78:79], 0.5, v[122:123] op_sel_hi:[1,0,1]
	v_pk_fma_f32 v[76:77], v[76:77], 0.5, v[120:121] op_sel_hi:[1,0,1]
	v_lshlrev_b32_e32 v120, 16, v162
	v_and_b32_e32 v121, 0xffff0000, v162
	v_lshlrev_b32_e32 v122, 16, v163
	v_and_b32_e32 v123, 0xffff0000, v163
	v_pk_fma_f32 v[68:69], v[68:69], 0.5, v[120:121] op_sel_hi:[1,0,1]
	v_mul_f32_e32 v120, v77, v77
	v_mul_f32_e32 v121, v79, v79
	v_pk_fma_f32 v[70:71], v[70:71], 0.5, v[122:123] op_sel_hi:[1,0,1]
	v_fmac_f32_e32 v120, v76, v76
	v_fmac_f32_e32 v121, v78, v78
	v_add_f32_e32 v120, v120, v121
	v_mul_f32_e32 v121, v69, v69
	v_mul_f32_e32 v122, v71, v71
	v_fmac_f32_e32 v121, v68, v68
	v_fmac_f32_e32 v122, v70, v70
	v_add_f32_e32 v121, v121, v122
	v_add_f32_e32 v120, v120, v121
	v_add_f32_e32 v120, v164, v120
	ds_bpermute_b32 v121, v232, v120
	v_lshlrev_b64 v[160:161], 6, v[210:211]
	s_waitcnt lgkmcnt(0)
	v_add_f32_e32 v120, v120, v121
	ds_bpermute_b32 v121, v233, v120
	s_and_saveexec_b64 s[40:41], s[0:1]
	s_cbranch_execz .LBB0_1376
	s_waitcnt lgkmcnt(0)
	v_add_f32_e32 v122, v120, v121
	v_lshl_add_u64 v[120:121], s[22:23], 0, v[160:161]
	v_lshl_add_u64 v[120:121], s[38:39], 2, v[120:121]
	s_lshl_b32 s16, s54, 2
	v_lshl_add_u64 v[120:121], v[120:121], 0, s[16:17]
	global_store_dword v[120:121], v122, off sc1
.LBB0_1376:
	s_or_b64 exec, exec, s[40:41]
	v_lshlrev_b32_e32 v120, 16, v156
	s_waitcnt lgkmcnt(0)
	v_and_b32_e32 v121, 0xffff0000, v156
	v_lshlrev_b32_e32 v122, 16, v157
	v_and_b32_e32 v123, 0xffff0000, v157
	v_pk_fma_f32 v[58:59], v[58:59], 0.5, v[122:123] op_sel_hi:[1,0,1]
	v_pk_fma_f32 v[56:57], v[56:57], 0.5, v[120:121] op_sel_hi:[1,0,1]
	v_lshlrev_b32_e32 v120, 16, v158
	v_and_b32_e32 v121, 0xffff0000, v158
	v_lshlrev_b32_e32 v122, 16, v159
	v_and_b32_e32 v123, 0xffff0000, v159
	v_pk_fma_f32 v[48:49], v[48:49], 0.5, v[120:121] op_sel_hi:[1,0,1]
	v_mul_f32_e32 v120, v57, v57
	v_mul_f32_e32 v121, v59, v59
	v_pk_fma_f32 v[50:51], v[50:51], 0.5, v[122:123] op_sel_hi:[1,0,1]
	v_fmac_f32_e32 v120, v56, v56
	v_fmac_f32_e32 v121, v58, v58
	v_add_f32_e32 v120, v120, v121
	v_mul_f32_e32 v121, v49, v49
	v_mul_f32_e32 v122, v51, v51
	v_fmac_f32_e32 v121, v48, v48
	v_fmac_f32_e32 v122, v50, v50
	v_add_f32_e32 v121, v121, v122
	v_add_f32_e32 v156, v120, v121
	v_lshlrev_b32_e32 v120, 16, v152
	v_and_b32_e32 v121, 0xffff0000, v152
	v_lshlrev_b32_e32 v122, 16, v153
	v_and_b32_e32 v123, 0xffff0000, v153
	v_pk_fma_f32 v[62:63], v[62:63], 0.5, v[122:123] op_sel_hi:[1,0,1]
	v_pk_fma_f32 v[60:61], v[60:61], 0.5, v[120:121] op_sel_hi:[1,0,1]
	v_lshlrev_b32_e32 v120, 16, v154
	v_and_b32_e32 v121, 0xffff0000, v154
	v_lshlrev_b32_e32 v122, 16, v155
	v_and_b32_e32 v123, 0xffff0000, v155
	v_pk_fma_f32 v[52:53], v[52:53], 0.5, v[120:121] op_sel_hi:[1,0,1]
	v_mul_f32_e32 v120, v61, v61
	v_mul_f32_e32 v121, v63, v63
	v_pk_fma_f32 v[54:55], v[54:55], 0.5, v[122:123] op_sel_hi:[1,0,1]
	v_fmac_f32_e32 v120, v60, v60
	v_fmac_f32_e32 v121, v62, v62
	v_add_f32_e32 v120, v120, v121
	v_mul_f32_e32 v121, v53, v53
	v_mul_f32_e32 v122, v55, v55
	v_fmac_f32_e32 v121, v52, v52
	v_fmac_f32_e32 v122, v54, v54
	v_add_f32_e32 v121, v121, v122
	v_add_f32_e32 v120, v120, v121
	v_add_f32_e32 v120, v156, v120
	ds_bpermute_b32 v121, v232, v120
	v_lshlrev_b64 v[152:153], 6, v[208:209]
	s_waitcnt lgkmcnt(0)
	v_add_f32_e32 v120, v120, v121
	ds_bpermute_b32 v121, v233, v120
	s_and_saveexec_b64 s[40:41], s[0:1]
	s_cbranch_execz .LBB0_1378
	s_waitcnt lgkmcnt(0)
	v_add_f32_e32 v122, v120, v121
	v_lshl_add_u64 v[120:121], s[22:23], 0, v[152:153]
	v_lshl_add_u64 v[120:121], s[38:39], 2, v[120:121]
	s_lshl_b32 s16, s54, 2
	v_lshl_add_u64 v[120:121], v[120:121], 0, s[16:17]
	global_store_dword v[120:121], v122, off sc1
.LBB0_1378:
	s_or_b64 exec, exec, s[40:41]
	v_lshlrev_b32_e32 v120, 16, v148
	s_waitcnt lgkmcnt(0)
	v_and_b32_e32 v121, 0xffff0000, v148
	v_lshlrev_b32_e32 v122, 16, v149
	v_and_b32_e32 v123, 0xffff0000, v149
	v_pk_fma_f32 v[42:43], v[42:43], 0.5, v[122:123] op_sel_hi:[1,0,1]
	v_pk_fma_f32 v[40:41], v[40:41], 0.5, v[120:121] op_sel_hi:[1,0,1]
	v_lshlrev_b32_e32 v120, 16, v150
	v_and_b32_e32 v121, 0xffff0000, v150
	v_lshlrev_b32_e32 v122, 16, v151
	v_and_b32_e32 v123, 0xffff0000, v151
	v_pk_fma_f32 v[32:33], v[32:33], 0.5, v[120:121] op_sel_hi:[1,0,1]
	v_mul_f32_e32 v120, v41, v41
	v_mul_f32_e32 v121, v43, v43
	v_pk_fma_f32 v[34:35], v[34:35], 0.5, v[122:123] op_sel_hi:[1,0,1]
	v_fmac_f32_e32 v120, v40, v40
	v_fmac_f32_e32 v121, v42, v42
	v_add_f32_e32 v120, v120, v121
	v_mul_f32_e32 v121, v33, v33
	v_mul_f32_e32 v122, v35, v35
	v_fmac_f32_e32 v121, v32, v32
	v_fmac_f32_e32 v122, v34, v34
	v_add_f32_e32 v121, v121, v122
	v_add_f32_e32 v148, v120, v121
	v_lshlrev_b32_e32 v120, 16, v144
	v_and_b32_e32 v121, 0xffff0000, v144
	v_lshlrev_b32_e32 v122, 16, v145
	v_and_b32_e32 v123, 0xffff0000, v145
	v_pk_fma_f32 v[46:47], v[46:47], 0.5, v[122:123] op_sel_hi:[1,0,1]
	v_pk_fma_f32 v[44:45], v[44:45], 0.5, v[120:121] op_sel_hi:[1,0,1]
	v_lshlrev_b32_e32 v120, 16, v146
	v_and_b32_e32 v121, 0xffff0000, v146
	v_lshlrev_b32_e32 v122, 16, v147
	v_and_b32_e32 v123, 0xffff0000, v147
	v_pk_fma_f32 v[36:37], v[36:37], 0.5, v[120:121] op_sel_hi:[1,0,1]
	v_mul_f32_e32 v120, v45, v45
	v_mul_f32_e32 v121, v47, v47
	v_pk_fma_f32 v[38:39], v[38:39], 0.5, v[122:123] op_sel_hi:[1,0,1]
	v_fmac_f32_e32 v120, v44, v44
	v_fmac_f32_e32 v121, v46, v46
	v_add_f32_e32 v120, v120, v121
	v_mul_f32_e32 v121, v37, v37
	v_mul_f32_e32 v122, v39, v39
	v_fmac_f32_e32 v121, v36, v36
	v_fmac_f32_e32 v122, v38, v38
	v_add_f32_e32 v121, v121, v122
	v_add_f32_e32 v120, v120, v121
	v_add_f32_e32 v120, v148, v120
	ds_bpermute_b32 v121, v232, v120
	v_lshlrev_b64 v[144:145], 6, v[206:207]
	s_waitcnt lgkmcnt(0)
	v_add_f32_e32 v120, v120, v121
	ds_bpermute_b32 v121, v233, v120
	s_and_saveexec_b64 s[40:41], s[0:1]
	s_cbranch_execz .LBB0_1380
	s_waitcnt lgkmcnt(0)
	v_add_f32_e32 v122, v120, v121
	v_lshl_add_u64 v[120:121], s[22:23], 0, v[144:145]
	v_lshl_add_u64 v[120:121], s[38:39], 2, v[120:121]
	s_lshl_b32 s16, s54, 2
	v_lshl_add_u64 v[120:121], v[120:121], 0, s[16:17]
	global_store_dword v[120:121], v122, off sc1
.LBB0_1380:
	s_or_b64 exec, exec, s[40:41]
	v_lshlrev_b32_e32 v120, 16, v140
	s_waitcnt lgkmcnt(0)
	v_and_b32_e32 v121, 0xffff0000, v140
	v_lshlrev_b32_e32 v122, 16, v141
	v_and_b32_e32 v123, 0xffff0000, v141
	v_pk_fma_f32 v[26:27], v[26:27], 0.5, v[122:123] op_sel_hi:[1,0,1]
	v_pk_fma_f32 v[24:25], v[24:25], 0.5, v[120:121] op_sel_hi:[1,0,1]
	v_lshlrev_b32_e32 v120, 16, v142
	v_and_b32_e32 v121, 0xffff0000, v142
	v_lshlrev_b32_e32 v122, 16, v143
	v_and_b32_e32 v123, 0xffff0000, v143
	v_pk_fma_f32 v[16:17], v[16:17], 0.5, v[120:121] op_sel_hi:[1,0,1]
	v_mul_f32_e32 v120, v25, v25
	v_mul_f32_e32 v121, v27, v27
	v_pk_fma_f32 v[18:19], v[18:19], 0.5, v[122:123] op_sel_hi:[1,0,1]
	v_fmac_f32_e32 v120, v24, v24
	v_fmac_f32_e32 v121, v26, v26
	v_add_f32_e32 v120, v120, v121
	v_mul_f32_e32 v121, v17, v17
	v_mul_f32_e32 v122, v19, v19
	v_fmac_f32_e32 v121, v16, v16
	v_fmac_f32_e32 v122, v18, v18
	v_add_f32_e32 v121, v121, v122
	v_add_f32_e32 v140, v120, v121
	v_lshlrev_b32_e32 v120, 16, v136
	v_and_b32_e32 v121, 0xffff0000, v136
	v_lshlrev_b32_e32 v122, 16, v137
	v_and_b32_e32 v123, 0xffff0000, v137
	v_pk_fma_f32 v[30:31], v[30:31], 0.5, v[122:123] op_sel_hi:[1,0,1]
	v_pk_fma_f32 v[28:29], v[28:29], 0.5, v[120:121] op_sel_hi:[1,0,1]
	v_lshlrev_b32_e32 v120, 16, v138
	v_and_b32_e32 v121, 0xffff0000, v138
	v_lshlrev_b32_e32 v122, 16, v139
	v_and_b32_e32 v123, 0xffff0000, v139
	v_pk_fma_f32 v[20:21], v[20:21], 0.5, v[120:121] op_sel_hi:[1,0,1]
	v_mul_f32_e32 v120, v29, v29
	v_mul_f32_e32 v121, v31, v31
	v_pk_fma_f32 v[22:23], v[22:23], 0.5, v[122:123] op_sel_hi:[1,0,1]
	v_fmac_f32_e32 v120, v28, v28
	v_fmac_f32_e32 v121, v30, v30
	v_add_f32_e32 v120, v120, v121
	v_mul_f32_e32 v121, v21, v21
	v_mul_f32_e32 v122, v23, v23
	v_fmac_f32_e32 v121, v20, v20
	v_fmac_f32_e32 v122, v22, v22
	v_add_f32_e32 v121, v121, v122
	v_add_f32_e32 v120, v120, v121
	v_add_f32_e32 v120, v140, v120
	ds_bpermute_b32 v121, v232, v120
	v_lshlrev_b64 v[136:137], 6, v[204:205]
	s_waitcnt lgkmcnt(0)
	v_add_f32_e32 v120, v120, v121
	ds_bpermute_b32 v121, v233, v120
	s_and_saveexec_b64 s[40:41], s[0:1]
	s_cbranch_execz .LBB0_1382
	s_waitcnt lgkmcnt(0)
	v_add_f32_e32 v122, v120, v121
	v_lshl_add_u64 v[120:121], s[22:23], 0, v[136:137]
	v_lshl_add_u64 v[120:121], s[38:39], 2, v[120:121]
	s_lshl_b32 s16, s54, 2
	v_lshl_add_u64 v[120:121], v[120:121], 0, s[16:17]
	global_store_dword v[120:121], v122, off sc1
.LBB0_1382:
	s_or_b64 exec, exec, s[40:41]
	v_lshlrev_b32_e32 v120, 16, v132
	s_waitcnt lgkmcnt(0)
	v_and_b32_e32 v121, 0xffff0000, v132
	v_lshlrev_b32_e32 v122, 16, v133
	v_and_b32_e32 v123, 0xffff0000, v133
	v_pk_fma_f32 v[10:11], v[10:11], 0.5, v[122:123] op_sel_hi:[1,0,1]
	v_pk_fma_f32 v[8:9], v[8:9], 0.5, v[120:121] op_sel_hi:[1,0,1]
	v_lshlrev_b32_e32 v122, 16, v134
	v_and_b32_e32 v123, 0xffff0000, v134
	v_lshlrev_b32_e32 v120, 16, v135
	v_and_b32_e32 v121, 0xffff0000, v135
	v_pk_fma_f32 v[122:123], v[0:1], 0.5, v[122:123] op_sel_hi:[1,0,1]
	v_mul_f32_e32 v0, v9, v9
	v_mul_f32_e32 v1, v11, v11
	v_pk_fma_f32 v[120:121], v[2:3], 0.5, v[120:121] op_sel_hi:[1,0,1]
	v_fmac_f32_e32 v0, v8, v8
	v_fmac_f32_e32 v1, v10, v10
	v_add_f32_e32 v0, v0, v1
	v_mul_f32_e32 v1, v123, v123
	v_mul_f32_e32 v2, v121, v121
	v_fmac_f32_e32 v1, v122, v122
	v_fmac_f32_e32 v2, v120, v120
	v_add_f32_e32 v1, v1, v2
	v_add_f32_e32 v132, v0, v1
	v_lshlrev_b32_e32 v2, 16, v128
	v_and_b32_e32 v3, 0xffff0000, v128
	v_lshlrev_b32_e32 v0, 16, v129
	v_and_b32_e32 v1, 0xffff0000, v129
	v_pk_fma_f32 v[0:1], v[14:15], 0.5, v[0:1] op_sel_hi:[1,0,1]
	v_pk_fma_f32 v[2:3], v[12:13], 0.5, v[2:3] op_sel_hi:[1,0,1]
	v_lshlrev_b32_e32 v12, 16, v130
	v_and_b32_e32 v13, 0xffff0000, v130
	v_lshlrev_b32_e32 v14, 16, v131
	v_and_b32_e32 v15, 0xffff0000, v131
	v_pk_fma_f32 v[4:5], v[4:5], 0.5, v[12:13] op_sel_hi:[1,0,1]
	v_mul_f32_e32 v12, v3, v3
	v_mul_f32_e32 v13, v1, v1
	v_pk_fma_f32 v[6:7], v[6:7], 0.5, v[14:15] op_sel_hi:[1,0,1]
	v_fmac_f32_e32 v12, v2, v2
	v_fmac_f32_e32 v13, v0, v0
	v_add_f32_e32 v12, v12, v13
	v_mul_f32_e32 v13, v5, v5
	v_mul_f32_e32 v14, v7, v7
	v_fmac_f32_e32 v13, v4, v4
	v_fmac_f32_e32 v14, v6, v6
	v_add_f32_e32 v13, v13, v14
	v_add_f32_e32 v12, v12, v13
	v_add_f32_e32 v12, v132, v12
	ds_bpermute_b32 v13, v232, v12
	s_waitcnt lgkmcnt(0)
	v_add_f32_e32 v14, v12, v13
	ds_bpermute_b32 v15, v233, v14
	v_lshlrev_b64 v[12:13], 6, v[202:203]
	s_and_saveexec_b64 s[40:41], s[0:1]
	s_cbranch_execz .LBB0_1384
	s_waitcnt lgkmcnt(0)
	v_add_f32_e32 v128, v14, v15
	v_lshl_add_u64 v[14:15], s[22:23], 0, v[12:13]
	v_lshl_add_u64 v[14:15], s[38:39], 2, v[14:15]
	s_lshl_b32 s16, s54, 2
	v_lshl_add_u64 v[14:15], v[14:15], 0, s[16:17]
	global_store_dword v[14:15], v128, off sc1

.LBB0_1388:
	s_waitcnt lgkmcnt(0)
	v_mov_b64_e32 v[14:15], s[38:39]
	global_load_dword v14, v[14:15], off sc1
	s_waitcnt vmcnt(0) lgkmcnt(0)
	v_readfirstlane_b32 s40, v14
	s_cmp_gt_u32 s40, 31
	s_mov_b64 s[40:41], -1
	s_cbranch_scc1 .LBB0_1387
	v_mov_b64_e32 v[14:15], s[38:39]
	s_sleep 2
	global_load_dword v14, v[14:15], off sc1
	s_waitcnt vmcnt(0) lgkmcnt(0)
	v_readfirstlane_b32 s40, v14
	s_cmp_lt_u32 s40, 32
	s_mov_b64 s[40:41], -1
	s_cbranch_scc0 .LBB0_1387
	v_mov_b64_e32 v[14:15], s[38:39]
	s_sleep 2
	global_load_dword v14, v[14:15], off sc1
	s_waitcnt vmcnt(0) lgkmcnt(0)
	v_readfirstlane_b32 s40, v14
	s_cmp_lt_u32 s40, 32
	s_mov_b64 s[40:41], -1
	s_cbranch_scc0 .LBB0_1387
	v_mov_b64_e32 v[14:15], s[38:39]
	s_sleep 2
	global_load_dword v14, v[14:15], off sc1
	s_waitcnt vmcnt(0) lgkmcnt(0)
	v_readfirstlane_b32 s40, v14
	s_cmp_lt_u32 s40, 32
	s_mov_b64 s[40:41], -1
	s_cbranch_scc0 .LBB0_1387
	v_mov_b64_e32 v[14:15], s[38:39]
	s_sleep 2
	global_load_dword v14, v[14:15], off sc1
	s_waitcnt vmcnt(0) lgkmcnt(0)
	v_readfirstlane_b32 s40, v14
	s_cmp_lt_u32 s40, 32
	s_mov_b64 s[40:41], -1
	s_cbranch_scc0 .LBB0_1387
	s_add_i32 s16, s16, -5
	s_cmp_eq_u32 s16, 0
	s_cselect_b64 s[40:41], -1, 0
	s_sleep 2
	s_branch .LBB0_1387
.LBB0_1394:
	v_lshl_add_u64 v[14:15], v[192:193], 0, v[124:125]
	global_load_dwordx2 v[132:133], v[14:15], off sc1
	global_load_dwordx2 v[150:151], v[14:15], off offset:8 sc1
	v_lshl_add_u64 v[14:15], v[192:193], 0, v[126:127]
	global_load_dwordx2 v[154:155], v[14:15], off sc1
	global_load_dwordx2 v[156:157], v[14:15], off offset:8 sc1
	v_lshl_add_u64 v[124:125], v[192:193], 0, v[168:169]
	v_lshl_add_u64 v[126:127], v[192:193], 0, v[160:161]
	v_lshl_add_u64 v[128:129], v[192:193], 0, v[152:153]
	v_lshl_add_u64 v[130:131], v[192:193], 0, v[144:145]
	v_lshl_add_u64 v[12:13], v[192:193], 0, v[12:13]
	v_lshlrev_b64 v[14:15], 2, v[218:219]
	v_lshl_add_u64 v[142:143], v[192:193], 0, v[136:137]
	global_load_dwordx2 v[152:153], v[124:125], off sc1
	global_load_dwordx2 v[158:159], v[124:125], off offset:8 sc1
	global_load_dwordx2 v[160:161], v[126:127], off sc1
	global_load_dwordx2 v[162:163], v[126:127], off offset:8 sc1
	global_load_dwordx2 v[136:137], v[128:129], off sc1
	global_load_dwordx2 v[134:135], v[128:129], off offset:8 sc1
	global_load_dwordx2 v[140:141], v[130:131], off sc1
	global_load_dwordx2 v[138:139], v[130:131], off offset:8 sc1
	s_nop 0
	global_load_dwordx2 v[126:127], v[142:143], off sc1
	global_load_dwordx2 v[124:125], v[142:143], off offset:8 sc1
	global_load_dwordx2 v[130:131], v[12:13], off sc1
	global_load_dwordx2 v[128:129], v[12:13], off offset:8 sc1
	v_lshl_add_u64 v[12:13], s[10:11], 0, v[14:15]
	global_load_dwordx4 v[142:145], v[12:13], off
	global_load_dwordx4 v[146:149], v[12:13], off offset:16
	s_waitcnt vmcnt(0) lgkmcnt(0)
	v_mov_b32_e32 v165, v132
	v_mov_b32_e32 v164, v154
	v_mov_b32_e32 v132, v155
	v_mov_b32_e32 v154, v156
	v_mov_b32_e32 v155, v150
	v_mov_b32_e32 v150, v157
	v_pk_add_f32 v[132:133], v[164:165], v[132:133]
	v_pk_add_f32 v[150:151], v[154:155], v[150:151]
	s_nop 0
	v_pk_add_f32 v[132:133], v[132:133], v[150:151]
	ds_bpermute_b32 v151, v232, v133
	ds_bpermute_b32 v150, v232, v132
	s_waitcnt lgkmcnt(0)
	v_pk_add_f32 v[150:151], v[132:133], v[150:151]
	ds_bpermute_b32 v155, v233, v151
	ds_bpermute_b32 v154, v233, v150
	v_mov_b64_e32 v[132:133], s[34:35]
	s_waitcnt lgkmcnt(0)
	v_pk_add_f32 v[150:151], v[150:151], v[154:155]
	s_nop 0
	v_pk_fma_f32 v[150:151], v[150:151], s[30:31], v[132:133] op_sel_hi:[1,0,0]
	s_nop 0
	v_mul_f32_e32 v154, 0x4b800000, v151
	v_cmp_gt_f32_e32 vcc, s61, v151
	s_nop 1
	v_cndmask_b32_e32 v151, v151, v154, vcc
	v_rsq_f32_e32 v151, v151
	v_lshlrev_b64 v[154:155], 12, v[216:217]
	v_lshl_add_u64 v[154:155], s[8:9], 0, v[154:155]
	v_lshl_add_u64 v[154:155], v[154:155], 0, v[14:15]
	v_mul_f32_e32 v156, 0x45800000, v151
	v_cndmask_b32_e32 v156, v151, v156, vcc
	v_pk_mul_f32 v[164:165], v[226:227], v[156:157] op_sel_hi:[1,0]
	v_pk_mul_f32 v[166:167], v[224:225], v[156:157] op_sel_hi:[1,0]
	v_pk_mul_f32 v[168:169], v[222:223], v[156:157] op_sel_hi:[1,0]
	v_pk_mul_f32 v[170:171], v[220:221], v[156:157] op_sel_hi:[1,0]
	v_pk_mul_f32 v[144:145], v[144:145], v[166:167]
	v_pk_mul_f32 v[142:143], v[142:143], v[164:165]
	v_pk_mul_f32 v[148:149], v[148:149], v[170:171]
	v_pk_mul_f32 v[146:147], v[146:147], v[168:169]
	global_store_dwordx4 v[154:155], v[142:145], off
	global_store_dwordx4 v[154:155], v[146:149], off offset:16
	global_load_dwordx4 v[142:145], v[12:13], off offset:512
	s_nop 0
	global_load_dwordx4 v[146:149], v[12:13], off offset:528
	v_pk_mul_f32 v[116:117], v[116:117], v[156:157] op_sel_hi:[1,0]
	v_pk_mul_f32 v[118:119], v[118:119], v[156:157] op_sel_hi:[1,0]
	v_pk_mul_f32 v[164:165], v[112:113], v[156:157] op_sel_hi:[1,0]
	v_pk_mul_f32 v[156:157], v[114:115], v[156:157] op_sel_hi:[1,0]
	v_cmp_gt_f32_e32 vcc, s61, v150
	s_waitcnt vmcnt(1)
	v_pk_mul_f32 v[112:113], v[142:143], v[118:119]
	v_pk_mul_f32 v[114:115], v[144:145], v[116:117]
	s_waitcnt vmcnt(0)
	v_pk_mul_f32 v[116:117], v[146:147], v[156:157]
	v_pk_mul_f32 v[118:119], v[148:149], v[164:165]
	global_store_dwordx4 v[154:155], v[112:115], off offset:512
	global_store_dwordx4 v[154:155], v[116:119], off offset:528
	global_load_dwordx4 v[112:115], v[12:13], off
	s_nop 0
	global_load_dwordx4 v[116:119], v[12:13], off offset:16
	v_mul_f32_e32 v142, 0x4b800000, v150
	v_cndmask_b32_e32 v142, v150, v142, vcc
	v_rsq_f32_e32 v144, v142
	v_lshlrev_b64 v[142:143], 12, v[214:215]
	v_lshl_add_u64 v[142:143], s[8:9], 0, v[142:143]
	v_lshl_add_u64 v[142:143], v[142:143], 0, v[14:15]
	v_mul_f32_e32 v145, 0x45800000, v144
	v_cndmask_b32_e32 v144, v144, v145, vcc
	v_pk_mul_f32 v[106:107], v[106:107], v[144:145] op_sel_hi:[1,0]
	v_pk_mul_f32 v[104:105], v[104:105], v[144:145] op_sel_hi:[1,0]
	v_pk_mul_f32 v[146:147], v[98:99], v[144:145] op_sel_hi:[1,0]
	v_pk_mul_f32 v[148:149], v[96:97], v[144:145] op_sel_hi:[1,0]
	v_pk_mul_f32 v[110:111], v[110:111], v[144:145] op_sel_hi:[1,0]
	v_pk_mul_f32 v[108:109], v[108:109], v[144:145] op_sel_hi:[1,0]
	v_pk_mul_f32 v[102:103], v[102:103], v[144:145] op_sel_hi:[1,0]
	v_pk_mul_f32 v[100:101], v[100:101], v[144:145] op_sel_hi:[1,0]
	s_waitcnt vmcnt(1)
	v_pk_mul_f32 v[96:97], v[112:113], v[104:105]
	v_pk_mul_f32 v[98:99], v[114:115], v[106:107]
	s_waitcnt vmcnt(0)
	v_pk_mul_f32 v[104:105], v[116:117], v[148:149]
	v_pk_mul_f32 v[106:107], v[118:119], v[146:147]
	global_store_dwordx4 v[142:143], v[96:99], off
	global_store_dwordx4 v[142:143], v[104:107], off offset:16
	global_load_dwordx4 v[96:99], v[12:13], off offset:512
	s_nop 0
	global_load_dwordx4 v[104:107], v[12:13], off offset:528
	s_waitcnt vmcnt(1)
	v_pk_mul_f32 v[96:97], v[96:97], v[108:109]
	v_pk_mul_f32 v[98:99], v[98:99], v[110:111]
	s_waitcnt vmcnt(0)
	v_pk_mul_f32 v[100:101], v[104:105], v[100:101]
	v_pk_mul_f32 v[102:103], v[106:107], v[102:103]
	global_store_dwordx4 v[142:143], v[96:99], off offset:512
	global_store_dwordx4 v[142:143], v[100:103], off offset:528
	global_load_dwordx4 v[96:99], v[12:13], off
	s_nop 0
	global_load_dwordx4 v[100:103], v[12:13], off offset:16
	v_mov_b32_e32 v104, v160
	v_mov_b32_e32 v105, v152
	v_mov_b32_e32 v152, v161
	v_mov_b32_e32 v106, v162
	v_mov_b32_e32 v107, v158
	v_mov_b32_e32 v158, v163
	v_pk_add_f32 v[104:105], v[104:105], v[152:153]
	v_pk_add_f32 v[106:107], v[106:107], v[158:159]
	s_nop 0
	v_pk_add_f32 v[104:105], v[104:105], v[106:107]
	ds_bpermute_b32 v107, v232, v105
	ds_bpermute_b32 v106, v232, v104
	s_waitcnt lgkmcnt(0)
	v_pk_add_f32 v[104:105], v[104:105], v[106:107]
	ds_bpermute_b32 v107, v233, v105
	ds_bpermute_b32 v106, v233, v104
	s_waitcnt lgkmcnt(0)
	v_pk_add_f32 v[104:105], v[104:105], v[106:107]
	s_nop 0
	v_pk_fma_f32 v[104:105], v[104:105], s[30:31], v[132:133] op_sel_hi:[1,0,0]
	s_nop 0
	v_mul_f32_e32 v106, 0x4b800000, v105
	v_cmp_gt_f32_e32 vcc, s61, v105
	s_nop 1
	v_cndmask_b32_e32 v105, v105, v106, vcc
	v_rsq_f32_e32 v105, v105
	v_lshlrev_b64 v[106:107], 12, v[212:213]
	v_lshl_add_u64 v[106:107], s[8:9], 0, v[106:107]
	v_lshl_add_u64 v[106:107], v[106:107], 0, v[14:15]
	v_mul_f32_e32 v108, 0x45800000, v105
	v_cndmask_b32_e32 v108, v105, v108, vcc
	v_pk_mul_f32 v[90:91], v[90:91], v[108:109] op_sel_hi:[1,0]
	v_pk_mul_f32 v[88:89], v[88:89], v[108:109] op_sel_hi:[1,0]
	v_pk_mul_f32 v[110:111], v[82:83], v[108:109] op_sel_hi:[1,0]
	v_pk_mul_f32 v[112:113], v[80:81], v[108:109] op_sel_hi:[1,0]
	v_pk_mul_f32 v[94:95], v[94:95], v[108:109] op_sel_hi:[1,0]
	v_pk_mul_f32 v[92:93], v[92:93], v[108:109] op_sel_hi:[1,0]
	v_pk_mul_f32 v[86:87], v[86:87], v[108:109] op_sel_hi:[1,0]
	v_pk_mul_f32 v[84:85], v[84:85], v[108:109] op_sel_hi:[1,0]
	v_cmp_gt_f32_e32 vcc, s61, v104
	s_waitcnt vmcnt(1)
	v_pk_mul_f32 v[80:81], v[96:97], v[88:89]
	v_pk_mul_f32 v[82:83], v[98:99], v[90:91]
	s_waitcnt vmcnt(0)
	v_pk_mul_f32 v[88:89], v[100:101], v[112:113]
	v_pk_mul_f32 v[90:91], v[102:103], v[110:111]
	global_store_dwordx4 v[106:107], v[80:83], off
	global_store_dwordx4 v[106:107], v[88:91], off offset:16
	global_load_dwordx4 v[80:83], v[12:13], off offset:512
	s_nop 0
	global_load_dwordx4 v[88:91], v[12:13], off offset:528
	s_waitcnt vmcnt(1)
	v_pk_mul_f32 v[80:81], v[80:81], v[92:93]
	v_pk_mul_f32 v[82:83], v[82:83], v[94:95]
	s_waitcnt vmcnt(0)
	v_pk_mul_f32 v[84:85], v[88:89], v[84:85]
	v_pk_mul_f32 v[86:87], v[90:91], v[86:87]
	global_store_dwordx4 v[106:107], v[80:83], off offset:512
	global_store_dwordx4 v[106:107], v[84:87], off offset:528
	global_load_dwordx4 v[80:83], v[12:13], off
	s_nop 0
	global_load_dwordx4 v[84:87], v[12:13], off offset:16
	v_mul_f32_e32 v88, 0x4b800000, v104
	v_cndmask_b32_e32 v88, v104, v88, vcc
	v_rsq_f32_e32 v90, v88
	v_lshlrev_b64 v[88:89], 12, v[210:211]
	v_lshl_add_u64 v[88:89], s[8:9], 0, v[88:89]
	v_lshl_add_u64 v[88:89], v[88:89], 0, v[14:15]
	v_mul_f32_e32 v91, 0x45800000, v90
	v_cndmask_b32_e32 v90, v90, v91, vcc
	v_pk_mul_f32 v[74:75], v[74:75], v[90:91] op_sel_hi:[1,0]
	v_pk_mul_f32 v[72:73], v[72:73], v[90:91] op_sel_hi:[1,0]
	v_pk_mul_f32 v[92:93], v[66:67], v[90:91] op_sel_hi:[1,0]
	v_pk_mul_f32 v[94:95], v[64:65], v[90:91] op_sel_hi:[1,0]
	v_pk_mul_f32 v[78:79], v[78:79], v[90:91] op_sel_hi:[1,0]
	v_pk_mul_f32 v[76:77], v[76:77], v[90:91] op_sel_hi:[1,0]
	v_pk_mul_f32 v[70:71], v[70:71], v[90:91] op_sel_hi:[1,0]
	v_pk_mul_f32 v[68:69], v[68:69], v[90:91] op_sel_hi:[1,0]
	s_waitcnt vmcnt(1)
	v_pk_mul_f32 v[64:65], v[80:81], v[72:73]
	v_pk_mul_f32 v[66:67], v[82:83], v[74:75]
	s_waitcnt vmcnt(0)
	v_pk_mul_f32 v[72:73], v[84:85], v[94:95]
	v_pk_mul_f32 v[74:75], v[86:87], v[92:93]
	global_store_dwordx4 v[88:89], v[64:67], off
	global_store_dwordx4 v[88:89], v[72:75], off offset:16
	global_load_dwordx4 v[64:67], v[12:13], off offset:512
	s_nop 0
	global_load_dwordx4 v[72:75], v[12:13], off offset:528
	s_waitcnt vmcnt(1)
	v_pk_mul_f32 v[64:65], v[64:65], v[76:77]
	v_pk_mul_f32 v[66:67], v[66:67], v[78:79]
	s_waitcnt vmcnt(0)
	v_pk_mul_f32 v[68:69], v[72:73], v[68:69]
	v_pk_mul_f32 v[70:71], v[74:75], v[70:71]
	global_store_dwordx4 v[88:89], v[64:67], off offset:512
	global_store_dwordx4 v[88:89], v[68:71], off offset:528
	global_load_dwordx4 v[64:67], v[12:13], off
	s_nop 0
	global_load_dwordx4 v[68:71], v[12:13], off offset:16
	v_mov_b32_e32 v72, v140
	v_mov_b32_e32 v73, v136
	v_mov_b32_e32 v136, v141
	v_mov_b32_e32 v74, v138
	v_mov_b32_e32 v75, v134
	v_mov_b32_e32 v134, v139
	v_pk_add_f32 v[72:73], v[72:73], v[136:137]
	v_pk_add_f32 v[74:75], v[74:75], v[134:135]
	s_nop 0
	v_pk_add_f32 v[72:73], v[72:73], v[74:75]
	ds_bpermute_b32 v75, v232, v73
	ds_bpermute_b32 v74, v232, v72
	s_waitcnt lgkmcnt(0)
	v_pk_add_f32 v[72:73], v[72:73], v[74:75]
	ds_bpermute_b32 v75, v233, v73
	ds_bpermute_b32 v74, v233, v72
	s_waitcnt lgkmcnt(0)
	v_pk_add_f32 v[72:73], v[72:73], v[74:75]
	s_nop 0
	v_pk_fma_f32 v[72:73], v[72:73], s[30:31], v[132:133] op_sel_hi:[1,0,0]
	s_nop 0
	v_mul_f32_e32 v74, 0x4b800000, v73
	v_cmp_gt_f32_e32 vcc, s61, v73
	s_nop 1
	v_cndmask_b32_e32 v73, v73, v74, vcc
	v_rsq_f32_e32 v73, v73
	v_lshlrev_b64 v[74:75], 12, v[208:209]
	v_lshl_add_u64 v[74:75], s[8:9], 0, v[74:75]
	v_lshl_add_u64 v[74:75], v[74:75], 0, v[14:15]
	v_mul_f32_e32 v76, 0x45800000, v73
	v_cndmask_b32_e32 v76, v73, v76, vcc
	v_pk_mul_f32 v[58:59], v[58:59], v[76:77] op_sel_hi:[1,0]
	v_pk_mul_f32 v[56:57], v[56:57], v[76:77] op_sel_hi:[1,0]
	v_pk_mul_f32 v[78:79], v[50:51], v[76:77] op_sel_hi:[1,0]
	v_pk_mul_f32 v[80:81], v[48:49], v[76:77] op_sel_hi:[1,0]
	v_pk_mul_f32 v[62:63], v[62:63], v[76:77] op_sel_hi:[1,0]
	v_pk_mul_f32 v[60:61], v[60:61], v[76:77] op_sel_hi:[1,0]
	v_pk_mul_f32 v[54:55], v[54:55], v[76:77] op_sel_hi:[1,0]
	v_pk_mul_f32 v[52:53], v[52:53], v[76:77] op_sel_hi:[1,0]
	v_cmp_gt_f32_e32 vcc, s61, v72
	s_waitcnt vmcnt(1)
	v_pk_mul_f32 v[48:49], v[64:65], v[56:57]
	v_pk_mul_f32 v[50:51], v[66:67], v[58:59]
	s_waitcnt vmcnt(0)
	v_pk_mul_f32 v[56:57], v[68:69], v[80:81]
	v_pk_mul_f32 v[58:59], v[70:71], v[78:79]
	global_store_dwordx4 v[74:75], v[48:51], off
	global_store_dwordx4 v[74:75], v[56:59], off offset:16
	global_load_dwordx4 v[48:51], v[12:13], off offset:512
	s_nop 0
	global_load_dwordx4 v[56:59], v[12:13], off offset:528
	s_waitcnt vmcnt(1)
	v_pk_mul_f32 v[48:49], v[48:49], v[60:61]
	v_pk_mul_f32 v[50:51], v[50:51], v[62:63]
	s_waitcnt vmcnt(0)
	v_pk_mul_f32 v[52:53], v[56:57], v[52:53]
	v_pk_mul_f32 v[54:55], v[58:59], v[54:55]
	global_store_dwordx4 v[74:75], v[48:51], off offset:512
	global_store_dwordx4 v[74:75], v[52:55], off offset:528
	global_load_dwordx4 v[48:51], v[12:13], off
	s_nop 0
	global_load_dwordx4 v[52:55], v[12:13], off offset:16
	v_mul_f32_e32 v56, 0x4b800000, v72
	v_cndmask_b32_e32 v56, v72, v56, vcc
	v_rsq_f32_e32 v58, v56
	v_lshlrev_b64 v[56:57], 12, v[206:207]
	v_lshl_add_u64 v[56:57], s[8:9], 0, v[56:57]
	v_lshl_add_u64 v[56:57], v[56:57], 0, v[14:15]
	v_mul_f32_e32 v59, 0x45800000, v58
	v_cndmask_b32_e32 v58, v58, v59, vcc
	v_pk_mul_f32 v[42:43], v[42:43], v[58:59] op_sel_hi:[1,0]
	v_pk_mul_f32 v[40:41], v[40:41], v[58:59] op_sel_hi:[1,0]
	v_pk_mul_f32 v[60:61], v[34:35], v[58:59] op_sel_hi:[1,0]
	v_pk_mul_f32 v[62:63], v[32:33], v[58:59] op_sel_hi:[1,0]
	v_pk_mul_f32 v[46:47], v[46:47], v[58:59] op_sel_hi:[1,0]
	v_pk_mul_f32 v[44:45], v[44:45], v[58:59] op_sel_hi:[1,0]
	v_pk_mul_f32 v[38:39], v[38:39], v[58:59] op_sel_hi:[1,0]
	v_pk_mul_f32 v[36:37], v[36:37], v[58:59] op_sel_hi:[1,0]
	s_waitcnt vmcnt(1)
	v_pk_mul_f32 v[32:33], v[48:49], v[40:41]
	v_pk_mul_f32 v[34:35], v[50:51], v[42:43]
	s_waitcnt vmcnt(0)
	v_pk_mul_f32 v[40:41], v[52:53], v[62:63]
	v_pk_mul_f32 v[42:43], v[54:55], v[60:61]
	global_store_dwordx4 v[56:57], v[32:35], off
	global_store_dwordx4 v[56:57], v[40:43], off offset:16
	global_load_dwordx4 v[32:35], v[12:13], off offset:512
	s_nop 0
	global_load_dwordx4 v[40:43], v[12:13], off offset:528
	s_waitcnt vmcnt(1)
	v_pk_mul_f32 v[32:33], v[32:33], v[44:45]
	v_pk_mul_f32 v[34:35], v[34:35], v[46:47]
	s_waitcnt vmcnt(0)
	v_pk_mul_f32 v[36:37], v[40:41], v[36:37]
	v_pk_mul_f32 v[38:39], v[42:43], v[38:39]
	global_store_dwordx4 v[56:57], v[32:35], off offset:512
	global_store_dwordx4 v[56:57], v[36:39], off offset:528
	global_load_dwordx4 v[32:35], v[12:13], off
	s_nop 0
	global_load_dwordx4 v[36:39], v[12:13], off offset:16
	v_mov_b32_e32 v40, v130
	v_mov_b32_e32 v41, v126
	v_mov_b32_e32 v126, v131
	v_mov_b32_e32 v42, v128
	v_mov_b32_e32 v43, v124
	v_mov_b32_e32 v124, v129
	v_pk_add_f32 v[40:41], v[40:41], v[126:127]
	v_pk_add_f32 v[42:43], v[42:43], v[124:125]
	s_nop 0
	v_pk_add_f32 v[40:41], v[40:41], v[42:43]
	ds_bpermute_b32 v43, v232, v41
	ds_bpermute_b32 v42, v232, v40
	s_waitcnt lgkmcnt(0)
	v_pk_add_f32 v[40:41], v[40:41], v[42:43]
	ds_bpermute_b32 v43, v233, v41
	ds_bpermute_b32 v42, v233, v40
	s_waitcnt lgkmcnt(0)
	v_pk_add_f32 v[40:41], v[40:41], v[42:43]
	s_nop 0
	v_pk_fma_f32 v[40:41], v[40:41], s[30:31], v[132:133] op_sel_hi:[1,0,0]
	s_nop 0
	v_mul_f32_e32 v42, 0x4b800000, v41
	v_cmp_gt_f32_e32 vcc, s61, v41
	s_nop 1
	v_cndmask_b32_e32 v41, v41, v42, vcc
	v_rsq_f32_e32 v41, v41
	v_lshlrev_b64 v[42:43], 12, v[204:205]
	v_lshl_add_u64 v[42:43], s[8:9], 0, v[42:43]
	v_lshl_add_u64 v[42:43], v[42:43], 0, v[14:15]
	v_mul_f32_e32 v44, 0x45800000, v41
	v_cndmask_b32_e32 v44, v41, v44, vcc
	v_pk_mul_f32 v[26:27], v[26:27], v[44:45] op_sel_hi:[1,0]
	v_pk_mul_f32 v[24:25], v[24:25], v[44:45] op_sel_hi:[1,0]
	v_pk_mul_f32 v[46:47], v[18:19], v[44:45] op_sel_hi:[1,0]
	v_pk_mul_f32 v[48:49], v[16:17], v[44:45] op_sel_hi:[1,0]
	v_pk_mul_f32 v[30:31], v[30:31], v[44:45] op_sel_hi:[1,0]
	v_pk_mul_f32 v[28:29], v[28:29], v[44:45] op_sel_hi:[1,0]
	v_pk_mul_f32 v[22:23], v[22:23], v[44:45] op_sel_hi:[1,0]
	v_pk_mul_f32 v[20:21], v[20:21], v[44:45] op_sel_hi:[1,0]
	v_cmp_gt_f32_e32 vcc, s61, v40
	s_waitcnt vmcnt(1)
	v_pk_mul_f32 v[16:17], v[32:33], v[24:25]
	v_pk_mul_f32 v[18:19], v[34:35], v[26:27]
	s_waitcnt vmcnt(0)
	v_pk_mul_f32 v[24:25], v[36:37], v[48:49]
	v_pk_mul_f32 v[26:27], v[38:39], v[46:47]
	global_store_dwordx4 v[42:43], v[16:19], off
	global_store_dwordx4 v[42:43], v[24:27], off offset:16
	global_load_dwordx4 v[16:19], v[12:13], off offset:512
	s_nop 0
	global_load_dwordx4 v[24:27], v[12:13], off offset:528
	s_waitcnt vmcnt(1)
	v_pk_mul_f32 v[16:17], v[16:17], v[28:29]
	v_pk_mul_f32 v[18:19], v[18:19], v[30:31]
	s_waitcnt vmcnt(0)
	v_pk_mul_f32 v[20:21], v[24:25], v[20:21]
	v_pk_mul_f32 v[22:23], v[26:27], v[22:23]
	global_store_dwordx4 v[42:43], v[16:19], off offset:512
	global_store_dwordx4 v[42:43], v[20:23], off offset:528
	global_load_dwordx4 v[16:19], v[12:13], off
	s_nop 0
	global_load_dwordx4 v[20:23], v[12:13], off offset:16
	v_mul_f32_e32 v24, 0x4b800000, v40
	v_cndmask_b32_e32 v24, v40, v24, vcc
	v_rsq_f32_e32 v26, v24
	v_lshlrev_b64 v[24:25], 12, v[202:203]
	v_lshl_add_u64 v[24:25], s[8:9], 0, v[24:25]
	v_lshl_add_u64 v[24:25], v[24:25], 0, v[14:15]
	v_mul_f32_e32 v14, 0x45800000, v26
	v_cndmask_b32_e32 v26, v26, v14, vcc
	v_pk_mul_f32 v[10:11], v[10:11], v[26:27] op_sel_hi:[1,0]
	v_pk_mul_f32 v[8:9], v[8:9], v[26:27] op_sel_hi:[1,0]
	v_pk_mul_f32 v[28:29], v[120:121], v[26:27] op_sel_hi:[1,0]
	v_pk_mul_f32 v[14:15], v[122:123], v[26:27] op_sel_hi:[1,0]
	v_pk_mul_f32 v[6:7], v[6:7], v[26:27] op_sel_hi:[1,0]
	v_pk_mul_f32 v[4:5], v[4:5], v[26:27] op_sel_hi:[1,0]
	s_and_b64 vcc, exec, s[4:5]
	s_mov_b64 s[4:5], -1
	s_waitcnt vmcnt(1)
	v_pk_mul_f32 v[8:9], v[16:17], v[8:9]
	v_pk_mul_f32 v[10:11], v[18:19], v[10:11]
	s_waitcnt vmcnt(0)
	v_pk_mul_f32 v[14:15], v[20:21], v[14:15]
	v_pk_mul_f32 v[16:17], v[22:23], v[28:29]
	global_store_dwordx4 v[24:25], v[8:11], off
	global_store_dwordx4 v[24:25], v[14:17], off offset:16
	global_load_dwordx4 v[8:11], v[12:13], off offset:512
	s_nop 0
	global_load_dwordx4 v[12:15], v[12:13], off offset:528
	v_pk_mul_f32 v[16:17], v[0:1], v[26:27] op_sel_hi:[1,0]
	v_pk_mul_f32 v[0:1], v[2:3], v[26:27] op_sel_hi:[1,0]
	s_waitcnt vmcnt(1)
	v_pk_mul_f32 v[2:3], v[10:11], v[16:17]
	v_pk_mul_f32 v[0:1], v[8:9], v[0:1]
	s_waitcnt vmcnt(0)
	v_pk_mul_f32 v[4:5], v[12:13], v[4:5]
	v_pk_mul_f32 v[6:7], v[14:15], v[6:7]
	global_store_dwordx4 v[24:25], v[0:3], off offset:512
	global_store_dwordx4 v[24:25], v[4:7], off offset:528
	s_cbranch_vccnz .LBB0_1352
	s_andn2_b64 vcc, exec, s[18:19]
	v_pk_mov_b32 v[112:113], 0, 0
	v_pk_mov_b32 v[114:115], 0, 0
	v_pk_mov_b32 v[116:117], 0, 0
	v_pk_mov_b32 v[118:119], 0, 0
	v_pk_mov_b32 v[104:105], 0, 0
	v_pk_mov_b32 v[106:107], 0, 0
	v_pk_mov_b32 v[96:97], 0, 0
	v_pk_mov_b32 v[98:99], 0, 0
	v_pk_mov_b32 v[88:89], 0, 0
	v_pk_mov_b32 v[90:91], 0, 0
	v_pk_mov_b32 v[80:81], 0, 0
	v_pk_mov_b32 v[82:83], 0, 0
	v_pk_mov_b32 v[72:73], 0, 0
	v_pk_mov_b32 v[74:75], 0, 0
	v_pk_mov_b32 v[64:65], 0, 0
	v_pk_mov_b32 v[66:67], 0, 0
	v_pk_mov_b32 v[124:125], 0, 0
	v_pk_mov_b32 v[126:127], 0, 0
	v_pk_mov_b32 v[120:121], 0, 0
	v_pk_mov_b32 v[122:123], 0, 0
	v_pk_mov_b32 v[108:109], 0, 0
	v_pk_mov_b32 v[110:111], 0, 0
	v_pk_mov_b32 v[100:101], 0, 0
	v_pk_mov_b32 v[102:103], 0, 0
	v_pk_mov_b32 v[92:93], 0, 0
	v_pk_mov_b32 v[94:95], 0, 0
	v_pk_mov_b32 v[84:85], 0, 0
	v_pk_mov_b32 v[86:87], 0, 0
	v_pk_mov_b32 v[76:77], 0, 0
	v_pk_mov_b32 v[78:79], 0, 0
	v_pk_mov_b32 v[68:69], 0, 0
	v_pk_mov_b32 v[70:71], 0, 0
	v_pk_mov_b32 v[56:57], 0, 0
	v_pk_mov_b32 v[58:59], 0, 0
	v_pk_mov_b32 v[48:49], 0, 0
	v_pk_mov_b32 v[50:51], 0, 0
	v_pk_mov_b32 v[40:41], 0, 0
	v_pk_mov_b32 v[42:43], 0, 0
	v_pk_mov_b32 v[32:33], 0, 0
	v_pk_mov_b32 v[34:35], 0, 0
	v_pk_mov_b32 v[24:25], 0, 0
	v_pk_mov_b32 v[26:27], 0, 0
	v_pk_mov_b32 v[16:17], 0, 0
	v_pk_mov_b32 v[18:19], 0, 0
	v_pk_mov_b32 v[8:9], 0, 0
	v_pk_mov_b32 v[10:11], 0, 0
	v_pk_mov_b32 v[0:1], 0, 0
	v_pk_mov_b32 v[2:3], 0, 0
	v_pk_mov_b32 v[60:61], 0, 0
	v_pk_mov_b32 v[62:63], 0, 0
	v_pk_mov_b32 v[52:53], 0, 0
	v_pk_mov_b32 v[54:55], 0, 0
	v_pk_mov_b32 v[44:45], 0, 0
	v_pk_mov_b32 v[46:47], 0, 0
	v_pk_mov_b32 v[36:37], 0, 0
	v_pk_mov_b32 v[38:39], 0, 0
	v_pk_mov_b32 v[28:29], 0, 0
	v_pk_mov_b32 v[30:31], 0, 0
	v_pk_mov_b32 v[20:21], 0, 0
	v_pk_mov_b32 v[22:23], 0, 0
	v_pk_mov_b32 v[12:13], 0, 0
	v_pk_mov_b32 v[14:15], 0, 0
	v_pk_mov_b32 v[4:5], 0, 0
	v_pk_mov_b32 v[6:7], 0, 0
	s_cbranch_vccnz .LBB0_1351
	s_barrier
	s_branch .LBB0_1351

	.amdhsa_kernel _Z6mk_fwd6MkArgs7InvFreq
		.amdhsa_group_segment_fixed_size 0
		.amdhsa_private_segment_fixed_size 0
		.amdhsa_kernarg_size 520
		.amdhsa_user_sgpr_count 2
		.amdhsa_user_sgpr_dispatch_ptr 0
		.amdhsa_user_sgpr_queue_ptr 0
		.amdhsa_user_sgpr_kernarg_segment_ptr 1
		.amdhsa_user_sgpr_dispatch_id 0
		.amdhsa_user_sgpr_kernarg_preload_length 0
		.amdhsa_user_sgpr_kernarg_preload_offset 0
		.amdhsa_user_sgpr_private_segment_size 0
		.amdhsa_uses_dynamic_stack 0
		.amdhsa_enable_private_segment 0
		.amdhsa_system_sgpr_workgroup_id_x 1
		.amdhsa_system_sgpr_workgroup_id_y 0
		.amdhsa_system_sgpr_workgroup_id_z 0
		.amdhsa_system_sgpr_workgroup_info 0
		.amdhsa_system_vgpr_workitem_id 0
		.amdhsa_next_free_vgpr 249
		.amdhsa_next_free_sgpr 102
		.amdhsa_accum_offset 252
		.amdhsa_reserve_vcc 1
		.amdhsa_float_round_mode_32 0
		.amdhsa_float_round_mode_16_64 0
		.amdhsa_float_denorm_mode_32 3
		.amdhsa_float_denorm_mode_16_64 3
		.amdhsa_dx10_clamp 1
		.amdhsa_ieee_mode 1
		.amdhsa_fp16_overflow 0
		.amdhsa_tg_split 0
		.amdhsa_exception_fp_ieee_invalid_op 0
		.amdhsa_exception_fp_denorm_src 0
		.amdhsa_exception_fp_ieee_div_zero 0
		.amdhsa_exception_fp_ieee_overflow 0
		.amdhsa_exception_fp_ieee_underflow 0
		.amdhsa_exception_fp_ieee_inexact 0
		.amdhsa_exception_int_div_zero 0
	.end_amdhsa_kernel

amdhsa.kernels:
  - .agpr_count:     0
    .args:
      - .offset:         0
        .size:           200
        .value_kind:     by_value
      - .offset:         200
        .size:           64
        .value_kind:     by_value
      - .offset:         264
        .size:           4
        .value_kind:     hidden_block_count_x
      - .offset:         268
        .size:           4
        .value_kind:     hidden_block_count_y
      - .offset:         272
        .size:           4
        .value_kind:     hidden_block_count_z
      - .offset:         276
        .size:           2
        .value_kind:     hidden_group_size_x
      - .offset:         278
        .size:           2
        .value_kind:     hidden_group_size_y
      - .offset:         280
        .size:           2
        .value_kind:     hidden_group_size_z
      - .offset:         282
        .size:           2
        .value_kind:     hidden_remainder_x
      - .offset:         284
        .size:           2
        .value_kind:     hidden_remainder_y
      - .offset:         286
        .size:           2
        .value_kind:     hidden_remainder_z
      - .offset:         304
        .size:           8
        .value_kind:     hidden_global_offset_x
      - .offset:         312
        .size:           8
        .value_kind:     hidden_global_offset_y
      - .offset:         320
        .size:           8
        .value_kind:     hidden_global_offset_z
      - .offset:         328
        .size:           2
        .value_kind:     hidden_grid_dims
      - .offset:         384
        .size:           4
        .value_kind:     hidden_dynamic_lds_size
    .group_segment_fixed_size: 0
    .kernarg_segment_align: 8
    .kernarg_segment_size: 520
    .language:       OpenCL C
    .language_version:
      - 2
      - 0
    .max_flat_workgroup_size: 512
    .name:           _Z6mk_fwd6MkArgs7InvFreq
    .private_segment_fixed_size: 0
    .sgpr_count:     108
    .sgpr_spill_count: 62
    .symbol:         _Z6mk_fwd6MkArgs7InvFreq.kd
    .uniform_work_group_size: 1
    .uses_dynamic_stack: false
    .vgpr_count:     249
    .vgpr_spill_count: 0
    .wavefront_size: 64
